# v21 plus s_setprio 0 issued before (not after) the barrier that ends each GEMM MFMA block (64 sites)
# speedup vs baseline: 1.0025x; 1.0016x over previous
;     __device__ __forceinline__ bool next(int i, Unit& u) const { if (i != 0 || !valid) return false; u.pm = pm; u.pn = pn; return true; }
; #define PG8_STAGE(bufoff, gbase, voff) do { _Pragma("unroll") for (int _i = 0; _i < 2; ++_i) \
;         __builtin_amdgcn_global_load_lds((const unsigned*)((const char*)(gbase) + (voff)[_i]), (LAS unsigned*)(lds + (bufoff) + ldsw + _i * 8192), 16, 0, 0); } while (0)
; #define PG8_LDA(dst, b, h) do { _Pragma("unroll") for (int m = 0; m < 4; ++m) _Pragma("unroll") for (int k = 0; k < 2; ++k) dst[m][k] = *(const LAS half8*)(lds + PG8_SA(b, h) + aoff + m * 2048 + k * 1024); } while (0)
; #define PG8_LDB(dst, b, h) do { _Pragma("unroll") for (int n = 0; n < 2; ++n) _Pragma("unroll") for (int k = 0; k < 2; ++k) dst[n][k] = *(const LAS half8*)(lds + PG8_SB(b, h) + boff + n * 2048 + k * 1024); } while (0)
; #define PG8_WAIT_V(n) asm volatile("s_waitcnt vmcnt(" #n ")" ::: "memory")
; #define PG8_WAIT_L(n) asm volatile("s_waitcnt lgkmcnt(" #n ")" ::: "memory")
; template <class Epi, class Sched, bool ALIGN_EPI = false, bool SP2 = false>
; __device__ __forceinline__ void gemm_phase(LAS unsigned char* lds, const Gemm g, const Sched& S, const Epi& E) {
;     ...
;         const bool has_next = S.next(ui + 1, nxt);
;         const char* nA = has_next ? (const char*)g.A + (size_t)nxt.pm * tstepA : cA; const char* nB = has_next ? (const char*)g.Bt + (size_t)nxt.pn * tstepB : cB;
;         for (int t = 0; t < nt; t += 2) {
;             const bool last = (t == nt - 2);
;             const char* a1 = cA + (size_t)(t + 1) * kstep;
;             const char* a2 = last ? nA : cA + (size_t)(t + 2) * kstep; const char* b2 = last ? nB : cB + (size_t)(t + 2) * kstep;
;             const char* a3 = a2 + kstep; const char* b3 = b2 + kstep;
;             if (last && has_next) S.a_ready(nxt);
;             if constexpr (SP2) {
;             PG8_LDB(B0, 0, 0); PG8_LDB(B1, 0, 1); PG8_SCHED; PG8_LDA(At, 0, 0); PG8_STAGE(PG8_SA(1, 1), a1 + hstepA, voffA);
;             PG8_WAIT_V(8); PG8_WAIT_L(0); PG8_BAR; PG8_MMA(0, 0, At, B0); PG8_MMA(0, 1, At, B1); PG8_BAR; PG8_SCHED;
;             PG8_LDA(At, 0, 1); PG8_STAGE(PG8_SB(0, 0), b2, voffB); PG8_STAGE(PG8_SB(0, 1), b2 + hstepB, voffB); PG8_STAGE(PG8_SA(0, 0), a2, voffA);
;             PG8_WAIT_V(8); PG8_WAIT_L(0); PG8_BAR; PG8_MMA(1, 0, At, B0); PG8_MMA(1, 1, At, B1); PG8_BAR; PG8_SCHED;
.LBB0_414:
	s_ashr_i32 s13, s12, 31
	s_lshl_b64 s[14:15], s[12:13], 20
	s_add_u32 s14, s34, s14
	s_addc_u32 s15, s35, s15
	s_and_b64 s[44:45], s[8:9], exec
	s_cselect_b32 s13, s15, s17
	s_cselect_b32 s60, s14, s16
	s_ashr_i32 s11, s10, 31
	s_lshl_b64 s[44:45], s[10:11], 20
	s_add_u32 s44, s2, s44
	s_addc_u32 s45, s24, s45
	s_and_b64 s[48:49], s[8:9], exec
	s_cselect_b32 s11, s45, s23
	s_cselect_b32 s61, s44, s22
	s_add_u32 s48, s16, 0x80080
	s_addc_u32 s49, s17, 0
	s_add_u32 s62, s22, 0x100
	v_mov_b32_e32 v4, 0
	s_addc_u32 s63, s23, 0
	s_mov_b32 s64, -2
	s_add_u32 s16, s48, 0xfff80080
	s_addc_u32 s17, s49, -1
	s_add_i32 s65, 0, 0x10000
	s_cmp_eq_u32 s64, 28
	s_cselect_b32 s23, s13, s17
	s_cselect_b32 s22, s60, s16
	s_cselect_b32 s17, s11, s63
	s_cselect_b32 s16, s61, s62
	s_add_i32 s68, 0, 0x14000
	v_add_u32_e32 v158, s65, v144
	v_add_u32_e32 v174, s68, v144
	ds_read_b128 v[146:149], v158
	ds_read_b128 v[150:153], v158 offset:1024
	ds_read_b128 v[154:157], v158 offset:2048
	ds_read_b128 v[158:161], v158 offset:3072
	ds_read_b128 v[162:165], v174
	ds_read_b128 v[166:169], v174 offset:1024
	ds_read_b128 v[170:173], v174 offset:2048
	ds_read_b128 v[174:177], v174 offset:3072
	v_lshl_add_u64 v[208:209], s[48:49], 0, v[140:141]
	s_add_i32 m0, s37, 0xc000
	ds_read_b128 v[178:181], v145
	ds_read_b128 v[182:185], v145 offset:1024
	ds_read_b128 v[186:189], v145 offset:2048
	ds_read_b128 v[190:193], v145 offset:3072
	ds_read_b128 v[194:197], v145 offset:4096
	ds_read_b128 v[204:207], v145 offset:5120
	ds_read_b128 v[220:223], v145 offset:6144
	ds_read_b128 v[224:227], v145 offset:7168
	global_load_lds_dwordx4 v[208:209], off
	v_lshl_add_u64 v[208:209], s[48:49], 0, v[142:143]
	s_add_i32 m0, s37, 0xe000
	s_nop 0
	global_load_lds_dwordx4 v[208:209], off
	s_waitcnt vmcnt(8)
	s_waitcnt lgkmcnt(0)
	s_setprio 1
	s_barrier
	v_mfma_f32_16x16x32_f16 v[128:131], v[146:149], v[178:181], 0
	v_mfma_f32_16x16x32_f16 v[124:127], v[154:157], v[178:181], 0
	v_mfma_f32_16x16x32_f16 v[120:123], v[146:149], v[186:189], 0
	v_mfma_f32_16x16x32_f16 v[116:119], v[154:157], v[186:189], 0
	v_mfma_f32_16x16x32_f16 v[104:107], v[146:149], v[194:197], 0
	v_mfma_f32_16x16x32_f16 v[100:103], v[154:157], v[194:197], 0
	v_mfma_f32_16x16x32_f16 v[88:91], v[146:149], v[220:223], 0
	v_mfma_f32_16x16x32_f16 v[84:87], v[154:157], v[220:223], 0
	v_mfma_f32_16x16x32_f16 v[128:131], v[150:153], v[182:185], v[128:131]
	v_mfma_f32_16x16x32_f16 v[124:127], v[158:161], v[182:185], v[124:127]
	v_mfma_f32_16x16x32_f16 v[120:123], v[150:153], v[190:193], v[120:123]
	v_mfma_f32_16x16x32_f16 v[116:119], v[158:161], v[190:193], v[116:119]
	v_mfma_f32_16x16x32_f16 v[104:107], v[150:153], v[204:207], v[104:107]
	v_mfma_f32_16x16x32_f16 v[100:103], v[158:161], v[204:207], v[100:103]
	v_mfma_f32_16x16x32_f16 v[88:91], v[150:153], v[224:227], v[88:91]
	v_mfma_f32_16x16x32_f16 v[84:87], v[158:161], v[224:227], v[84:87]
	v_mfma_f32_16x16x32_f16 v[112:115], v[162:165], v[178:181], 0
	v_mfma_f32_16x16x32_f16 v[108:111], v[170:173], v[178:181], 0
	v_mfma_f32_16x16x32_f16 v[96:99], v[162:165], v[186:189], 0
	v_mfma_f32_16x16x32_f16 v[92:95], v[170:173], v[186:189], 0
	v_mfma_f32_16x16x32_f16 v[80:83], v[162:165], v[194:197], 0
	v_mfma_f32_16x16x32_f16 v[76:79], v[170:173], v[194:197], 0
	v_mfma_f32_16x16x32_f16 v[72:75], v[162:165], v[220:223], 0
	v_mfma_f32_16x16x32_f16 v[68:71], v[170:173], v[220:223], 0
	v_mfma_f32_16x16x32_f16 v[112:115], v[166:169], v[182:185], v[112:115]
	v_mfma_f32_16x16x32_f16 v[108:111], v[174:177], v[182:185], v[108:111]
	v_mfma_f32_16x16x32_f16 v[96:99], v[166:169], v[190:193], v[96:99]
	v_mfma_f32_16x16x32_f16 v[92:95], v[174:177], v[190:193], v[92:95]
	v_mfma_f32_16x16x32_f16 v[80:83], v[166:169], v[204:207], v[80:83]
	v_mfma_f32_16x16x32_f16 v[76:79], v[174:177], v[204:207], v[76:79]
	v_mfma_f32_16x16x32_f16 v[72:75], v[166:169], v[224:227], v[72:75]
	v_mfma_f32_16x16x32_f16 v[68:71], v[174:177], v[224:227], v[68:71]
	s_setprio 0
	s_barrier
	s_add_i32 s65, s65, s25
	v_lshl_add_u64 v[208:209], s[16:17], 0, v[2:3]
	s_mov_b32 m0, s65
	ds_read_b128 v[178:181], v145 offset:16384
	ds_read_b128 v[182:185], v145 offset:17408
	ds_read_b128 v[186:189], v145 offset:18432
	ds_read_b128 v[190:193], v145 offset:19456
	ds_read_b128 v[194:197], v145 offset:20480
	ds_read_b128 v[204:207], v145 offset:21504
	ds_read_b128 v[220:223], v145 offset:22528
	ds_read_b128 v[224:227], v145 offset:23552
	global_load_lds_dwordx4 v[208:209], off
	s_add_i32 m0, s65, 0x2000
	s_add_u32 s66, s16, 0x80000
	v_lshl_add_u64 v[228:229], s[16:17], 0, v[132:133]
	s_addc_u32 s67, s17, 0
	s_add_i32 s65, s68, s25
	global_load_lds_dwordx4 v[228:229], off
	v_lshl_add_u64 v[230:231], s[66:67], 0, v[2:3]
	s_mov_b32 m0, s65
	v_lshl_add_u64 v[232:233], s[22:23], 0, v[134:135]
	global_load_lds_dwordx4 v[230:231], off
	v_lshl_add_u64 v[230:231], s[66:67], 0, v[132:133]
	s_add_i32 m0, s65, 0x2000
	s_nop 0
	global_load_lds_dwordx4 v[230:231], off
	v_lshl_add_u64 v[230:231], s[22:23], 0, v[136:137]
	s_mov_b32 m0, s37
	s_nop 0
	global_load_lds_dwordx4 v[230:231], off
	s_mov_b32 m0, s52
	s_nop 0
	global_load_lds_dwordx4 v[232:233], off
	s_waitcnt vmcnt(8)
	s_waitcnt lgkmcnt(0)
	s_setprio 1
	s_barrier
; #define PG8_STAGE(bufoff, gbase, voff) do { _Pragma("unroll") for (int _i = 0; _i < 2; ++_i) \
;         __builtin_amdgcn_global_load_lds((const unsigned*)((const char*)(gbase) + (voff)[_i]), (LAS unsigned*)(lds + (bufoff) + ldsw + _i * 8192), 16, 0, 0); } while (0)
; #define PG8_LDA(dst, b, h) do { _Pragma("unroll") for (int m = 0; m < 4; ++m) _Pragma("unroll") for (int k = 0; k < 2; ++k) dst[m][k] = *(const LAS half8*)(lds + PG8_SA(b, h) + aoff + m * 2048 + k * 1024); } while (0)
; #define PG8_LDB(dst, b, h) do { _Pragma("unroll") for (int n = 0; n < 2; ++n) _Pragma("unroll") for (int k = 0; k < 2; ++k) dst[n][k] = *(const LAS half8*)(lds + PG8_SB(b, h) + boff + n * 2048 + k * 1024); } while (0)
; #define PG8_MMA(ai, bj, At, Bt) do { __builtin_amdgcn_s_setprio(1); _Pragma("unroll") for (int m = 0; m < 4; ++m) _Pragma("unroll") for (int n = 0; n < 2; ++n) _Pragma("unroll") for (int k = 0; k < 2; ++k) \
;         acc[ai][bj][m][n] = __builtin_amdgcn_mfma_f32_16x16x32_f16(Bt[n][k], At[m][k], acc[ai][bj][m][n], 0, 0, 0); __builtin_amdgcn_s_setprio(0); } while (0)
; #define PG8_WAIT_V(n) asm volatile("s_waitcnt vmcnt(" #n ")" ::: "memory")
; #define PG8_WAIT_L(n) asm volatile("s_waitcnt lgkmcnt(" #n ")" ::: "memory")
; #define PG8_BAR __builtin_amdgcn_s_barrier()
; #define PG8_SCHED __builtin_amdgcn_sched_barrier(0)
; template <class Epi, class Sched, bool ALIGN_EPI = false, bool SP2 = false>
; __device__ __forceinline__ void gemm_phase(LAS unsigned char* lds, const Gemm g, const Sched& S, const Epi& E) {
;     ...
;             PG8_WAIT_V(8); PG8_WAIT_L(0); PG8_BAR; PG8_MMA(1, 0, At, B0); PG8_MMA(1, 1, At, B1); PG8_BAR; PG8_SCHED;
;             PG8_LDB(B0, 1, 0); PG8_LDB(B1, 1, 1); PG8_SCHED; PG8_LDA(At, 1, 0); PG8_STAGE(PG8_SA(0, 1), a2 + hstepA, voffA);
;             PG8_WAIT_V(8); PG8_WAIT_L(0); PG8_BAR; PG8_MMA(0, 0, At, B0); PG8_MMA(0, 1, At, B1); PG8_BAR; PG8_SCHED;
	v_mfma_f32_16x16x32_f16 v[64:67], v[146:149], v[178:181], 0
	v_mfma_f32_16x16x32_f16 v[60:63], v[154:157], v[178:181], 0
	v_mfma_f32_16x16x32_f16 v[56:59], v[146:149], v[186:189], 0
	v_mfma_f32_16x16x32_f16 v[52:55], v[154:157], v[186:189], 0
	v_mfma_f32_16x16x32_f16 v[40:43], v[146:149], v[194:197], 0
	v_mfma_f32_16x16x32_f16 v[36:39], v[154:157], v[194:197], 0
	v_mfma_f32_16x16x32_f16 v[24:27], v[146:149], v[220:223], 0
	v_mfma_f32_16x16x32_f16 v[20:23], v[154:157], v[220:223], 0
	v_mfma_f32_16x16x32_f16 v[64:67], v[150:153], v[182:185], v[64:67]
	v_mfma_f32_16x16x32_f16 v[60:63], v[158:161], v[182:185], v[60:63]
	v_mfma_f32_16x16x32_f16 v[56:59], v[150:153], v[190:193], v[56:59]
	v_mfma_f32_16x16x32_f16 v[52:55], v[158:161], v[190:193], v[52:55]
	v_mfma_f32_16x16x32_f16 v[40:43], v[150:153], v[204:207], v[40:43]
	v_mfma_f32_16x16x32_f16 v[36:39], v[158:161], v[204:207], v[36:39]
	v_mfma_f32_16x16x32_f16 v[24:27], v[150:153], v[224:227], v[24:27]
	v_mfma_f32_16x16x32_f16 v[20:23], v[158:161], v[224:227], v[20:23]
	v_mfma_f32_16x16x32_f16 v[48:51], v[162:165], v[178:181], 0
	v_mfma_f32_16x16x32_f16 v[44:47], v[170:173], v[178:181], 0
	v_mfma_f32_16x16x32_f16 v[32:35], v[162:165], v[186:189], 0
	v_mfma_f32_16x16x32_f16 v[28:31], v[170:173], v[186:189], 0
	v_mfma_f32_16x16x32_f16 v[16:19], v[162:165], v[194:197], 0
	v_mfma_f32_16x16x32_f16 v[12:15], v[170:173], v[194:197], 0
	v_mfma_f32_16x16x32_f16 v[8:11], v[162:165], v[220:223], 0
	v_mfma_f32_16x16x32_f16 v[4:7], v[170:173], v[220:223], 0
	v_mfma_f32_16x16x32_f16 v[48:51], v[166:169], v[182:185], v[48:51]
	v_mfma_f32_16x16x32_f16 v[44:47], v[174:177], v[182:185], v[44:47]
	v_mfma_f32_16x16x32_f16 v[32:35], v[166:169], v[190:193], v[32:35]
	v_mfma_f32_16x16x32_f16 v[28:31], v[174:177], v[190:193], v[28:31]
	v_mfma_f32_16x16x32_f16 v[16:19], v[166:169], v[204:207], v[16:19]
	v_mfma_f32_16x16x32_f16 v[12:15], v[174:177], v[204:207], v[12:15]
	v_mfma_f32_16x16x32_f16 v[8:11], v[166:169], v[224:227], v[8:11]
	v_mfma_f32_16x16x32_f16 v[4:7], v[174:177], v[224:227], v[4:7]
	s_setprio 0
	s_barrier
	s_add_i32 s65, 0, 0x18000
	s_add_i32 s66, 0, 0x1c000
	v_add_u32_e32 v158, s65, v144
	v_add_u32_e32 v174, s66, v144
	ds_read_b128 v[146:149], v158
	ds_read_b128 v[150:153], v158 offset:1024
	ds_read_b128 v[154:157], v158 offset:2048
	ds_read_b128 v[158:161], v158 offset:3072
	ds_read_b128 v[162:165], v174
	ds_read_b128 v[166:169], v174 offset:1024
	ds_read_b128 v[170:173], v174 offset:2048
	ds_read_b128 v[174:177], v174 offset:3072
	s_add_u32 s22, s22, 0x80000
	s_addc_u32 s23, s23, 0
	s_mov_b32 m0, s53
	v_lshl_add_u64 v[234:235], s[22:23], 0, v[136:137]
	ds_read_b128 v[178:181], v145 offset:32768
	ds_read_b128 v[182:185], v145 offset:33792
	ds_read_b128 v[186:189], v145 offset:34816
	ds_read_b128 v[190:193], v145 offset:35840
	ds_read_b128 v[194:197], v145 offset:36864
	ds_read_b128 v[204:207], v145 offset:37888
	ds_read_b128 v[220:223], v145 offset:38912
	ds_read_b128 v[224:227], v145 offset:39936
	global_load_lds_dwordx4 v[234:235], off
	v_lshl_add_u64 v[234:235], s[22:23], 0, v[134:135]
	s_mov_b32 m0, s54
	s_nop 0
	global_load_lds_dwordx4 v[234:235], off
	s_waitcnt vmcnt(8)
	s_waitcnt lgkmcnt(0)
	s_setprio 1
	s_barrier
	v_mfma_f32_16x16x32_f16 v[128:131], v[146:149], v[178:181], v[128:131]
	v_mfma_f32_16x16x32_f16 v[124:127], v[154:157], v[178:181], v[124:127]
	v_mfma_f32_16x16x32_f16 v[120:123], v[146:149], v[186:189], v[120:123]
	v_mfma_f32_16x16x32_f16 v[116:119], v[154:157], v[186:189], v[116:119]
	v_mfma_f32_16x16x32_f16 v[104:107], v[146:149], v[194:197], v[104:107]
	v_mfma_f32_16x16x32_f16 v[100:103], v[154:157], v[194:197], v[100:103]
	v_mfma_f32_16x16x32_f16 v[88:91], v[146:149], v[220:223], v[88:91]
	v_mfma_f32_16x16x32_f16 v[84:87], v[154:157], v[220:223], v[84:87]
	v_mfma_f32_16x16x32_f16 v[128:131], v[150:153], v[182:185], v[128:131]
	v_mfma_f32_16x16x32_f16 v[124:127], v[158:161], v[182:185], v[124:127]
	v_mfma_f32_16x16x32_f16 v[120:123], v[150:153], v[190:193], v[120:123]
	v_mfma_f32_16x16x32_f16 v[116:119], v[158:161], v[190:193], v[116:119]
	v_mfma_f32_16x16x32_f16 v[104:107], v[150:153], v[204:207], v[104:107]
	v_mfma_f32_16x16x32_f16 v[100:103], v[158:161], v[204:207], v[100:103]
	v_mfma_f32_16x16x32_f16 v[88:91], v[150:153], v[224:227], v[88:91]
	v_mfma_f32_16x16x32_f16 v[84:87], v[158:161], v[224:227], v[84:87]
	v_mfma_f32_16x16x32_f16 v[112:115], v[162:165], v[178:181], v[112:115]
	v_mfma_f32_16x16x32_f16 v[108:111], v[170:173], v[178:181], v[108:111]
	v_mfma_f32_16x16x32_f16 v[96:99], v[162:165], v[186:189], v[96:99]
	v_mfma_f32_16x16x32_f16 v[92:95], v[170:173], v[186:189], v[92:95]
	v_mfma_f32_16x16x32_f16 v[80:83], v[162:165], v[194:197], v[80:83]
	v_mfma_f32_16x16x32_f16 v[76:79], v[170:173], v[194:197], v[76:79]
	v_mfma_f32_16x16x32_f16 v[72:75], v[162:165], v[220:223], v[72:75]
	v_mfma_f32_16x16x32_f16 v[68:71], v[170:173], v[220:223], v[68:71]
	v_mfma_f32_16x16x32_f16 v[112:115], v[166:169], v[182:185], v[112:115]
	v_mfma_f32_16x16x32_f16 v[108:111], v[174:177], v[182:185], v[108:111]
	v_mfma_f32_16x16x32_f16 v[96:99], v[166:169], v[190:193], v[96:99]
	v_mfma_f32_16x16x32_f16 v[92:95], v[174:177], v[190:193], v[92:95]
	v_mfma_f32_16x16x32_f16 v[80:83], v[166:169], v[204:207], v[80:83]
	v_mfma_f32_16x16x32_f16 v[76:79], v[174:177], v[204:207], v[76:79]
	v_mfma_f32_16x16x32_f16 v[72:75], v[166:169], v[224:227], v[72:75]
	v_mfma_f32_16x16x32_f16 v[68:71], v[174:177], v[224:227], v[68:71]
	s_setprio 0
	s_barrier
; #define PG8_STAGE(bufoff, gbase, voff) do { _Pragma("unroll") for (int _i = 0; _i < 2; ++_i) \
;         __builtin_amdgcn_global_load_lds((const unsigned*)((const char*)(gbase) + (voff)[_i]), (LAS unsigned*)(lds + (bufoff) + ldsw + _i * 8192), 16, 0, 0); } while (0)
; #define PG8_LDA(dst, b, h) do { _Pragma("unroll") for (int m = 0; m < 4; ++m) _Pragma("unroll") for (int k = 0; k < 2; ++k) dst[m][k] = *(const LAS half8*)(lds + PG8_SA(b, h) + aoff + m * 2048 + k * 1024); } while (0)
; #define PG8_LDB(dst, b, h) do { _Pragma("unroll") for (int n = 0; n < 2; ++n) _Pragma("unroll") for (int k = 0; k < 2; ++k) dst[n][k] = *(const LAS half8*)(lds + PG8_SB(b, h) + boff + n * 2048 + k * 1024); } while (0)
; template <class Epi, class Sched, bool ALIGN_EPI = false, bool SP2 = false>
; __device__ __forceinline__ void gemm_phase(LAS unsigned char* lds, const Gemm g, const Sched& S, const Epi& E) {
;     ...
;         for (int t = 0; t < nt; t += 2) {
;             const bool last = (t == nt - 2);
;             const char* a1 = cA + (size_t)(t + 1) * kstep;
;             const char* a2 = last ? nA : cA + (size_t)(t + 2) * kstep; const char* b2 = last ? nB : cB + (size_t)(t + 2) * kstep;
;             const char* a3 = a2 + kstep; const char* b3 = b2 + kstep;
;             if (last && has_next) S.a_ready(nxt);
;             if constexpr (SP2) {
;             PG8_LDB(B0, 0, 0); PG8_LDB(B1, 0, 1); PG8_SCHED; PG8_LDA(At, 0, 0); PG8_STAGE(PG8_SA(1, 1), a1 + hstepA, voffA);
;             PG8_WAIT_V(8); PG8_WAIT_L(0); PG8_BAR; PG8_MMA(0, 0, At, B0); PG8_MMA(0, 1, At, B1); PG8_BAR; PG8_SCHED;
;             PG8_LDA(At, 0, 1); PG8_STAGE(PG8_SB(0, 0), b2, voffB); PG8_STAGE(PG8_SB(0, 1), b2 + hstepB, voffB); PG8_STAGE(PG8_SA(0, 0), a2, voffA);
;             PG8_WAIT_V(8); PG8_WAIT_L(0); PG8_BAR; PG8_MMA(1, 0, At, B0); PG8_MMA(1, 1, At, B1); PG8_BAR; PG8_SCHED;
;             PG8_LDB(B0, 1, 0); PG8_LDB(B1, 1, 1); PG8_SCHED; PG8_LDA(At, 1, 0); PG8_STAGE(PG8_SA(0, 1), a2 + hstepA, voffA);
;             PG8_WAIT_V(8); PG8_WAIT_L(0); PG8_BAR; PG8_MMA(0, 0, At, B0); PG8_MMA(0, 1, At, B1); PG8_BAR; PG8_SCHED;
;             PG8_LDA(At, 1, 1); PG8_STAGE(PG8_SB(1, 0), b3, voffB); PG8_STAGE(PG8_SB(1, 1), b3 + hstepB, voffB); PG8_STAGE(PG8_SA(1, 0), a3, voffA);
;             PG8_WAIT_V(8); PG8_WAIT_L(0); PG8_BAR; PG8_MMA(1, 0, At, B0); PG8_MMA(1, 1, At, B1); PG8_BAR; PG8_SCHED;
	s_add_i32 s22, s65, s25
	v_lshl_add_u64 v[208:209], v[208:209], 0, s[96:97]
	s_mov_b32 m0, s22
	ds_read_b128 v[178:181], v145 offset:49152
	ds_read_b128 v[182:185], v145 offset:50176
	ds_read_b128 v[186:189], v145 offset:51200
	ds_read_b128 v[190:193], v145 offset:52224
	ds_read_b128 v[194:197], v145 offset:53248
	ds_read_b128 v[204:207], v145 offset:54272
	ds_read_b128 v[220:223], v145 offset:55296
	ds_read_b128 v[224:227], v145 offset:56320
	global_load_lds_dwordx4 v[208:209], off
	s_add_i32 m0, s22, 0x2000
	s_add_u32 s16, s16, 0x80080
	v_lshl_add_u64 v[208:209], v[228:229], 0, s[96:97]
	s_addc_u32 s17, s17, 0
	s_add_i32 s22, s66, s25
	global_load_lds_dwordx4 v[208:209], off
	v_lshl_add_u64 v[208:209], s[16:17], 0, v[2:3]
	s_mov_b32 m0, s22
	s_nop 0
	global_load_lds_dwordx4 v[208:209], off
	v_lshl_add_u64 v[208:209], s[16:17], 0, v[132:133]
	s_add_i32 m0, s22, 0x2000
	s_nop 0
	global_load_lds_dwordx4 v[208:209], off
	v_lshl_add_u64 v[208:209], v[230:231], 0, s[96:97]
	s_mov_b32 m0, s55
	s_nop 0
	global_load_lds_dwordx4 v[208:209], off
	v_lshl_add_u64 v[208:209], v[232:233], 0, s[96:97]
	s_mov_b32 m0, s56
	s_nop 0
	global_load_lds_dwordx4 v[208:209], off
	s_waitcnt vmcnt(8)
	s_waitcnt lgkmcnt(0)
	s_setprio 1
	s_barrier
	v_mfma_f32_16x16x32_f16 v[64:67], v[146:149], v[178:181], v[64:67]
	v_mfma_f32_16x16x32_f16 v[60:63], v[154:157], v[178:181], v[60:63]
	v_mfma_f32_16x16x32_f16 v[56:59], v[146:149], v[186:189], v[56:59]
	v_mfma_f32_16x16x32_f16 v[52:55], v[154:157], v[186:189], v[52:55]
	v_mfma_f32_16x16x32_f16 v[40:43], v[146:149], v[194:197], v[40:43]
	v_mfma_f32_16x16x32_f16 v[36:39], v[154:157], v[194:197], v[36:39]
	v_mfma_f32_16x16x32_f16 v[24:27], v[146:149], v[220:223], v[24:27]
	v_mfma_f32_16x16x32_f16 v[20:23], v[154:157], v[220:223], v[20:23]
	v_mfma_f32_16x16x32_f16 v[64:67], v[150:153], v[182:185], v[64:67]
	v_mfma_f32_16x16x32_f16 v[60:63], v[158:161], v[182:185], v[60:63]
	v_mfma_f32_16x16x32_f16 v[56:59], v[150:153], v[190:193], v[56:59]
	v_mfma_f32_16x16x32_f16 v[52:55], v[158:161], v[190:193], v[52:55]
	v_mfma_f32_16x16x32_f16 v[40:43], v[150:153], v[204:207], v[40:43]
	v_mfma_f32_16x16x32_f16 v[36:39], v[158:161], v[204:207], v[36:39]
	v_mfma_f32_16x16x32_f16 v[24:27], v[150:153], v[224:227], v[24:27]
	v_mfma_f32_16x16x32_f16 v[20:23], v[158:161], v[224:227], v[20:23]
	v_mfma_f32_16x16x32_f16 v[48:51], v[162:165], v[178:181], v[48:51]
	v_mfma_f32_16x16x32_f16 v[44:47], v[170:173], v[178:181], v[44:47]
	v_mfma_f32_16x16x32_f16 v[32:35], v[162:165], v[186:189], v[32:35]
	v_mfma_f32_16x16x32_f16 v[28:31], v[170:173], v[186:189], v[28:31]
	v_mfma_f32_16x16x32_f16 v[16:19], v[162:165], v[194:197], v[16:19]
	v_mfma_f32_16x16x32_f16 v[12:15], v[170:173], v[194:197], v[12:15]
	v_mfma_f32_16x16x32_f16 v[8:11], v[162:165], v[220:223], v[8:11]
	v_mfma_f32_16x16x32_f16 v[4:7], v[170:173], v[220:223], v[4:7]
	v_mfma_f32_16x16x32_f16 v[48:51], v[166:169], v[182:185], v[48:51]
	v_mfma_f32_16x16x32_f16 v[44:47], v[174:177], v[182:185], v[44:47]
	v_mfma_f32_16x16x32_f16 v[32:35], v[166:169], v[190:193], v[32:35]
	v_mfma_f32_16x16x32_f16 v[28:31], v[174:177], v[190:193], v[28:31]
	v_mfma_f32_16x16x32_f16 v[16:19], v[166:169], v[204:207], v[16:19]
	v_mfma_f32_16x16x32_f16 v[12:15], v[174:177], v[204:207], v[12:15]
	v_mfma_f32_16x16x32_f16 v[8:11], v[166:169], v[224:227], v[8:11]
	v_mfma_f32_16x16x32_f16 v[4:7], v[174:177], v[224:227], v[4:7]
	s_setprio 0
	s_barrier
	s_add_i32 s64, s64, 2
	s_add_u32 s48, s48, 0x100
	s_addc_u32 s49, s49, 0
	s_add_u32 s62, s62, 0x100
	s_addc_u32 s63, s63, 0
	s_cmp_gt_u32 s64, 29
	s_cbranch_scc0 .LBB0_415
.LBB0_415:
	s_add_u32 s16, s48, 0xfff80080
	s_addc_u32 s17, s49, -1
	s_add_i32 s65, 0, 0x10000
	s_cmp_eq_u32 s64, 28
	s_cselect_b32 s23, s13, s17
	s_cselect_b32 s22, s60, s16
	s_cselect_b32 s17, s11, s63
	s_cselect_b32 s16, s61, s62
	s_add_i32 s68, 0, 0x14000
	v_add_u32_e32 v158, s65, v144
	v_add_u32_e32 v174, s68, v144
	ds_read_b128 v[146:149], v158
	ds_read_b128 v[150:153], v158 offset:1024
	ds_read_b128 v[154:157], v158 offset:2048
	ds_read_b128 v[158:161], v158 offset:3072
	ds_read_b128 v[162:165], v174
	ds_read_b128 v[166:169], v174 offset:1024
	ds_read_b128 v[170:173], v174 offset:2048
	ds_read_b128 v[174:177], v174 offset:3072
	v_lshl_add_u64 v[208:209], s[48:49], 0, v[140:141]
	s_add_i32 m0, s37, 0xc000
	ds_read_b128 v[178:181], v145
	ds_read_b128 v[182:185], v145 offset:1024
	ds_read_b128 v[186:189], v145 offset:2048
	ds_read_b128 v[190:193], v145 offset:3072
	ds_read_b128 v[194:197], v145 offset:4096
	ds_read_b128 v[204:207], v145 offset:5120
	ds_read_b128 v[220:223], v145 offset:6144
	ds_read_b128 v[224:227], v145 offset:7168
	global_load_lds_dwordx4 v[208:209], off
	v_lshl_add_u64 v[208:209], s[48:49], 0, v[142:143]
	s_add_i32 m0, s37, 0xe000
	s_nop 0
	global_load_lds_dwordx4 v[208:209], off
	s_waitcnt vmcnt(8)
	s_waitcnt lgkmcnt(0)
	s_setprio 1
	s_barrier
; #define PG8_STAGE(bufoff, gbase, voff) do { _Pragma("unroll") for (int _i = 0; _i < 2; ++_i) \
;         __builtin_amdgcn_global_load_lds((const unsigned*)((const char*)(gbase) + (voff)[_i]), (LAS unsigned*)(lds + (bufoff) + ldsw + _i * 8192), 16, 0, 0); } while (0)
; #define PG8_LDA(dst, b, h) do { _Pragma("unroll") for (int m = 0; m < 4; ++m) _Pragma("unroll") for (int k = 0; k < 2; ++k) dst[m][k] = *(const LAS half8*)(lds + PG8_SA(b, h) + aoff + m * 2048 + k * 1024); } while (0)
; #define PG8_MMA(ai, bj, At, Bt) do { __builtin_amdgcn_s_setprio(1); _Pragma("unroll") for (int m = 0; m < 4; ++m) _Pragma("unroll") for (int n = 0; n < 2; ++n) _Pragma("unroll") for (int k = 0; k < 2; ++k) \
;         acc[ai][bj][m][n] = __builtin_amdgcn_mfma_f32_16x16x32_f16(Bt[n][k], At[m][k], acc[ai][bj][m][n], 0, 0, 0); __builtin_amdgcn_s_setprio(0); } while (0)
; #define PG8_WAIT_V(n) asm volatile("s_waitcnt vmcnt(" #n ")" ::: "memory")
; #define PG8_WAIT_L(n) asm volatile("s_waitcnt lgkmcnt(" #n ")" ::: "memory")
; #define PG8_BAR __builtin_amdgcn_s_barrier()
; #define PG8_SCHED __builtin_amdgcn_sched_barrier(0)
; template <class Epi, class Sched, bool ALIGN_EPI = false, bool SP2 = false>
; __device__ __forceinline__ void gemm_phase(LAS unsigned char* lds, const Gemm g, const Sched& S, const Epi& E) {
;     ...
;             PG8_WAIT_V(8); PG8_WAIT_L(0); PG8_BAR; PG8_MMA(0, 0, At, B0); PG8_MMA(0, 1, At, B1); PG8_BAR; PG8_SCHED;
;             PG8_LDA(At, 0, 1); PG8_STAGE(PG8_SB(0, 0), b2, voffB); PG8_STAGE(PG8_SB(0, 1), b2 + hstepB, voffB); PG8_STAGE(PG8_SA(0, 0), a2, voffA);
;             PG8_WAIT_V(8); PG8_WAIT_L(0); PG8_BAR; PG8_MMA(1, 0, At, B0); PG8_MMA(1, 1, At, B1); PG8_BAR; PG8_SCHED;
	v_mfma_f32_16x16x32_f16 v[128:131], v[146:149], v[178:181], v[128:131]
	v_mfma_f32_16x16x32_f16 v[124:127], v[154:157], v[178:181], v[124:127]
	v_mfma_f32_16x16x32_f16 v[120:123], v[146:149], v[186:189], v[120:123]
	v_mfma_f32_16x16x32_f16 v[116:119], v[154:157], v[186:189], v[116:119]
	v_mfma_f32_16x16x32_f16 v[104:107], v[146:149], v[194:197], v[104:107]
	v_mfma_f32_16x16x32_f16 v[100:103], v[154:157], v[194:197], v[100:103]
	v_mfma_f32_16x16x32_f16 v[88:91], v[146:149], v[220:223], v[88:91]
	v_mfma_f32_16x16x32_f16 v[84:87], v[154:157], v[220:223], v[84:87]
	v_mfma_f32_16x16x32_f16 v[128:131], v[150:153], v[182:185], v[128:131]
	v_mfma_f32_16x16x32_f16 v[124:127], v[158:161], v[182:185], v[124:127]
	v_mfma_f32_16x16x32_f16 v[120:123], v[150:153], v[190:193], v[120:123]
	v_mfma_f32_16x16x32_f16 v[116:119], v[158:161], v[190:193], v[116:119]
	v_mfma_f32_16x16x32_f16 v[104:107], v[150:153], v[204:207], v[104:107]
	v_mfma_f32_16x16x32_f16 v[100:103], v[158:161], v[204:207], v[100:103]
	v_mfma_f32_16x16x32_f16 v[88:91], v[150:153], v[224:227], v[88:91]
	v_mfma_f32_16x16x32_f16 v[84:87], v[158:161], v[224:227], v[84:87]
	v_mfma_f32_16x16x32_f16 v[112:115], v[162:165], v[178:181], v[112:115]
	v_mfma_f32_16x16x32_f16 v[108:111], v[170:173], v[178:181], v[108:111]
	v_mfma_f32_16x16x32_f16 v[96:99], v[162:165], v[186:189], v[96:99]
	v_mfma_f32_16x16x32_f16 v[92:95], v[170:173], v[186:189], v[92:95]
	v_mfma_f32_16x16x32_f16 v[80:83], v[162:165], v[194:197], v[80:83]
	v_mfma_f32_16x16x32_f16 v[76:79], v[170:173], v[194:197], v[76:79]
	v_mfma_f32_16x16x32_f16 v[72:75], v[162:165], v[220:223], v[72:75]
	v_mfma_f32_16x16x32_f16 v[68:71], v[170:173], v[220:223], v[68:71]
	v_mfma_f32_16x16x32_f16 v[112:115], v[166:169], v[182:185], v[112:115]
	v_mfma_f32_16x16x32_f16 v[108:111], v[174:177], v[182:185], v[108:111]
	v_mfma_f32_16x16x32_f16 v[96:99], v[166:169], v[190:193], v[96:99]
	v_mfma_f32_16x16x32_f16 v[92:95], v[174:177], v[190:193], v[92:95]
	v_mfma_f32_16x16x32_f16 v[80:83], v[166:169], v[204:207], v[80:83]
	v_mfma_f32_16x16x32_f16 v[76:79], v[174:177], v[204:207], v[76:79]
	v_mfma_f32_16x16x32_f16 v[72:75], v[166:169], v[224:227], v[72:75]
	v_mfma_f32_16x16x32_f16 v[68:71], v[174:177], v[224:227], v[68:71]
	s_setprio 0
	s_barrier
	s_add_i32 s65, s65, s25
	v_lshl_add_u64 v[208:209], s[16:17], 0, v[2:3]
	s_mov_b32 m0, s65
	ds_read_b128 v[178:181], v145 offset:16384
	ds_read_b128 v[182:185], v145 offset:17408
	ds_read_b128 v[186:189], v145 offset:18432
	ds_read_b128 v[190:193], v145 offset:19456
	ds_read_b128 v[194:197], v145 offset:20480
	ds_read_b128 v[204:207], v145 offset:21504
	ds_read_b128 v[220:223], v145 offset:22528
	ds_read_b128 v[224:227], v145 offset:23552
	global_load_lds_dwordx4 v[208:209], off
	s_add_i32 m0, s65, 0x2000
	s_add_u32 s66, s16, 0x80000
	v_lshl_add_u64 v[228:229], s[16:17], 0, v[132:133]
	s_addc_u32 s67, s17, 0
	s_add_i32 s65, s68, s25
	global_load_lds_dwordx4 v[228:229], off
	v_lshl_add_u64 v[230:231], s[66:67], 0, v[2:3]
	s_mov_b32 m0, s65
	v_lshl_add_u64 v[232:233], s[22:23], 0, v[134:135]
	global_load_lds_dwordx4 v[230:231], off
	v_lshl_add_u64 v[230:231], s[66:67], 0, v[132:133]
	s_add_i32 m0, s65, 0x2000
	s_nop 0
	global_load_lds_dwordx4 v[230:231], off
	v_lshl_add_u64 v[230:231], s[22:23], 0, v[136:137]
	s_mov_b32 m0, s37
	s_nop 0
	global_load_lds_dwordx4 v[230:231], off
	s_mov_b32 m0, s52
	s_nop 0
	global_load_lds_dwordx4 v[232:233], off
	s_waitcnt vmcnt(8)
	s_waitcnt lgkmcnt(0)
	s_setprio 1
	s_barrier
	v_mfma_f32_16x16x32_f16 v[64:67], v[146:149], v[178:181], v[64:67]
	v_mfma_f32_16x16x32_f16 v[60:63], v[154:157], v[178:181], v[60:63]
	v_mfma_f32_16x16x32_f16 v[56:59], v[146:149], v[186:189], v[56:59]
	v_mfma_f32_16x16x32_f16 v[52:55], v[154:157], v[186:189], v[52:55]
	v_mfma_f32_16x16x32_f16 v[40:43], v[146:149], v[194:197], v[40:43]
	v_mfma_f32_16x16x32_f16 v[36:39], v[154:157], v[194:197], v[36:39]
	v_mfma_f32_16x16x32_f16 v[24:27], v[146:149], v[220:223], v[24:27]
	v_mfma_f32_16x16x32_f16 v[20:23], v[154:157], v[220:223], v[20:23]
	v_mfma_f32_16x16x32_f16 v[64:67], v[150:153], v[182:185], v[64:67]
	v_mfma_f32_16x16x32_f16 v[60:63], v[158:161], v[182:185], v[60:63]
	v_mfma_f32_16x16x32_f16 v[56:59], v[150:153], v[190:193], v[56:59]
	v_mfma_f32_16x16x32_f16 v[52:55], v[158:161], v[190:193], v[52:55]
	v_mfma_f32_16x16x32_f16 v[40:43], v[150:153], v[204:207], v[40:43]
	v_mfma_f32_16x16x32_f16 v[36:39], v[158:161], v[204:207], v[36:39]
	v_mfma_f32_16x16x32_f16 v[24:27], v[150:153], v[224:227], v[24:27]
	v_mfma_f32_16x16x32_f16 v[20:23], v[158:161], v[224:227], v[20:23]
	v_mfma_f32_16x16x32_f16 v[48:51], v[162:165], v[178:181], v[48:51]
	v_mfma_f32_16x16x32_f16 v[44:47], v[170:173], v[178:181], v[44:47]
	v_mfma_f32_16x16x32_f16 v[32:35], v[162:165], v[186:189], v[32:35]
	v_mfma_f32_16x16x32_f16 v[28:31], v[170:173], v[186:189], v[28:31]
	v_mfma_f32_16x16x32_f16 v[16:19], v[162:165], v[194:197], v[16:19]
	v_mfma_f32_16x16x32_f16 v[12:15], v[170:173], v[194:197], v[12:15]
	v_mfma_f32_16x16x32_f16 v[8:11], v[162:165], v[220:223], v[8:11]
	v_mfma_f32_16x16x32_f16 v[4:7], v[170:173], v[220:223], v[4:7]
	v_mfma_f32_16x16x32_f16 v[48:51], v[166:169], v[182:185], v[48:51]
	v_mfma_f32_16x16x32_f16 v[44:47], v[174:177], v[182:185], v[44:47]
	v_mfma_f32_16x16x32_f16 v[32:35], v[166:169], v[190:193], v[32:35]
	v_mfma_f32_16x16x32_f16 v[28:31], v[174:177], v[190:193], v[28:31]
	v_mfma_f32_16x16x32_f16 v[16:19], v[166:169], v[204:207], v[16:19]
	v_mfma_f32_16x16x32_f16 v[12:15], v[174:177], v[204:207], v[12:15]
	v_mfma_f32_16x16x32_f16 v[8:11], v[166:169], v[224:227], v[8:11]
	v_mfma_f32_16x16x32_f16 v[4:7], v[174:177], v[224:227], v[4:7]
	s_setprio 0
	s_barrier
; #define PG8_STAGE(bufoff, gbase, voff) do { _Pragma("unroll") for (int _i = 0; _i < 2; ++_i) \
;         __builtin_amdgcn_global_load_lds((const unsigned*)((const char*)(gbase) + (voff)[_i]), (LAS unsigned*)(lds + (bufoff) + ldsw + _i * 8192), 16, 0, 0); } while (0)
; #define PG8_LDA(dst, b, h) do { _Pragma("unroll") for (int m = 0; m < 4; ++m) _Pragma("unroll") for (int k = 0; k < 2; ++k) dst[m][k] = *(const LAS half8*)(lds + PG8_SA(b, h) + aoff + m * 2048 + k * 1024); } while (0)
; #define PG8_LDB(dst, b, h) do { _Pragma("unroll") for (int n = 0; n < 2; ++n) _Pragma("unroll") for (int k = 0; k < 2; ++k) dst[n][k] = *(const LAS half8*)(lds + PG8_SB(b, h) + boff + n * 2048 + k * 1024); } while (0)
; #define PG8_MMA(ai, bj, At, Bt) do { __builtin_amdgcn_s_setprio(1); _Pragma("unroll") for (int m = 0; m < 4; ++m) _Pragma("unroll") for (int n = 0; n < 2; ++n) _Pragma("unroll") for (int k = 0; k < 2; ++k) \
;         acc[ai][bj][m][n] = __builtin_amdgcn_mfma_f32_16x16x32_f16(Bt[n][k], At[m][k], acc[ai][bj][m][n], 0, 0, 0); __builtin_amdgcn_s_setprio(0); } while (0)
; #define PG8_WAIT_V(n) asm volatile("s_waitcnt vmcnt(" #n ")" ::: "memory")
; #define PG8_WAIT_L(n) asm volatile("s_waitcnt lgkmcnt(" #n ")" ::: "memory")
; #define PG8_BAR __builtin_amdgcn_s_barrier()
; #define PG8_SCHED __builtin_amdgcn_sched_barrier(0)
; template <class Epi, class Sched, bool ALIGN_EPI = false, bool SP2 = false>
; __device__ __forceinline__ void gemm_phase(LAS unsigned char* lds, const Gemm g, const Sched& S, const Epi& E) {
;     ...
;             PG8_LDB(B0, 1, 0); PG8_LDB(B1, 1, 1); PG8_SCHED; PG8_LDA(At, 1, 0); PG8_STAGE(PG8_SA(0, 1), a2 + hstepA, voffA);
;             PG8_WAIT_V(8); PG8_WAIT_L(0); PG8_BAR; PG8_MMA(0, 0, At, B0); PG8_MMA(0, 1, At, B1); PG8_BAR; PG8_SCHED;
	s_add_i32 s65, 0, 0x18000
	s_add_i32 s66, 0, 0x1c000
	v_add_u32_e32 v158, s65, v144
	v_add_u32_e32 v174, s66, v144
	ds_read_b128 v[146:149], v158
	ds_read_b128 v[150:153], v158 offset:1024
	ds_read_b128 v[154:157], v158 offset:2048
	ds_read_b128 v[158:161], v158 offset:3072
	ds_read_b128 v[162:165], v174
	ds_read_b128 v[166:169], v174 offset:1024
	ds_read_b128 v[170:173], v174 offset:2048
	ds_read_b128 v[174:177], v174 offset:3072
	s_add_u32 s22, s22, 0x80000
	s_addc_u32 s23, s23, 0
	s_mov_b32 m0, s53
	v_lshl_add_u64 v[234:235], s[22:23], 0, v[136:137]
	ds_read_b128 v[178:181], v145 offset:32768
	ds_read_b128 v[182:185], v145 offset:33792
	ds_read_b128 v[186:189], v145 offset:34816
	ds_read_b128 v[190:193], v145 offset:35840
	ds_read_b128 v[194:197], v145 offset:36864
	ds_read_b128 v[204:207], v145 offset:37888
	ds_read_b128 v[220:223], v145 offset:38912
	ds_read_b128 v[224:227], v145 offset:39936
	global_load_lds_dwordx4 v[234:235], off
	v_lshl_add_u64 v[234:235], s[22:23], 0, v[134:135]
	s_mov_b32 m0, s54
	s_nop 0
	global_load_lds_dwordx4 v[234:235], off
	s_waitcnt vmcnt(8)
	s_waitcnt lgkmcnt(0)
	s_setprio 1
	s_barrier
	v_mfma_f32_16x16x32_f16 v[128:131], v[146:149], v[178:181], v[128:131]
	v_mfma_f32_16x16x32_f16 v[124:127], v[154:157], v[178:181], v[124:127]
	v_mfma_f32_16x16x32_f16 v[120:123], v[146:149], v[186:189], v[120:123]
	v_mfma_f32_16x16x32_f16 v[116:119], v[154:157], v[186:189], v[116:119]
	v_mfma_f32_16x16x32_f16 v[104:107], v[146:149], v[194:197], v[104:107]
	v_mfma_f32_16x16x32_f16 v[100:103], v[154:157], v[194:197], v[100:103]
	v_mfma_f32_16x16x32_f16 v[88:91], v[146:149], v[220:223], v[88:91]
	v_mfma_f32_16x16x32_f16 v[84:87], v[154:157], v[220:223], v[84:87]
	v_mfma_f32_16x16x32_f16 v[128:131], v[150:153], v[182:185], v[128:131]
	v_mfma_f32_16x16x32_f16 v[124:127], v[158:161], v[182:185], v[124:127]
	v_mfma_f32_16x16x32_f16 v[120:123], v[150:153], v[190:193], v[120:123]
	v_mfma_f32_16x16x32_f16 v[116:119], v[158:161], v[190:193], v[116:119]
	v_mfma_f32_16x16x32_f16 v[104:107], v[150:153], v[204:207], v[104:107]
	v_mfma_f32_16x16x32_f16 v[100:103], v[158:161], v[204:207], v[100:103]
	v_mfma_f32_16x16x32_f16 v[88:91], v[150:153], v[224:227], v[88:91]
	v_mfma_f32_16x16x32_f16 v[84:87], v[158:161], v[224:227], v[84:87]
	v_mfma_f32_16x16x32_f16 v[112:115], v[162:165], v[178:181], v[112:115]
	v_mfma_f32_16x16x32_f16 v[108:111], v[170:173], v[178:181], v[108:111]
	v_mfma_f32_16x16x32_f16 v[96:99], v[162:165], v[186:189], v[96:99]
	v_mfma_f32_16x16x32_f16 v[92:95], v[170:173], v[186:189], v[92:95]
	v_mfma_f32_16x16x32_f16 v[80:83], v[162:165], v[194:197], v[80:83]
	v_mfma_f32_16x16x32_f16 v[76:79], v[170:173], v[194:197], v[76:79]
	v_mfma_f32_16x16x32_f16 v[72:75], v[162:165], v[220:223], v[72:75]
	v_mfma_f32_16x16x32_f16 v[68:71], v[170:173], v[220:223], v[68:71]
	v_mfma_f32_16x16x32_f16 v[112:115], v[166:169], v[182:185], v[112:115]
	v_mfma_f32_16x16x32_f16 v[108:111], v[174:177], v[182:185], v[108:111]
	v_mfma_f32_16x16x32_f16 v[96:99], v[166:169], v[190:193], v[96:99]
	v_mfma_f32_16x16x32_f16 v[92:95], v[174:177], v[190:193], v[92:95]
	v_mfma_f32_16x16x32_f16 v[80:83], v[166:169], v[204:207], v[80:83]
	v_mfma_f32_16x16x32_f16 v[76:79], v[174:177], v[204:207], v[76:79]
	v_mfma_f32_16x16x32_f16 v[72:75], v[166:169], v[224:227], v[72:75]
	v_mfma_f32_16x16x32_f16 v[68:71], v[174:177], v[224:227], v[68:71]
	s_setprio 0
	s_barrier
; #define PG8_STAGE(bufoff, gbase, voff) do { _Pragma("unroll") for (int _i = 0; _i < 2; ++_i) \
;         __builtin_amdgcn_global_load_lds((const unsigned*)((const char*)(gbase) + (voff)[_i]), (LAS unsigned*)(lds + (bufoff) + ldsw + _i * 8192), 16, 0, 0); } while (0)
; #define PG8_LDA(dst, b, h) do { _Pragma("unroll") for (int m = 0; m < 4; ++m) _Pragma("unroll") for (int k = 0; k < 2; ++k) dst[m][k] = *(const LAS half8*)(lds + PG8_SA(b, h) + aoff + m * 2048 + k * 1024); } while (0)
; #define PG8_MMA(ai, bj, At, Bt) do { __builtin_amdgcn_s_setprio(1); _Pragma("unroll") for (int m = 0; m < 4; ++m) _Pragma("unroll") for (int n = 0; n < 2; ++n) _Pragma("unroll") for (int k = 0; k < 2; ++k) \
;         acc[ai][bj][m][n] = __builtin_amdgcn_mfma_f32_16x16x32_f16(Bt[n][k], At[m][k], acc[ai][bj][m][n], 0, 0, 0); __builtin_amdgcn_s_setprio(0); } while (0)
; #define PG8_WAIT_V(n) asm volatile("s_waitcnt vmcnt(" #n ")" ::: "memory")
; #define PG8_WAIT_L(n) asm volatile("s_waitcnt lgkmcnt(" #n ")" ::: "memory")
; #define PG8_BAR __builtin_amdgcn_s_barrier()
; #define PG8_SCHED __builtin_amdgcn_sched_barrier(0)
; template <class Epi, class Sched, bool ALIGN_EPI = false, bool SP2 = false>
; __device__ __forceinline__ void gemm_phase(LAS unsigned char* lds, const Gemm g, const Sched& S, const Epi& E) {
;     ...
;             PG8_LDA(At, 1, 1); PG8_STAGE(PG8_SB(1, 0), b3, voffB); PG8_STAGE(PG8_SB(1, 1), b3 + hstepB, voffB); PG8_STAGE(PG8_SA(1, 0), a3, voffA);
;             PG8_WAIT_V(8); PG8_WAIT_L(0); PG8_BAR; PG8_MMA(1, 0, At, B0); PG8_MMA(1, 1, At, B1); PG8_BAR; PG8_SCHED;
;     ...
;         if constexpr (ALIGN_EPI) { if (wr == 0) PG8_BAR; }
	s_add_i32 s22, s65, s25
	v_lshl_add_u64 v[208:209], v[208:209], 0, s[96:97]
	s_mov_b32 m0, s22
	ds_read_b128 v[178:181], v145 offset:49152
	ds_read_b128 v[182:185], v145 offset:50176
	ds_read_b128 v[186:189], v145 offset:51200
	ds_read_b128 v[190:193], v145 offset:52224
	ds_read_b128 v[194:197], v145 offset:53248
	ds_read_b128 v[204:207], v145 offset:54272
	ds_read_b128 v[220:223], v145 offset:55296
	ds_read_b128 v[224:227], v145 offset:56320
	global_load_lds_dwordx4 v[208:209], off
	s_add_i32 m0, s22, 0x2000
	s_add_u32 s16, s16, 0x80080
	v_lshl_add_u64 v[208:209], v[228:229], 0, s[96:97]
	s_addc_u32 s17, s17, 0
	s_add_i32 s22, s66, s25
	global_load_lds_dwordx4 v[208:209], off
	v_lshl_add_u64 v[208:209], s[16:17], 0, v[2:3]
	s_mov_b32 m0, s22
	s_nop 0
	global_load_lds_dwordx4 v[208:209], off
	v_lshl_add_u64 v[208:209], s[16:17], 0, v[132:133]
	s_add_i32 m0, s22, 0x2000
	s_nop 0
	global_load_lds_dwordx4 v[208:209], off
	v_lshl_add_u64 v[208:209], v[230:231], 0, s[96:97]
	s_mov_b32 m0, s55
	s_nop 0
	global_load_lds_dwordx4 v[208:209], off
	v_lshl_add_u64 v[208:209], v[232:233], 0, s[96:97]
	s_mov_b32 m0, s56
	s_nop 0
	global_load_lds_dwordx4 v[208:209], off
	s_waitcnt vmcnt(8)
	s_waitcnt lgkmcnt(0)
	s_setprio 1
	s_barrier
	v_mfma_f32_16x16x32_f16 v[64:67], v[146:149], v[178:181], v[64:67]
	v_mfma_f32_16x16x32_f16 v[60:63], v[154:157], v[178:181], v[60:63]
	v_mfma_f32_16x16x32_f16 v[56:59], v[146:149], v[186:189], v[56:59]
	v_mfma_f32_16x16x32_f16 v[52:55], v[154:157], v[186:189], v[52:55]
	v_mfma_f32_16x16x32_f16 v[40:43], v[146:149], v[194:197], v[40:43]
	v_mfma_f32_16x16x32_f16 v[36:39], v[154:157], v[194:197], v[36:39]
	v_mfma_f32_16x16x32_f16 v[24:27], v[146:149], v[220:223], v[24:27]
	v_mfma_f32_16x16x32_f16 v[20:23], v[154:157], v[220:223], v[20:23]
	v_mfma_f32_16x16x32_f16 v[64:67], v[150:153], v[182:185], v[64:67]
	v_mfma_f32_16x16x32_f16 v[60:63], v[158:161], v[182:185], v[60:63]
	v_mfma_f32_16x16x32_f16 v[56:59], v[150:153], v[190:193], v[56:59]
	v_mfma_f32_16x16x32_f16 v[52:55], v[158:161], v[190:193], v[52:55]
	v_mfma_f32_16x16x32_f16 v[40:43], v[150:153], v[204:207], v[40:43]
	v_mfma_f32_16x16x32_f16 v[36:39], v[158:161], v[204:207], v[36:39]
	v_mfma_f32_16x16x32_f16 v[24:27], v[150:153], v[224:227], v[24:27]
	v_mfma_f32_16x16x32_f16 v[20:23], v[158:161], v[224:227], v[20:23]
	v_mfma_f32_16x16x32_f16 v[48:51], v[162:165], v[178:181], v[48:51]
	v_mfma_f32_16x16x32_f16 v[44:47], v[170:173], v[178:181], v[44:47]
	v_mfma_f32_16x16x32_f16 v[32:35], v[162:165], v[186:189], v[32:35]
	v_mfma_f32_16x16x32_f16 v[28:31], v[170:173], v[186:189], v[28:31]
	v_mfma_f32_16x16x32_f16 v[16:19], v[162:165], v[194:197], v[16:19]
	v_mfma_f32_16x16x32_f16 v[12:15], v[170:173], v[194:197], v[12:15]
	v_mfma_f32_16x16x32_f16 v[8:11], v[162:165], v[220:223], v[8:11]
	v_mfma_f32_16x16x32_f16 v[4:7], v[170:173], v[220:223], v[4:7]
	v_mfma_f32_16x16x32_f16 v[48:51], v[166:169], v[182:185], v[48:51]
	v_mfma_f32_16x16x32_f16 v[44:47], v[174:177], v[182:185], v[44:47]
	v_mfma_f32_16x16x32_f16 v[32:35], v[166:169], v[190:193], v[32:35]
	v_mfma_f32_16x16x32_f16 v[28:31], v[174:177], v[190:193], v[28:31]
	v_mfma_f32_16x16x32_f16 v[16:19], v[166:169], v[204:207], v[16:19]
	v_mfma_f32_16x16x32_f16 v[12:15], v[174:177], v[204:207], v[12:15]
	v_mfma_f32_16x16x32_f16 v[8:11], v[166:169], v[224:227], v[8:11]
	v_mfma_f32_16x16x32_f16 v[4:7], v[174:177], v[224:227], v[4:7]
	s_setprio 0
	s_barrier
	s_add_i32 s64, s64, 2
	s_add_u32 s48, s48, 0x100
	s_addc_u32 s49, s49, 0
	s_add_u32 s62, s62, 0x100
	s_addc_u32 s63, s63, 0
	s_cmp_gt_u32 s64, 29
	s_cbranch_scc0 .LBB0_415
	s_and_b64 vcc, exec, s[6:7]
	s_cbranch_vccz .LBB0_418
	s_barrier

; #define PG8_WAIT_V(n) asm volatile("s_waitcnt vmcnt(" #n ")" ::: "memory")
; template <class Epi, class Sched, bool ALIGN_EPI = false, bool SP2 = false>
; __device__ __forceinline__ void gemm_phase(LAS unsigned char* lds, const Gemm g, const Sched& S, const Epi& E) {
;     ...
;     for (int i = 0; i < 2; ++i) { int R, C; stage_rc(tid * 16 + i * 8192, R, C); const int Rb = Epi::PERM ? ((R & ~31) + perm32(R & 31)) : R;
;         voffA[i] = (unsigned)(R * lda + C) * 2u; voffB[i] = (unsigned)(Rb * ldb + C) * 2u; }
;     const size_t kstep = (size_t)(BK * 2);
;     const size_t hstepA = (size_t)HALF * lda * 2, hstepB = (size_t)HALF * ldb * 2;
;     const size_t tstepA = 2 * hstepA, tstepB = 2 * hstepB;
;     const unsigned ldsw = (unsigned)wid * 1024u;
;     const int aoff = lds_byte(wr * 64 + fr, fq * 8), boff = lds_byte(wc * 32 + fr, fq * 8);
;     ...
;         PG8_STAGE(PG8_SB(0, 0), cB, voffB); PG8_STAGE(PG8_SB(0, 1), cB + hstepB, voffB); PG8_STAGE(PG8_SA(0, 0), cA, voffA); PG8_STAGE(PG8_SA(0, 1), cA + hstepA, voffA);
;         if (wr == 1) PG8_BAR;
;         PG8_WAIT_V(2); PG8_BAR;
;         PG8_STAGE(PG8_SB(1, 0), cB + kstep, voffB); PG8_STAGE(PG8_SA(1, 0), cA + kstep, voffA); PG8_STAGE(PG8_SB(1, 1), cB + hstepB + kstep, voffB);
;         PG8_WAIT_V(6); PG8_BAR;
;     } else {
;         PG8_STAGE(PG8_SB(0, 0), cB, voffB); PG8_STAGE(PG8_SA(0, 0), cA, voffA); PG8_STAGE(PG8_SB(0, 1), cB + hstepB, voffB); PG8_STAGE(PG8_SA(0, 1), cA + hstepA, voffA);
;         if (wr == 1) PG8_BAR;
;         PG8_WAIT_V(4); PG8_BAR;
;         PG8_STAGE(PG8_SB(1, 0), cB + kstep, voffB); PG8_STAGE(PG8_SA(1, 0), cA + kstep, voffA); PG8_STAGE(PG8_SB(1, 1), cB + hstepB + kstep, voffB);
;         PG8_WAIT_V(6); PG8_BAR;
;     }
;     for (;;) {
;         const bool has_next = S.next(ui + 1, nxt);
;         const char* nA = has_next ? (const char*)g.A + (size_t)nxt.pm * tstepA : cA; const char* nB = has_next ? (const char*)g.Bt + (size_t)nxt.pn * tstepB : cB;
;         for (int t = 0; t < nt; t += 2) {
;             const bool last = (t == nt - 2);
;             const char* a1 = cA + (size_t)(t + 1) * kstep;
;             const char* a2 = last ? nA : cA + (size_t)(t + 2) * kstep; const char* b2 = last ? nB : cB + (size_t)(t + 2) * kstep;
;             const char* a3 = a2 + kstep; const char* b3 = b2 + kstep;
;             if (last && has_next) S.a_ready(nxt);
;             if constexpr (SP2) {
.LBB0_425:
	v_lshrrev_b32_e32 v1, 1, v11
	v_and_b32_e32 v15, 15, v11
	v_and_b32_e32 v1, 24, v1
	v_lshl_or_b32 v132, s6, 6, v15
	v_lshlrev_b32_e32 v16, 1, v1
	v_lshlrev_b32_e32 v15, 6, v15
	v_lshlrev_b32_e32 v11, 2, v11
	v_or_b32_e32 v17, v15, v16
	s_lshl_b32 s6, s6, 13
	v_and_b32_e32 v11, 32, v11
	v_bitop3_b32 v15, v15, v11, v16 bitop3:0x36
	v_bitop3_b32 v11, v17, s6, v11 bitop3:0xde
	s_lshl_b32 s6, s2, 12
	s_and_b32 s6, s6, 0x3000
	v_or_b32_e32 v133, s6, v15
	v_readlane_b32 s6, v255, 32
	v_readlane_b32 s7, v255, 33
	s_lshl_b64 s[6:7], s[6:7], 22
	v_readlane_b32 s8, v254, 35
	s_add_u32 s22, s8, s6
	s_addc_u32 s23, 0, s7
	s_add_i32 m0, s14, 0x18000
	v_lshl_add_u64 v[4:5], v[4:5], 0, s[96:97]
	v_readlane_b32 s6, v251, 33
	v_mov_b32_e32 v139, v3
	s_waitcnt vmcnt(2)
	s_barrier
	global_load_lds_dwordx4 v[4:5], off
	v_lshl_add_u64 v[4:5], v[6:7], 0, s[96:97]
	s_add_i32 m0, s14, 0x1a000
	v_readlane_b32 s7, v251, 34
	s_add_i32 s24, s14, 0x8000
	v_mov_b32_e32 v137, v3
	global_load_lds_dwordx4 v[4:5], off
	v_lshl_add_u64 v[4:5], s[6:7], 0, v[138:139]
	s_mov_b32 m0, s24
	s_add_i32 s25, s14, 0xa000
	global_load_lds_dwordx4 v[4:5], off
	v_lshl_add_u64 v[4:5], s[6:7], 0, v[136:137]
	s_add_u32 s6, s0, 0x80080
	s_mov_b32 m0, s25
	s_addc_u32 s7, s1, 0
	global_load_lds_dwordx4 v[4:5], off
	s_add_i32 m0, s14, 0x1c000
	v_lshl_add_u64 v[4:5], s[6:7], 0, v[2:3]
	global_load_lds_dwordx4 v[4:5], off
	v_lshl_add_u64 v[4:5], s[6:7], 0, v[134:135]
	s_add_i32 m0, s14, 0x1e000
	s_mov_b64 s[6:7], 0x3c080080
	global_load_lds_dwordx4 v[4:5], off
	v_lshlrev_b32_e32 v4, 15, v13
	v_and_b32_e32 v4, 0xffff0000, v4
	v_lshl_add_u32 v4, v12, 12, v4
	v_and_b32_e32 v5, 1, v13
	v_lshl_or_b32 v4, v5, 6, v4
	v_lshl_add_u32 v4, v14, 1, v4
	v_mov_b32_e32 v5, v3
	v_lshl_add_u64 v[140:141], v[4:5], 0, s[6:7]
	v_lshlrev_b32_e32 v4, 15, v8
	v_and_b32_e32 v4, 0xffff0000, v4
	v_lshl_add_u32 v4, v9, 12, v4
	v_and_b32_e32 v5, 1, v8
	v_lshl_or_b32 v4, v5, 6, v4
	s_waitcnt vmcnt(6)
	v_lshl_add_u32 v4, v10, 1, v4
	v_mov_b32_e32 v5, v3
	v_lshl_add_u64 v[142:143], v[4:5], 0, s[6:7]
	v_mov_b32_e32 v4, 0
	s_mov_b32 s37, -2
	v_add_u32_e32 v144, 0, v11
	s_mov_b64 s[6:7], s[74:75]
	s_barrier
	s_add_u32 s8, s6, 0x3c000100
	s_addc_u32 s9, s7, 0
	s_add_u32 s44, s6, s22
	s_addc_u32 s45, s7, s23
	s_add_i32 s48, 0, 0x10000
	s_cmp_eq_u32 s37, 28
	s_cselect_b32 s11, s53, s9
	s_cselect_b32 s10, s52, s8
	v_add_u32_e32 v145, s48, v133
	s_cselect_b32 s9, s1, s45
	s_cselect_b32 s8, s0, s44
	s_add_i32 s49, 0, 0x14000
	ds_read_b128 v[146:149], v145
	ds_read_b128 v[150:153], v145 offset:1024
	ds_read_b128 v[154:157], v145 offset:2048
	ds_read_b128 v[158:161], v145 offset:3072
	v_add_u32_e32 v145, s49, v133
	ds_read_b128 v[162:165], v145
	ds_read_b128 v[166:169], v145 offset:1024
	ds_read_b128 v[170:173], v145 offset:2048
	ds_read_b128 v[174:177], v145 offset:3072
	v_lshl_add_u64 v[208:209], s[6:7], 0, v[140:141]
	s_add_i32 m0, s14, 0xc000
	ds_read_b128 v[178:181], v144
	ds_read_b128 v[182:185], v144 offset:1024
	ds_read_b128 v[186:189], v144 offset:2048
	ds_read_b128 v[190:193], v144 offset:3072
	ds_read_b128 v[194:197], v144 offset:4096
	ds_read_b128 v[204:207], v144 offset:5120
	ds_read_b128 v[220:223], v144 offset:6144
	ds_read_b128 v[224:227], v144 offset:7168
	global_load_lds_dwordx4 v[208:209], off
	v_lshl_add_u64 v[208:209], s[6:7], 0, v[142:143]
	s_add_i32 m0, s14, 0xe000
	s_nop 0
	global_load_lds_dwordx4 v[208:209], off
	s_waitcnt vmcnt(8)
	s_waitcnt lgkmcnt(0)
	s_setprio 1
	s_barrier
	v_mfma_f32_16x16x32_f16 v[128:131], v[146:149], v[178:181], 0
	v_mfma_f32_16x16x32_f16 v[124:127], v[154:157], v[178:181], 0
	v_mfma_f32_16x16x32_f16 v[120:123], v[146:149], v[186:189], 0
	v_mfma_f32_16x16x32_f16 v[116:119], v[154:157], v[186:189], 0
	v_mfma_f32_16x16x32_f16 v[104:107], v[146:149], v[194:197], 0
	v_mfma_f32_16x16x32_f16 v[100:103], v[154:157], v[194:197], 0
	v_mfma_f32_16x16x32_f16 v[88:91], v[146:149], v[220:223], 0
	v_mfma_f32_16x16x32_f16 v[84:87], v[154:157], v[220:223], 0
	v_mfma_f32_16x16x32_f16 v[128:131], v[150:153], v[182:185], v[128:131]
	v_mfma_f32_16x16x32_f16 v[124:127], v[158:161], v[182:185], v[124:127]
	v_mfma_f32_16x16x32_f16 v[120:123], v[150:153], v[190:193], v[120:123]
	v_mfma_f32_16x16x32_f16 v[116:119], v[158:161], v[190:193], v[116:119]
	v_mfma_f32_16x16x32_f16 v[104:107], v[150:153], v[204:207], v[104:107]
	v_mfma_f32_16x16x32_f16 v[100:103], v[158:161], v[204:207], v[100:103]
	v_mfma_f32_16x16x32_f16 v[88:91], v[150:153], v[224:227], v[88:91]
	v_mfma_f32_16x16x32_f16 v[84:87], v[158:161], v[224:227], v[84:87]
	v_mfma_f32_16x16x32_f16 v[112:115], v[162:165], v[178:181], 0
	v_mfma_f32_16x16x32_f16 v[108:111], v[170:173], v[178:181], 0
	v_mfma_f32_16x16x32_f16 v[96:99], v[162:165], v[186:189], 0
	v_mfma_f32_16x16x32_f16 v[92:95], v[170:173], v[186:189], 0
	v_mfma_f32_16x16x32_f16 v[80:83], v[162:165], v[194:197], 0
	v_mfma_f32_16x16x32_f16 v[76:79], v[170:173], v[194:197], 0
	v_mfma_f32_16x16x32_f16 v[72:75], v[162:165], v[220:223], 0
	v_mfma_f32_16x16x32_f16 v[68:71], v[170:173], v[220:223], 0
	v_mfma_f32_16x16x32_f16 v[112:115], v[166:169], v[182:185], v[112:115]
	v_mfma_f32_16x16x32_f16 v[108:111], v[174:177], v[182:185], v[108:111]
	v_mfma_f32_16x16x32_f16 v[96:99], v[166:169], v[190:193], v[96:99]
	v_mfma_f32_16x16x32_f16 v[92:95], v[174:177], v[190:193], v[92:95]
	v_mfma_f32_16x16x32_f16 v[80:83], v[166:169], v[204:207], v[80:83]
	v_mfma_f32_16x16x32_f16 v[76:79], v[174:177], v[204:207], v[76:79]
	v_mfma_f32_16x16x32_f16 v[72:75], v[166:169], v[224:227], v[72:75]
	v_mfma_f32_16x16x32_f16 v[68:71], v[174:177], v[224:227], v[68:71]
	s_setprio 0
	s_barrier
; #define PG8_STAGE(bufoff, gbase, voff) do { _Pragma("unroll") for (int _i = 0; _i < 2; ++_i) \
;         __builtin_amdgcn_global_load_lds((const unsigned*)((const char*)(gbase) + (voff)[_i]), (LAS unsigned*)(lds + (bufoff) + ldsw + _i * 8192), 16, 0, 0); } while (0)
; #define PG8_LDA(dst, b, h) do { _Pragma("unroll") for (int m = 0; m < 4; ++m) _Pragma("unroll") for (int k = 0; k < 2; ++k) dst[m][k] = *(const LAS half8*)(lds + PG8_SA(b, h) + aoff + m * 2048 + k * 1024); } while (0)
; #define PG8_LDB(dst, b, h) do { _Pragma("unroll") for (int n = 0; n < 2; ++n) _Pragma("unroll") for (int k = 0; k < 2; ++k) dst[n][k] = *(const LAS half8*)(lds + PG8_SB(b, h) + boff + n * 2048 + k * 1024); } while (0)
; #define PG8_MMA(ai, bj, At, Bt) do { __builtin_amdgcn_s_setprio(1); _Pragma("unroll") for (int m = 0; m < 4; ++m) _Pragma("unroll") for (int n = 0; n < 2; ++n) _Pragma("unroll") for (int k = 0; k < 2; ++k) \
;         acc[ai][bj][m][n] = __builtin_amdgcn_mfma_f32_16x16x32_f16(Bt[n][k], At[m][k], acc[ai][bj][m][n], 0, 0, 0); __builtin_amdgcn_s_setprio(0); } while (0)
; #define PG8_BAR __builtin_amdgcn_s_barrier()
; template <class Epi, class Sched, bool ALIGN_EPI = false, bool SP2 = false>
; __device__ __forceinline__ void gemm_phase(LAS unsigned char* lds, const Gemm g, const Sched& S, const Epi& E) {
;     ...
;             if constexpr (SP2) {
;             PG8_LDB(B0, 0, 0); PG8_LDB(B1, 0, 1); PG8_SCHED; PG8_LDA(At, 0, 0); PG8_STAGE(PG8_SA(1, 1), a1 + hstepA, voffA);
;             PG8_WAIT_V(8); PG8_WAIT_L(0); PG8_BAR; PG8_MMA(0, 0, At, B0); PG8_MMA(0, 1, At, B1); PG8_BAR; PG8_SCHED;
;             PG8_LDA(At, 0, 1); PG8_STAGE(PG8_SB(0, 0), b2, voffB); PG8_STAGE(PG8_SB(0, 1), b2 + hstepB, voffB); PG8_STAGE(PG8_SA(0, 0), a2, voffA);
;             PG8_WAIT_V(8); PG8_WAIT_L(0); PG8_BAR; PG8_MMA(1, 0, At, B0); PG8_MMA(1, 1, At, B1); PG8_BAR; PG8_SCHED;
;             PG8_LDB(B0, 1, 0); PG8_LDB(B1, 1, 1); PG8_SCHED; PG8_LDA(At, 1, 0); PG8_STAGE(PG8_SA(0, 1), a2 + hstepA, voffA);
;             PG8_WAIT_V(8); PG8_WAIT_L(0); PG8_BAR; PG8_MMA(0, 0, At, B0); PG8_MMA(0, 1, At, B1); PG8_BAR; PG8_SCHED;
;             PG8_LDA(At, 1, 1); PG8_STAGE(PG8_SB(1, 0), b3, voffB); PG8_STAGE(PG8_SB(1, 1), b3 + hstepB, voffB); PG8_STAGE(PG8_SA(1, 0), a3, voffA);
;             PG8_WAIT_V(8); PG8_WAIT_L(0); PG8_BAR; PG8_MMA(1, 0, At, B0); PG8_MMA(1, 1, At, B1); PG8_BAR; PG8_SCHED;
	s_add_i32 s44, s48, s13
	v_lshl_add_u64 v[208:209], s[8:9], 0, v[2:3]
	s_mov_b32 m0, s44
	ds_read_b128 v[178:181], v144 offset:16384
	ds_read_b128 v[182:185], v144 offset:17408
	ds_read_b128 v[186:189], v144 offset:18432
	ds_read_b128 v[190:193], v144 offset:19456
	ds_read_b128 v[194:197], v144 offset:20480
	ds_read_b128 v[204:207], v144 offset:21504
	ds_read_b128 v[220:223], v144 offset:22528
	ds_read_b128 v[224:227], v144 offset:23552
	global_load_lds_dwordx4 v[208:209], off
	s_add_i32 m0, s44, 0x2000
	s_add_u32 s44, s8, 0x80000
	v_lshl_add_u64 v[228:229], s[8:9], 0, v[134:135]
	s_addc_u32 s45, s9, 0
	s_add_i32 s48, s49, s13
	global_load_lds_dwordx4 v[228:229], off
	v_lshl_add_u64 v[230:231], s[44:45], 0, v[2:3]
	s_mov_b32 m0, s48
	v_lshl_add_u64 v[232:233], s[10:11], 0, v[136:137]
	global_load_lds_dwordx4 v[230:231], off
	v_lshl_add_u64 v[230:231], s[44:45], 0, v[134:135]
	s_add_i32 m0, s48, 0x2000
	s_nop 0
	global_load_lds_dwordx4 v[230:231], off
	v_lshl_add_u64 v[230:231], s[10:11], 0, v[138:139]
	s_mov_b32 m0, s14
	s_nop 0
	global_load_lds_dwordx4 v[230:231], off
	s_mov_b32 m0, s15
	s_nop 0
	global_load_lds_dwordx4 v[232:233], off
	s_waitcnt vmcnt(8)
	s_waitcnt lgkmcnt(0)
	s_setprio 1
	s_barrier
	v_mfma_f32_16x16x32_f16 v[64:67], v[146:149], v[178:181], 0
	v_mfma_f32_16x16x32_f16 v[60:63], v[154:157], v[178:181], 0
	v_mfma_f32_16x16x32_f16 v[56:59], v[146:149], v[186:189], 0
	v_mfma_f32_16x16x32_f16 v[52:55], v[154:157], v[186:189], 0
	v_mfma_f32_16x16x32_f16 v[40:43], v[146:149], v[194:197], 0
	v_mfma_f32_16x16x32_f16 v[36:39], v[154:157], v[194:197], 0
	v_mfma_f32_16x16x32_f16 v[24:27], v[146:149], v[220:223], 0
	v_mfma_f32_16x16x32_f16 v[20:23], v[154:157], v[220:223], 0
	v_mfma_f32_16x16x32_f16 v[64:67], v[150:153], v[182:185], v[64:67]
	v_mfma_f32_16x16x32_f16 v[60:63], v[158:161], v[182:185], v[60:63]
	v_mfma_f32_16x16x32_f16 v[56:59], v[150:153], v[190:193], v[56:59]
	v_mfma_f32_16x16x32_f16 v[52:55], v[158:161], v[190:193], v[52:55]
	v_mfma_f32_16x16x32_f16 v[40:43], v[150:153], v[204:207], v[40:43]
	v_mfma_f32_16x16x32_f16 v[36:39], v[158:161], v[204:207], v[36:39]
	v_mfma_f32_16x16x32_f16 v[24:27], v[150:153], v[224:227], v[24:27]
	v_mfma_f32_16x16x32_f16 v[20:23], v[158:161], v[224:227], v[20:23]
	v_mfma_f32_16x16x32_f16 v[48:51], v[162:165], v[178:181], 0
	v_mfma_f32_16x16x32_f16 v[44:47], v[170:173], v[178:181], 0
	v_mfma_f32_16x16x32_f16 v[32:35], v[162:165], v[186:189], 0
	v_mfma_f32_16x16x32_f16 v[28:31], v[170:173], v[186:189], 0
	v_mfma_f32_16x16x32_f16 v[16:19], v[162:165], v[194:197], 0
	v_mfma_f32_16x16x32_f16 v[12:15], v[170:173], v[194:197], 0
	v_mfma_f32_16x16x32_f16 v[8:11], v[162:165], v[220:223], 0
	v_mfma_f32_16x16x32_f16 v[4:7], v[170:173], v[220:223], 0
	v_mfma_f32_16x16x32_f16 v[48:51], v[166:169], v[182:185], v[48:51]
	v_mfma_f32_16x16x32_f16 v[44:47], v[174:177], v[182:185], v[44:47]
	v_mfma_f32_16x16x32_f16 v[32:35], v[166:169], v[190:193], v[32:35]
	v_mfma_f32_16x16x32_f16 v[28:31], v[174:177], v[190:193], v[28:31]
	v_mfma_f32_16x16x32_f16 v[16:19], v[166:169], v[204:207], v[16:19]
	v_mfma_f32_16x16x32_f16 v[12:15], v[174:177], v[204:207], v[12:15]
	v_mfma_f32_16x16x32_f16 v[8:11], v[166:169], v[224:227], v[8:11]
	v_mfma_f32_16x16x32_f16 v[4:7], v[174:177], v[224:227], v[4:7]
	s_setprio 0
	s_barrier
	s_add_i32 s44, 0, 0x18000
	v_add_u32_e32 v145, s44, v133
	s_add_i32 s45, 0, 0x1c000
	ds_read_b128 v[146:149], v145
	ds_read_b128 v[150:153], v145 offset:1024
	ds_read_b128 v[154:157], v145 offset:2048
	ds_read_b128 v[158:161], v145 offset:3072
	v_add_u32_e32 v145, s45, v133
	ds_read_b128 v[162:165], v145
	ds_read_b128 v[166:169], v145 offset:1024
	ds_read_b128 v[170:173], v145 offset:2048
	ds_read_b128 v[174:177], v145 offset:3072
	s_add_u32 s10, s10, 0x80000
	s_addc_u32 s11, s11, 0
	s_mov_b32 m0, s16
	v_lshl_add_u64 v[234:235], s[10:11], 0, v[138:139]
	ds_read_b128 v[178:181], v144 offset:32768
	ds_read_b128 v[182:185], v144 offset:33792
	ds_read_b128 v[186:189], v144 offset:34816
	ds_read_b128 v[190:193], v144 offset:35840
	ds_read_b128 v[194:197], v144 offset:36864
	ds_read_b128 v[204:207], v144 offset:37888
	ds_read_b128 v[220:223], v144 offset:38912
	ds_read_b128 v[224:227], v144 offset:39936
	global_load_lds_dwordx4 v[234:235], off
	v_lshl_add_u64 v[234:235], s[10:11], 0, v[136:137]
	s_mov_b32 m0, s17
	s_nop 0
	global_load_lds_dwordx4 v[234:235], off
	s_waitcnt vmcnt(8)
	s_waitcnt lgkmcnt(0)
	s_setprio 1
	s_barrier
	v_mfma_f32_16x16x32_f16 v[128:131], v[146:149], v[178:181], v[128:131]
	v_mfma_f32_16x16x32_f16 v[124:127], v[154:157], v[178:181], v[124:127]
	v_mfma_f32_16x16x32_f16 v[120:123], v[146:149], v[186:189], v[120:123]
	v_mfma_f32_16x16x32_f16 v[116:119], v[154:157], v[186:189], v[116:119]
	v_mfma_f32_16x16x32_f16 v[104:107], v[146:149], v[194:197], v[104:107]
	v_mfma_f32_16x16x32_f16 v[100:103], v[154:157], v[194:197], v[100:103]
	v_mfma_f32_16x16x32_f16 v[88:91], v[146:149], v[220:223], v[88:91]
	v_mfma_f32_16x16x32_f16 v[84:87], v[154:157], v[220:223], v[84:87]
	v_mfma_f32_16x16x32_f16 v[128:131], v[150:153], v[182:185], v[128:131]
	v_mfma_f32_16x16x32_f16 v[124:127], v[158:161], v[182:185], v[124:127]
	v_mfma_f32_16x16x32_f16 v[120:123], v[150:153], v[190:193], v[120:123]
	v_mfma_f32_16x16x32_f16 v[116:119], v[158:161], v[190:193], v[116:119]
	v_mfma_f32_16x16x32_f16 v[104:107], v[150:153], v[204:207], v[104:107]
	v_mfma_f32_16x16x32_f16 v[100:103], v[158:161], v[204:207], v[100:103]
	v_mfma_f32_16x16x32_f16 v[88:91], v[150:153], v[224:227], v[88:91]
	v_mfma_f32_16x16x32_f16 v[84:87], v[158:161], v[224:227], v[84:87]
	v_mfma_f32_16x16x32_f16 v[112:115], v[162:165], v[178:181], v[112:115]
	v_mfma_f32_16x16x32_f16 v[108:111], v[170:173], v[178:181], v[108:111]
	v_mfma_f32_16x16x32_f16 v[96:99], v[162:165], v[186:189], v[96:99]
	v_mfma_f32_16x16x32_f16 v[92:95], v[170:173], v[186:189], v[92:95]
	v_mfma_f32_16x16x32_f16 v[80:83], v[162:165], v[194:197], v[80:83]
	v_mfma_f32_16x16x32_f16 v[76:79], v[170:173], v[194:197], v[76:79]
	v_mfma_f32_16x16x32_f16 v[72:75], v[162:165], v[220:223], v[72:75]
	v_mfma_f32_16x16x32_f16 v[68:71], v[170:173], v[220:223], v[68:71]
	v_mfma_f32_16x16x32_f16 v[112:115], v[166:169], v[182:185], v[112:115]
	v_mfma_f32_16x16x32_f16 v[108:111], v[174:177], v[182:185], v[108:111]
	v_mfma_f32_16x16x32_f16 v[96:99], v[166:169], v[190:193], v[96:99]
	v_mfma_f32_16x16x32_f16 v[92:95], v[174:177], v[190:193], v[92:95]
	v_mfma_f32_16x16x32_f16 v[80:83], v[166:169], v[204:207], v[80:83]
	v_mfma_f32_16x16x32_f16 v[76:79], v[174:177], v[204:207], v[76:79]
	v_mfma_f32_16x16x32_f16 v[72:75], v[166:169], v[224:227], v[72:75]
	v_mfma_f32_16x16x32_f16 v[68:71], v[174:177], v[224:227], v[68:71]
	s_setprio 0
	s_barrier
; #define PG8_STAGE(bufoff, gbase, voff) do { _Pragma("unroll") for (int _i = 0; _i < 2; ++_i) \
;         __builtin_amdgcn_global_load_lds((const unsigned*)((const char*)(gbase) + (voff)[_i]), (LAS unsigned*)(lds + (bufoff) + ldsw + _i * 8192), 16, 0, 0); } while (0)
; #define PG8_LDA(dst, b, h) do { _Pragma("unroll") for (int m = 0; m < 4; ++m) _Pragma("unroll") for (int k = 0; k < 2; ++k) dst[m][k] = *(const LAS half8*)(lds + PG8_SA(b, h) + aoff + m * 2048 + k * 1024); } while (0)
; #define PG8_LDB(dst, b, h) do { _Pragma("unroll") for (int n = 0; n < 2; ++n) _Pragma("unroll") for (int k = 0; k < 2; ++k) dst[n][k] = *(const LAS half8*)(lds + PG8_SB(b, h) + boff + n * 2048 + k * 1024); } while (0)
; template <class Epi, class Sched, bool ALIGN_EPI = false, bool SP2 = false>
; __device__ __forceinline__ void gemm_phase(LAS unsigned char* lds, const Gemm g, const Sched& S, const Epi& E) {
;     ...
;         for (int t = 0; t < nt; t += 2) {
;             const bool last = (t == nt - 2);
;             const char* a1 = cA + (size_t)(t + 1) * kstep;
;             const char* a2 = last ? nA : cA + (size_t)(t + 2) * kstep; const char* b2 = last ? nB : cB + (size_t)(t + 2) * kstep;
;             const char* a3 = a2 + kstep; const char* b3 = b2 + kstep;
;             if (last && has_next) S.a_ready(nxt);
;             if constexpr (SP2) {
;             PG8_LDB(B0, 0, 0); PG8_LDB(B1, 0, 1); PG8_SCHED; PG8_LDA(At, 0, 0); PG8_STAGE(PG8_SA(1, 1), a1 + hstepA, voffA);
;             PG8_WAIT_V(8); PG8_WAIT_L(0); PG8_BAR; PG8_MMA(0, 0, At, B0); PG8_MMA(0, 1, At, B1); PG8_BAR; PG8_SCHED;
;             PG8_LDA(At, 0, 1); PG8_STAGE(PG8_SB(0, 0), b2, voffB); PG8_STAGE(PG8_SB(0, 1), b2 + hstepB, voffB); PG8_STAGE(PG8_SA(0, 0), a2, voffA);
;             PG8_WAIT_V(8); PG8_WAIT_L(0); PG8_BAR; PG8_MMA(1, 0, At, B0); PG8_MMA(1, 1, At, B1); PG8_BAR; PG8_SCHED;
;             PG8_LDB(B0, 1, 0); PG8_LDB(B1, 1, 1); PG8_SCHED; PG8_LDA(At, 1, 0); PG8_STAGE(PG8_SA(0, 1), a2 + hstepA, voffA);
;             PG8_WAIT_V(8); PG8_WAIT_L(0); PG8_BAR; PG8_MMA(0, 0, At, B0); PG8_MMA(0, 1, At, B1); PG8_BAR; PG8_SCHED;
;             PG8_LDA(At, 1, 1); PG8_STAGE(PG8_SB(1, 0), b3, voffB); PG8_STAGE(PG8_SB(1, 1), b3 + hstepB, voffB); PG8_STAGE(PG8_SA(1, 0), a3, voffA);
;             PG8_WAIT_V(8); PG8_WAIT_L(0); PG8_BAR; PG8_MMA(1, 0, At, B0); PG8_MMA(1, 1, At, B1); PG8_BAR; PG8_SCHED;
	s_add_i32 s10, s44, s13
	v_lshl_add_u64 v[208:209], v[208:209], 0, s[96:97]
	s_mov_b32 m0, s10
	ds_read_b128 v[178:181], v144 offset:49152
	ds_read_b128 v[182:185], v144 offset:50176
	ds_read_b128 v[186:189], v144 offset:51200
	ds_read_b128 v[190:193], v144 offset:52224
	ds_read_b128 v[194:197], v144 offset:53248
	ds_read_b128 v[204:207], v144 offset:54272
	ds_read_b128 v[220:223], v144 offset:55296
	ds_read_b128 v[224:227], v144 offset:56320
	global_load_lds_dwordx4 v[208:209], off
	s_add_i32 m0, s10, 0x2000
	s_add_u32 s8, s8, 0x80080
	v_lshl_add_u64 v[208:209], v[228:229], 0, s[96:97]
	s_addc_u32 s9, s9, 0
	s_add_i32 s10, s45, s13
	global_load_lds_dwordx4 v[208:209], off
	v_lshl_add_u64 v[208:209], s[8:9], 0, v[2:3]
	s_mov_b32 m0, s10
	s_nop 0
	global_load_lds_dwordx4 v[208:209], off
	v_lshl_add_u64 v[208:209], s[8:9], 0, v[134:135]
	s_add_i32 m0, s10, 0x2000
	s_nop 0
	global_load_lds_dwordx4 v[208:209], off
	v_lshl_add_u64 v[208:209], v[230:231], 0, s[96:97]
	s_mov_b32 m0, s24
	s_nop 0
	global_load_lds_dwordx4 v[208:209], off
	v_lshl_add_u64 v[208:209], v[232:233], 0, s[96:97]
	s_mov_b32 m0, s25
	s_nop 0
	global_load_lds_dwordx4 v[208:209], off
	s_waitcnt vmcnt(8)
	s_waitcnt lgkmcnt(0)
	s_setprio 1
	s_barrier
	v_mfma_f32_16x16x32_f16 v[64:67], v[146:149], v[178:181], v[64:67]
	v_mfma_f32_16x16x32_f16 v[60:63], v[154:157], v[178:181], v[60:63]
	v_mfma_f32_16x16x32_f16 v[56:59], v[146:149], v[186:189], v[56:59]
	v_mfma_f32_16x16x32_f16 v[52:55], v[154:157], v[186:189], v[52:55]
	v_mfma_f32_16x16x32_f16 v[40:43], v[146:149], v[194:197], v[40:43]
	v_mfma_f32_16x16x32_f16 v[36:39], v[154:157], v[194:197], v[36:39]
	v_mfma_f32_16x16x32_f16 v[24:27], v[146:149], v[220:223], v[24:27]
	v_mfma_f32_16x16x32_f16 v[20:23], v[154:157], v[220:223], v[20:23]
	v_mfma_f32_16x16x32_f16 v[64:67], v[150:153], v[182:185], v[64:67]
	v_mfma_f32_16x16x32_f16 v[60:63], v[158:161], v[182:185], v[60:63]
	v_mfma_f32_16x16x32_f16 v[56:59], v[150:153], v[190:193], v[56:59]
	v_mfma_f32_16x16x32_f16 v[52:55], v[158:161], v[190:193], v[52:55]
	v_mfma_f32_16x16x32_f16 v[40:43], v[150:153], v[204:207], v[40:43]
	v_mfma_f32_16x16x32_f16 v[36:39], v[158:161], v[204:207], v[36:39]
	v_mfma_f32_16x16x32_f16 v[24:27], v[150:153], v[224:227], v[24:27]
	v_mfma_f32_16x16x32_f16 v[20:23], v[158:161], v[224:227], v[20:23]
	v_mfma_f32_16x16x32_f16 v[48:51], v[162:165], v[178:181], v[48:51]
	v_mfma_f32_16x16x32_f16 v[44:47], v[170:173], v[178:181], v[44:47]
	v_mfma_f32_16x16x32_f16 v[32:35], v[162:165], v[186:189], v[32:35]
	v_mfma_f32_16x16x32_f16 v[28:31], v[170:173], v[186:189], v[28:31]
	v_mfma_f32_16x16x32_f16 v[16:19], v[162:165], v[194:197], v[16:19]
	v_mfma_f32_16x16x32_f16 v[12:15], v[170:173], v[194:197], v[12:15]
	v_mfma_f32_16x16x32_f16 v[8:11], v[162:165], v[220:223], v[8:11]
	v_mfma_f32_16x16x32_f16 v[4:7], v[170:173], v[220:223], v[4:7]
	v_mfma_f32_16x16x32_f16 v[48:51], v[166:169], v[182:185], v[48:51]
	v_mfma_f32_16x16x32_f16 v[44:47], v[174:177], v[182:185], v[44:47]
	v_mfma_f32_16x16x32_f16 v[32:35], v[166:169], v[190:193], v[32:35]
	v_mfma_f32_16x16x32_f16 v[28:31], v[174:177], v[190:193], v[28:31]
	v_mfma_f32_16x16x32_f16 v[16:19], v[166:169], v[204:207], v[16:19]
	v_mfma_f32_16x16x32_f16 v[12:15], v[174:177], v[204:207], v[12:15]
	v_mfma_f32_16x16x32_f16 v[8:11], v[166:169], v[224:227], v[8:11]
	v_mfma_f32_16x16x32_f16 v[4:7], v[174:177], v[224:227], v[4:7]
	s_setprio 0
	s_barrier
	s_add_i32 s37, s37, 2
	s_add_u32 s6, s6, 0x100
	s_addc_u32 s7, s7, 0
	s_cmp_gt_u32 s37, 29
	s_cbranch_scc0 .LBB0_426
.LBB0_426:
	s_add_u32 s8, s6, 0x3c000100
	s_addc_u32 s9, s7, 0
	s_add_u32 s44, s6, s22
	s_addc_u32 s45, s7, s23
	s_add_i32 s48, 0, 0x10000
	s_cmp_eq_u32 s37, 28
	s_cselect_b32 s11, s53, s9
	s_cselect_b32 s10, s52, s8
	v_add_u32_e32 v145, s48, v133
	s_cselect_b32 s9, s1, s45
	s_cselect_b32 s8, s0, s44
	s_add_i32 s49, 0, 0x14000
	ds_read_b128 v[146:149], v145
	ds_read_b128 v[150:153], v145 offset:1024
	ds_read_b128 v[154:157], v145 offset:2048
	ds_read_b128 v[158:161], v145 offset:3072
	v_add_u32_e32 v145, s49, v133
	ds_read_b128 v[162:165], v145
	ds_read_b128 v[166:169], v145 offset:1024
	ds_read_b128 v[170:173], v145 offset:2048
	ds_read_b128 v[174:177], v145 offset:3072
	v_lshl_add_u64 v[208:209], s[6:7], 0, v[140:141]
	s_add_i32 m0, s14, 0xc000
	ds_read_b128 v[178:181], v144
	ds_read_b128 v[182:185], v144 offset:1024
	ds_read_b128 v[186:189], v144 offset:2048
	ds_read_b128 v[190:193], v144 offset:3072
	ds_read_b128 v[194:197], v144 offset:4096
	ds_read_b128 v[204:207], v144 offset:5120
	ds_read_b128 v[220:223], v144 offset:6144
	ds_read_b128 v[224:227], v144 offset:7168
	global_load_lds_dwordx4 v[208:209], off
	v_lshl_add_u64 v[208:209], s[6:7], 0, v[142:143]
	s_add_i32 m0, s14, 0xe000
	s_nop 0
	global_load_lds_dwordx4 v[208:209], off
	s_waitcnt vmcnt(8)
	s_waitcnt lgkmcnt(0)
	s_setprio 1
	s_barrier
; #define PG8_STAGE(bufoff, gbase, voff) do { _Pragma("unroll") for (int _i = 0; _i < 2; ++_i) \
;         __builtin_amdgcn_global_load_lds((const unsigned*)((const char*)(gbase) + (voff)[_i]), (LAS unsigned*)(lds + (bufoff) + ldsw + _i * 8192), 16, 0, 0); } while (0)
; #define PG8_LDA(dst, b, h) do { _Pragma("unroll") for (int m = 0; m < 4; ++m) _Pragma("unroll") for (int k = 0; k < 2; ++k) dst[m][k] = *(const LAS half8*)(lds + PG8_SA(b, h) + aoff + m * 2048 + k * 1024); } while (0)
; #define PG8_LDB(dst, b, h) do { _Pragma("unroll") for (int n = 0; n < 2; ++n) _Pragma("unroll") for (int k = 0; k < 2; ++k) dst[n][k] = *(const LAS half8*)(lds + PG8_SB(b, h) + boff + n * 2048 + k * 1024); } while (0)
; #define PG8_MMA(ai, bj, At, Bt) do { __builtin_amdgcn_s_setprio(1); _Pragma("unroll") for (int m = 0; m < 4; ++m) _Pragma("unroll") for (int n = 0; n < 2; ++n) _Pragma("unroll") for (int k = 0; k < 2; ++k) \
;         acc[ai][bj][m][n] = __builtin_amdgcn_mfma_f32_16x16x32_f16(Bt[n][k], At[m][k], acc[ai][bj][m][n], 0, 0, 0); __builtin_amdgcn_s_setprio(0); } while (0)
; #define PG8_WAIT_V(n) asm volatile("s_waitcnt vmcnt(" #n ")" ::: "memory")
; #define PG8_WAIT_L(n) asm volatile("s_waitcnt lgkmcnt(" #n ")" ::: "memory")
; #define PG8_BAR __builtin_amdgcn_s_barrier()
; #define PG8_SCHED __builtin_amdgcn_sched_barrier(0)
; template <class Epi, class Sched, bool ALIGN_EPI = false, bool SP2 = false>
; __device__ __forceinline__ void gemm_phase(LAS unsigned char* lds, const Gemm g, const Sched& S, const Epi& E) {
;     ...
;             if constexpr (SP2) {
;             PG8_LDB(B0, 0, 0); PG8_LDB(B1, 0, 1); PG8_SCHED; PG8_LDA(At, 0, 0); PG8_STAGE(PG8_SA(1, 1), a1 + hstepA, voffA);
;             PG8_WAIT_V(8); PG8_WAIT_L(0); PG8_BAR; PG8_MMA(0, 0, At, B0); PG8_MMA(0, 1, At, B1); PG8_BAR; PG8_SCHED;
;             PG8_LDA(At, 0, 1); PG8_STAGE(PG8_SB(0, 0), b2, voffB); PG8_STAGE(PG8_SB(0, 1), b2 + hstepB, voffB); PG8_STAGE(PG8_SA(0, 0), a2, voffA);
;             PG8_WAIT_V(8); PG8_WAIT_L(0); PG8_BAR; PG8_MMA(1, 0, At, B0); PG8_MMA(1, 1, At, B1); PG8_BAR; PG8_SCHED;
	v_mfma_f32_16x16x32_f16 v[128:131], v[146:149], v[178:181], v[128:131]
	v_mfma_f32_16x16x32_f16 v[124:127], v[154:157], v[178:181], v[124:127]
	v_mfma_f32_16x16x32_f16 v[120:123], v[146:149], v[186:189], v[120:123]
	v_mfma_f32_16x16x32_f16 v[116:119], v[154:157], v[186:189], v[116:119]
	v_mfma_f32_16x16x32_f16 v[104:107], v[146:149], v[194:197], v[104:107]
	v_mfma_f32_16x16x32_f16 v[100:103], v[154:157], v[194:197], v[100:103]
	v_mfma_f32_16x16x32_f16 v[88:91], v[146:149], v[220:223], v[88:91]
	v_mfma_f32_16x16x32_f16 v[84:87], v[154:157], v[220:223], v[84:87]
	v_mfma_f32_16x16x32_f16 v[128:131], v[150:153], v[182:185], v[128:131]
	v_mfma_f32_16x16x32_f16 v[124:127], v[158:161], v[182:185], v[124:127]
	v_mfma_f32_16x16x32_f16 v[120:123], v[150:153], v[190:193], v[120:123]
	v_mfma_f32_16x16x32_f16 v[116:119], v[158:161], v[190:193], v[116:119]
	v_mfma_f32_16x16x32_f16 v[104:107], v[150:153], v[204:207], v[104:107]
	v_mfma_f32_16x16x32_f16 v[100:103], v[158:161], v[204:207], v[100:103]
	v_mfma_f32_16x16x32_f16 v[88:91], v[150:153], v[224:227], v[88:91]
	v_mfma_f32_16x16x32_f16 v[84:87], v[158:161], v[224:227], v[84:87]
	v_mfma_f32_16x16x32_f16 v[112:115], v[162:165], v[178:181], v[112:115]
	v_mfma_f32_16x16x32_f16 v[108:111], v[170:173], v[178:181], v[108:111]
	v_mfma_f32_16x16x32_f16 v[96:99], v[162:165], v[186:189], v[96:99]
	v_mfma_f32_16x16x32_f16 v[92:95], v[170:173], v[186:189], v[92:95]
	v_mfma_f32_16x16x32_f16 v[80:83], v[162:165], v[194:197], v[80:83]
	v_mfma_f32_16x16x32_f16 v[76:79], v[170:173], v[194:197], v[76:79]
	v_mfma_f32_16x16x32_f16 v[72:75], v[162:165], v[220:223], v[72:75]
	v_mfma_f32_16x16x32_f16 v[68:71], v[170:173], v[220:223], v[68:71]
	v_mfma_f32_16x16x32_f16 v[112:115], v[166:169], v[182:185], v[112:115]
	v_mfma_f32_16x16x32_f16 v[108:111], v[174:177], v[182:185], v[108:111]
	v_mfma_f32_16x16x32_f16 v[96:99], v[166:169], v[190:193], v[96:99]
	v_mfma_f32_16x16x32_f16 v[92:95], v[174:177], v[190:193], v[92:95]
	v_mfma_f32_16x16x32_f16 v[80:83], v[166:169], v[204:207], v[80:83]
	v_mfma_f32_16x16x32_f16 v[76:79], v[174:177], v[204:207], v[76:79]
	v_mfma_f32_16x16x32_f16 v[72:75], v[166:169], v[224:227], v[72:75]
	v_mfma_f32_16x16x32_f16 v[68:71], v[174:177], v[224:227], v[68:71]
	s_setprio 0
	s_barrier
	s_add_i32 s44, s48, s13
	v_lshl_add_u64 v[208:209], s[8:9], 0, v[2:3]
	s_mov_b32 m0, s44
	ds_read_b128 v[178:181], v144 offset:16384
	ds_read_b128 v[182:185], v144 offset:17408
	ds_read_b128 v[186:189], v144 offset:18432
	ds_read_b128 v[190:193], v144 offset:19456
	ds_read_b128 v[194:197], v144 offset:20480
	ds_read_b128 v[204:207], v144 offset:21504
	ds_read_b128 v[220:223], v144 offset:22528
	ds_read_b128 v[224:227], v144 offset:23552
	global_load_lds_dwordx4 v[208:209], off
	s_add_i32 m0, s44, 0x2000
	s_add_u32 s44, s8, 0x80000
	v_lshl_add_u64 v[228:229], s[8:9], 0, v[134:135]
	s_addc_u32 s45, s9, 0
	s_add_i32 s48, s49, s13
	global_load_lds_dwordx4 v[228:229], off
	v_lshl_add_u64 v[230:231], s[44:45], 0, v[2:3]
	s_mov_b32 m0, s48
	v_lshl_add_u64 v[232:233], s[10:11], 0, v[136:137]
	global_load_lds_dwordx4 v[230:231], off
	v_lshl_add_u64 v[230:231], s[44:45], 0, v[134:135]
	s_add_i32 m0, s48, 0x2000
	s_nop 0
	global_load_lds_dwordx4 v[230:231], off
	v_lshl_add_u64 v[230:231], s[10:11], 0, v[138:139]
	s_mov_b32 m0, s14
	s_nop 0
	global_load_lds_dwordx4 v[230:231], off
	s_mov_b32 m0, s15
	s_nop 0
	global_load_lds_dwordx4 v[232:233], off
	s_waitcnt vmcnt(8)
	s_waitcnt lgkmcnt(0)
	s_setprio 1
	s_barrier
	v_mfma_f32_16x16x32_f16 v[64:67], v[146:149], v[178:181], v[64:67]
	v_mfma_f32_16x16x32_f16 v[60:63], v[154:157], v[178:181], v[60:63]
	v_mfma_f32_16x16x32_f16 v[56:59], v[146:149], v[186:189], v[56:59]
	v_mfma_f32_16x16x32_f16 v[52:55], v[154:157], v[186:189], v[52:55]
	v_mfma_f32_16x16x32_f16 v[40:43], v[146:149], v[194:197], v[40:43]
	v_mfma_f32_16x16x32_f16 v[36:39], v[154:157], v[194:197], v[36:39]
	v_mfma_f32_16x16x32_f16 v[24:27], v[146:149], v[220:223], v[24:27]
	v_mfma_f32_16x16x32_f16 v[20:23], v[154:157], v[220:223], v[20:23]
	v_mfma_f32_16x16x32_f16 v[64:67], v[150:153], v[182:185], v[64:67]
	v_mfma_f32_16x16x32_f16 v[60:63], v[158:161], v[182:185], v[60:63]
	v_mfma_f32_16x16x32_f16 v[56:59], v[150:153], v[190:193], v[56:59]
	v_mfma_f32_16x16x32_f16 v[52:55], v[158:161], v[190:193], v[52:55]
	v_mfma_f32_16x16x32_f16 v[40:43], v[150:153], v[204:207], v[40:43]
	v_mfma_f32_16x16x32_f16 v[36:39], v[158:161], v[204:207], v[36:39]
	v_mfma_f32_16x16x32_f16 v[24:27], v[150:153], v[224:227], v[24:27]
	v_mfma_f32_16x16x32_f16 v[20:23], v[158:161], v[224:227], v[20:23]
	v_mfma_f32_16x16x32_f16 v[48:51], v[162:165], v[178:181], v[48:51]
	v_mfma_f32_16x16x32_f16 v[44:47], v[170:173], v[178:181], v[44:47]
	v_mfma_f32_16x16x32_f16 v[32:35], v[162:165], v[186:189], v[32:35]
	v_mfma_f32_16x16x32_f16 v[28:31], v[170:173], v[186:189], v[28:31]
	v_mfma_f32_16x16x32_f16 v[16:19], v[162:165], v[194:197], v[16:19]
	v_mfma_f32_16x16x32_f16 v[12:15], v[170:173], v[194:197], v[12:15]
	v_mfma_f32_16x16x32_f16 v[8:11], v[162:165], v[220:223], v[8:11]
	v_mfma_f32_16x16x32_f16 v[4:7], v[170:173], v[220:223], v[4:7]
	v_mfma_f32_16x16x32_f16 v[48:51], v[166:169], v[182:185], v[48:51]
	v_mfma_f32_16x16x32_f16 v[44:47], v[174:177], v[182:185], v[44:47]
	v_mfma_f32_16x16x32_f16 v[32:35], v[166:169], v[190:193], v[32:35]
	v_mfma_f32_16x16x32_f16 v[28:31], v[174:177], v[190:193], v[28:31]
	v_mfma_f32_16x16x32_f16 v[16:19], v[166:169], v[204:207], v[16:19]
	v_mfma_f32_16x16x32_f16 v[12:15], v[174:177], v[204:207], v[12:15]
	v_mfma_f32_16x16x32_f16 v[8:11], v[166:169], v[224:227], v[8:11]
	v_mfma_f32_16x16x32_f16 v[4:7], v[174:177], v[224:227], v[4:7]
	s_setprio 0
	s_barrier
; #define PG8_STAGE(bufoff, gbase, voff) do { _Pragma("unroll") for (int _i = 0; _i < 2; ++_i) \
;         __builtin_amdgcn_global_load_lds((const unsigned*)((const char*)(gbase) + (voff)[_i]), (LAS unsigned*)(lds + (bufoff) + ldsw + _i * 8192), 16, 0, 0); } while (0)
; #define PG8_LDA(dst, b, h) do { _Pragma("unroll") for (int m = 0; m < 4; ++m) _Pragma("unroll") for (int k = 0; k < 2; ++k) dst[m][k] = *(const LAS half8*)(lds + PG8_SA(b, h) + aoff + m * 2048 + k * 1024); } while (0)
; #define PG8_LDB(dst, b, h) do { _Pragma("unroll") for (int n = 0; n < 2; ++n) _Pragma("unroll") for (int k = 0; k < 2; ++k) dst[n][k] = *(const LAS half8*)(lds + PG8_SB(b, h) + boff + n * 2048 + k * 1024); } while (0)
; #define PG8_MMA(ai, bj, At, Bt) do { __builtin_amdgcn_s_setprio(1); _Pragma("unroll") for (int m = 0; m < 4; ++m) _Pragma("unroll") for (int n = 0; n < 2; ++n) _Pragma("unroll") for (int k = 0; k < 2; ++k) \
;         acc[ai][bj][m][n] = __builtin_amdgcn_mfma_f32_16x16x32_f16(Bt[n][k], At[m][k], acc[ai][bj][m][n], 0, 0, 0); __builtin_amdgcn_s_setprio(0); } while (0)
; #define PG8_WAIT_V(n) asm volatile("s_waitcnt vmcnt(" #n ")" ::: "memory")
; #define PG8_WAIT_L(n) asm volatile("s_waitcnt lgkmcnt(" #n ")" ::: "memory")
; #define PG8_BAR __builtin_amdgcn_s_barrier()
; #define PG8_SCHED __builtin_amdgcn_sched_barrier(0)
; template <class Epi, class Sched, bool ALIGN_EPI = false, bool SP2 = false>
; __device__ __forceinline__ void gemm_phase(LAS unsigned char* lds, const Gemm g, const Sched& S, const Epi& E) {
;     ...
;             PG8_LDB(B0, 1, 0); PG8_LDB(B1, 1, 1); PG8_SCHED; PG8_LDA(At, 1, 0); PG8_STAGE(PG8_SA(0, 1), a2 + hstepA, voffA);
;             PG8_WAIT_V(8); PG8_WAIT_L(0); PG8_BAR; PG8_MMA(0, 0, At, B0); PG8_MMA(0, 1, At, B1); PG8_BAR; PG8_SCHED;
;             PG8_LDA(At, 1, 1); PG8_STAGE(PG8_SB(1, 0), b3, voffB); PG8_STAGE(PG8_SB(1, 1), b3 + hstepB, voffB); PG8_STAGE(PG8_SA(1, 0), a3, voffA);
;             PG8_WAIT_V(8); PG8_WAIT_L(0); PG8_BAR; PG8_MMA(1, 0, At, B0); PG8_MMA(1, 1, At, B1); PG8_BAR; PG8_SCHED;
;     ...
;         if constexpr (ALIGN_EPI) { if (wr == 0) PG8_BAR; }
	s_add_i32 s44, 0, 0x18000
	v_add_u32_e32 v145, s44, v133
	s_add_i32 s45, 0, 0x1c000
	ds_read_b128 v[146:149], v145
	ds_read_b128 v[150:153], v145 offset:1024
	ds_read_b128 v[154:157], v145 offset:2048
	ds_read_b128 v[158:161], v145 offset:3072
	v_add_u32_e32 v145, s45, v133
	ds_read_b128 v[162:165], v145
	ds_read_b128 v[166:169], v145 offset:1024
	ds_read_b128 v[170:173], v145 offset:2048
	ds_read_b128 v[174:177], v145 offset:3072
	s_add_u32 s10, s10, 0x80000
	s_addc_u32 s11, s11, 0
	s_mov_b32 m0, s16
	v_lshl_add_u64 v[234:235], s[10:11], 0, v[138:139]
	ds_read_b128 v[178:181], v144 offset:32768
	ds_read_b128 v[182:185], v144 offset:33792
	ds_read_b128 v[186:189], v144 offset:34816
	ds_read_b128 v[190:193], v144 offset:35840
	ds_read_b128 v[194:197], v144 offset:36864
	ds_read_b128 v[204:207], v144 offset:37888
	ds_read_b128 v[220:223], v144 offset:38912
	ds_read_b128 v[224:227], v144 offset:39936
	global_load_lds_dwordx4 v[234:235], off
	v_lshl_add_u64 v[234:235], s[10:11], 0, v[136:137]
	s_mov_b32 m0, s17
	s_nop 0
	global_load_lds_dwordx4 v[234:235], off
	s_waitcnt vmcnt(8)
	s_waitcnt lgkmcnt(0)
	s_setprio 1
	s_barrier
	v_mfma_f32_16x16x32_f16 v[128:131], v[146:149], v[178:181], v[128:131]
	v_mfma_f32_16x16x32_f16 v[124:127], v[154:157], v[178:181], v[124:127]
	v_mfma_f32_16x16x32_f16 v[120:123], v[146:149], v[186:189], v[120:123]
	v_mfma_f32_16x16x32_f16 v[116:119], v[154:157], v[186:189], v[116:119]
	v_mfma_f32_16x16x32_f16 v[104:107], v[146:149], v[194:197], v[104:107]
	v_mfma_f32_16x16x32_f16 v[100:103], v[154:157], v[194:197], v[100:103]
	v_mfma_f32_16x16x32_f16 v[88:91], v[146:149], v[220:223], v[88:91]
	v_mfma_f32_16x16x32_f16 v[84:87], v[154:157], v[220:223], v[84:87]
	v_mfma_f32_16x16x32_f16 v[128:131], v[150:153], v[182:185], v[128:131]
	v_mfma_f32_16x16x32_f16 v[124:127], v[158:161], v[182:185], v[124:127]
	v_mfma_f32_16x16x32_f16 v[120:123], v[150:153], v[190:193], v[120:123]
	v_mfma_f32_16x16x32_f16 v[116:119], v[158:161], v[190:193], v[116:119]
	v_mfma_f32_16x16x32_f16 v[104:107], v[150:153], v[204:207], v[104:107]
	v_mfma_f32_16x16x32_f16 v[100:103], v[158:161], v[204:207], v[100:103]
	v_mfma_f32_16x16x32_f16 v[88:91], v[150:153], v[224:227], v[88:91]
	v_mfma_f32_16x16x32_f16 v[84:87], v[158:161], v[224:227], v[84:87]
	v_mfma_f32_16x16x32_f16 v[112:115], v[162:165], v[178:181], v[112:115]
	v_mfma_f32_16x16x32_f16 v[108:111], v[170:173], v[178:181], v[108:111]
	v_mfma_f32_16x16x32_f16 v[96:99], v[162:165], v[186:189], v[96:99]
	v_mfma_f32_16x16x32_f16 v[92:95], v[170:173], v[186:189], v[92:95]
	v_mfma_f32_16x16x32_f16 v[80:83], v[162:165], v[194:197], v[80:83]
	v_mfma_f32_16x16x32_f16 v[76:79], v[170:173], v[194:197], v[76:79]
	v_mfma_f32_16x16x32_f16 v[72:75], v[162:165], v[220:223], v[72:75]
	v_mfma_f32_16x16x32_f16 v[68:71], v[170:173], v[220:223], v[68:71]
	v_mfma_f32_16x16x32_f16 v[112:115], v[166:169], v[182:185], v[112:115]
	v_mfma_f32_16x16x32_f16 v[108:111], v[174:177], v[182:185], v[108:111]
	v_mfma_f32_16x16x32_f16 v[96:99], v[166:169], v[190:193], v[96:99]
	v_mfma_f32_16x16x32_f16 v[92:95], v[174:177], v[190:193], v[92:95]
	v_mfma_f32_16x16x32_f16 v[80:83], v[166:169], v[204:207], v[80:83]
	v_mfma_f32_16x16x32_f16 v[76:79], v[174:177], v[204:207], v[76:79]
	v_mfma_f32_16x16x32_f16 v[72:75], v[166:169], v[224:227], v[72:75]
	v_mfma_f32_16x16x32_f16 v[68:71], v[174:177], v[224:227], v[68:71]
	s_setprio 0
	s_barrier
	s_add_i32 s10, s44, s13
	v_lshl_add_u64 v[208:209], v[208:209], 0, s[96:97]
	s_mov_b32 m0, s10
	ds_read_b128 v[178:181], v144 offset:49152
	ds_read_b128 v[182:185], v144 offset:50176
	ds_read_b128 v[186:189], v144 offset:51200
	ds_read_b128 v[190:193], v144 offset:52224
	ds_read_b128 v[194:197], v144 offset:53248
	ds_read_b128 v[204:207], v144 offset:54272
	ds_read_b128 v[220:223], v144 offset:55296
	ds_read_b128 v[224:227], v144 offset:56320
	global_load_lds_dwordx4 v[208:209], off
	s_add_i32 m0, s10, 0x2000
	s_add_u32 s8, s8, 0x80080
	v_lshl_add_u64 v[208:209], v[228:229], 0, s[96:97]
	s_addc_u32 s9, s9, 0
	s_add_i32 s10, s45, s13
	global_load_lds_dwordx4 v[208:209], off
	v_lshl_add_u64 v[208:209], s[8:9], 0, v[2:3]
	s_mov_b32 m0, s10
	s_nop 0
	global_load_lds_dwordx4 v[208:209], off
	v_lshl_add_u64 v[208:209], s[8:9], 0, v[134:135]
	s_add_i32 m0, s10, 0x2000
	s_nop 0
	global_load_lds_dwordx4 v[208:209], off
	v_lshl_add_u64 v[208:209], v[230:231], 0, s[96:97]
	s_mov_b32 m0, s24
	s_nop 0
	global_load_lds_dwordx4 v[208:209], off
	v_lshl_add_u64 v[208:209], v[232:233], 0, s[96:97]
	s_mov_b32 m0, s25
	s_nop 0
	global_load_lds_dwordx4 v[208:209], off
	s_waitcnt vmcnt(8)
	s_waitcnt lgkmcnt(0)
	s_setprio 1
	s_barrier
	v_mfma_f32_16x16x32_f16 v[64:67], v[146:149], v[178:181], v[64:67]
	v_mfma_f32_16x16x32_f16 v[60:63], v[154:157], v[178:181], v[60:63]
	v_mfma_f32_16x16x32_f16 v[56:59], v[146:149], v[186:189], v[56:59]
	v_mfma_f32_16x16x32_f16 v[52:55], v[154:157], v[186:189], v[52:55]
	v_mfma_f32_16x16x32_f16 v[40:43], v[146:149], v[194:197], v[40:43]
	v_mfma_f32_16x16x32_f16 v[36:39], v[154:157], v[194:197], v[36:39]
	v_mfma_f32_16x16x32_f16 v[24:27], v[146:149], v[220:223], v[24:27]
	v_mfma_f32_16x16x32_f16 v[20:23], v[154:157], v[220:223], v[20:23]
	v_mfma_f32_16x16x32_f16 v[64:67], v[150:153], v[182:185], v[64:67]
	v_mfma_f32_16x16x32_f16 v[60:63], v[158:161], v[182:185], v[60:63]
	v_mfma_f32_16x16x32_f16 v[56:59], v[150:153], v[190:193], v[56:59]
	v_mfma_f32_16x16x32_f16 v[52:55], v[158:161], v[190:193], v[52:55]
	v_mfma_f32_16x16x32_f16 v[40:43], v[150:153], v[204:207], v[40:43]
	v_mfma_f32_16x16x32_f16 v[36:39], v[158:161], v[204:207], v[36:39]
	v_mfma_f32_16x16x32_f16 v[24:27], v[150:153], v[224:227], v[24:27]
	v_mfma_f32_16x16x32_f16 v[20:23], v[158:161], v[224:227], v[20:23]
	v_mfma_f32_16x16x32_f16 v[48:51], v[162:165], v[178:181], v[48:51]
	v_mfma_f32_16x16x32_f16 v[44:47], v[170:173], v[178:181], v[44:47]
	v_mfma_f32_16x16x32_f16 v[32:35], v[162:165], v[186:189], v[32:35]
	v_mfma_f32_16x16x32_f16 v[28:31], v[170:173], v[186:189], v[28:31]
	v_mfma_f32_16x16x32_f16 v[16:19], v[162:165], v[194:197], v[16:19]
	v_mfma_f32_16x16x32_f16 v[12:15], v[170:173], v[194:197], v[12:15]
	v_mfma_f32_16x16x32_f16 v[8:11], v[162:165], v[220:223], v[8:11]
	v_mfma_f32_16x16x32_f16 v[4:7], v[170:173], v[220:223], v[4:7]
	v_mfma_f32_16x16x32_f16 v[48:51], v[166:169], v[182:185], v[48:51]
	v_mfma_f32_16x16x32_f16 v[44:47], v[174:177], v[182:185], v[44:47]
	v_mfma_f32_16x16x32_f16 v[32:35], v[166:169], v[190:193], v[32:35]
	v_mfma_f32_16x16x32_f16 v[28:31], v[174:177], v[190:193], v[28:31]
	v_mfma_f32_16x16x32_f16 v[16:19], v[166:169], v[204:207], v[16:19]
	v_mfma_f32_16x16x32_f16 v[12:15], v[174:177], v[204:207], v[12:15]
	v_mfma_f32_16x16x32_f16 v[8:11], v[166:169], v[224:227], v[8:11]
	v_mfma_f32_16x16x32_f16 v[4:7], v[174:177], v[224:227], v[4:7]
	s_setprio 0
	s_barrier
	s_add_i32 s37, s37, 2
	s_add_u32 s6, s6, 0x100
	s_addc_u32 s7, s7, 0
	s_cmp_gt_u32 s37, 29
	s_cbranch_scc0 .LBB0_426
	s_cmpk_lt_u32 s12, 0x100
	s_cbranch_scc0 .LBB0_429
	s_barrier

;     __device__ __forceinline__ bool next(int i, Unit& u) const { if (i != 0 || !valid) return false; u.pm = pm; u.pn = pn; return true; }
; #define PG8_WAIT_V(n) asm volatile("s_waitcnt vmcnt(" #n ")" ::: "memory")
; template <class Epi, class Sched, bool ALIGN_EPI = false, bool SP2 = false>
; __device__ __forceinline__ void gemm_phase(LAS unsigned char* lds, const Gemm g, const Sched& S, const Epi& E) {
;     ...
;     const char* cA = (const char*)g.A + (size_t)cur.pm * tstepA; const char* cB = (const char*)g.Bt + (size_t)cur.pn * tstepB;
;     S.a_ready(cur);
;     if constexpr (SP2) {
;         PG8_STAGE(PG8_SB(0, 0), cB, voffB); PG8_STAGE(PG8_SB(0, 1), cB + hstepB, voffB); PG8_STAGE(PG8_SA(0, 0), cA, voffA); PG8_STAGE(PG8_SA(0, 1), cA + hstepA, voffA);
;         if (wr == 1) PG8_BAR;
;         PG8_WAIT_V(2); PG8_BAR;
;         PG8_STAGE(PG8_SB(1, 0), cB + kstep, voffB); PG8_STAGE(PG8_SA(1, 0), cA + kstep, voffA); PG8_STAGE(PG8_SB(1, 1), cB + hstepB + kstep, voffB);
;         PG8_WAIT_V(6); PG8_BAR;
;     } else {
;         PG8_STAGE(PG8_SB(0, 0), cB, voffB); PG8_STAGE(PG8_SA(0, 0), cA, voffA); PG8_STAGE(PG8_SB(0, 1), cB + hstepB, voffB); PG8_STAGE(PG8_SA(0, 1), cA + hstepA, voffA);
;         if (wr == 1) PG8_BAR;
;         PG8_WAIT_V(4); PG8_BAR;
;         PG8_STAGE(PG8_SB(1, 0), cB + kstep, voffB); PG8_STAGE(PG8_SA(1, 0), cA + kstep, voffA); PG8_STAGE(PG8_SB(1, 1), cB + hstepB + kstep, voffB);
;         PG8_WAIT_V(6); PG8_BAR;
;     }
;     for (;;) {
;         const bool has_next = S.next(ui + 1, nxt);
;         const char* nA = has_next ? (const char*)g.A + (size_t)nxt.pm * tstepA : cA; const char* nB = has_next ? (const char*)g.Bt + (size_t)nxt.pn * tstepB : cB;
;         for (int t = 0; t < nt; t += 2) {
;             const bool last = (t == nt - 2);
;             const char* a1 = cA + (size_t)(t + 1) * kstep;
;             const char* a2 = last ? nA : cA + (size_t)(t + 2) * kstep; const char* b2 = last ? nB : cB + (size_t)(t + 2) * kstep;
;             const char* a3 = a2 + kstep; const char* b3 = b2 + kstep;
;             if (last && has_next) S.a_ready(nxt);
;             if constexpr (SP2) {
;             PG8_LDB(B0, 0, 0); PG8_LDB(B1, 0, 1); PG8_SCHED; PG8_LDA(At, 0, 0); PG8_STAGE(PG8_SA(1, 1), a1 + hstepA, voffA);
;             PG8_WAIT_V(8); PG8_WAIT_L(0); PG8_BAR; PG8_MMA(0, 0, At, B0); PG8_MMA(0, 1, At, B1); PG8_BAR; PG8_SCHED;
.LBB0_1100:
	s_ashr_i32 s15, s14, 31
	s_lshl_b64 s[38:39], s[14:15], 20
	s_add_u32 s38, s34, s38
	s_addc_u32 s39, s35, s39
	s_and_b64 s[40:41], s[0:1], exec
	s_cselect_b32 s15, s39, s23
	s_cselect_b32 s58, s38, s22
	s_ashr_i32 s13, s12, 31
	s_lshl_b64 s[40:41], s[12:13], 20
	s_add_u32 s40, s2, s40
	s_addc_u32 s41, s24, s41
	s_and_b64 s[46:47], s[0:1], exec
	s_cselect_b32 s13, s41, s17
	s_cselect_b32 s59, s40, s16
	s_add_u32 s46, s22, 0x80080
	s_addc_u32 s47, s23, 0
	s_add_u32 s60, s16, 0x100
	v_mov_b32_e32 v4, 0
	s_addc_u32 s61, s17, 0
	s_mov_b32 s62, -2
	s_add_u32 s16, s46, 0xfff80080
	s_addc_u32 s17, s47, -1
	s_add_i32 s63, 0, 0x10000
	s_cmp_eq_u32 s62, 28
	s_cselect_b32 s23, s15, s17
	s_cselect_b32 s22, s58, s16
	v_add_u32_e32 v145, s63, v142
	s_cselect_b32 s17, s13, s61
	s_cselect_b32 s16, s59, s60
	s_add_i32 s66, 0, 0x14000
	ds_read_b128 v[146:149], v145
	ds_read_b128 v[150:153], v145 offset:1024
	ds_read_b128 v[154:157], v145 offset:2048
	ds_read_b128 v[158:161], v145 offset:3072
	v_add_u32_e32 v145, s66, v142
	ds_read_b128 v[162:165], v145
	ds_read_b128 v[166:169], v145 offset:1024
	ds_read_b128 v[170:173], v145 offset:2048
	ds_read_b128 v[174:177], v145 offset:3072
	v_lshl_add_u64 v[194:195], s[46:47], 0, v[138:139]
	s_add_i32 m0, s37, 0xc000
	ds_read_b128 v[178:181], v144
	ds_read_b128 v[182:185], v144 offset:1024
	ds_read_b128 v[186:189], v144 offset:2048
	ds_read_b128 v[190:193], v144 offset:3072
	ds_read_b128 v[204:207], v144 offset:4096
	ds_read_b128 v[220:223], v144 offset:5120
	ds_read_b128 v[224:227], v144 offset:6144
	ds_read_b128 v[228:231], v144 offset:7168
	global_load_lds_dwordx4 v[194:195], off
	v_lshl_add_u64 v[194:195], s[46:47], 0, v[140:141]
	s_add_i32 m0, s37, 0xe000
	s_nop 0
	global_load_lds_dwordx4 v[194:195], off
	s_waitcnt vmcnt(8)
	s_waitcnt lgkmcnt(0)
	s_setprio 1
	s_barrier
	v_mfma_f32_16x16x32_f16 v[128:131], v[146:149], v[178:181], 0
	v_mfma_f32_16x16x32_f16 v[124:127], v[154:157], v[178:181], 0
	v_mfma_f32_16x16x32_f16 v[112:115], v[146:149], v[186:189], 0
	v_mfma_f32_16x16x32_f16 v[108:111], v[154:157], v[186:189], 0
	v_mfma_f32_16x16x32_f16 v[96:99], v[146:149], v[204:207], 0
	v_mfma_f32_16x16x32_f16 v[92:95], v[154:157], v[204:207], 0
	v_mfma_f32_16x16x32_f16 v[80:83], v[146:149], v[224:227], 0
	v_mfma_f32_16x16x32_f16 v[76:79], v[154:157], v[224:227], 0
	v_mfma_f32_16x16x32_f16 v[128:131], v[150:153], v[182:185], v[128:131]
	v_mfma_f32_16x16x32_f16 v[124:127], v[158:161], v[182:185], v[124:127]
	v_mfma_f32_16x16x32_f16 v[112:115], v[150:153], v[190:193], v[112:115]
	v_mfma_f32_16x16x32_f16 v[108:111], v[158:161], v[190:193], v[108:111]
	v_mfma_f32_16x16x32_f16 v[96:99], v[150:153], v[220:223], v[96:99]
	v_mfma_f32_16x16x32_f16 v[92:95], v[158:161], v[220:223], v[92:95]
	v_mfma_f32_16x16x32_f16 v[80:83], v[150:153], v[228:231], v[80:83]
	v_mfma_f32_16x16x32_f16 v[76:79], v[158:161], v[228:231], v[76:79]
	v_mfma_f32_16x16x32_f16 v[120:123], v[162:165], v[178:181], 0
	v_mfma_f32_16x16x32_f16 v[116:119], v[170:173], v[178:181], 0
	v_mfma_f32_16x16x32_f16 v[104:107], v[162:165], v[186:189], 0
	v_mfma_f32_16x16x32_f16 v[100:103], v[170:173], v[186:189], 0
	v_mfma_f32_16x16x32_f16 v[88:91], v[162:165], v[204:207], 0
	v_mfma_f32_16x16x32_f16 v[84:87], v[170:173], v[204:207], 0
	v_mfma_f32_16x16x32_f16 v[72:75], v[162:165], v[224:227], 0
	v_mfma_f32_16x16x32_f16 v[68:71], v[170:173], v[224:227], 0
	v_mfma_f32_16x16x32_f16 v[120:123], v[166:169], v[182:185], v[120:123]
	v_mfma_f32_16x16x32_f16 v[116:119], v[174:177], v[182:185], v[116:119]
	v_mfma_f32_16x16x32_f16 v[104:107], v[166:169], v[190:193], v[104:107]
	v_mfma_f32_16x16x32_f16 v[100:103], v[174:177], v[190:193], v[100:103]
	v_mfma_f32_16x16x32_f16 v[88:91], v[166:169], v[220:223], v[88:91]
	v_mfma_f32_16x16x32_f16 v[84:87], v[174:177], v[220:223], v[84:87]
	v_mfma_f32_16x16x32_f16 v[72:75], v[166:169], v[228:231], v[72:75]
	v_mfma_f32_16x16x32_f16 v[68:71], v[174:177], v[228:231], v[68:71]
	s_setprio 0
	s_barrier
	s_add_i32 s63, s63, s25
	v_lshl_add_u64 v[194:195], s[16:17], 0, v[2:3]
	s_mov_b32 m0, s63
	ds_read_b128 v[178:181], v144 offset:16384
	ds_read_b128 v[182:185], v144 offset:17408
	ds_read_b128 v[186:189], v144 offset:18432
	ds_read_b128 v[190:193], v144 offset:19456
	ds_read_b128 v[204:207], v144 offset:20480
	ds_read_b128 v[220:223], v144 offset:21504
	ds_read_b128 v[224:227], v144 offset:22528
	ds_read_b128 v[228:231], v144 offset:23552
	global_load_lds_dwordx4 v[194:195], off
	s_add_i32 m0, s63, 0x2000
	s_add_u32 s64, s16, 0x80000
	v_lshl_add_u64 v[196:197], s[16:17], 0, v[132:133]
	s_addc_u32 s65, s17, 0
	s_add_i32 s63, s66, s25
	global_load_lds_dwordx4 v[196:197], off
	v_lshl_add_u64 v[208:209], s[64:65], 0, v[2:3]
	s_mov_b32 m0, s63
	v_lshl_add_u64 v[232:233], s[22:23], 0, v[134:135]
	global_load_lds_dwordx4 v[208:209], off
	v_lshl_add_u64 v[208:209], s[64:65], 0, v[132:133]
	s_add_i32 m0, s63, 0x2000
	s_nop 0
	global_load_lds_dwordx4 v[208:209], off
	v_lshl_add_u64 v[208:209], s[22:23], 0, v[136:137]
	s_mov_b32 m0, s37
	s_nop 0
	global_load_lds_dwordx4 v[208:209], off
	s_mov_b32 m0, s48
	s_nop 0
	global_load_lds_dwordx4 v[232:233], off
	s_waitcnt vmcnt(8)
	s_waitcnt lgkmcnt(0)
	s_setprio 1
	s_barrier
; #define PG8_STAGE(bufoff, gbase, voff) do { _Pragma("unroll") for (int _i = 0; _i < 2; ++_i) \
;         __builtin_amdgcn_global_load_lds((const unsigned*)((const char*)(gbase) + (voff)[_i]), (LAS unsigned*)(lds + (bufoff) + ldsw + _i * 8192), 16, 0, 0); } while (0)
; #define PG8_LDA(dst, b, h) do { _Pragma("unroll") for (int m = 0; m < 4; ++m) _Pragma("unroll") for (int k = 0; k < 2; ++k) dst[m][k] = *(const LAS half8*)(lds + PG8_SA(b, h) + aoff + m * 2048 + k * 1024); } while (0)
; #define PG8_LDB(dst, b, h) do { _Pragma("unroll") for (int n = 0; n < 2; ++n) _Pragma("unroll") for (int k = 0; k < 2; ++k) dst[n][k] = *(const LAS half8*)(lds + PG8_SB(b, h) + boff + n * 2048 + k * 1024); } while (0)
; #define PG8_MMA(ai, bj, At, Bt) do { __builtin_amdgcn_s_setprio(1); _Pragma("unroll") for (int m = 0; m < 4; ++m) _Pragma("unroll") for (int n = 0; n < 2; ++n) _Pragma("unroll") for (int k = 0; k < 2; ++k) \
;         acc[ai][bj][m][n] = __builtin_amdgcn_mfma_f32_16x16x32_f16(Bt[n][k], At[m][k], acc[ai][bj][m][n], 0, 0, 0); __builtin_amdgcn_s_setprio(0); } while (0)
; #define PG8_WAIT_V(n) asm volatile("s_waitcnt vmcnt(" #n ")" ::: "memory")
; #define PG8_WAIT_L(n) asm volatile("s_waitcnt lgkmcnt(" #n ")" ::: "memory")
; #define PG8_BAR __builtin_amdgcn_s_barrier()
; #define PG8_SCHED __builtin_amdgcn_sched_barrier(0)
; template <class Epi, class Sched, bool ALIGN_EPI = false, bool SP2 = false>
; __device__ __forceinline__ void gemm_phase(LAS unsigned char* lds, const Gemm g, const Sched& S, const Epi& E) {
;     ...
;             if constexpr (SP2) {
;             PG8_LDB(B0, 0, 0); PG8_LDB(B1, 0, 1); PG8_SCHED; PG8_LDA(At, 0, 0); PG8_STAGE(PG8_SA(1, 1), a1 + hstepA, voffA);
;             PG8_WAIT_V(8); PG8_WAIT_L(0); PG8_BAR; PG8_MMA(0, 0, At, B0); PG8_MMA(0, 1, At, B1); PG8_BAR; PG8_SCHED;
;             PG8_LDA(At, 0, 1); PG8_STAGE(PG8_SB(0, 0), b2, voffB); PG8_STAGE(PG8_SB(0, 1), b2 + hstepB, voffB); PG8_STAGE(PG8_SA(0, 0), a2, voffA);
;             PG8_WAIT_V(8); PG8_WAIT_L(0); PG8_BAR; PG8_MMA(1, 0, At, B0); PG8_MMA(1, 1, At, B1); PG8_BAR; PG8_SCHED;
;             PG8_LDB(B0, 1, 0); PG8_LDB(B1, 1, 1); PG8_SCHED; PG8_LDA(At, 1, 0); PG8_STAGE(PG8_SA(0, 1), a2 + hstepA, voffA);
;             PG8_WAIT_V(8); PG8_WAIT_L(0); PG8_BAR; PG8_MMA(0, 0, At, B0); PG8_MMA(0, 1, At, B1); PG8_BAR; PG8_SCHED;
	v_mfma_f32_16x16x32_f16 v[64:67], v[146:149], v[178:181], 0
	v_mfma_f32_16x16x32_f16 v[60:63], v[154:157], v[178:181], 0
	v_mfma_f32_16x16x32_f16 v[48:51], v[146:149], v[186:189], 0
	v_mfma_f32_16x16x32_f16 v[44:47], v[154:157], v[186:189], 0
	v_mfma_f32_16x16x32_f16 v[32:35], v[146:149], v[204:207], 0
	v_mfma_f32_16x16x32_f16 v[28:31], v[154:157], v[204:207], 0
	v_mfma_f32_16x16x32_f16 v[16:19], v[146:149], v[224:227], 0
	v_mfma_f32_16x16x32_f16 v[12:15], v[154:157], v[224:227], 0
	v_mfma_f32_16x16x32_f16 v[64:67], v[150:153], v[182:185], v[64:67]
	v_mfma_f32_16x16x32_f16 v[60:63], v[158:161], v[182:185], v[60:63]
	v_mfma_f32_16x16x32_f16 v[48:51], v[150:153], v[190:193], v[48:51]
	v_mfma_f32_16x16x32_f16 v[44:47], v[158:161], v[190:193], v[44:47]
	v_mfma_f32_16x16x32_f16 v[32:35], v[150:153], v[220:223], v[32:35]
	v_mfma_f32_16x16x32_f16 v[28:31], v[158:161], v[220:223], v[28:31]
	v_mfma_f32_16x16x32_f16 v[16:19], v[150:153], v[228:231], v[16:19]
	v_mfma_f32_16x16x32_f16 v[12:15], v[158:161], v[228:231], v[12:15]
	v_mfma_f32_16x16x32_f16 v[56:59], v[162:165], v[178:181], 0
	v_mfma_f32_16x16x32_f16 v[52:55], v[170:173], v[178:181], 0
	v_mfma_f32_16x16x32_f16 v[40:43], v[162:165], v[186:189], 0
	v_mfma_f32_16x16x32_f16 v[36:39], v[170:173], v[186:189], 0
	v_mfma_f32_16x16x32_f16 v[24:27], v[162:165], v[204:207], 0
	v_mfma_f32_16x16x32_f16 v[20:23], v[170:173], v[204:207], 0
	v_mfma_f32_16x16x32_f16 v[8:11], v[162:165], v[224:227], 0
	v_mfma_f32_16x16x32_f16 v[4:7], v[170:173], v[224:227], 0
	v_mfma_f32_16x16x32_f16 v[56:59], v[166:169], v[182:185], v[56:59]
	v_mfma_f32_16x16x32_f16 v[52:55], v[174:177], v[182:185], v[52:55]
	v_mfma_f32_16x16x32_f16 v[40:43], v[166:169], v[190:193], v[40:43]
	v_mfma_f32_16x16x32_f16 v[36:39], v[174:177], v[190:193], v[36:39]
	v_mfma_f32_16x16x32_f16 v[24:27], v[166:169], v[220:223], v[24:27]
	v_mfma_f32_16x16x32_f16 v[20:23], v[174:177], v[220:223], v[20:23]
	v_mfma_f32_16x16x32_f16 v[8:11], v[166:169], v[228:231], v[8:11]
	v_mfma_f32_16x16x32_f16 v[4:7], v[174:177], v[228:231], v[4:7]
	s_setprio 0
	s_barrier
	s_add_i32 s63, 0, 0x18000
	v_add_u32_e32 v145, s63, v142
	s_add_i32 s64, 0, 0x1c000
	ds_read_b128 v[146:149], v145
	ds_read_b128 v[150:153], v145 offset:1024
	ds_read_b128 v[154:157], v145 offset:2048
	ds_read_b128 v[158:161], v145 offset:3072
	v_add_u32_e32 v145, s64, v142
	ds_read_b128 v[162:165], v145
	ds_read_b128 v[166:169], v145 offset:1024
	ds_read_b128 v[170:173], v145 offset:2048
	ds_read_b128 v[174:177], v145 offset:3072
	s_add_u32 s22, s22, 0x80000
	s_addc_u32 s23, s23, 0
	s_mov_b32 m0, s49
	v_lshl_add_u64 v[234:235], s[22:23], 0, v[136:137]
	ds_read_b128 v[178:181], v144 offset:32768
	ds_read_b128 v[182:185], v144 offset:33792
	ds_read_b128 v[186:189], v144 offset:34816
	ds_read_b128 v[190:193], v144 offset:35840
	ds_read_b128 v[204:207], v144 offset:36864
	ds_read_b128 v[220:223], v144 offset:37888
	ds_read_b128 v[224:227], v144 offset:38912
	ds_read_b128 v[228:231], v144 offset:39936
	global_load_lds_dwordx4 v[234:235], off
	v_lshl_add_u64 v[234:235], s[22:23], 0, v[134:135]
	s_mov_b32 m0, s52
	s_nop 0
	global_load_lds_dwordx4 v[234:235], off
	s_waitcnt vmcnt(8)
	s_waitcnt lgkmcnt(0)
	s_setprio 1
	s_barrier
	v_mfma_f32_16x16x32_f16 v[128:131], v[146:149], v[178:181], v[128:131]
	v_mfma_f32_16x16x32_f16 v[124:127], v[154:157], v[178:181], v[124:127]
	v_mfma_f32_16x16x32_f16 v[112:115], v[146:149], v[186:189], v[112:115]
	v_mfma_f32_16x16x32_f16 v[108:111], v[154:157], v[186:189], v[108:111]
	v_mfma_f32_16x16x32_f16 v[96:99], v[146:149], v[204:207], v[96:99]
	v_mfma_f32_16x16x32_f16 v[92:95], v[154:157], v[204:207], v[92:95]
	v_mfma_f32_16x16x32_f16 v[80:83], v[146:149], v[224:227], v[80:83]
	v_mfma_f32_16x16x32_f16 v[76:79], v[154:157], v[224:227], v[76:79]
	v_mfma_f32_16x16x32_f16 v[128:131], v[150:153], v[182:185], v[128:131]
	v_mfma_f32_16x16x32_f16 v[124:127], v[158:161], v[182:185], v[124:127]
	v_mfma_f32_16x16x32_f16 v[112:115], v[150:153], v[190:193], v[112:115]
	v_mfma_f32_16x16x32_f16 v[108:111], v[158:161], v[190:193], v[108:111]
	v_mfma_f32_16x16x32_f16 v[96:99], v[150:153], v[220:223], v[96:99]
	v_mfma_f32_16x16x32_f16 v[92:95], v[158:161], v[220:223], v[92:95]
	v_mfma_f32_16x16x32_f16 v[80:83], v[150:153], v[228:231], v[80:83]
	v_mfma_f32_16x16x32_f16 v[76:79], v[158:161], v[228:231], v[76:79]
	v_mfma_f32_16x16x32_f16 v[120:123], v[162:165], v[178:181], v[120:123]
	v_mfma_f32_16x16x32_f16 v[116:119], v[170:173], v[178:181], v[116:119]
	v_mfma_f32_16x16x32_f16 v[104:107], v[162:165], v[186:189], v[104:107]
	v_mfma_f32_16x16x32_f16 v[100:103], v[170:173], v[186:189], v[100:103]
	v_mfma_f32_16x16x32_f16 v[88:91], v[162:165], v[204:207], v[88:91]
	v_mfma_f32_16x16x32_f16 v[84:87], v[170:173], v[204:207], v[84:87]
	v_mfma_f32_16x16x32_f16 v[72:75], v[162:165], v[224:227], v[72:75]
	v_mfma_f32_16x16x32_f16 v[68:71], v[170:173], v[224:227], v[68:71]
	v_mfma_f32_16x16x32_f16 v[120:123], v[166:169], v[182:185], v[120:123]
	v_mfma_f32_16x16x32_f16 v[116:119], v[174:177], v[182:185], v[116:119]
	v_mfma_f32_16x16x32_f16 v[104:107], v[166:169], v[190:193], v[104:107]
	v_mfma_f32_16x16x32_f16 v[100:103], v[174:177], v[190:193], v[100:103]
	v_mfma_f32_16x16x32_f16 v[88:91], v[166:169], v[220:223], v[88:91]
	v_mfma_f32_16x16x32_f16 v[84:87], v[174:177], v[220:223], v[84:87]
	v_mfma_f32_16x16x32_f16 v[72:75], v[166:169], v[228:231], v[72:75]
	v_mfma_f32_16x16x32_f16 v[68:71], v[174:177], v[228:231], v[68:71]
	s_setprio 0
	s_barrier
; #define PG8_STAGE(bufoff, gbase, voff) do { _Pragma("unroll") for (int _i = 0; _i < 2; ++_i) \
;         __builtin_amdgcn_global_load_lds((const unsigned*)((const char*)(gbase) + (voff)[_i]), (LAS unsigned*)(lds + (bufoff) + ldsw + _i * 8192), 16, 0, 0); } while (0)
; #define PG8_LDA(dst, b, h) do { _Pragma("unroll") for (int m = 0; m < 4; ++m) _Pragma("unroll") for (int k = 0; k < 2; ++k) dst[m][k] = *(const LAS half8*)(lds + PG8_SA(b, h) + aoff + m * 2048 + k * 1024); } while (0)
; #define PG8_WAIT_V(n) asm volatile("s_waitcnt vmcnt(" #n ")" ::: "memory")
; template <class Epi, class Sched, bool ALIGN_EPI = false, bool SP2 = false>
; __device__ __forceinline__ void gemm_phase(LAS unsigned char* lds, const Gemm g, const Sched& S, const Epi& E) {
;     ...
;         for (int t = 0; t < nt; t += 2) {
;             const bool last = (t == nt - 2);
;             const char* a1 = cA + (size_t)(t + 1) * kstep;
;             const char* a2 = last ? nA : cA + (size_t)(t + 2) * kstep; const char* b2 = last ? nB : cB + (size_t)(t + 2) * kstep;
;             const char* a3 = a2 + kstep; const char* b3 = b2 + kstep;
;             if (last && has_next) S.a_ready(nxt);
;             if constexpr (SP2) {
;             PG8_LDB(B0, 0, 0); PG8_LDB(B1, 0, 1); PG8_SCHED; PG8_LDA(At, 0, 0); PG8_STAGE(PG8_SA(1, 1), a1 + hstepA, voffA);
;             PG8_WAIT_V(8); PG8_WAIT_L(0); PG8_BAR; PG8_MMA(0, 0, At, B0); PG8_MMA(0, 1, At, B1); PG8_BAR; PG8_SCHED;
;             PG8_LDA(At, 0, 1); PG8_STAGE(PG8_SB(0, 0), b2, voffB); PG8_STAGE(PG8_SB(0, 1), b2 + hstepB, voffB); PG8_STAGE(PG8_SA(0, 0), a2, voffA);
;             PG8_WAIT_V(8); PG8_WAIT_L(0); PG8_BAR; PG8_MMA(1, 0, At, B0); PG8_MMA(1, 1, At, B1); PG8_BAR; PG8_SCHED;
;             PG8_LDB(B0, 1, 0); PG8_LDB(B1, 1, 1); PG8_SCHED; PG8_LDA(At, 1, 0); PG8_STAGE(PG8_SA(0, 1), a2 + hstepA, voffA);
;             PG8_WAIT_V(8); PG8_WAIT_L(0); PG8_BAR; PG8_MMA(0, 0, At, B0); PG8_MMA(0, 1, At, B1); PG8_BAR; PG8_SCHED;
;             PG8_LDA(At, 1, 1); PG8_STAGE(PG8_SB(1, 0), b3, voffB); PG8_STAGE(PG8_SB(1, 1), b3 + hstepB, voffB); PG8_STAGE(PG8_SA(1, 0), a3, voffA);
;             PG8_WAIT_V(8); PG8_WAIT_L(0); PG8_BAR; PG8_MMA(1, 0, At, B0); PG8_MMA(1, 1, At, B1); PG8_BAR; PG8_SCHED;
;             } else {
;             PG8_LDB(B0, 0, 0); PG8_SCHED; PG8_LDA(At, 0, 0); PG8_STAGE(PG8_SA(1, 1), a1 + hstepA, voffA);
	s_add_i32 s22, s63, s25
	v_lshl_add_u64 v[194:195], v[194:195], 0, s[96:97]
	s_mov_b32 m0, s22
	ds_read_b128 v[178:181], v144 offset:49152
	ds_read_b128 v[182:185], v144 offset:50176
	ds_read_b128 v[186:189], v144 offset:51200
	ds_read_b128 v[190:193], v144 offset:52224
	ds_read_b128 v[204:207], v144 offset:53248
	ds_read_b128 v[220:223], v144 offset:54272
	ds_read_b128 v[224:227], v144 offset:55296
	ds_read_b128 v[228:231], v144 offset:56320
	global_load_lds_dwordx4 v[194:195], off
	s_add_i32 m0, s22, 0x2000
	s_add_u32 s16, s16, 0x80080
	v_lshl_add_u64 v[194:195], v[196:197], 0, s[96:97]
	s_addc_u32 s17, s17, 0
	s_add_i32 s22, s64, s25
	global_load_lds_dwordx4 v[194:195], off
	v_lshl_add_u64 v[194:195], s[16:17], 0, v[2:3]
	s_mov_b32 m0, s22
	s_nop 0
	global_load_lds_dwordx4 v[194:195], off
	v_lshl_add_u64 v[194:195], s[16:17], 0, v[132:133]
	s_add_i32 m0, s22, 0x2000
	s_nop 0
	global_load_lds_dwordx4 v[194:195], off
	v_lshl_add_u64 v[194:195], v[208:209], 0, s[96:97]
	s_mov_b32 m0, s53
	s_nop 0
	global_load_lds_dwordx4 v[194:195], off
	v_lshl_add_u64 v[194:195], v[232:233], 0, s[96:97]
	s_mov_b32 m0, s54
	s_nop 0
	global_load_lds_dwordx4 v[194:195], off
	s_waitcnt vmcnt(8)
	s_waitcnt lgkmcnt(0)
	s_setprio 1
	s_barrier
	v_mfma_f32_16x16x32_f16 v[64:67], v[146:149], v[178:181], v[64:67]
	v_mfma_f32_16x16x32_f16 v[60:63], v[154:157], v[178:181], v[60:63]
	v_mfma_f32_16x16x32_f16 v[48:51], v[146:149], v[186:189], v[48:51]
	v_mfma_f32_16x16x32_f16 v[44:47], v[154:157], v[186:189], v[44:47]
	v_mfma_f32_16x16x32_f16 v[32:35], v[146:149], v[204:207], v[32:35]
	v_mfma_f32_16x16x32_f16 v[28:31], v[154:157], v[204:207], v[28:31]
	v_mfma_f32_16x16x32_f16 v[16:19], v[146:149], v[224:227], v[16:19]
	v_mfma_f32_16x16x32_f16 v[12:15], v[154:157], v[224:227], v[12:15]
	v_mfma_f32_16x16x32_f16 v[64:67], v[150:153], v[182:185], v[64:67]
	v_mfma_f32_16x16x32_f16 v[60:63], v[158:161], v[182:185], v[60:63]
	v_mfma_f32_16x16x32_f16 v[48:51], v[150:153], v[190:193], v[48:51]
	v_mfma_f32_16x16x32_f16 v[44:47], v[158:161], v[190:193], v[44:47]
	v_mfma_f32_16x16x32_f16 v[32:35], v[150:153], v[220:223], v[32:35]
	v_mfma_f32_16x16x32_f16 v[28:31], v[158:161], v[220:223], v[28:31]
	v_mfma_f32_16x16x32_f16 v[16:19], v[150:153], v[228:231], v[16:19]
	v_mfma_f32_16x16x32_f16 v[12:15], v[158:161], v[228:231], v[12:15]
	v_mfma_f32_16x16x32_f16 v[56:59], v[162:165], v[178:181], v[56:59]
	v_mfma_f32_16x16x32_f16 v[52:55], v[170:173], v[178:181], v[52:55]
	v_mfma_f32_16x16x32_f16 v[40:43], v[162:165], v[186:189], v[40:43]
	v_mfma_f32_16x16x32_f16 v[36:39], v[170:173], v[186:189], v[36:39]
	v_mfma_f32_16x16x32_f16 v[24:27], v[162:165], v[204:207], v[24:27]
	v_mfma_f32_16x16x32_f16 v[20:23], v[170:173], v[204:207], v[20:23]
	v_mfma_f32_16x16x32_f16 v[8:11], v[162:165], v[224:227], v[8:11]
	v_mfma_f32_16x16x32_f16 v[4:7], v[170:173], v[224:227], v[4:7]
	v_mfma_f32_16x16x32_f16 v[56:59], v[166:169], v[182:185], v[56:59]
	v_mfma_f32_16x16x32_f16 v[52:55], v[174:177], v[182:185], v[52:55]
	v_mfma_f32_16x16x32_f16 v[40:43], v[166:169], v[190:193], v[40:43]
	v_mfma_f32_16x16x32_f16 v[36:39], v[174:177], v[190:193], v[36:39]
	v_mfma_f32_16x16x32_f16 v[24:27], v[166:169], v[220:223], v[24:27]
	v_mfma_f32_16x16x32_f16 v[20:23], v[174:177], v[220:223], v[20:23]
	v_mfma_f32_16x16x32_f16 v[8:11], v[166:169], v[228:231], v[8:11]
	v_mfma_f32_16x16x32_f16 v[4:7], v[174:177], v[228:231], v[4:7]
	s_setprio 0
	s_barrier
	s_add_i32 s62, s62, 2
	s_add_u32 s46, s46, 0x100
	s_addc_u32 s47, s47, 0
	s_add_u32 s60, s60, 0x100
	s_addc_u32 s61, s61, 0
	s_cmp_gt_u32 s62, 29
	s_cbranch_scc0 .LBB0_1101
.LBB0_1101:
	s_add_u32 s16, s46, 0xfff80080
	s_addc_u32 s17, s47, -1
	s_add_i32 s63, 0, 0x10000
	s_cmp_eq_u32 s62, 28
	s_cselect_b32 s23, s15, s17
	s_cselect_b32 s22, s58, s16
	v_add_u32_e32 v145, s63, v142
	s_cselect_b32 s17, s13, s61
	s_cselect_b32 s16, s59, s60
	s_add_i32 s66, 0, 0x14000
	ds_read_b128 v[146:149], v145
	ds_read_b128 v[150:153], v145 offset:1024
	ds_read_b128 v[154:157], v145 offset:2048
	ds_read_b128 v[158:161], v145 offset:3072
	v_add_u32_e32 v145, s66, v142
	ds_read_b128 v[162:165], v145
	ds_read_b128 v[166:169], v145 offset:1024
	ds_read_b128 v[170:173], v145 offset:2048
	ds_read_b128 v[174:177], v145 offset:3072
	v_lshl_add_u64 v[194:195], s[46:47], 0, v[138:139]
	s_add_i32 m0, s37, 0xc000
	ds_read_b128 v[178:181], v144
	ds_read_b128 v[182:185], v144 offset:1024
	ds_read_b128 v[186:189], v144 offset:2048
	ds_read_b128 v[190:193], v144 offset:3072
	ds_read_b128 v[204:207], v144 offset:4096
	ds_read_b128 v[220:223], v144 offset:5120
	ds_read_b128 v[224:227], v144 offset:6144
	ds_read_b128 v[228:231], v144 offset:7168
	global_load_lds_dwordx4 v[194:195], off
	v_lshl_add_u64 v[194:195], s[46:47], 0, v[140:141]
	s_add_i32 m0, s37, 0xe000
	s_nop 0
	global_load_lds_dwordx4 v[194:195], off
	s_waitcnt vmcnt(8)
	s_waitcnt lgkmcnt(0)
	s_setprio 1
	s_barrier
; #define PG8_STAGE(bufoff, gbase, voff) do { _Pragma("unroll") for (int _i = 0; _i < 2; ++_i) \
;         __builtin_amdgcn_global_load_lds((const unsigned*)((const char*)(gbase) + (voff)[_i]), (LAS unsigned*)(lds + (bufoff) + ldsw + _i * 8192), 16, 0, 0); } while (0)
; #define PG8_LDA(dst, b, h) do { _Pragma("unroll") for (int m = 0; m < 4; ++m) _Pragma("unroll") for (int k = 0; k < 2; ++k) dst[m][k] = *(const LAS half8*)(lds + PG8_SA(b, h) + aoff + m * 2048 + k * 1024); } while (0)
; #define PG8_LDB(dst, b, h) do { _Pragma("unroll") for (int n = 0; n < 2; ++n) _Pragma("unroll") for (int k = 0; k < 2; ++k) dst[n][k] = *(const LAS half8*)(lds + PG8_SB(b, h) + boff + n * 2048 + k * 1024); } while (0)
; #define PG8_MMA(ai, bj, At, Bt) do { __builtin_amdgcn_s_setprio(1); _Pragma("unroll") for (int m = 0; m < 4; ++m) _Pragma("unroll") for (int n = 0; n < 2; ++n) _Pragma("unroll") for (int k = 0; k < 2; ++k) \
;         acc[ai][bj][m][n] = __builtin_amdgcn_mfma_f32_16x16x32_f16(Bt[n][k], At[m][k], acc[ai][bj][m][n], 0, 0, 0); __builtin_amdgcn_s_setprio(0); } while (0)
; #define PG8_WAIT_V(n) asm volatile("s_waitcnt vmcnt(" #n ")" ::: "memory")
; #define PG8_WAIT_L(n) asm volatile("s_waitcnt lgkmcnt(" #n ")" ::: "memory")
; #define PG8_BAR __builtin_amdgcn_s_barrier()
; #define PG8_SCHED __builtin_amdgcn_sched_barrier(0)
; template <class Epi, class Sched, bool ALIGN_EPI = false, bool SP2 = false>
; __device__ __forceinline__ void gemm_phase(LAS unsigned char* lds, const Gemm g, const Sched& S, const Epi& E) {
;     ...
;             if constexpr (SP2) {
;             PG8_LDB(B0, 0, 0); PG8_LDB(B1, 0, 1); PG8_SCHED; PG8_LDA(At, 0, 0); PG8_STAGE(PG8_SA(1, 1), a1 + hstepA, voffA);
;             PG8_WAIT_V(8); PG8_WAIT_L(0); PG8_BAR; PG8_MMA(0, 0, At, B0); PG8_MMA(0, 1, At, B1); PG8_BAR; PG8_SCHED;
;             PG8_LDA(At, 0, 1); PG8_STAGE(PG8_SB(0, 0), b2, voffB); PG8_STAGE(PG8_SB(0, 1), b2 + hstepB, voffB); PG8_STAGE(PG8_SA(0, 0), a2, voffA);
;             PG8_WAIT_V(8); PG8_WAIT_L(0); PG8_BAR; PG8_MMA(1, 0, At, B0); PG8_MMA(1, 1, At, B1); PG8_BAR; PG8_SCHED;
	v_mfma_f32_16x16x32_f16 v[128:131], v[146:149], v[178:181], v[128:131]
	v_mfma_f32_16x16x32_f16 v[124:127], v[154:157], v[178:181], v[124:127]
	v_mfma_f32_16x16x32_f16 v[112:115], v[146:149], v[186:189], v[112:115]
	v_mfma_f32_16x16x32_f16 v[108:111], v[154:157], v[186:189], v[108:111]
	v_mfma_f32_16x16x32_f16 v[96:99], v[146:149], v[204:207], v[96:99]
	v_mfma_f32_16x16x32_f16 v[92:95], v[154:157], v[204:207], v[92:95]
	v_mfma_f32_16x16x32_f16 v[80:83], v[146:149], v[224:227], v[80:83]
	v_mfma_f32_16x16x32_f16 v[76:79], v[154:157], v[224:227], v[76:79]
	v_mfma_f32_16x16x32_f16 v[128:131], v[150:153], v[182:185], v[128:131]
	v_mfma_f32_16x16x32_f16 v[124:127], v[158:161], v[182:185], v[124:127]
	v_mfma_f32_16x16x32_f16 v[112:115], v[150:153], v[190:193], v[112:115]
	v_mfma_f32_16x16x32_f16 v[108:111], v[158:161], v[190:193], v[108:111]
	v_mfma_f32_16x16x32_f16 v[96:99], v[150:153], v[220:223], v[96:99]
	v_mfma_f32_16x16x32_f16 v[92:95], v[158:161], v[220:223], v[92:95]
	v_mfma_f32_16x16x32_f16 v[80:83], v[150:153], v[228:231], v[80:83]
	v_mfma_f32_16x16x32_f16 v[76:79], v[158:161], v[228:231], v[76:79]
	v_mfma_f32_16x16x32_f16 v[120:123], v[162:165], v[178:181], v[120:123]
	v_mfma_f32_16x16x32_f16 v[116:119], v[170:173], v[178:181], v[116:119]
	v_mfma_f32_16x16x32_f16 v[104:107], v[162:165], v[186:189], v[104:107]
	v_mfma_f32_16x16x32_f16 v[100:103], v[170:173], v[186:189], v[100:103]
	v_mfma_f32_16x16x32_f16 v[88:91], v[162:165], v[204:207], v[88:91]
	v_mfma_f32_16x16x32_f16 v[84:87], v[170:173], v[204:207], v[84:87]
	v_mfma_f32_16x16x32_f16 v[72:75], v[162:165], v[224:227], v[72:75]
	v_mfma_f32_16x16x32_f16 v[68:71], v[170:173], v[224:227], v[68:71]
	v_mfma_f32_16x16x32_f16 v[120:123], v[166:169], v[182:185], v[120:123]
	v_mfma_f32_16x16x32_f16 v[116:119], v[174:177], v[182:185], v[116:119]
	v_mfma_f32_16x16x32_f16 v[104:107], v[166:169], v[190:193], v[104:107]
	v_mfma_f32_16x16x32_f16 v[100:103], v[174:177], v[190:193], v[100:103]
	v_mfma_f32_16x16x32_f16 v[88:91], v[166:169], v[220:223], v[88:91]
	v_mfma_f32_16x16x32_f16 v[84:87], v[174:177], v[220:223], v[84:87]
	v_mfma_f32_16x16x32_f16 v[72:75], v[166:169], v[228:231], v[72:75]
	v_mfma_f32_16x16x32_f16 v[68:71], v[174:177], v[228:231], v[68:71]
	s_setprio 0
	s_barrier
	s_add_i32 s63, s63, s25
	v_lshl_add_u64 v[194:195], s[16:17], 0, v[2:3]
	s_mov_b32 m0, s63
	ds_read_b128 v[178:181], v144 offset:16384
	ds_read_b128 v[182:185], v144 offset:17408
	ds_read_b128 v[186:189], v144 offset:18432
	ds_read_b128 v[190:193], v144 offset:19456
	ds_read_b128 v[204:207], v144 offset:20480
	ds_read_b128 v[220:223], v144 offset:21504
	ds_read_b128 v[224:227], v144 offset:22528
	ds_read_b128 v[228:231], v144 offset:23552
	global_load_lds_dwordx4 v[194:195], off
	s_add_i32 m0, s63, 0x2000
	s_add_u32 s64, s16, 0x80000
	v_lshl_add_u64 v[196:197], s[16:17], 0, v[132:133]
	s_addc_u32 s65, s17, 0
	s_add_i32 s63, s66, s25
	global_load_lds_dwordx4 v[196:197], off
	v_lshl_add_u64 v[208:209], s[64:65], 0, v[2:3]
	s_mov_b32 m0, s63
	v_lshl_add_u64 v[232:233], s[22:23], 0, v[134:135]
	global_load_lds_dwordx4 v[208:209], off
	v_lshl_add_u64 v[208:209], s[64:65], 0, v[132:133]
	s_add_i32 m0, s63, 0x2000
	s_nop 0
	global_load_lds_dwordx4 v[208:209], off
	v_lshl_add_u64 v[208:209], s[22:23], 0, v[136:137]
	s_mov_b32 m0, s37
	s_nop 0
	global_load_lds_dwordx4 v[208:209], off
	s_mov_b32 m0, s48
	s_nop 0
	global_load_lds_dwordx4 v[232:233], off
	s_waitcnt vmcnt(8)
	s_waitcnt lgkmcnt(0)
	s_setprio 1
	s_barrier
	v_mfma_f32_16x16x32_f16 v[64:67], v[146:149], v[178:181], v[64:67]
	v_mfma_f32_16x16x32_f16 v[60:63], v[154:157], v[178:181], v[60:63]
	v_mfma_f32_16x16x32_f16 v[48:51], v[146:149], v[186:189], v[48:51]
	v_mfma_f32_16x16x32_f16 v[44:47], v[154:157], v[186:189], v[44:47]
	v_mfma_f32_16x16x32_f16 v[32:35], v[146:149], v[204:207], v[32:35]
	v_mfma_f32_16x16x32_f16 v[28:31], v[154:157], v[204:207], v[28:31]
	v_mfma_f32_16x16x32_f16 v[16:19], v[146:149], v[224:227], v[16:19]
	v_mfma_f32_16x16x32_f16 v[12:15], v[154:157], v[224:227], v[12:15]
	v_mfma_f32_16x16x32_f16 v[64:67], v[150:153], v[182:185], v[64:67]
	v_mfma_f32_16x16x32_f16 v[60:63], v[158:161], v[182:185], v[60:63]
	v_mfma_f32_16x16x32_f16 v[48:51], v[150:153], v[190:193], v[48:51]
	v_mfma_f32_16x16x32_f16 v[44:47], v[158:161], v[190:193], v[44:47]
	v_mfma_f32_16x16x32_f16 v[32:35], v[150:153], v[220:223], v[32:35]
	v_mfma_f32_16x16x32_f16 v[28:31], v[158:161], v[220:223], v[28:31]
	v_mfma_f32_16x16x32_f16 v[16:19], v[150:153], v[228:231], v[16:19]
	v_mfma_f32_16x16x32_f16 v[12:15], v[158:161], v[228:231], v[12:15]
	v_mfma_f32_16x16x32_f16 v[56:59], v[162:165], v[178:181], v[56:59]
	v_mfma_f32_16x16x32_f16 v[52:55], v[170:173], v[178:181], v[52:55]
	v_mfma_f32_16x16x32_f16 v[40:43], v[162:165], v[186:189], v[40:43]
	v_mfma_f32_16x16x32_f16 v[36:39], v[170:173], v[186:189], v[36:39]
	v_mfma_f32_16x16x32_f16 v[24:27], v[162:165], v[204:207], v[24:27]
	v_mfma_f32_16x16x32_f16 v[20:23], v[170:173], v[204:207], v[20:23]
	v_mfma_f32_16x16x32_f16 v[8:11], v[162:165], v[224:227], v[8:11]
	v_mfma_f32_16x16x32_f16 v[4:7], v[170:173], v[224:227], v[4:7]
	v_mfma_f32_16x16x32_f16 v[56:59], v[166:169], v[182:185], v[56:59]
	v_mfma_f32_16x16x32_f16 v[52:55], v[174:177], v[182:185], v[52:55]
	v_mfma_f32_16x16x32_f16 v[40:43], v[166:169], v[190:193], v[40:43]
	v_mfma_f32_16x16x32_f16 v[36:39], v[174:177], v[190:193], v[36:39]
	v_mfma_f32_16x16x32_f16 v[24:27], v[166:169], v[220:223], v[24:27]
	v_mfma_f32_16x16x32_f16 v[20:23], v[174:177], v[220:223], v[20:23]
	v_mfma_f32_16x16x32_f16 v[8:11], v[166:169], v[228:231], v[8:11]
	v_mfma_f32_16x16x32_f16 v[4:7], v[174:177], v[228:231], v[4:7]
	s_setprio 0
	s_barrier
; #define PG8_STAGE(bufoff, gbase, voff) do { _Pragma("unroll") for (int _i = 0; _i < 2; ++_i) \
;         __builtin_amdgcn_global_load_lds((const unsigned*)((const char*)(gbase) + (voff)[_i]), (LAS unsigned*)(lds + (bufoff) + ldsw + _i * 8192), 16, 0, 0); } while (0)
; #define PG8_LDA(dst, b, h) do { _Pragma("unroll") for (int m = 0; m < 4; ++m) _Pragma("unroll") for (int k = 0; k < 2; ++k) dst[m][k] = *(const LAS half8*)(lds + PG8_SA(b, h) + aoff + m * 2048 + k * 1024); } while (0)
; #define PG8_LDB(dst, b, h) do { _Pragma("unroll") for (int n = 0; n < 2; ++n) _Pragma("unroll") for (int k = 0; k < 2; ++k) dst[n][k] = *(const LAS half8*)(lds + PG8_SB(b, h) + boff + n * 2048 + k * 1024); } while (0)
; #define PG8_MMA(ai, bj, At, Bt) do { __builtin_amdgcn_s_setprio(1); _Pragma("unroll") for (int m = 0; m < 4; ++m) _Pragma("unroll") for (int n = 0; n < 2; ++n) _Pragma("unroll") for (int k = 0; k < 2; ++k) \
;         acc[ai][bj][m][n] = __builtin_amdgcn_mfma_f32_16x16x32_f16(Bt[n][k], At[m][k], acc[ai][bj][m][n], 0, 0, 0); __builtin_amdgcn_s_setprio(0); } while (0)
; #define PG8_WAIT_V(n) asm volatile("s_waitcnt vmcnt(" #n ")" ::: "memory")
; #define PG8_WAIT_L(n) asm volatile("s_waitcnt lgkmcnt(" #n ")" ::: "memory")
; #define PG8_BAR __builtin_amdgcn_s_barrier()
; #define PG8_SCHED __builtin_amdgcn_sched_barrier(0)
; template <class Epi, class Sched, bool ALIGN_EPI = false, bool SP2 = false>
; __device__ __forceinline__ void gemm_phase(LAS unsigned char* lds, const Gemm g, const Sched& S, const Epi& E) {
;     ...
;             PG8_LDB(B0, 1, 0); PG8_LDB(B1, 1, 1); PG8_SCHED; PG8_LDA(At, 1, 0); PG8_STAGE(PG8_SA(0, 1), a2 + hstepA, voffA);
;             PG8_WAIT_V(8); PG8_WAIT_L(0); PG8_BAR; PG8_MMA(0, 0, At, B0); PG8_MMA(0, 1, At, B1); PG8_BAR; PG8_SCHED;
	s_add_i32 s63, 0, 0x18000
	v_add_u32_e32 v145, s63, v142
	s_add_i32 s64, 0, 0x1c000
	ds_read_b128 v[146:149], v145
	ds_read_b128 v[150:153], v145 offset:1024
	ds_read_b128 v[154:157], v145 offset:2048
	ds_read_b128 v[158:161], v145 offset:3072
	v_add_u32_e32 v145, s64, v142
	ds_read_b128 v[162:165], v145
	ds_read_b128 v[166:169], v145 offset:1024
	ds_read_b128 v[170:173], v145 offset:2048
	ds_read_b128 v[174:177], v145 offset:3072
	s_add_u32 s22, s22, 0x80000
	s_addc_u32 s23, s23, 0
	s_mov_b32 m0, s49
	v_lshl_add_u64 v[234:235], s[22:23], 0, v[136:137]
	ds_read_b128 v[178:181], v144 offset:32768
	ds_read_b128 v[182:185], v144 offset:33792
	ds_read_b128 v[186:189], v144 offset:34816
	ds_read_b128 v[190:193], v144 offset:35840
	ds_read_b128 v[204:207], v144 offset:36864
	ds_read_b128 v[220:223], v144 offset:37888
	ds_read_b128 v[224:227], v144 offset:38912
	ds_read_b128 v[228:231], v144 offset:39936
	global_load_lds_dwordx4 v[234:235], off
	v_lshl_add_u64 v[234:235], s[22:23], 0, v[134:135]
	s_mov_b32 m0, s52
	s_nop 0
	global_load_lds_dwordx4 v[234:235], off
	s_waitcnt vmcnt(8)
	s_waitcnt lgkmcnt(0)
	s_setprio 1
	s_barrier
	v_mfma_f32_16x16x32_f16 v[128:131], v[146:149], v[178:181], v[128:131]
	v_mfma_f32_16x16x32_f16 v[124:127], v[154:157], v[178:181], v[124:127]
	v_mfma_f32_16x16x32_f16 v[112:115], v[146:149], v[186:189], v[112:115]
	v_mfma_f32_16x16x32_f16 v[108:111], v[154:157], v[186:189], v[108:111]
	v_mfma_f32_16x16x32_f16 v[96:99], v[146:149], v[204:207], v[96:99]
	v_mfma_f32_16x16x32_f16 v[92:95], v[154:157], v[204:207], v[92:95]
	v_mfma_f32_16x16x32_f16 v[80:83], v[146:149], v[224:227], v[80:83]
	v_mfma_f32_16x16x32_f16 v[76:79], v[154:157], v[224:227], v[76:79]
	v_mfma_f32_16x16x32_f16 v[128:131], v[150:153], v[182:185], v[128:131]
	v_mfma_f32_16x16x32_f16 v[124:127], v[158:161], v[182:185], v[124:127]
	v_mfma_f32_16x16x32_f16 v[112:115], v[150:153], v[190:193], v[112:115]
	v_mfma_f32_16x16x32_f16 v[108:111], v[158:161], v[190:193], v[108:111]
	v_mfma_f32_16x16x32_f16 v[96:99], v[150:153], v[220:223], v[96:99]
	v_mfma_f32_16x16x32_f16 v[92:95], v[158:161], v[220:223], v[92:95]
	v_mfma_f32_16x16x32_f16 v[80:83], v[150:153], v[228:231], v[80:83]
	v_mfma_f32_16x16x32_f16 v[76:79], v[158:161], v[228:231], v[76:79]
	v_mfma_f32_16x16x32_f16 v[120:123], v[162:165], v[178:181], v[120:123]
	v_mfma_f32_16x16x32_f16 v[116:119], v[170:173], v[178:181], v[116:119]
	v_mfma_f32_16x16x32_f16 v[104:107], v[162:165], v[186:189], v[104:107]
	v_mfma_f32_16x16x32_f16 v[100:103], v[170:173], v[186:189], v[100:103]
	v_mfma_f32_16x16x32_f16 v[88:91], v[162:165], v[204:207], v[88:91]
	v_mfma_f32_16x16x32_f16 v[84:87], v[170:173], v[204:207], v[84:87]
	v_mfma_f32_16x16x32_f16 v[72:75], v[162:165], v[224:227], v[72:75]
	v_mfma_f32_16x16x32_f16 v[68:71], v[170:173], v[224:227], v[68:71]
	v_mfma_f32_16x16x32_f16 v[120:123], v[166:169], v[182:185], v[120:123]
	v_mfma_f32_16x16x32_f16 v[116:119], v[174:177], v[182:185], v[116:119]
	v_mfma_f32_16x16x32_f16 v[104:107], v[166:169], v[190:193], v[104:107]
	v_mfma_f32_16x16x32_f16 v[100:103], v[174:177], v[190:193], v[100:103]
	v_mfma_f32_16x16x32_f16 v[88:91], v[166:169], v[220:223], v[88:91]
	v_mfma_f32_16x16x32_f16 v[84:87], v[174:177], v[220:223], v[84:87]
	v_mfma_f32_16x16x32_f16 v[72:75], v[166:169], v[228:231], v[72:75]
	v_mfma_f32_16x16x32_f16 v[68:71], v[174:177], v[228:231], v[68:71]
	s_setprio 0
	s_barrier
; #define PG8_STAGE(bufoff, gbase, voff) do { _Pragma("unroll") for (int _i = 0; _i < 2; ++_i) \
;         __builtin_amdgcn_global_load_lds((const unsigned*)((const char*)(gbase) + (voff)[_i]), (LAS unsigned*)(lds + (bufoff) + ldsw + _i * 8192), 16, 0, 0); } while (0)
; #define PG8_LDA(dst, b, h) do { _Pragma("unroll") for (int m = 0; m < 4; ++m) _Pragma("unroll") for (int k = 0; k < 2; ++k) dst[m][k] = *(const LAS half8*)(lds + PG8_SA(b, h) + aoff + m * 2048 + k * 1024); } while (0)
; #define PG8_MMA(ai, bj, At, Bt) do { __builtin_amdgcn_s_setprio(1); _Pragma("unroll") for (int m = 0; m < 4; ++m) _Pragma("unroll") for (int n = 0; n < 2; ++n) _Pragma("unroll") for (int k = 0; k < 2; ++k) \
;         acc[ai][bj][m][n] = __builtin_amdgcn_mfma_f32_16x16x32_f16(Bt[n][k], At[m][k], acc[ai][bj][m][n], 0, 0, 0); __builtin_amdgcn_s_setprio(0); } while (0)
; #define PG8_WAIT_V(n) asm volatile("s_waitcnt vmcnt(" #n ")" ::: "memory")
; #define PG8_WAIT_L(n) asm volatile("s_waitcnt lgkmcnt(" #n ")" ::: "memory")
; #define PG8_BAR __builtin_amdgcn_s_barrier()
; #define PG8_SCHED __builtin_amdgcn_sched_barrier(0)
; template <class Epi, class Sched, bool ALIGN_EPI = false, bool SP2 = false>
; __device__ __forceinline__ void gemm_phase(LAS unsigned char* lds, const Gemm g, const Sched& S, const Epi& E) {
;     ...
;         for (int t = 0; t < nt; t += 2) {
;     ...
;             PG8_LDA(At, 1, 1); PG8_STAGE(PG8_SB(1, 0), b3, voffB); PG8_STAGE(PG8_SB(1, 1), b3 + hstepB, voffB); PG8_STAGE(PG8_SA(1, 0), a3, voffA);
;             PG8_WAIT_V(8); PG8_WAIT_L(0); PG8_BAR; PG8_MMA(1, 0, At, B0); PG8_MMA(1, 1, At, B1); PG8_BAR; PG8_SCHED;
;     ...
;         if constexpr (ALIGN_EPI) { if (wr == 0) PG8_BAR; }
	s_add_i32 s22, s63, s25
	v_lshl_add_u64 v[194:195], v[194:195], 0, s[96:97]
	s_mov_b32 m0, s22
	ds_read_b128 v[178:181], v144 offset:49152
	ds_read_b128 v[182:185], v144 offset:50176
	ds_read_b128 v[186:189], v144 offset:51200
	ds_read_b128 v[190:193], v144 offset:52224
	ds_read_b128 v[204:207], v144 offset:53248
	ds_read_b128 v[220:223], v144 offset:54272
	ds_read_b128 v[224:227], v144 offset:55296
	ds_read_b128 v[228:231], v144 offset:56320
	global_load_lds_dwordx4 v[194:195], off
	s_add_i32 m0, s22, 0x2000
	s_add_u32 s16, s16, 0x80080
	v_lshl_add_u64 v[194:195], v[196:197], 0, s[96:97]
	s_addc_u32 s17, s17, 0
	s_add_i32 s22, s64, s25
	global_load_lds_dwordx4 v[194:195], off
	v_lshl_add_u64 v[194:195], s[16:17], 0, v[2:3]
	s_mov_b32 m0, s22
	s_nop 0
	global_load_lds_dwordx4 v[194:195], off
	v_lshl_add_u64 v[194:195], s[16:17], 0, v[132:133]
	s_add_i32 m0, s22, 0x2000
	s_nop 0
	global_load_lds_dwordx4 v[194:195], off
	v_lshl_add_u64 v[194:195], v[208:209], 0, s[96:97]
	s_mov_b32 m0, s53
	s_nop 0
	global_load_lds_dwordx4 v[194:195], off
	v_lshl_add_u64 v[194:195], v[232:233], 0, s[96:97]
	s_mov_b32 m0, s54
	s_nop 0
	global_load_lds_dwordx4 v[194:195], off
	s_waitcnt vmcnt(8)
	s_waitcnt lgkmcnt(0)
	s_setprio 1
	s_barrier
	v_mfma_f32_16x16x32_f16 v[64:67], v[146:149], v[178:181], v[64:67]
	v_mfma_f32_16x16x32_f16 v[60:63], v[154:157], v[178:181], v[60:63]
	v_mfma_f32_16x16x32_f16 v[48:51], v[146:149], v[186:189], v[48:51]
	v_mfma_f32_16x16x32_f16 v[44:47], v[154:157], v[186:189], v[44:47]
	v_mfma_f32_16x16x32_f16 v[32:35], v[146:149], v[204:207], v[32:35]
	v_mfma_f32_16x16x32_f16 v[28:31], v[154:157], v[204:207], v[28:31]
	v_mfma_f32_16x16x32_f16 v[16:19], v[146:149], v[224:227], v[16:19]
	v_mfma_f32_16x16x32_f16 v[12:15], v[154:157], v[224:227], v[12:15]
	v_mfma_f32_16x16x32_f16 v[64:67], v[150:153], v[182:185], v[64:67]
	v_mfma_f32_16x16x32_f16 v[60:63], v[158:161], v[182:185], v[60:63]
	v_mfma_f32_16x16x32_f16 v[48:51], v[150:153], v[190:193], v[48:51]
	v_mfma_f32_16x16x32_f16 v[44:47], v[158:161], v[190:193], v[44:47]
	v_mfma_f32_16x16x32_f16 v[32:35], v[150:153], v[220:223], v[32:35]
	v_mfma_f32_16x16x32_f16 v[28:31], v[158:161], v[220:223], v[28:31]
	v_mfma_f32_16x16x32_f16 v[16:19], v[150:153], v[228:231], v[16:19]
	v_mfma_f32_16x16x32_f16 v[12:15], v[158:161], v[228:231], v[12:15]
	v_mfma_f32_16x16x32_f16 v[56:59], v[162:165], v[178:181], v[56:59]
	v_mfma_f32_16x16x32_f16 v[52:55], v[170:173], v[178:181], v[52:55]
	v_mfma_f32_16x16x32_f16 v[40:43], v[162:165], v[186:189], v[40:43]
	v_mfma_f32_16x16x32_f16 v[36:39], v[170:173], v[186:189], v[36:39]
	v_mfma_f32_16x16x32_f16 v[24:27], v[162:165], v[204:207], v[24:27]
	v_mfma_f32_16x16x32_f16 v[20:23], v[170:173], v[204:207], v[20:23]
	v_mfma_f32_16x16x32_f16 v[8:11], v[162:165], v[224:227], v[8:11]
	v_mfma_f32_16x16x32_f16 v[4:7], v[170:173], v[224:227], v[4:7]
	v_mfma_f32_16x16x32_f16 v[56:59], v[166:169], v[182:185], v[56:59]
	v_mfma_f32_16x16x32_f16 v[52:55], v[174:177], v[182:185], v[52:55]
	v_mfma_f32_16x16x32_f16 v[40:43], v[166:169], v[190:193], v[40:43]
	v_mfma_f32_16x16x32_f16 v[36:39], v[174:177], v[190:193], v[36:39]
	v_mfma_f32_16x16x32_f16 v[24:27], v[166:169], v[220:223], v[24:27]
	v_mfma_f32_16x16x32_f16 v[20:23], v[174:177], v[220:223], v[20:23]
	v_mfma_f32_16x16x32_f16 v[8:11], v[166:169], v[228:231], v[8:11]
	v_mfma_f32_16x16x32_f16 v[4:7], v[174:177], v[228:231], v[4:7]
	s_setprio 0
	s_barrier
	s_add_i32 s62, s62, 2
	s_add_u32 s46, s46, 0x100
	s_addc_u32 s47, s47, 0
	s_add_u32 s60, s60, 0x100
	s_addc_u32 s61, s61, 0
	s_cmp_gt_u32 s62, 29
	s_cbranch_scc0 .LBB0_1101
	s_and_b64 vcc, exec, s[10:11]
	s_cbranch_vccz .LBB0_1104
	s_barrier

;     __device__ __forceinline__ bool next(int i, Unit& u) const { if (i != 0 || !valid) return false; u.pm = pm; u.pn = pn; return true; }
; #define PG8_WAIT_V(n) asm volatile("s_waitcnt vmcnt(" #n ")" ::: "memory")
; template <class Epi, class Sched, bool ALIGN_EPI = false, bool SP2 = false>
; __device__ __forceinline__ void gemm_phase(LAS unsigned char* lds, const Gemm g, const Sched& S, const Epi& E) {
;     ...
;     const char* cA = (const char*)g.A + (size_t)cur.pm * tstepA; const char* cB = (const char*)g.Bt + (size_t)cur.pn * tstepB;
;     S.a_ready(cur);
;     if constexpr (SP2) {
;         PG8_STAGE(PG8_SB(0, 0), cB, voffB); PG8_STAGE(PG8_SB(0, 1), cB + hstepB, voffB); PG8_STAGE(PG8_SA(0, 0), cA, voffA); PG8_STAGE(PG8_SA(0, 1), cA + hstepA, voffA);
;         if (wr == 1) PG8_BAR;
;         PG8_WAIT_V(2); PG8_BAR;
;         PG8_STAGE(PG8_SB(1, 0), cB + kstep, voffB); PG8_STAGE(PG8_SA(1, 0), cA + kstep, voffA); PG8_STAGE(PG8_SB(1, 1), cB + hstepB + kstep, voffB);
;         PG8_WAIT_V(6); PG8_BAR;
;     } else {
;         PG8_STAGE(PG8_SB(0, 0), cB, voffB); PG8_STAGE(PG8_SA(0, 0), cA, voffA); PG8_STAGE(PG8_SB(0, 1), cB + hstepB, voffB); PG8_STAGE(PG8_SA(0, 1), cA + hstepA, voffA);
;         if (wr == 1) PG8_BAR;
;         PG8_WAIT_V(4); PG8_BAR;
;         PG8_STAGE(PG8_SB(1, 0), cB + kstep, voffB); PG8_STAGE(PG8_SA(1, 0), cA + kstep, voffA); PG8_STAGE(PG8_SB(1, 1), cB + hstepB + kstep, voffB);
;         PG8_WAIT_V(6); PG8_BAR;
;     }
;     for (;;) {
;         const bool has_next = S.next(ui + 1, nxt);
;         const char* nA = has_next ? (const char*)g.A + (size_t)nxt.pm * tstepA : cA; const char* nB = has_next ? (const char*)g.Bt + (size_t)nxt.pn * tstepB : cB;
;         for (int t = 0; t < nt; t += 2) {
;             const bool last = (t == nt - 2);
;             const char* a1 = cA + (size_t)(t + 1) * kstep;
;             const char* a2 = last ? nA : cA + (size_t)(t + 2) * kstep; const char* b2 = last ? nB : cB + (size_t)(t + 2) * kstep;
;             const char* a3 = a2 + kstep; const char* b3 = b2 + kstep;
;             if (last && has_next) S.a_ready(nxt);
;             if constexpr (SP2) {
;             PG8_LDB(B0, 0, 0); PG8_LDB(B1, 0, 1); PG8_SCHED; PG8_LDA(At, 0, 0); PG8_STAGE(PG8_SA(1, 1), a1 + hstepA, voffA);
;             PG8_WAIT_V(8); PG8_WAIT_L(0); PG8_BAR; PG8_MMA(0, 0, At, B0); PG8_MMA(0, 1, At, B1); PG8_BAR; PG8_SCHED;
.LBB0_1707:
	s_ashr_i32 s69, s68, 31
	s_lshl_b64 s[6:7], s[68:69], 20
	s_add_u32 s50, s34, s6
	s_addc_u32 s51, s35, s7
	s_and_b64 s[6:7], s[40:41], exec
	s_cselect_b32 s2, s51, s1
	s_cselect_b32 s12, s50, s0
	s_ashr_i32 s67, s66, 31
	s_lshl_b64 s[6:7], s[66:67], 20
	s_add_u32 s6, s37, s6
	s_addc_u32 s7, s25, s7
	s_and_b64 s[10:11], s[40:41], exec
	s_cselect_b32 s13, s7, s9
	s_cselect_b32 s14, s6, s8
	s_add_u32 s0, s0, 0x80080
	s_addc_u32 s1, s1, 0
	s_add_u32 s15, s8, 0x100
	v_mov_b32_e32 v4, 0
	s_addc_u32 s16, s9, 0
	s_mov_b32 s17, -2
	s_waitcnt lgkmcnt(0)
	s_waitcnt vmcnt(0)
	s_add_u32 s8, s0, 0xfff80080
	s_addc_u32 s9, s1, -1
	s_add_i32 s22, 0, 0x10000
	s_cmp_eq_u32 s17, 28
	s_cselect_b32 s11, s2, s9
	s_cselect_b32 s10, s12, s8
	v_add_u32_e32 v2, s22, v189
	s_cselect_b32 s9, s13, s16
	s_cselect_b32 s8, s14, s15
	s_add_i32 s44, 0, 0x14000
	ds_read_b128 v[132:135], v2
	ds_read_b128 v[136:139], v2 offset:1024
	ds_read_b128 v[140:143], v2 offset:2048
	ds_read_b128 v[144:147], v2 offset:3072
	v_add_u32_e32 v2, s44, v189
	ds_read_b128 v[148:151], v2
	ds_read_b128 v[152:155], v2 offset:1024
	ds_read_b128 v[156:159], v2 offset:2048
	ds_read_b128 v[160:163], v2 offset:3072
	v_lshl_add_u64 v[194:195], s[0:1], 0, v[172:173]
	s_add_i32 m0, s57, 0xc000
	ds_read_b128 v[176:179], v193
	ds_read_b128 v[180:183], v193 offset:1024
	ds_read_b128 v[184:187], v193 offset:2048
	ds_read_b128 v[204:207], v193 offset:3072
	ds_read_b128 v[220:223], v193 offset:4096
	ds_read_b128 v[224:227], v193 offset:5120
	ds_read_b128 v[228:231], v193 offset:6144
	ds_read_b128 v[232:235], v193 offset:7168
	global_load_lds_dwordx4 v[194:195], off
	v_lshl_add_u64 v[194:195], s[0:1], 0, v[174:175]
	s_add_i32 m0, s57, 0xe000
	s_nop 0
	global_load_lds_dwordx4 v[194:195], off
	s_waitcnt vmcnt(8)
	s_waitcnt lgkmcnt(0)
	s_setprio 1
	s_barrier
	v_mfma_f32_16x16x32_f16 v[128:131], v[132:135], v[176:179], 0
	v_mfma_f32_16x16x32_f16 v[124:127], v[140:143], v[176:179], 0
	v_mfma_f32_16x16x32_f16 v[112:115], v[132:135], v[184:187], 0
	v_mfma_f32_16x16x32_f16 v[108:111], v[140:143], v[184:187], 0
	v_mfma_f32_16x16x32_f16 v[96:99], v[132:135], v[220:223], 0
	v_mfma_f32_16x16x32_f16 v[92:95], v[140:143], v[220:223], 0
	v_mfma_f32_16x16x32_f16 v[80:83], v[132:135], v[228:231], 0
	v_mfma_f32_16x16x32_f16 v[76:79], v[140:143], v[228:231], 0
	v_mfma_f32_16x16x32_f16 v[128:131], v[136:139], v[180:183], v[128:131]
	v_mfma_f32_16x16x32_f16 v[124:127], v[144:147], v[180:183], v[124:127]
	v_mfma_f32_16x16x32_f16 v[112:115], v[136:139], v[204:207], v[112:115]
	v_mfma_f32_16x16x32_f16 v[108:111], v[144:147], v[204:207], v[108:111]
	v_mfma_f32_16x16x32_f16 v[96:99], v[136:139], v[224:227], v[96:99]
	v_mfma_f32_16x16x32_f16 v[92:95], v[144:147], v[224:227], v[92:95]
	v_mfma_f32_16x16x32_f16 v[80:83], v[136:139], v[232:235], v[80:83]
	v_mfma_f32_16x16x32_f16 v[76:79], v[144:147], v[232:235], v[76:79]
	v_mfma_f32_16x16x32_f16 v[120:123], v[148:151], v[176:179], 0
	v_mfma_f32_16x16x32_f16 v[116:119], v[156:159], v[176:179], 0
	v_mfma_f32_16x16x32_f16 v[104:107], v[148:151], v[184:187], 0
	v_mfma_f32_16x16x32_f16 v[100:103], v[156:159], v[184:187], 0
	v_mfma_f32_16x16x32_f16 v[88:91], v[148:151], v[220:223], 0
	v_mfma_f32_16x16x32_f16 v[84:87], v[156:159], v[220:223], 0
	v_mfma_f32_16x16x32_f16 v[72:75], v[148:151], v[228:231], 0
	v_mfma_f32_16x16x32_f16 v[68:71], v[156:159], v[228:231], 0
	v_mfma_f32_16x16x32_f16 v[120:123], v[152:155], v[180:183], v[120:123]
	v_mfma_f32_16x16x32_f16 v[116:119], v[160:163], v[180:183], v[116:119]
	v_mfma_f32_16x16x32_f16 v[104:107], v[152:155], v[204:207], v[104:107]
	v_mfma_f32_16x16x32_f16 v[100:103], v[160:163], v[204:207], v[100:103]
	v_mfma_f32_16x16x32_f16 v[88:91], v[152:155], v[224:227], v[88:91]
	v_mfma_f32_16x16x32_f16 v[84:87], v[160:163], v[224:227], v[84:87]
	v_mfma_f32_16x16x32_f16 v[72:75], v[152:155], v[232:235], v[72:75]
	v_mfma_f32_16x16x32_f16 v[68:71], v[160:163], v[232:235], v[68:71]
	s_setprio 0
	s_barrier
	s_add_i32 s22, s22, s56
	v_lshl_add_u64 v[194:195], s[8:9], 0, v[168:169]
	s_mov_b32 m0, s22
	ds_read_b128 v[176:179], v193 offset:16384
	ds_read_b128 v[180:183], v193 offset:17408
	ds_read_b128 v[184:187], v193 offset:18432
	ds_read_b128 v[204:207], v193 offset:19456
	ds_read_b128 v[220:223], v193 offset:20480
	ds_read_b128 v[224:227], v193 offset:21504
	ds_read_b128 v[228:231], v193 offset:22528
	ds_read_b128 v[232:235], v193 offset:23552
	global_load_lds_dwordx4 v[194:195], off
	s_add_i32 m0, s22, 0x2000
	s_add_u32 s22, s8, 0x80000
	v_lshl_add_u64 v[196:197], s[8:9], 0, v[164:165]
	s_addc_u32 s23, s9, 0
	s_add_i32 s44, s44, s56
	global_load_lds_dwordx4 v[196:197], off
	v_lshl_add_u64 v[208:209], s[22:23], 0, v[168:169]
	s_mov_b32 m0, s44
	v_lshl_add_u64 v[236:237], s[10:11], 0, v[166:167]
	global_load_lds_dwordx4 v[208:209], off
	v_lshl_add_u64 v[208:209], s[22:23], 0, v[164:165]
	s_add_i32 m0, s44, 0x2000
	s_nop 0
	global_load_lds_dwordx4 v[208:209], off
	v_lshl_add_u64 v[208:209], s[10:11], 0, v[170:171]
	s_mov_b32 m0, s57
	s_nop 0
	global_load_lds_dwordx4 v[208:209], off
	s_mov_b32 m0, s58
	s_nop 0
	global_load_lds_dwordx4 v[236:237], off
	s_waitcnt vmcnt(8)
	s_waitcnt lgkmcnt(0)
	s_setprio 1
	s_barrier
; #define PG8_STAGE(bufoff, gbase, voff) do { _Pragma("unroll") for (int _i = 0; _i < 2; ++_i) \
;         __builtin_amdgcn_global_load_lds((const unsigned*)((const char*)(gbase) + (voff)[_i]), (LAS unsigned*)(lds + (bufoff) + ldsw + _i * 8192), 16, 0, 0); } while (0)
; #define PG8_LDA(dst, b, h) do { _Pragma("unroll") for (int m = 0; m < 4; ++m) _Pragma("unroll") for (int k = 0; k < 2; ++k) dst[m][k] = *(const LAS half8*)(lds + PG8_SA(b, h) + aoff + m * 2048 + k * 1024); } while (0)
; #define PG8_LDB(dst, b, h) do { _Pragma("unroll") for (int n = 0; n < 2; ++n) _Pragma("unroll") for (int k = 0; k < 2; ++k) dst[n][k] = *(const LAS half8*)(lds + PG8_SB(b, h) + boff + n * 2048 + k * 1024); } while (0)
; #define PG8_MMA(ai, bj, At, Bt) do { __builtin_amdgcn_s_setprio(1); _Pragma("unroll") for (int m = 0; m < 4; ++m) _Pragma("unroll") for (int n = 0; n < 2; ++n) _Pragma("unroll") for (int k = 0; k < 2; ++k) \
;         acc[ai][bj][m][n] = __builtin_amdgcn_mfma_f32_16x16x32_f16(Bt[n][k], At[m][k], acc[ai][bj][m][n], 0, 0, 0); __builtin_amdgcn_s_setprio(0); } while (0)
; #define PG8_WAIT_V(n) asm volatile("s_waitcnt vmcnt(" #n ")" ::: "memory")
; #define PG8_WAIT_L(n) asm volatile("s_waitcnt lgkmcnt(" #n ")" ::: "memory")
; #define PG8_BAR __builtin_amdgcn_s_barrier()
; #define PG8_SCHED __builtin_amdgcn_sched_barrier(0)
; template <class Epi, class Sched, bool ALIGN_EPI = false, bool SP2 = false>
; __device__ __forceinline__ void gemm_phase(LAS unsigned char* lds, const Gemm g, const Sched& S, const Epi& E) {
;     ...
;             if constexpr (SP2) {
;             PG8_LDB(B0, 0, 0); PG8_LDB(B1, 0, 1); PG8_SCHED; PG8_LDA(At, 0, 0); PG8_STAGE(PG8_SA(1, 1), a1 + hstepA, voffA);
;             PG8_WAIT_V(8); PG8_WAIT_L(0); PG8_BAR; PG8_MMA(0, 0, At, B0); PG8_MMA(0, 1, At, B1); PG8_BAR; PG8_SCHED;
;             PG8_LDA(At, 0, 1); PG8_STAGE(PG8_SB(0, 0), b2, voffB); PG8_STAGE(PG8_SB(0, 1), b2 + hstepB, voffB); PG8_STAGE(PG8_SA(0, 0), a2, voffA);
;             PG8_WAIT_V(8); PG8_WAIT_L(0); PG8_BAR; PG8_MMA(1, 0, At, B0); PG8_MMA(1, 1, At, B1); PG8_BAR; PG8_SCHED;
;             PG8_LDB(B0, 1, 0); PG8_LDB(B1, 1, 1); PG8_SCHED; PG8_LDA(At, 1, 0); PG8_STAGE(PG8_SA(0, 1), a2 + hstepA, voffA);
;             PG8_WAIT_V(8); PG8_WAIT_L(0); PG8_BAR; PG8_MMA(0, 0, At, B0); PG8_MMA(0, 1, At, B1); PG8_BAR; PG8_SCHED;
	v_mfma_f32_16x16x32_f16 v[64:67], v[132:135], v[176:179], 0
	v_mfma_f32_16x16x32_f16 v[60:63], v[140:143], v[176:179], 0
	v_mfma_f32_16x16x32_f16 v[48:51], v[132:135], v[184:187], 0
	v_mfma_f32_16x16x32_f16 v[44:47], v[140:143], v[184:187], 0
	v_mfma_f32_16x16x32_f16 v[32:35], v[132:135], v[220:223], 0
	v_mfma_f32_16x16x32_f16 v[28:31], v[140:143], v[220:223], 0
	v_mfma_f32_16x16x32_f16 v[16:19], v[132:135], v[228:231], 0
	v_mfma_f32_16x16x32_f16 v[12:15], v[140:143], v[228:231], 0
	v_mfma_f32_16x16x32_f16 v[64:67], v[136:139], v[180:183], v[64:67]
	v_mfma_f32_16x16x32_f16 v[60:63], v[144:147], v[180:183], v[60:63]
	v_mfma_f32_16x16x32_f16 v[48:51], v[136:139], v[204:207], v[48:51]
	v_mfma_f32_16x16x32_f16 v[44:47], v[144:147], v[204:207], v[44:47]
	v_mfma_f32_16x16x32_f16 v[32:35], v[136:139], v[224:227], v[32:35]
	v_mfma_f32_16x16x32_f16 v[28:31], v[144:147], v[224:227], v[28:31]
	v_mfma_f32_16x16x32_f16 v[16:19], v[136:139], v[232:235], v[16:19]
	v_mfma_f32_16x16x32_f16 v[12:15], v[144:147], v[232:235], v[12:15]
	v_mfma_f32_16x16x32_f16 v[56:59], v[148:151], v[176:179], 0
	v_mfma_f32_16x16x32_f16 v[52:55], v[156:159], v[176:179], 0
	v_mfma_f32_16x16x32_f16 v[40:43], v[148:151], v[184:187], 0
	v_mfma_f32_16x16x32_f16 v[36:39], v[156:159], v[184:187], 0
	v_mfma_f32_16x16x32_f16 v[24:27], v[148:151], v[220:223], 0
	v_mfma_f32_16x16x32_f16 v[20:23], v[156:159], v[220:223], 0
	v_mfma_f32_16x16x32_f16 v[8:11], v[148:151], v[228:231], 0
	v_mfma_f32_16x16x32_f16 v[4:7], v[156:159], v[228:231], 0
	v_mfma_f32_16x16x32_f16 v[56:59], v[152:155], v[180:183], v[56:59]
	v_mfma_f32_16x16x32_f16 v[52:55], v[160:163], v[180:183], v[52:55]
	v_mfma_f32_16x16x32_f16 v[40:43], v[152:155], v[204:207], v[40:43]
	v_mfma_f32_16x16x32_f16 v[36:39], v[160:163], v[204:207], v[36:39]
	v_mfma_f32_16x16x32_f16 v[24:27], v[152:155], v[224:227], v[24:27]
	v_mfma_f32_16x16x32_f16 v[20:23], v[160:163], v[224:227], v[20:23]
	v_mfma_f32_16x16x32_f16 v[8:11], v[152:155], v[232:235], v[8:11]
	v_mfma_f32_16x16x32_f16 v[4:7], v[160:163], v[232:235], v[4:7]
	s_setprio 0
	s_barrier
	s_add_i32 s22, 0, 0x18000
	v_add_u32_e32 v2, s22, v189
	s_add_i32 s23, 0, 0x1c000
	ds_read_b128 v[132:135], v2
	ds_read_b128 v[136:139], v2 offset:1024
	ds_read_b128 v[140:143], v2 offset:2048
	ds_read_b128 v[144:147], v2 offset:3072
	v_add_u32_e32 v2, s23, v189
	ds_read_b128 v[148:151], v2
	ds_read_b128 v[152:155], v2 offset:1024
	ds_read_b128 v[156:159], v2 offset:2048
	ds_read_b128 v[160:163], v2 offset:3072
	s_add_u32 s10, s10, 0x80000
	s_addc_u32 s11, s11, 0
	s_mov_b32 m0, s59
	v_lshl_add_u64 v[240:241], s[10:11], 0, v[170:171]
	ds_read_b128 v[176:179], v193 offset:32768
	ds_read_b128 v[180:183], v193 offset:33792
	ds_read_b128 v[184:187], v193 offset:34816
	ds_read_b128 v[204:207], v193 offset:35840
	ds_read_b128 v[220:223], v193 offset:36864
	ds_read_b128 v[224:227], v193 offset:37888
	ds_read_b128 v[228:231], v193 offset:38912
	ds_read_b128 v[232:235], v193 offset:39936
	global_load_lds_dwordx4 v[240:241], off
	v_lshl_add_u64 v[240:241], s[10:11], 0, v[166:167]
	s_mov_b32 m0, s60
	s_nop 0
	global_load_lds_dwordx4 v[240:241], off
	s_waitcnt vmcnt(8)
	s_waitcnt lgkmcnt(0)
	s_setprio 1
	s_barrier
	v_mfma_f32_16x16x32_f16 v[128:131], v[132:135], v[176:179], v[128:131]
	v_mfma_f32_16x16x32_f16 v[124:127], v[140:143], v[176:179], v[124:127]
	v_mfma_f32_16x16x32_f16 v[112:115], v[132:135], v[184:187], v[112:115]
	v_mfma_f32_16x16x32_f16 v[108:111], v[140:143], v[184:187], v[108:111]
	v_mfma_f32_16x16x32_f16 v[96:99], v[132:135], v[220:223], v[96:99]
	v_mfma_f32_16x16x32_f16 v[92:95], v[140:143], v[220:223], v[92:95]
	v_mfma_f32_16x16x32_f16 v[80:83], v[132:135], v[228:231], v[80:83]
	v_mfma_f32_16x16x32_f16 v[76:79], v[140:143], v[228:231], v[76:79]
	v_mfma_f32_16x16x32_f16 v[128:131], v[136:139], v[180:183], v[128:131]
	v_mfma_f32_16x16x32_f16 v[124:127], v[144:147], v[180:183], v[124:127]
	v_mfma_f32_16x16x32_f16 v[112:115], v[136:139], v[204:207], v[112:115]
	v_mfma_f32_16x16x32_f16 v[108:111], v[144:147], v[204:207], v[108:111]
	v_mfma_f32_16x16x32_f16 v[96:99], v[136:139], v[224:227], v[96:99]
	v_mfma_f32_16x16x32_f16 v[92:95], v[144:147], v[224:227], v[92:95]
	v_mfma_f32_16x16x32_f16 v[80:83], v[136:139], v[232:235], v[80:83]
	v_mfma_f32_16x16x32_f16 v[76:79], v[144:147], v[232:235], v[76:79]
	v_mfma_f32_16x16x32_f16 v[120:123], v[148:151], v[176:179], v[120:123]
	v_mfma_f32_16x16x32_f16 v[116:119], v[156:159], v[176:179], v[116:119]
	v_mfma_f32_16x16x32_f16 v[104:107], v[148:151], v[184:187], v[104:107]
	v_mfma_f32_16x16x32_f16 v[100:103], v[156:159], v[184:187], v[100:103]
	v_mfma_f32_16x16x32_f16 v[88:91], v[148:151], v[220:223], v[88:91]
	v_mfma_f32_16x16x32_f16 v[84:87], v[156:159], v[220:223], v[84:87]
	v_mfma_f32_16x16x32_f16 v[72:75], v[148:151], v[228:231], v[72:75]
	v_mfma_f32_16x16x32_f16 v[68:71], v[156:159], v[228:231], v[68:71]
	v_mfma_f32_16x16x32_f16 v[120:123], v[152:155], v[180:183], v[120:123]
	v_mfma_f32_16x16x32_f16 v[116:119], v[160:163], v[180:183], v[116:119]
	v_mfma_f32_16x16x32_f16 v[104:107], v[152:155], v[204:207], v[104:107]
	v_mfma_f32_16x16x32_f16 v[100:103], v[160:163], v[204:207], v[100:103]
	v_mfma_f32_16x16x32_f16 v[88:91], v[152:155], v[224:227], v[88:91]
	v_mfma_f32_16x16x32_f16 v[84:87], v[160:163], v[224:227], v[84:87]
	v_mfma_f32_16x16x32_f16 v[72:75], v[152:155], v[232:235], v[72:75]
	v_mfma_f32_16x16x32_f16 v[68:71], v[160:163], v[232:235], v[68:71]
	s_setprio 0
	s_barrier
; #define PG8_STAGE(bufoff, gbase, voff) do { _Pragma("unroll") for (int _i = 0; _i < 2; ++_i) \
;         __builtin_amdgcn_global_load_lds((const unsigned*)((const char*)(gbase) + (voff)[_i]), (LAS unsigned*)(lds + (bufoff) + ldsw + _i * 8192), 16, 0, 0); } while (0)
; #define PG8_LDA(dst, b, h) do { _Pragma("unroll") for (int m = 0; m < 4; ++m) _Pragma("unroll") for (int k = 0; k < 2; ++k) dst[m][k] = *(const LAS half8*)(lds + PG8_SA(b, h) + aoff + m * 2048 + k * 1024); } while (0)
; #define PG8_WAIT_V(n) asm volatile("s_waitcnt vmcnt(" #n ")" ::: "memory")
; template <class Epi, class Sched, bool ALIGN_EPI = false, bool SP2 = false>
; __device__ __forceinline__ void gemm_phase(LAS unsigned char* lds, const Gemm g, const Sched& S, const Epi& E) {
;     ...
;         for (int t = 0; t < nt; t += 2) {
;             const bool last = (t == nt - 2);
;             const char* a1 = cA + (size_t)(t + 1) * kstep;
;             const char* a2 = last ? nA : cA + (size_t)(t + 2) * kstep; const char* b2 = last ? nB : cB + (size_t)(t + 2) * kstep;
;             const char* a3 = a2 + kstep; const char* b3 = b2 + kstep;
;             if (last && has_next) S.a_ready(nxt);
;             if constexpr (SP2) {
;             PG8_LDB(B0, 0, 0); PG8_LDB(B1, 0, 1); PG8_SCHED; PG8_LDA(At, 0, 0); PG8_STAGE(PG8_SA(1, 1), a1 + hstepA, voffA);
;             PG8_WAIT_V(8); PG8_WAIT_L(0); PG8_BAR; PG8_MMA(0, 0, At, B0); PG8_MMA(0, 1, At, B1); PG8_BAR; PG8_SCHED;
;             PG8_LDA(At, 0, 1); PG8_STAGE(PG8_SB(0, 0), b2, voffB); PG8_STAGE(PG8_SB(0, 1), b2 + hstepB, voffB); PG8_STAGE(PG8_SA(0, 0), a2, voffA);
;             PG8_WAIT_V(8); PG8_WAIT_L(0); PG8_BAR; PG8_MMA(1, 0, At, B0); PG8_MMA(1, 1, At, B1); PG8_BAR; PG8_SCHED;
;             PG8_LDB(B0, 1, 0); PG8_LDB(B1, 1, 1); PG8_SCHED; PG8_LDA(At, 1, 0); PG8_STAGE(PG8_SA(0, 1), a2 + hstepA, voffA);
;             PG8_WAIT_V(8); PG8_WAIT_L(0); PG8_BAR; PG8_MMA(0, 0, At, B0); PG8_MMA(0, 1, At, B1); PG8_BAR; PG8_SCHED;
;             PG8_LDA(At, 1, 1); PG8_STAGE(PG8_SB(1, 0), b3, voffB); PG8_STAGE(PG8_SB(1, 1), b3 + hstepB, voffB); PG8_STAGE(PG8_SA(1, 0), a3, voffA);
;             PG8_WAIT_V(8); PG8_WAIT_L(0); PG8_BAR; PG8_MMA(1, 0, At, B0); PG8_MMA(1, 1, At, B1); PG8_BAR; PG8_SCHED;
;             } else {
;             PG8_LDB(B0, 0, 0); PG8_SCHED; PG8_LDA(At, 0, 0); PG8_STAGE(PG8_SA(1, 1), a1 + hstepA, voffA);
	s_add_i32 s10, s22, s56
	v_lshl_add_u64 v[194:195], v[194:195], 0, s[96:97]
	s_mov_b32 m0, s10
	ds_read_b128 v[176:179], v193 offset:49152
	ds_read_b128 v[180:183], v193 offset:50176
	ds_read_b128 v[184:187], v193 offset:51200
	ds_read_b128 v[204:207], v193 offset:52224
	ds_read_b128 v[220:223], v193 offset:53248
	ds_read_b128 v[224:227], v193 offset:54272
	ds_read_b128 v[228:231], v193 offset:55296
	ds_read_b128 v[232:235], v193 offset:56320
	global_load_lds_dwordx4 v[194:195], off
	s_add_i32 m0, s10, 0x2000
	s_add_u32 s8, s8, 0x80080
	v_lshl_add_u64 v[194:195], v[196:197], 0, s[96:97]
	s_addc_u32 s9, s9, 0
	s_add_i32 s10, s23, s56
	global_load_lds_dwordx4 v[194:195], off
	v_lshl_add_u64 v[194:195], s[8:9], 0, v[168:169]
	s_mov_b32 m0, s10
	s_nop 0
	global_load_lds_dwordx4 v[194:195], off
	v_lshl_add_u64 v[194:195], s[8:9], 0, v[164:165]
	s_add_i32 m0, s10, 0x2000
	s_nop 0
	global_load_lds_dwordx4 v[194:195], off
	v_lshl_add_u64 v[194:195], v[208:209], 0, s[96:97]
	s_mov_b32 m0, s62
	s_nop 0
	global_load_lds_dwordx4 v[194:195], off
	v_lshl_add_u64 v[194:195], v[236:237], 0, s[96:97]
	s_mov_b32 m0, s63
	s_nop 0
	global_load_lds_dwordx4 v[194:195], off
	s_waitcnt vmcnt(8)
	s_waitcnt lgkmcnt(0)
	s_setprio 1
	s_barrier
	v_mfma_f32_16x16x32_f16 v[64:67], v[132:135], v[176:179], v[64:67]
	v_mfma_f32_16x16x32_f16 v[60:63], v[140:143], v[176:179], v[60:63]
	v_mfma_f32_16x16x32_f16 v[48:51], v[132:135], v[184:187], v[48:51]
	v_mfma_f32_16x16x32_f16 v[44:47], v[140:143], v[184:187], v[44:47]
	v_mfma_f32_16x16x32_f16 v[32:35], v[132:135], v[220:223], v[32:35]
	v_mfma_f32_16x16x32_f16 v[28:31], v[140:143], v[220:223], v[28:31]
	v_mfma_f32_16x16x32_f16 v[16:19], v[132:135], v[228:231], v[16:19]
	v_mfma_f32_16x16x32_f16 v[12:15], v[140:143], v[228:231], v[12:15]
	v_mfma_f32_16x16x32_f16 v[64:67], v[136:139], v[180:183], v[64:67]
	v_mfma_f32_16x16x32_f16 v[60:63], v[144:147], v[180:183], v[60:63]
	v_mfma_f32_16x16x32_f16 v[48:51], v[136:139], v[204:207], v[48:51]
	v_mfma_f32_16x16x32_f16 v[44:47], v[144:147], v[204:207], v[44:47]
	v_mfma_f32_16x16x32_f16 v[32:35], v[136:139], v[224:227], v[32:35]
	v_mfma_f32_16x16x32_f16 v[28:31], v[144:147], v[224:227], v[28:31]
	v_mfma_f32_16x16x32_f16 v[16:19], v[136:139], v[232:235], v[16:19]
	v_mfma_f32_16x16x32_f16 v[12:15], v[144:147], v[232:235], v[12:15]
	v_mfma_f32_16x16x32_f16 v[56:59], v[148:151], v[176:179], v[56:59]
	v_mfma_f32_16x16x32_f16 v[52:55], v[156:159], v[176:179], v[52:55]
	v_mfma_f32_16x16x32_f16 v[40:43], v[148:151], v[184:187], v[40:43]
	v_mfma_f32_16x16x32_f16 v[36:39], v[156:159], v[184:187], v[36:39]
	v_mfma_f32_16x16x32_f16 v[24:27], v[148:151], v[220:223], v[24:27]
	v_mfma_f32_16x16x32_f16 v[20:23], v[156:159], v[220:223], v[20:23]
	v_mfma_f32_16x16x32_f16 v[8:11], v[148:151], v[228:231], v[8:11]
	v_mfma_f32_16x16x32_f16 v[4:7], v[156:159], v[228:231], v[4:7]
	v_mfma_f32_16x16x32_f16 v[56:59], v[152:155], v[180:183], v[56:59]
	v_mfma_f32_16x16x32_f16 v[52:55], v[160:163], v[180:183], v[52:55]
	v_mfma_f32_16x16x32_f16 v[40:43], v[152:155], v[204:207], v[40:43]
	v_mfma_f32_16x16x32_f16 v[36:39], v[160:163], v[204:207], v[36:39]
	v_mfma_f32_16x16x32_f16 v[24:27], v[152:155], v[224:227], v[24:27]
	v_mfma_f32_16x16x32_f16 v[20:23], v[160:163], v[224:227], v[20:23]
	v_mfma_f32_16x16x32_f16 v[8:11], v[152:155], v[232:235], v[8:11]
	v_mfma_f32_16x16x32_f16 v[4:7], v[160:163], v[232:235], v[4:7]
	s_setprio 0
	s_barrier
	s_add_i32 s17, s17, 2
	s_add_u32 s0, s0, 0x100
	s_addc_u32 s1, s1, 0
	s_add_u32 s15, s15, 0x100
	s_addc_u32 s16, s16, 0
	s_cmp_gt_u32 s17, 29
	s_cbranch_scc0 .LBB0_1708
.LBB0_1708:
	s_add_u32 s8, s0, 0xfff80080
	s_addc_u32 s9, s1, -1
	s_add_i32 s22, 0, 0x10000
	s_cmp_eq_u32 s17, 28
	s_cselect_b32 s11, s2, s9
	s_cselect_b32 s10, s12, s8
	v_add_u32_e32 v2, s22, v189
	s_cselect_b32 s9, s13, s16
	s_cselect_b32 s8, s14, s15
	s_add_i32 s44, 0, 0x14000
	ds_read_b128 v[132:135], v2
	ds_read_b128 v[136:139], v2 offset:1024
	ds_read_b128 v[140:143], v2 offset:2048
	ds_read_b128 v[144:147], v2 offset:3072
	v_add_u32_e32 v2, s44, v189
	ds_read_b128 v[148:151], v2
	ds_read_b128 v[152:155], v2 offset:1024
	ds_read_b128 v[156:159], v2 offset:2048
	ds_read_b128 v[160:163], v2 offset:3072
	v_lshl_add_u64 v[194:195], s[0:1], 0, v[172:173]
	s_add_i32 m0, s57, 0xc000
	ds_read_b128 v[176:179], v193
	ds_read_b128 v[180:183], v193 offset:1024
	ds_read_b128 v[184:187], v193 offset:2048
	ds_read_b128 v[204:207], v193 offset:3072
	ds_read_b128 v[220:223], v193 offset:4096
	ds_read_b128 v[224:227], v193 offset:5120
	ds_read_b128 v[228:231], v193 offset:6144
	ds_read_b128 v[232:235], v193 offset:7168
	global_load_lds_dwordx4 v[194:195], off
	v_lshl_add_u64 v[194:195], s[0:1], 0, v[174:175]
	s_add_i32 m0, s57, 0xe000
	s_nop 0
	global_load_lds_dwordx4 v[194:195], off
	s_waitcnt vmcnt(8)
	s_waitcnt lgkmcnt(0)
	s_setprio 1
	s_barrier
; #define PG8_STAGE(bufoff, gbase, voff) do { _Pragma("unroll") for (int _i = 0; _i < 2; ++_i) \
;         __builtin_amdgcn_global_load_lds((const unsigned*)((const char*)(gbase) + (voff)[_i]), (LAS unsigned*)(lds + (bufoff) + ldsw + _i * 8192), 16, 0, 0); } while (0)
; #define PG8_LDA(dst, b, h) do { _Pragma("unroll") for (int m = 0; m < 4; ++m) _Pragma("unroll") for (int k = 0; k < 2; ++k) dst[m][k] = *(const LAS half8*)(lds + PG8_SA(b, h) + aoff + m * 2048 + k * 1024); } while (0)
; #define PG8_LDB(dst, b, h) do { _Pragma("unroll") for (int n = 0; n < 2; ++n) _Pragma("unroll") for (int k = 0; k < 2; ++k) dst[n][k] = *(const LAS half8*)(lds + PG8_SB(b, h) + boff + n * 2048 + k * 1024); } while (0)
; #define PG8_MMA(ai, bj, At, Bt) do { __builtin_amdgcn_s_setprio(1); _Pragma("unroll") for (int m = 0; m < 4; ++m) _Pragma("unroll") for (int n = 0; n < 2; ++n) _Pragma("unroll") for (int k = 0; k < 2; ++k) \
;         acc[ai][bj][m][n] = __builtin_amdgcn_mfma_f32_16x16x32_f16(Bt[n][k], At[m][k], acc[ai][bj][m][n], 0, 0, 0); __builtin_amdgcn_s_setprio(0); } while (0)
; #define PG8_WAIT_V(n) asm volatile("s_waitcnt vmcnt(" #n ")" ::: "memory")
; #define PG8_WAIT_L(n) asm volatile("s_waitcnt lgkmcnt(" #n ")" ::: "memory")
; #define PG8_BAR __builtin_amdgcn_s_barrier()
; #define PG8_SCHED __builtin_amdgcn_sched_barrier(0)
; template <class Epi, class Sched, bool ALIGN_EPI = false, bool SP2 = false>
; __device__ __forceinline__ void gemm_phase(LAS unsigned char* lds, const Gemm g, const Sched& S, const Epi& E) {
;     ...
;             if constexpr (SP2) {
;             PG8_LDB(B0, 0, 0); PG8_LDB(B1, 0, 1); PG8_SCHED; PG8_LDA(At, 0, 0); PG8_STAGE(PG8_SA(1, 1), a1 + hstepA, voffA);
;             PG8_WAIT_V(8); PG8_WAIT_L(0); PG8_BAR; PG8_MMA(0, 0, At, B0); PG8_MMA(0, 1, At, B1); PG8_BAR; PG8_SCHED;
;             PG8_LDA(At, 0, 1); PG8_STAGE(PG8_SB(0, 0), b2, voffB); PG8_STAGE(PG8_SB(0, 1), b2 + hstepB, voffB); PG8_STAGE(PG8_SA(0, 0), a2, voffA);
;             PG8_WAIT_V(8); PG8_WAIT_L(0); PG8_BAR; PG8_MMA(1, 0, At, B0); PG8_MMA(1, 1, At, B1); PG8_BAR; PG8_SCHED;
	v_mfma_f32_16x16x32_f16 v[128:131], v[132:135], v[176:179], v[128:131]
	v_mfma_f32_16x16x32_f16 v[124:127], v[140:143], v[176:179], v[124:127]
	v_mfma_f32_16x16x32_f16 v[112:115], v[132:135], v[184:187], v[112:115]
	v_mfma_f32_16x16x32_f16 v[108:111], v[140:143], v[184:187], v[108:111]
	v_mfma_f32_16x16x32_f16 v[96:99], v[132:135], v[220:223], v[96:99]
	v_mfma_f32_16x16x32_f16 v[92:95], v[140:143], v[220:223], v[92:95]
	v_mfma_f32_16x16x32_f16 v[80:83], v[132:135], v[228:231], v[80:83]
	v_mfma_f32_16x16x32_f16 v[76:79], v[140:143], v[228:231], v[76:79]
	v_mfma_f32_16x16x32_f16 v[128:131], v[136:139], v[180:183], v[128:131]
	v_mfma_f32_16x16x32_f16 v[124:127], v[144:147], v[180:183], v[124:127]
	v_mfma_f32_16x16x32_f16 v[112:115], v[136:139], v[204:207], v[112:115]
	v_mfma_f32_16x16x32_f16 v[108:111], v[144:147], v[204:207], v[108:111]
	v_mfma_f32_16x16x32_f16 v[96:99], v[136:139], v[224:227], v[96:99]
	v_mfma_f32_16x16x32_f16 v[92:95], v[144:147], v[224:227], v[92:95]
	v_mfma_f32_16x16x32_f16 v[80:83], v[136:139], v[232:235], v[80:83]
	v_mfma_f32_16x16x32_f16 v[76:79], v[144:147], v[232:235], v[76:79]
	v_mfma_f32_16x16x32_f16 v[120:123], v[148:151], v[176:179], v[120:123]
	v_mfma_f32_16x16x32_f16 v[116:119], v[156:159], v[176:179], v[116:119]
	v_mfma_f32_16x16x32_f16 v[104:107], v[148:151], v[184:187], v[104:107]
	v_mfma_f32_16x16x32_f16 v[100:103], v[156:159], v[184:187], v[100:103]
	v_mfma_f32_16x16x32_f16 v[88:91], v[148:151], v[220:223], v[88:91]
	v_mfma_f32_16x16x32_f16 v[84:87], v[156:159], v[220:223], v[84:87]
	v_mfma_f32_16x16x32_f16 v[72:75], v[148:151], v[228:231], v[72:75]
	v_mfma_f32_16x16x32_f16 v[68:71], v[156:159], v[228:231], v[68:71]
	v_mfma_f32_16x16x32_f16 v[120:123], v[152:155], v[180:183], v[120:123]
	v_mfma_f32_16x16x32_f16 v[116:119], v[160:163], v[180:183], v[116:119]
	v_mfma_f32_16x16x32_f16 v[104:107], v[152:155], v[204:207], v[104:107]
	v_mfma_f32_16x16x32_f16 v[100:103], v[160:163], v[204:207], v[100:103]
	v_mfma_f32_16x16x32_f16 v[88:91], v[152:155], v[224:227], v[88:91]
	v_mfma_f32_16x16x32_f16 v[84:87], v[160:163], v[224:227], v[84:87]
	v_mfma_f32_16x16x32_f16 v[72:75], v[152:155], v[232:235], v[72:75]
	v_mfma_f32_16x16x32_f16 v[68:71], v[160:163], v[232:235], v[68:71]
	s_setprio 0
	s_barrier
	s_add_i32 s22, s22, s56
	v_lshl_add_u64 v[194:195], s[8:9], 0, v[168:169]
	s_mov_b32 m0, s22
	ds_read_b128 v[176:179], v193 offset:16384
	ds_read_b128 v[180:183], v193 offset:17408
	ds_read_b128 v[184:187], v193 offset:18432
	ds_read_b128 v[204:207], v193 offset:19456
	ds_read_b128 v[220:223], v193 offset:20480
	ds_read_b128 v[224:227], v193 offset:21504
	ds_read_b128 v[228:231], v193 offset:22528
	ds_read_b128 v[232:235], v193 offset:23552
	global_load_lds_dwordx4 v[194:195], off
	s_add_i32 m0, s22, 0x2000
	s_add_u32 s22, s8, 0x80000
	v_lshl_add_u64 v[196:197], s[8:9], 0, v[164:165]
	s_addc_u32 s23, s9, 0
	s_add_i32 s44, s44, s56
	global_load_lds_dwordx4 v[196:197], off
	v_lshl_add_u64 v[208:209], s[22:23], 0, v[168:169]
	s_mov_b32 m0, s44
	v_lshl_add_u64 v[236:237], s[10:11], 0, v[166:167]
	global_load_lds_dwordx4 v[208:209], off
	v_lshl_add_u64 v[208:209], s[22:23], 0, v[164:165]
	s_add_i32 m0, s44, 0x2000
	s_nop 0
	global_load_lds_dwordx4 v[208:209], off
	v_lshl_add_u64 v[208:209], s[10:11], 0, v[170:171]
	s_mov_b32 m0, s57
	s_nop 0
	global_load_lds_dwordx4 v[208:209], off
	s_mov_b32 m0, s58
	s_nop 0
	global_load_lds_dwordx4 v[236:237], off
	s_waitcnt vmcnt(8)
	s_waitcnt lgkmcnt(0)
	s_setprio 1
	s_barrier
	v_mfma_f32_16x16x32_f16 v[64:67], v[132:135], v[176:179], v[64:67]
	v_mfma_f32_16x16x32_f16 v[60:63], v[140:143], v[176:179], v[60:63]
	v_mfma_f32_16x16x32_f16 v[48:51], v[132:135], v[184:187], v[48:51]
	v_mfma_f32_16x16x32_f16 v[44:47], v[140:143], v[184:187], v[44:47]
	v_mfma_f32_16x16x32_f16 v[32:35], v[132:135], v[220:223], v[32:35]
	v_mfma_f32_16x16x32_f16 v[28:31], v[140:143], v[220:223], v[28:31]
	v_mfma_f32_16x16x32_f16 v[16:19], v[132:135], v[228:231], v[16:19]
	v_mfma_f32_16x16x32_f16 v[12:15], v[140:143], v[228:231], v[12:15]
	v_mfma_f32_16x16x32_f16 v[64:67], v[136:139], v[180:183], v[64:67]
	v_mfma_f32_16x16x32_f16 v[60:63], v[144:147], v[180:183], v[60:63]
	v_mfma_f32_16x16x32_f16 v[48:51], v[136:139], v[204:207], v[48:51]
	v_mfma_f32_16x16x32_f16 v[44:47], v[144:147], v[204:207], v[44:47]
	v_mfma_f32_16x16x32_f16 v[32:35], v[136:139], v[224:227], v[32:35]
	v_mfma_f32_16x16x32_f16 v[28:31], v[144:147], v[224:227], v[28:31]
	v_mfma_f32_16x16x32_f16 v[16:19], v[136:139], v[232:235], v[16:19]
	v_mfma_f32_16x16x32_f16 v[12:15], v[144:147], v[232:235], v[12:15]
	v_mfma_f32_16x16x32_f16 v[56:59], v[148:151], v[176:179], v[56:59]
	v_mfma_f32_16x16x32_f16 v[52:55], v[156:159], v[176:179], v[52:55]
	v_mfma_f32_16x16x32_f16 v[40:43], v[148:151], v[184:187], v[40:43]
	v_mfma_f32_16x16x32_f16 v[36:39], v[156:159], v[184:187], v[36:39]
	v_mfma_f32_16x16x32_f16 v[24:27], v[148:151], v[220:223], v[24:27]
	v_mfma_f32_16x16x32_f16 v[20:23], v[156:159], v[220:223], v[20:23]
	v_mfma_f32_16x16x32_f16 v[8:11], v[148:151], v[228:231], v[8:11]
	v_mfma_f32_16x16x32_f16 v[4:7], v[156:159], v[228:231], v[4:7]
	v_mfma_f32_16x16x32_f16 v[56:59], v[152:155], v[180:183], v[56:59]
	v_mfma_f32_16x16x32_f16 v[52:55], v[160:163], v[180:183], v[52:55]
	v_mfma_f32_16x16x32_f16 v[40:43], v[152:155], v[204:207], v[40:43]
	v_mfma_f32_16x16x32_f16 v[36:39], v[160:163], v[204:207], v[36:39]
	v_mfma_f32_16x16x32_f16 v[24:27], v[152:155], v[224:227], v[24:27]
	v_mfma_f32_16x16x32_f16 v[20:23], v[160:163], v[224:227], v[20:23]
	v_mfma_f32_16x16x32_f16 v[8:11], v[152:155], v[232:235], v[8:11]
	v_mfma_f32_16x16x32_f16 v[4:7], v[160:163], v[232:235], v[4:7]
	s_setprio 0
	s_barrier
; #define PG8_STAGE(bufoff, gbase, voff) do { _Pragma("unroll") for (int _i = 0; _i < 2; ++_i) \
;         __builtin_amdgcn_global_load_lds((const unsigned*)((const char*)(gbase) + (voff)[_i]), (LAS unsigned*)(lds + (bufoff) + ldsw + _i * 8192), 16, 0, 0); } while (0)
; #define PG8_LDA(dst, b, h) do { _Pragma("unroll") for (int m = 0; m < 4; ++m) _Pragma("unroll") for (int k = 0; k < 2; ++k) dst[m][k] = *(const LAS half8*)(lds + PG8_SA(b, h) + aoff + m * 2048 + k * 1024); } while (0)
; #define PG8_LDB(dst, b, h) do { _Pragma("unroll") for (int n = 0; n < 2; ++n) _Pragma("unroll") for (int k = 0; k < 2; ++k) dst[n][k] = *(const LAS half8*)(lds + PG8_SB(b, h) + boff + n * 2048 + k * 1024); } while (0)
; #define PG8_MMA(ai, bj, At, Bt) do { __builtin_amdgcn_s_setprio(1); _Pragma("unroll") for (int m = 0; m < 4; ++m) _Pragma("unroll") for (int n = 0; n < 2; ++n) _Pragma("unroll") for (int k = 0; k < 2; ++k) \
;         acc[ai][bj][m][n] = __builtin_amdgcn_mfma_f32_16x16x32_f16(Bt[n][k], At[m][k], acc[ai][bj][m][n], 0, 0, 0); __builtin_amdgcn_s_setprio(0); } while (0)
; #define PG8_WAIT_V(n) asm volatile("s_waitcnt vmcnt(" #n ")" ::: "memory")
; #define PG8_WAIT_L(n) asm volatile("s_waitcnt lgkmcnt(" #n ")" ::: "memory")
; #define PG8_BAR __builtin_amdgcn_s_barrier()
; #define PG8_SCHED __builtin_amdgcn_sched_barrier(0)
; template <class Epi, class Sched, bool ALIGN_EPI = false, bool SP2 = false>
; __device__ __forceinline__ void gemm_phase(LAS unsigned char* lds, const Gemm g, const Sched& S, const Epi& E) {
;     ...
;         for (int t = 0; t < nt; t += 2) {
;     ...
;             PG8_LDB(B0, 1, 0); PG8_LDB(B1, 1, 1); PG8_SCHED; PG8_LDA(At, 1, 0); PG8_STAGE(PG8_SA(0, 1), a2 + hstepA, voffA);
;             PG8_WAIT_V(8); PG8_WAIT_L(0); PG8_BAR; PG8_MMA(0, 0, At, B0); PG8_MMA(0, 1, At, B1); PG8_BAR; PG8_SCHED;
;             PG8_LDA(At, 1, 1); PG8_STAGE(PG8_SB(1, 0), b3, voffB); PG8_STAGE(PG8_SB(1, 1), b3 + hstepB, voffB); PG8_STAGE(PG8_SA(1, 0), a3, voffA);
;             PG8_WAIT_V(8); PG8_WAIT_L(0); PG8_BAR; PG8_MMA(1, 0, At, B0); PG8_MMA(1, 1, At, B1); PG8_BAR; PG8_SCHED;
;     ...
;         if constexpr (ALIGN_EPI) { if (wr == 0) PG8_BAR; }
	s_add_i32 s22, 0, 0x18000
	v_add_u32_e32 v2, s22, v189
	s_add_i32 s23, 0, 0x1c000
	ds_read_b128 v[132:135], v2
	ds_read_b128 v[136:139], v2 offset:1024
	ds_read_b128 v[140:143], v2 offset:2048
	ds_read_b128 v[144:147], v2 offset:3072
	v_add_u32_e32 v2, s23, v189
	ds_read_b128 v[148:151], v2
	ds_read_b128 v[152:155], v2 offset:1024
	ds_read_b128 v[156:159], v2 offset:2048
	ds_read_b128 v[160:163], v2 offset:3072
	s_add_u32 s10, s10, 0x80000
	s_addc_u32 s11, s11, 0
	s_mov_b32 m0, s59
	v_lshl_add_u64 v[240:241], s[10:11], 0, v[170:171]
	ds_read_b128 v[176:179], v193 offset:32768
	ds_read_b128 v[180:183], v193 offset:33792
	ds_read_b128 v[184:187], v193 offset:34816
	ds_read_b128 v[204:207], v193 offset:35840
	ds_read_b128 v[220:223], v193 offset:36864
	ds_read_b128 v[224:227], v193 offset:37888
	ds_read_b128 v[228:231], v193 offset:38912
	ds_read_b128 v[232:235], v193 offset:39936
	global_load_lds_dwordx4 v[240:241], off
	v_lshl_add_u64 v[240:241], s[10:11], 0, v[166:167]
	s_mov_b32 m0, s60
	s_nop 0
	global_load_lds_dwordx4 v[240:241], off
	s_waitcnt vmcnt(8)
	s_waitcnt lgkmcnt(0)
	s_setprio 1
	s_barrier
	v_mfma_f32_16x16x32_f16 v[128:131], v[132:135], v[176:179], v[128:131]
	v_mfma_f32_16x16x32_f16 v[124:127], v[140:143], v[176:179], v[124:127]
	v_mfma_f32_16x16x32_f16 v[112:115], v[132:135], v[184:187], v[112:115]
	v_mfma_f32_16x16x32_f16 v[108:111], v[140:143], v[184:187], v[108:111]
	v_mfma_f32_16x16x32_f16 v[96:99], v[132:135], v[220:223], v[96:99]
	v_mfma_f32_16x16x32_f16 v[92:95], v[140:143], v[220:223], v[92:95]
	v_mfma_f32_16x16x32_f16 v[80:83], v[132:135], v[228:231], v[80:83]
	v_mfma_f32_16x16x32_f16 v[76:79], v[140:143], v[228:231], v[76:79]
	v_mfma_f32_16x16x32_f16 v[128:131], v[136:139], v[180:183], v[128:131]
	v_mfma_f32_16x16x32_f16 v[124:127], v[144:147], v[180:183], v[124:127]
	v_mfma_f32_16x16x32_f16 v[112:115], v[136:139], v[204:207], v[112:115]
	v_mfma_f32_16x16x32_f16 v[108:111], v[144:147], v[204:207], v[108:111]
	v_mfma_f32_16x16x32_f16 v[96:99], v[136:139], v[224:227], v[96:99]
	v_mfma_f32_16x16x32_f16 v[92:95], v[144:147], v[224:227], v[92:95]
	v_mfma_f32_16x16x32_f16 v[80:83], v[136:139], v[232:235], v[80:83]
	v_mfma_f32_16x16x32_f16 v[76:79], v[144:147], v[232:235], v[76:79]
	v_mfma_f32_16x16x32_f16 v[120:123], v[148:151], v[176:179], v[120:123]
	v_mfma_f32_16x16x32_f16 v[116:119], v[156:159], v[176:179], v[116:119]
	v_mfma_f32_16x16x32_f16 v[104:107], v[148:151], v[184:187], v[104:107]
	v_mfma_f32_16x16x32_f16 v[100:103], v[156:159], v[184:187], v[100:103]
	v_mfma_f32_16x16x32_f16 v[88:91], v[148:151], v[220:223], v[88:91]
	v_mfma_f32_16x16x32_f16 v[84:87], v[156:159], v[220:223], v[84:87]
	v_mfma_f32_16x16x32_f16 v[72:75], v[148:151], v[228:231], v[72:75]
	v_mfma_f32_16x16x32_f16 v[68:71], v[156:159], v[228:231], v[68:71]
	v_mfma_f32_16x16x32_f16 v[120:123], v[152:155], v[180:183], v[120:123]
	v_mfma_f32_16x16x32_f16 v[116:119], v[160:163], v[180:183], v[116:119]
	v_mfma_f32_16x16x32_f16 v[104:107], v[152:155], v[204:207], v[104:107]
	v_mfma_f32_16x16x32_f16 v[100:103], v[160:163], v[204:207], v[100:103]
	v_mfma_f32_16x16x32_f16 v[88:91], v[152:155], v[224:227], v[88:91]
	v_mfma_f32_16x16x32_f16 v[84:87], v[160:163], v[224:227], v[84:87]
	v_mfma_f32_16x16x32_f16 v[72:75], v[152:155], v[232:235], v[72:75]
	v_mfma_f32_16x16x32_f16 v[68:71], v[160:163], v[232:235], v[68:71]
	s_setprio 0
	s_barrier
	s_add_i32 s10, s22, s56
	v_lshl_add_u64 v[194:195], v[194:195], 0, s[96:97]
	s_mov_b32 m0, s10
	ds_read_b128 v[176:179], v193 offset:49152
	ds_read_b128 v[180:183], v193 offset:50176
	ds_read_b128 v[184:187], v193 offset:51200
	ds_read_b128 v[204:207], v193 offset:52224
	ds_read_b128 v[220:223], v193 offset:53248
	ds_read_b128 v[224:227], v193 offset:54272
	ds_read_b128 v[228:231], v193 offset:55296
	ds_read_b128 v[232:235], v193 offset:56320
	global_load_lds_dwordx4 v[194:195], off
	s_add_i32 m0, s10, 0x2000
	s_add_u32 s8, s8, 0x80080
	v_lshl_add_u64 v[194:195], v[196:197], 0, s[96:97]
	s_addc_u32 s9, s9, 0
	s_add_i32 s10, s23, s56
	global_load_lds_dwordx4 v[194:195], off
	v_lshl_add_u64 v[194:195], s[8:9], 0, v[168:169]
	s_mov_b32 m0, s10
	s_nop 0
	global_load_lds_dwordx4 v[194:195], off
	v_lshl_add_u64 v[194:195], s[8:9], 0, v[164:165]
	s_add_i32 m0, s10, 0x2000
	s_nop 0
	global_load_lds_dwordx4 v[194:195], off
	v_lshl_add_u64 v[194:195], v[208:209], 0, s[96:97]
	s_mov_b32 m0, s62
	s_nop 0
	global_load_lds_dwordx4 v[194:195], off
	v_lshl_add_u64 v[194:195], v[236:237], 0, s[96:97]
	s_mov_b32 m0, s63
	s_nop 0
	global_load_lds_dwordx4 v[194:195], off
	s_waitcnt vmcnt(8)
	s_waitcnt lgkmcnt(0)
	s_setprio 1
	s_barrier
	v_mfma_f32_16x16x32_f16 v[64:67], v[132:135], v[176:179], v[64:67]
	v_mfma_f32_16x16x32_f16 v[60:63], v[140:143], v[176:179], v[60:63]
	v_mfma_f32_16x16x32_f16 v[48:51], v[132:135], v[184:187], v[48:51]
	v_mfma_f32_16x16x32_f16 v[44:47], v[140:143], v[184:187], v[44:47]
	v_mfma_f32_16x16x32_f16 v[32:35], v[132:135], v[220:223], v[32:35]
	v_mfma_f32_16x16x32_f16 v[28:31], v[140:143], v[220:223], v[28:31]
	v_mfma_f32_16x16x32_f16 v[16:19], v[132:135], v[228:231], v[16:19]
	v_mfma_f32_16x16x32_f16 v[12:15], v[140:143], v[228:231], v[12:15]
	v_mfma_f32_16x16x32_f16 v[64:67], v[136:139], v[180:183], v[64:67]
	v_mfma_f32_16x16x32_f16 v[60:63], v[144:147], v[180:183], v[60:63]
	v_mfma_f32_16x16x32_f16 v[48:51], v[136:139], v[204:207], v[48:51]
	v_mfma_f32_16x16x32_f16 v[44:47], v[144:147], v[204:207], v[44:47]
	v_mfma_f32_16x16x32_f16 v[32:35], v[136:139], v[224:227], v[32:35]
	v_mfma_f32_16x16x32_f16 v[28:31], v[144:147], v[224:227], v[28:31]
	v_mfma_f32_16x16x32_f16 v[16:19], v[136:139], v[232:235], v[16:19]
	v_mfma_f32_16x16x32_f16 v[12:15], v[144:147], v[232:235], v[12:15]
	v_mfma_f32_16x16x32_f16 v[56:59], v[148:151], v[176:179], v[56:59]
	v_mfma_f32_16x16x32_f16 v[52:55], v[156:159], v[176:179], v[52:55]
	v_mfma_f32_16x16x32_f16 v[40:43], v[148:151], v[184:187], v[40:43]
	v_mfma_f32_16x16x32_f16 v[36:39], v[156:159], v[184:187], v[36:39]
	v_mfma_f32_16x16x32_f16 v[24:27], v[148:151], v[220:223], v[24:27]
	v_mfma_f32_16x16x32_f16 v[20:23], v[156:159], v[220:223], v[20:23]
	v_mfma_f32_16x16x32_f16 v[8:11], v[148:151], v[228:231], v[8:11]
	v_mfma_f32_16x16x32_f16 v[4:7], v[156:159], v[228:231], v[4:7]
	v_mfma_f32_16x16x32_f16 v[56:59], v[152:155], v[180:183], v[56:59]
	v_mfma_f32_16x16x32_f16 v[52:55], v[160:163], v[180:183], v[52:55]
	v_mfma_f32_16x16x32_f16 v[40:43], v[152:155], v[204:207], v[40:43]
	v_mfma_f32_16x16x32_f16 v[36:39], v[160:163], v[204:207], v[36:39]
	v_mfma_f32_16x16x32_f16 v[24:27], v[152:155], v[224:227], v[24:27]
	v_mfma_f32_16x16x32_f16 v[20:23], v[160:163], v[224:227], v[20:23]
	v_mfma_f32_16x16x32_f16 v[8:11], v[152:155], v[232:235], v[8:11]
	v_mfma_f32_16x16x32_f16 v[4:7], v[160:163], v[232:235], v[4:7]
	s_setprio 0
	s_barrier
	s_add_i32 s17, s17, 2
	s_add_u32 s0, s0, 0x100
	s_addc_u32 s1, s1, 0
	s_add_u32 s15, s15, 0x100
	s_addc_u32 s16, s16, 0
	s_cmp_gt_u32 s17, 29
	s_cbranch_scc0 .LBB0_1708
	s_and_b64 vcc, exec, s[54:55]
	s_cbranch_vccz .LBB0_1711
	s_barrier

; #define PG8_WAIT_V(n) asm volatile("s_waitcnt vmcnt(" #n ")" ::: "memory")
; template <class Epi, class Sched, bool ALIGN_EPI = false, bool SP2 = false>
; __device__ __forceinline__ void gemm_phase(LAS unsigned char* lds, const Gemm g, const Sched& S, const Epi& E) {
;     ...
;     for (int i = 0; i < 2; ++i) { int R, C; stage_rc(tid * 16 + i * 8192, R, C); const int Rb = Epi::PERM ? ((R & ~31) + perm32(R & 31)) : R;
;         voffA[i] = (unsigned)(R * lda + C) * 2u; voffB[i] = (unsigned)(Rb * ldb + C) * 2u; }
;     const size_t kstep = (size_t)(BK * 2);
;     const size_t hstepA = (size_t)HALF * lda * 2, hstepB = (size_t)HALF * ldb * 2;
;     const size_t tstepA = 2 * hstepA, tstepB = 2 * hstepB;
;     const unsigned ldsw = (unsigned)wid * 1024u;
;     const int aoff = lds_byte(wr * 64 + fr, fq * 8), boff = lds_byte(wc * 32 + fr, fq * 8);
;     ...
;     Unit cur, nxt; int ui = 0;
;     if (!S.next(0, cur)) return;
;     f32x4 acc[2][2][4][2];
; #pragma unroll
;     for (int a = 0; a < 2; ++a)
; #pragma unroll
;         for (int b = 0; b < 2; ++b)
; #pragma unroll
;             for (int m = 0; m < 4; ++m)
; #pragma unroll
;                 for (int n = 0; n < 2; ++n) acc[a][b][m][n] = (f32x4){0.f, 0.f, 0.f, 0.f};
;     half8 At[4][2], B0[2][2], B1[2][2];
;     const char* cA = (const char*)g.A + (size_t)cur.pm * tstepA; const char* cB = (const char*)g.Bt + (size_t)cur.pn * tstepB;
;     S.a_ready(cur);
;     if constexpr (SP2) {
;         PG8_STAGE(PG8_SB(0, 0), cB, voffB); PG8_STAGE(PG8_SB(0, 1), cB + hstepB, voffB); PG8_STAGE(PG8_SA(0, 0), cA, voffA); PG8_STAGE(PG8_SA(0, 1), cA + hstepA, voffA);
;         if (wr == 1) PG8_BAR;
;         PG8_WAIT_V(2); PG8_BAR;
;         PG8_STAGE(PG8_SB(1, 0), cB + kstep, voffB); PG8_STAGE(PG8_SA(1, 0), cA + kstep, voffA); PG8_STAGE(PG8_SB(1, 1), cB + hstepB + kstep, voffB);
;         PG8_WAIT_V(6); PG8_BAR;
;     } else {
;         PG8_STAGE(PG8_SB(0, 0), cB, voffB); PG8_STAGE(PG8_SA(0, 0), cA, voffA); PG8_STAGE(PG8_SB(0, 1), cB + hstepB, voffB); PG8_STAGE(PG8_SA(0, 1), cA + hstepA, voffA);
;         if (wr == 1) PG8_BAR;
;         PG8_WAIT_V(4); PG8_BAR;
;         PG8_STAGE(PG8_SB(1, 0), cB + kstep, voffB); PG8_STAGE(PG8_SA(1, 0), cA + kstep, voffA); PG8_STAGE(PG8_SB(1, 1), cB + hstepB + kstep, voffB);
;         PG8_WAIT_V(6); PG8_BAR;
;     }
;     for (;;) {
;         const bool has_next = S.next(ui + 1, nxt);
.LBB0_2221:
	v_lshrrev_b32_e32 v20, 1, v17
	v_and_b32_e32 v142, 24, v20
	s_lshl_b32 s2, s2, 5
	v_and_b32_e32 v19, 15, v17
	v_lshlrev_b32_e32 v20, 1, v142
	v_lshlrev_b32_e32 v17, 2, v17
	s_and_b32 s58, s2, 0x60
	v_lshl_or_b32 v1, s13, 6, v19
	v_lshl_or_b32 v19, v19, 6, v20
	v_and_b32_e32 v17, 32, v17
	s_lshl_b32 s2, s58, 7
	s_lshl_b32 s13, s13, 13
	v_bitop3_b32 v143, v19, s2, v17 bitop3:0xde
	s_lshl_b32 s2, s56, 19
	v_bitop3_b32 v20, v19, s13, v17 bitop3:0xde
	s_and_b32 s13, s2, 0x100000
	s_lshl_b32 s2, s53, 7
	s_and_b32 s2, s2, 0xfffffe00
	v_cndmask_b32_e64 v17, 0, 1, s[44:45]
	s_lshl_b64 s[14:15], s[2:3], 1
	v_readfirstlane_b32 s2, v17
	s_lshl_b32 s2, s2, 19
	s_add_i32 s2, s22, s2
	s_lshl_b64 s[16:17], s[2:3], 1
	s_add_u32 s2, s14, s16
	s_addc_u32 s16, s15, s17
	v_readlane_b32 s17, v254, 42
	s_add_u32 s2, s17, s2
	v_readlane_b32 s17, v254, 43
	s_addc_u32 s59, s17, s16
	s_add_i32 m0, s37, 0x18000
	v_lshl_add_u64 v[10:11], v[10:11], 0, s[96:97]
	s_waitcnt vmcnt(2)
	s_barrier
	global_load_lds_dwordx4 v[10:11], off
	v_lshl_add_u64 v[8:9], v[8:9], 0, s[96:97]
	s_add_i32 m0, s37, 0x1a000
	s_add_i32 s60, s37, 0x8000
	s_add_i32 s61, s37, 0xa000
	global_load_lds_dwordx4 v[8:9], off
	v_lshl_add_u64 v[6:7], v[6:7], 0, s[96:97]
	s_mov_b32 m0, s60
	s_add_u32 s16, s8, 0x80080
	global_load_lds_dwordx4 v[6:7], off
	v_lshl_add_u64 v[4:5], v[4:5], 0, s[96:97]
	s_mov_b32 m0, s61
	s_addc_u32 s17, s9, 0
	global_load_lds_dwordx4 v[4:5], off
	s_add_i32 m0, s37, 0x1c000
	v_lshl_add_u64 v[4:5], s[16:17], 0, v[2:3]
	global_load_lds_dwordx4 v[4:5], off
	v_lshl_add_u64 v[4:5], s[16:17], 0, v[132:133]
	s_add_i32 m0, s37, 0x1e000
	s_add_u32 s12, s12, s13
	global_load_lds_dwordx4 v[4:5], off
	s_addc_u32 s13, 0, 0
	s_add_u32 s12, s12, s14
	s_addc_u32 s13, s13, s15
	v_lshlrev_b32_e32 v4, 15, v16
	s_add_u32 s62, s74, s12
	v_and_b32_e32 v4, 0xffff0000, v4
	s_addc_u32 s63, s75, s13
	v_lshl_add_u32 v4, v15, 12, v4
	v_and_b32_e32 v5, 1, v16
	v_readlane_b32 s14, v254, 40
	v_lshl_or_b32 v4, v5, 6, v4
	s_add_u32 s12, s14, s12
	v_readlane_b32 s14, v254, 41
	v_lshl_add_u32 v4, v18, 1, v4
	v_mov_b32_e32 v5, v3
	s_addc_u32 s13, s14, s13
	v_lshl_add_u64 v[138:139], s[12:13], 0, v[4:5]
	v_lshlrev_b32_e32 v4, 15, v12
	v_and_b32_e32 v4, 0xffff0000, v4
	v_lshl_add_u32 v4, v13, 12, v4
	v_and_b32_e32 v5, 1, v12
	v_lshl_or_b32 v4, v5, 6, v4
	s_waitcnt vmcnt(6)
	v_lshl_add_u32 v4, v14, 1, v4
	v_mov_b32_e32 v5, v3
	v_lshl_add_u64 v[140:141], s[12:13], 0, v[4:5]
	v_mov_b32_e32 v4, 0
	s_mov_b32 s64, -2
	s_mov_b64 s[12:13], 0
	v_add_u32_e32 v144, 0, v20
	s_waitcnt vmcnt(0)
	s_barrier
	s_add_u32 s14, s62, s12
	s_addc_u32 s15, s63, s13
	s_add_u32 s14, s14, 0x100
	s_addc_u32 s15, s15, 0
	s_add_u32 s65, s2, s12
	s_addc_u32 s66, s59, s13
	s_add_i32 s67, 0, 0x10000
	s_cmpk_eq_i32 s12, 0x300
	s_cselect_b32 s17, s11, s15
	s_cselect_b32 s16, s10, s14
	v_add_u32_e32 v145, s67, v143
	s_cselect_b32 s15, s9, s66
	s_cselect_b32 s14, s8, s65
	s_add_i32 s65, 0, 0x14000
	ds_read_b128 v[146:149], v145
	ds_read_b128 v[150:153], v145 offset:1024
	ds_read_b128 v[154:157], v145 offset:2048
	ds_read_b128 v[158:161], v145 offset:3072
	v_add_u32_e32 v145, s65, v143
	ds_read_b128 v[162:165], v145
	ds_read_b128 v[166:169], v145 offset:1024
	ds_read_b128 v[170:173], v145 offset:2048
	ds_read_b128 v[174:177], v145 offset:3072
	v_lshl_add_u64 v[194:195], v[138:139], 0, s[12:13]
	s_add_i32 m0, s37, 0xc000
	ds_read_b128 v[178:181], v144
	ds_read_b128 v[182:185], v144 offset:1024
	ds_read_b128 v[186:189], v144 offset:2048
	ds_read_b128 v[190:193], v144 offset:3072
	ds_read_b128 v[204:207], v144 offset:4096
	ds_read_b128 v[220:223], v144 offset:5120
	ds_read_b128 v[224:227], v144 offset:6144
	ds_read_b128 v[228:231], v144 offset:7168
	global_load_lds_dwordx4 v[194:195], off
	v_lshl_add_u64 v[194:195], v[140:141], 0, s[12:13]
	s_add_i32 m0, s37, 0xe000
	s_nop 0
	global_load_lds_dwordx4 v[194:195], off
	s_waitcnt vmcnt(8)
	s_waitcnt lgkmcnt(0)
	s_setprio 1
	s_barrier
	v_mfma_f32_16x16x32_f16 v[128:131], v[146:149], v[178:181], 0
	v_mfma_f32_16x16x32_f16 v[124:127], v[154:157], v[178:181], 0
	v_mfma_f32_16x16x32_f16 v[120:123], v[146:149], v[186:189], 0
	v_mfma_f32_16x16x32_f16 v[116:119], v[154:157], v[186:189], 0
	v_mfma_f32_16x16x32_f16 v[108:111], v[146:149], v[204:207], 0
	v_mfma_f32_16x16x32_f16 v[100:103], v[154:157], v[204:207], 0
	v_mfma_f32_16x16x32_f16 v[92:95], v[146:149], v[224:227], 0
	v_mfma_f32_16x16x32_f16 v[84:87], v[154:157], v[224:227], 0
	v_mfma_f32_16x16x32_f16 v[128:131], v[150:153], v[182:185], v[128:131]
	v_mfma_f32_16x16x32_f16 v[124:127], v[158:161], v[182:185], v[124:127]
	v_mfma_f32_16x16x32_f16 v[120:123], v[150:153], v[190:193], v[120:123]
	v_mfma_f32_16x16x32_f16 v[116:119], v[158:161], v[190:193], v[116:119]
	v_mfma_f32_16x16x32_f16 v[108:111], v[150:153], v[220:223], v[108:111]
	v_mfma_f32_16x16x32_f16 v[100:103], v[158:161], v[220:223], v[100:103]
	v_mfma_f32_16x16x32_f16 v[92:95], v[150:153], v[228:231], v[92:95]
	v_mfma_f32_16x16x32_f16 v[84:87], v[158:161], v[228:231], v[84:87]
	v_mfma_f32_16x16x32_f16 v[112:115], v[162:165], v[178:181], 0
	v_mfma_f32_16x16x32_f16 v[104:107], v[170:173], v[178:181], 0
	v_mfma_f32_16x16x32_f16 v[96:99], v[162:165], v[186:189], 0
	v_mfma_f32_16x16x32_f16 v[88:91], v[170:173], v[186:189], 0
	v_mfma_f32_16x16x32_f16 v[80:83], v[162:165], v[204:207], 0
	v_mfma_f32_16x16x32_f16 v[76:79], v[170:173], v[204:207], 0
	v_mfma_f32_16x16x32_f16 v[72:75], v[162:165], v[224:227], 0
	v_mfma_f32_16x16x32_f16 v[68:71], v[170:173], v[224:227], 0
	v_mfma_f32_16x16x32_f16 v[112:115], v[166:169], v[182:185], v[112:115]
	v_mfma_f32_16x16x32_f16 v[104:107], v[174:177], v[182:185], v[104:107]
	v_mfma_f32_16x16x32_f16 v[96:99], v[166:169], v[190:193], v[96:99]
	v_mfma_f32_16x16x32_f16 v[88:91], v[174:177], v[190:193], v[88:91]
	v_mfma_f32_16x16x32_f16 v[80:83], v[166:169], v[220:223], v[80:83]
	v_mfma_f32_16x16x32_f16 v[76:79], v[174:177], v[220:223], v[76:79]
	v_mfma_f32_16x16x32_f16 v[72:75], v[166:169], v[228:231], v[72:75]
	v_mfma_f32_16x16x32_f16 v[68:71], v[174:177], v[228:231], v[68:71]
	s_setprio 0
	s_barrier
; #define PG8_STAGE(bufoff, gbase, voff) do { _Pragma("unroll") for (int _i = 0; _i < 2; ++_i) \
;         __builtin_amdgcn_global_load_lds((const unsigned*)((const char*)(gbase) + (voff)[_i]), (LAS unsigned*)(lds + (bufoff) + ldsw + _i * 8192), 16, 0, 0); } while (0)
; #define PG8_LDA(dst, b, h) do { _Pragma("unroll") for (int m = 0; m < 4; ++m) _Pragma("unroll") for (int k = 0; k < 2; ++k) dst[m][k] = *(const LAS half8*)(lds + PG8_SA(b, h) + aoff + m * 2048 + k * 1024); } while (0)
; #define PG8_LDB(dst, b, h) do { _Pragma("unroll") for (int n = 0; n < 2; ++n) _Pragma("unroll") for (int k = 0; k < 2; ++k) dst[n][k] = *(const LAS half8*)(lds + PG8_SB(b, h) + boff + n * 2048 + k * 1024); } while (0)
; #define PG8_MMA(ai, bj, At, Bt) do { __builtin_amdgcn_s_setprio(1); _Pragma("unroll") for (int m = 0; m < 4; ++m) _Pragma("unroll") for (int n = 0; n < 2; ++n) _Pragma("unroll") for (int k = 0; k < 2; ++k) \
;         acc[ai][bj][m][n] = __builtin_amdgcn_mfma_f32_16x16x32_f16(Bt[n][k], At[m][k], acc[ai][bj][m][n], 0, 0, 0); __builtin_amdgcn_s_setprio(0); } while (0)
; #define PG8_WAIT_V(n) asm volatile("s_waitcnt vmcnt(" #n ")" ::: "memory")
; #define PG8_WAIT_L(n) asm volatile("s_waitcnt lgkmcnt(" #n ")" ::: "memory")
; #define PG8_BAR __builtin_amdgcn_s_barrier()
; #define PG8_SCHED __builtin_amdgcn_sched_barrier(0)
; template <class Epi, class Sched, bool ALIGN_EPI = false, bool SP2 = false>
; __device__ __forceinline__ void gemm_phase(LAS unsigned char* lds, const Gemm g, const Sched& S, const Epi& E) {
;     ...
;             if constexpr (SP2) {
;             PG8_LDB(B0, 0, 0); PG8_LDB(B1, 0, 1); PG8_SCHED; PG8_LDA(At, 0, 0); PG8_STAGE(PG8_SA(1, 1), a1 + hstepA, voffA);
;             PG8_WAIT_V(8); PG8_WAIT_L(0); PG8_BAR; PG8_MMA(0, 0, At, B0); PG8_MMA(0, 1, At, B1); PG8_BAR; PG8_SCHED;
;             PG8_LDA(At, 0, 1); PG8_STAGE(PG8_SB(0, 0), b2, voffB); PG8_STAGE(PG8_SB(0, 1), b2 + hstepB, voffB); PG8_STAGE(PG8_SA(0, 0), a2, voffA);
;             PG8_WAIT_V(8); PG8_WAIT_L(0); PG8_BAR; PG8_MMA(1, 0, At, B0); PG8_MMA(1, 1, At, B1); PG8_BAR; PG8_SCHED;
;             PG8_LDB(B0, 1, 0); PG8_LDB(B1, 1, 1); PG8_SCHED; PG8_LDA(At, 1, 0); PG8_STAGE(PG8_SA(0, 1), a2 + hstepA, voffA);
;             PG8_WAIT_V(8); PG8_WAIT_L(0); PG8_BAR; PG8_MMA(0, 0, At, B0); PG8_MMA(0, 1, At, B1); PG8_BAR; PG8_SCHED;
	s_add_i32 s66, s67, s25
	v_lshl_add_u64 v[194:195], s[14:15], 0, v[2:3]
	s_mov_b32 m0, s66
	ds_read_b128 v[178:181], v144 offset:16384
	ds_read_b128 v[182:185], v144 offset:17408
	ds_read_b128 v[186:189], v144 offset:18432
	ds_read_b128 v[190:193], v144 offset:19456
	ds_read_b128 v[204:207], v144 offset:20480
	ds_read_b128 v[220:223], v144 offset:21504
	ds_read_b128 v[224:227], v144 offset:22528
	ds_read_b128 v[228:231], v144 offset:23552
	global_load_lds_dwordx4 v[194:195], off
	s_add_i32 m0, s66, 0x2000
	s_add_u32 s66, s14, 0x80000
	v_lshl_add_u64 v[196:197], s[14:15], 0, v[132:133]
	s_addc_u32 s67, s15, 0
	s_add_i32 s65, s65, s25
	global_load_lds_dwordx4 v[196:197], off
	v_lshl_add_u64 v[208:209], s[66:67], 0, v[2:3]
	s_mov_b32 m0, s65
	v_lshl_add_u64 v[232:233], s[16:17], 0, v[134:135]
	global_load_lds_dwordx4 v[208:209], off
	v_lshl_add_u64 v[208:209], s[66:67], 0, v[132:133]
	s_add_i32 m0, s65, 0x2000
	s_nop 0
	global_load_lds_dwordx4 v[208:209], off
	v_lshl_add_u64 v[208:209], s[16:17], 0, v[136:137]
	s_mov_b32 m0, s37
	s_nop 0
	global_load_lds_dwordx4 v[208:209], off
	s_mov_b32 m0, s38
	s_nop 0
	global_load_lds_dwordx4 v[232:233], off
	s_waitcnt vmcnt(8)
	s_waitcnt lgkmcnt(0)
	s_setprio 1
	s_barrier
	v_mfma_f32_16x16x32_f16 v[64:67], v[146:149], v[178:181], 0
	v_mfma_f32_16x16x32_f16 v[60:63], v[154:157], v[178:181], 0
	v_mfma_f32_16x16x32_f16 v[56:59], v[146:149], v[186:189], 0
	v_mfma_f32_16x16x32_f16 v[52:55], v[154:157], v[186:189], 0
	v_mfma_f32_16x16x32_f16 v[44:47], v[146:149], v[204:207], 0
	v_mfma_f32_16x16x32_f16 v[36:39], v[154:157], v[204:207], 0
	v_mfma_f32_16x16x32_f16 v[28:31], v[146:149], v[224:227], 0
	v_mfma_f32_16x16x32_f16 v[20:23], v[154:157], v[224:227], 0
	v_mfma_f32_16x16x32_f16 v[64:67], v[150:153], v[182:185], v[64:67]
	v_mfma_f32_16x16x32_f16 v[60:63], v[158:161], v[182:185], v[60:63]
	v_mfma_f32_16x16x32_f16 v[56:59], v[150:153], v[190:193], v[56:59]
	v_mfma_f32_16x16x32_f16 v[52:55], v[158:161], v[190:193], v[52:55]
	v_mfma_f32_16x16x32_f16 v[44:47], v[150:153], v[220:223], v[44:47]
	v_mfma_f32_16x16x32_f16 v[36:39], v[158:161], v[220:223], v[36:39]
	v_mfma_f32_16x16x32_f16 v[28:31], v[150:153], v[228:231], v[28:31]
	v_mfma_f32_16x16x32_f16 v[20:23], v[158:161], v[228:231], v[20:23]
	v_mfma_f32_16x16x32_f16 v[48:51], v[162:165], v[178:181], 0
	v_mfma_f32_16x16x32_f16 v[40:43], v[170:173], v[178:181], 0
	v_mfma_f32_16x16x32_f16 v[32:35], v[162:165], v[186:189], 0
	v_mfma_f32_16x16x32_f16 v[24:27], v[170:173], v[186:189], 0
	v_mfma_f32_16x16x32_f16 v[16:19], v[162:165], v[204:207], 0
	v_mfma_f32_16x16x32_f16 v[12:15], v[170:173], v[204:207], 0
	v_mfma_f32_16x16x32_f16 v[8:11], v[162:165], v[224:227], 0
	v_mfma_f32_16x16x32_f16 v[4:7], v[170:173], v[224:227], 0
	v_mfma_f32_16x16x32_f16 v[48:51], v[166:169], v[182:185], v[48:51]
	v_mfma_f32_16x16x32_f16 v[40:43], v[174:177], v[182:185], v[40:43]
	v_mfma_f32_16x16x32_f16 v[32:35], v[166:169], v[190:193], v[32:35]
	v_mfma_f32_16x16x32_f16 v[24:27], v[174:177], v[190:193], v[24:27]
	v_mfma_f32_16x16x32_f16 v[16:19], v[166:169], v[220:223], v[16:19]
	v_mfma_f32_16x16x32_f16 v[12:15], v[174:177], v[220:223], v[12:15]
	v_mfma_f32_16x16x32_f16 v[8:11], v[166:169], v[228:231], v[8:11]
	v_mfma_f32_16x16x32_f16 v[4:7], v[174:177], v[228:231], v[4:7]
	s_setprio 0
	s_barrier
	s_add_i32 s65, 0, 0x18000
	v_add_u32_e32 v145, s65, v143
	s_add_i32 s66, 0, 0x1c000
	ds_read_b128 v[146:149], v145
	ds_read_b128 v[150:153], v145 offset:1024
	ds_read_b128 v[154:157], v145 offset:2048
	ds_read_b128 v[158:161], v145 offset:3072
	v_add_u32_e32 v145, s66, v143
	ds_read_b128 v[162:165], v145
	ds_read_b128 v[166:169], v145 offset:1024
	ds_read_b128 v[170:173], v145 offset:2048
	ds_read_b128 v[174:177], v145 offset:3072
	s_add_u32 s16, s16, 0x80000
	s_addc_u32 s17, s17, 0
	s_mov_b32 m0, s39
	v_lshl_add_u64 v[234:235], s[16:17], 0, v[136:137]
	ds_read_b128 v[178:181], v144 offset:32768
	ds_read_b128 v[182:185], v144 offset:33792
	ds_read_b128 v[186:189], v144 offset:34816
	ds_read_b128 v[190:193], v144 offset:35840
	ds_read_b128 v[204:207], v144 offset:36864
	ds_read_b128 v[220:223], v144 offset:37888
	ds_read_b128 v[224:227], v144 offset:38912
	ds_read_b128 v[228:231], v144 offset:39936
	global_load_lds_dwordx4 v[234:235], off
	v_lshl_add_u64 v[234:235], s[16:17], 0, v[134:135]
	s_mov_b32 m0, s57
	s_nop 0
	global_load_lds_dwordx4 v[234:235], off
	s_waitcnt vmcnt(8)
	s_waitcnt lgkmcnt(0)
	s_setprio 1
	s_barrier
	v_mfma_f32_16x16x32_f16 v[128:131], v[146:149], v[178:181], v[128:131]
	v_mfma_f32_16x16x32_f16 v[124:127], v[154:157], v[178:181], v[124:127]
	v_mfma_f32_16x16x32_f16 v[120:123], v[146:149], v[186:189], v[120:123]
	v_mfma_f32_16x16x32_f16 v[116:119], v[154:157], v[186:189], v[116:119]
	v_mfma_f32_16x16x32_f16 v[108:111], v[146:149], v[204:207], v[108:111]
	v_mfma_f32_16x16x32_f16 v[100:103], v[154:157], v[204:207], v[100:103]
	v_mfma_f32_16x16x32_f16 v[92:95], v[146:149], v[224:227], v[92:95]
	v_mfma_f32_16x16x32_f16 v[84:87], v[154:157], v[224:227], v[84:87]
	v_mfma_f32_16x16x32_f16 v[128:131], v[150:153], v[182:185], v[128:131]
	v_mfma_f32_16x16x32_f16 v[124:127], v[158:161], v[182:185], v[124:127]
	v_mfma_f32_16x16x32_f16 v[120:123], v[150:153], v[190:193], v[120:123]
	v_mfma_f32_16x16x32_f16 v[116:119], v[158:161], v[190:193], v[116:119]
	v_mfma_f32_16x16x32_f16 v[108:111], v[150:153], v[220:223], v[108:111]
	v_mfma_f32_16x16x32_f16 v[100:103], v[158:161], v[220:223], v[100:103]
	v_mfma_f32_16x16x32_f16 v[92:95], v[150:153], v[228:231], v[92:95]
	v_mfma_f32_16x16x32_f16 v[84:87], v[158:161], v[228:231], v[84:87]
	v_mfma_f32_16x16x32_f16 v[112:115], v[162:165], v[178:181], v[112:115]
	v_mfma_f32_16x16x32_f16 v[104:107], v[170:173], v[178:181], v[104:107]
	v_mfma_f32_16x16x32_f16 v[96:99], v[162:165], v[186:189], v[96:99]
	v_mfma_f32_16x16x32_f16 v[88:91], v[170:173], v[186:189], v[88:91]
	v_mfma_f32_16x16x32_f16 v[80:83], v[162:165], v[204:207], v[80:83]
	v_mfma_f32_16x16x32_f16 v[76:79], v[170:173], v[204:207], v[76:79]
	v_mfma_f32_16x16x32_f16 v[72:75], v[162:165], v[224:227], v[72:75]
	v_mfma_f32_16x16x32_f16 v[68:71], v[170:173], v[224:227], v[68:71]
	v_mfma_f32_16x16x32_f16 v[112:115], v[166:169], v[182:185], v[112:115]
	v_mfma_f32_16x16x32_f16 v[104:107], v[174:177], v[182:185], v[104:107]
	v_mfma_f32_16x16x32_f16 v[96:99], v[166:169], v[190:193], v[96:99]
	v_mfma_f32_16x16x32_f16 v[88:91], v[174:177], v[190:193], v[88:91]
	v_mfma_f32_16x16x32_f16 v[80:83], v[166:169], v[220:223], v[80:83]
	v_mfma_f32_16x16x32_f16 v[76:79], v[174:177], v[220:223], v[76:79]
	v_mfma_f32_16x16x32_f16 v[72:75], v[166:169], v[228:231], v[72:75]
	v_mfma_f32_16x16x32_f16 v[68:71], v[174:177], v[228:231], v[68:71]
	s_setprio 0
	s_barrier
; #define PG8_STAGE(bufoff, gbase, voff) do { _Pragma("unroll") for (int _i = 0; _i < 2; ++_i) \
;         __builtin_amdgcn_global_load_lds((const unsigned*)((const char*)(gbase) + (voff)[_i]), (LAS unsigned*)(lds + (bufoff) + ldsw + _i * 8192), 16, 0, 0); } while (0)
; #define PG8_LDA(dst, b, h) do { _Pragma("unroll") for (int m = 0; m < 4; ++m) _Pragma("unroll") for (int k = 0; k < 2; ++k) dst[m][k] = *(const LAS half8*)(lds + PG8_SA(b, h) + aoff + m * 2048 + k * 1024); } while (0)
; #define PG8_WAIT_V(n) asm volatile("s_waitcnt vmcnt(" #n ")" ::: "memory")
; template <class Epi, class Sched, bool ALIGN_EPI = false, bool SP2 = false>
; __device__ __forceinline__ void gemm_phase(LAS unsigned char* lds, const Gemm g, const Sched& S, const Epi& E) {
;     ...
;         for (int t = 0; t < nt; t += 2) {
;             const bool last = (t == nt - 2);
;             const char* a1 = cA + (size_t)(t + 1) * kstep;
;             const char* a2 = last ? nA : cA + (size_t)(t + 2) * kstep; const char* b2 = last ? nB : cB + (size_t)(t + 2) * kstep;
;             const char* a3 = a2 + kstep; const char* b3 = b2 + kstep;
;             if (last && has_next) S.a_ready(nxt);
;             if constexpr (SP2) {
;             PG8_LDB(B0, 0, 0); PG8_LDB(B1, 0, 1); PG8_SCHED; PG8_LDA(At, 0, 0); PG8_STAGE(PG8_SA(1, 1), a1 + hstepA, voffA);
;             PG8_WAIT_V(8); PG8_WAIT_L(0); PG8_BAR; PG8_MMA(0, 0, At, B0); PG8_MMA(0, 1, At, B1); PG8_BAR; PG8_SCHED;
;             PG8_LDA(At, 0, 1); PG8_STAGE(PG8_SB(0, 0), b2, voffB); PG8_STAGE(PG8_SB(0, 1), b2 + hstepB, voffB); PG8_STAGE(PG8_SA(0, 0), a2, voffA);
;             PG8_WAIT_V(8); PG8_WAIT_L(0); PG8_BAR; PG8_MMA(1, 0, At, B0); PG8_MMA(1, 1, At, B1); PG8_BAR; PG8_SCHED;
;             PG8_LDB(B0, 1, 0); PG8_LDB(B1, 1, 1); PG8_SCHED; PG8_LDA(At, 1, 0); PG8_STAGE(PG8_SA(0, 1), a2 + hstepA, voffA);
;             PG8_WAIT_V(8); PG8_WAIT_L(0); PG8_BAR; PG8_MMA(0, 0, At, B0); PG8_MMA(0, 1, At, B1); PG8_BAR; PG8_SCHED;
;             PG8_LDA(At, 1, 1); PG8_STAGE(PG8_SB(1, 0), b3, voffB); PG8_STAGE(PG8_SB(1, 1), b3 + hstepB, voffB); PG8_STAGE(PG8_SA(1, 0), a3, voffA);
;             PG8_WAIT_V(8); PG8_WAIT_L(0); PG8_BAR; PG8_MMA(1, 0, At, B0); PG8_MMA(1, 1, At, B1); PG8_BAR; PG8_SCHED;
;             } else {
;             PG8_LDB(B0, 0, 0); PG8_SCHED; PG8_LDA(At, 0, 0); PG8_STAGE(PG8_SA(1, 1), a1 + hstepA, voffA);
	s_add_i32 s16, s65, s25
	v_lshl_add_u64 v[194:195], v[194:195], 0, s[96:97]
	s_mov_b32 m0, s16
	ds_read_b128 v[178:181], v144 offset:49152
	ds_read_b128 v[182:185], v144 offset:50176
	ds_read_b128 v[186:189], v144 offset:51200
	ds_read_b128 v[190:193], v144 offset:52224
	ds_read_b128 v[204:207], v144 offset:53248
	ds_read_b128 v[220:223], v144 offset:54272
	ds_read_b128 v[224:227], v144 offset:55296
	ds_read_b128 v[228:231], v144 offset:56320
	global_load_lds_dwordx4 v[194:195], off
	s_add_i32 m0, s16, 0x2000
	s_add_u32 s14, s14, 0x80080
	v_lshl_add_u64 v[194:195], v[196:197], 0, s[96:97]
	s_addc_u32 s15, s15, 0
	s_add_i32 s16, s66, s25
	global_load_lds_dwordx4 v[194:195], off
	v_lshl_add_u64 v[194:195], s[14:15], 0, v[2:3]
	s_mov_b32 m0, s16
	s_nop 0
	global_load_lds_dwordx4 v[194:195], off
	v_lshl_add_u64 v[194:195], s[14:15], 0, v[132:133]
	s_add_i32 m0, s16, 0x2000
	s_nop 0
	global_load_lds_dwordx4 v[194:195], off
	v_lshl_add_u64 v[194:195], v[208:209], 0, s[96:97]
	s_mov_b32 m0, s60
	s_nop 0
	global_load_lds_dwordx4 v[194:195], off
	v_lshl_add_u64 v[194:195], v[232:233], 0, s[96:97]
	s_mov_b32 m0, s61
	s_nop 0
	global_load_lds_dwordx4 v[194:195], off
	s_waitcnt vmcnt(8)
	s_waitcnt lgkmcnt(0)
	s_setprio 1
	s_barrier
	v_mfma_f32_16x16x32_f16 v[64:67], v[146:149], v[178:181], v[64:67]
	v_mfma_f32_16x16x32_f16 v[60:63], v[154:157], v[178:181], v[60:63]
	v_mfma_f32_16x16x32_f16 v[56:59], v[146:149], v[186:189], v[56:59]
	v_mfma_f32_16x16x32_f16 v[52:55], v[154:157], v[186:189], v[52:55]
	v_mfma_f32_16x16x32_f16 v[44:47], v[146:149], v[204:207], v[44:47]
	v_mfma_f32_16x16x32_f16 v[36:39], v[154:157], v[204:207], v[36:39]
	v_mfma_f32_16x16x32_f16 v[28:31], v[146:149], v[224:227], v[28:31]
	v_mfma_f32_16x16x32_f16 v[20:23], v[154:157], v[224:227], v[20:23]
	v_mfma_f32_16x16x32_f16 v[64:67], v[150:153], v[182:185], v[64:67]
	v_mfma_f32_16x16x32_f16 v[60:63], v[158:161], v[182:185], v[60:63]
	v_mfma_f32_16x16x32_f16 v[56:59], v[150:153], v[190:193], v[56:59]
	v_mfma_f32_16x16x32_f16 v[52:55], v[158:161], v[190:193], v[52:55]
	v_mfma_f32_16x16x32_f16 v[44:47], v[150:153], v[220:223], v[44:47]
	v_mfma_f32_16x16x32_f16 v[36:39], v[158:161], v[220:223], v[36:39]
	v_mfma_f32_16x16x32_f16 v[28:31], v[150:153], v[228:231], v[28:31]
	v_mfma_f32_16x16x32_f16 v[20:23], v[158:161], v[228:231], v[20:23]
	v_mfma_f32_16x16x32_f16 v[48:51], v[162:165], v[178:181], v[48:51]
	v_mfma_f32_16x16x32_f16 v[40:43], v[170:173], v[178:181], v[40:43]
	v_mfma_f32_16x16x32_f16 v[32:35], v[162:165], v[186:189], v[32:35]
	v_mfma_f32_16x16x32_f16 v[24:27], v[170:173], v[186:189], v[24:27]
	v_mfma_f32_16x16x32_f16 v[16:19], v[162:165], v[204:207], v[16:19]
	v_mfma_f32_16x16x32_f16 v[12:15], v[170:173], v[204:207], v[12:15]
	v_mfma_f32_16x16x32_f16 v[8:11], v[162:165], v[224:227], v[8:11]
	v_mfma_f32_16x16x32_f16 v[4:7], v[170:173], v[224:227], v[4:7]
	v_mfma_f32_16x16x32_f16 v[48:51], v[166:169], v[182:185], v[48:51]
	v_mfma_f32_16x16x32_f16 v[40:43], v[174:177], v[182:185], v[40:43]
	v_mfma_f32_16x16x32_f16 v[32:35], v[166:169], v[190:193], v[32:35]
	v_mfma_f32_16x16x32_f16 v[24:27], v[174:177], v[190:193], v[24:27]
	v_mfma_f32_16x16x32_f16 v[16:19], v[166:169], v[220:223], v[16:19]
	v_mfma_f32_16x16x32_f16 v[12:15], v[174:177], v[220:223], v[12:15]
	v_mfma_f32_16x16x32_f16 v[8:11], v[166:169], v[228:231], v[8:11]
	v_mfma_f32_16x16x32_f16 v[4:7], v[174:177], v[228:231], v[4:7]
	s_setprio 0
	s_barrier
	s_add_i32 s64, s64, 2
	s_add_u32 s12, s12, 0x100
	s_addc_u32 s13, s13, 0
	s_cmp_gt_u32 s64, 5
	s_cbranch_scc0 .LBB0_2222
.LBB0_2222:
	s_add_u32 s14, s62, s12
	s_addc_u32 s15, s63, s13
	s_add_u32 s14, s14, 0x100
	s_addc_u32 s15, s15, 0
	s_add_u32 s65, s2, s12
	s_addc_u32 s66, s59, s13
	s_add_i32 s67, 0, 0x10000
	s_cmpk_eq_i32 s12, 0x300
	s_cselect_b32 s17, s11, s15
	s_cselect_b32 s16, s10, s14
	v_add_u32_e32 v145, s67, v143
	s_cselect_b32 s15, s9, s66
	s_cselect_b32 s14, s8, s65
	s_add_i32 s65, 0, 0x14000
	ds_read_b128 v[146:149], v145
	ds_read_b128 v[150:153], v145 offset:1024
	ds_read_b128 v[154:157], v145 offset:2048
	ds_read_b128 v[158:161], v145 offset:3072
	v_add_u32_e32 v145, s65, v143
	ds_read_b128 v[162:165], v145
	ds_read_b128 v[166:169], v145 offset:1024
	ds_read_b128 v[170:173], v145 offset:2048
	ds_read_b128 v[174:177], v145 offset:3072
	v_lshl_add_u64 v[194:195], v[138:139], 0, s[12:13]
	s_add_i32 m0, s37, 0xc000
	ds_read_b128 v[178:181], v144
	ds_read_b128 v[182:185], v144 offset:1024
	ds_read_b128 v[186:189], v144 offset:2048
	ds_read_b128 v[190:193], v144 offset:3072
	ds_read_b128 v[204:207], v144 offset:4096
	ds_read_b128 v[220:223], v144 offset:5120
	ds_read_b128 v[224:227], v144 offset:6144
	ds_read_b128 v[228:231], v144 offset:7168
	global_load_lds_dwordx4 v[194:195], off
	v_lshl_add_u64 v[194:195], v[140:141], 0, s[12:13]
	s_add_i32 m0, s37, 0xe000
	s_nop 0
	global_load_lds_dwordx4 v[194:195], off
	s_waitcnt vmcnt(8)
	s_waitcnt lgkmcnt(0)
	s_setprio 1
	s_barrier
; #define PG8_STAGE(bufoff, gbase, voff) do { _Pragma("unroll") for (int _i = 0; _i < 2; ++_i) \
;         __builtin_amdgcn_global_load_lds((const unsigned*)((const char*)(gbase) + (voff)[_i]), (LAS unsigned*)(lds + (bufoff) + ldsw + _i * 8192), 16, 0, 0); } while (0)
; #define PG8_LDA(dst, b, h) do { _Pragma("unroll") for (int m = 0; m < 4; ++m) _Pragma("unroll") for (int k = 0; k < 2; ++k) dst[m][k] = *(const LAS half8*)(lds + PG8_SA(b, h) + aoff + m * 2048 + k * 1024); } while (0)
; #define PG8_LDB(dst, b, h) do { _Pragma("unroll") for (int n = 0; n < 2; ++n) _Pragma("unroll") for (int k = 0; k < 2; ++k) dst[n][k] = *(const LAS half8*)(lds + PG8_SB(b, h) + boff + n * 2048 + k * 1024); } while (0)
; #define PG8_MMA(ai, bj, At, Bt) do { __builtin_amdgcn_s_setprio(1); _Pragma("unroll") for (int m = 0; m < 4; ++m) _Pragma("unroll") for (int n = 0; n < 2; ++n) _Pragma("unroll") for (int k = 0; k < 2; ++k) \
;         acc[ai][bj][m][n] = __builtin_amdgcn_mfma_f32_16x16x32_f16(Bt[n][k], At[m][k], acc[ai][bj][m][n], 0, 0, 0); __builtin_amdgcn_s_setprio(0); } while (0)
; #define PG8_WAIT_V(n) asm volatile("s_waitcnt vmcnt(" #n ")" ::: "memory")
; #define PG8_WAIT_L(n) asm volatile("s_waitcnt lgkmcnt(" #n ")" ::: "memory")
; #define PG8_BAR __builtin_amdgcn_s_barrier()
; #define PG8_SCHED __builtin_amdgcn_sched_barrier(0)
; template <class Epi, class Sched, bool ALIGN_EPI = false, bool SP2 = false>
; __device__ __forceinline__ void gemm_phase(LAS unsigned char* lds, const Gemm g, const Sched& S, const Epi& E) {
;     ...
;             if constexpr (SP2) {
;             PG8_LDB(B0, 0, 0); PG8_LDB(B1, 0, 1); PG8_SCHED; PG8_LDA(At, 0, 0); PG8_STAGE(PG8_SA(1, 1), a1 + hstepA, voffA);
;             PG8_WAIT_V(8); PG8_WAIT_L(0); PG8_BAR; PG8_MMA(0, 0, At, B0); PG8_MMA(0, 1, At, B1); PG8_BAR; PG8_SCHED;
;             PG8_LDA(At, 0, 1); PG8_STAGE(PG8_SB(0, 0), b2, voffB); PG8_STAGE(PG8_SB(0, 1), b2 + hstepB, voffB); PG8_STAGE(PG8_SA(0, 0), a2, voffA);
;             PG8_WAIT_V(8); PG8_WAIT_L(0); PG8_BAR; PG8_MMA(1, 0, At, B0); PG8_MMA(1, 1, At, B1); PG8_BAR; PG8_SCHED;
	v_mfma_f32_16x16x32_f16 v[128:131], v[146:149], v[178:181], v[128:131]
	v_mfma_f32_16x16x32_f16 v[124:127], v[154:157], v[178:181], v[124:127]
	v_mfma_f32_16x16x32_f16 v[120:123], v[146:149], v[186:189], v[120:123]
	v_mfma_f32_16x16x32_f16 v[116:119], v[154:157], v[186:189], v[116:119]
	v_mfma_f32_16x16x32_f16 v[108:111], v[146:149], v[204:207], v[108:111]
	v_mfma_f32_16x16x32_f16 v[100:103], v[154:157], v[204:207], v[100:103]
	v_mfma_f32_16x16x32_f16 v[92:95], v[146:149], v[224:227], v[92:95]
	v_mfma_f32_16x16x32_f16 v[84:87], v[154:157], v[224:227], v[84:87]
	v_mfma_f32_16x16x32_f16 v[128:131], v[150:153], v[182:185], v[128:131]
	v_mfma_f32_16x16x32_f16 v[124:127], v[158:161], v[182:185], v[124:127]
	v_mfma_f32_16x16x32_f16 v[120:123], v[150:153], v[190:193], v[120:123]
	v_mfma_f32_16x16x32_f16 v[116:119], v[158:161], v[190:193], v[116:119]
	v_mfma_f32_16x16x32_f16 v[108:111], v[150:153], v[220:223], v[108:111]
	v_mfma_f32_16x16x32_f16 v[100:103], v[158:161], v[220:223], v[100:103]
	v_mfma_f32_16x16x32_f16 v[92:95], v[150:153], v[228:231], v[92:95]
	v_mfma_f32_16x16x32_f16 v[84:87], v[158:161], v[228:231], v[84:87]
	v_mfma_f32_16x16x32_f16 v[112:115], v[162:165], v[178:181], v[112:115]
	v_mfma_f32_16x16x32_f16 v[104:107], v[170:173], v[178:181], v[104:107]
	v_mfma_f32_16x16x32_f16 v[96:99], v[162:165], v[186:189], v[96:99]
	v_mfma_f32_16x16x32_f16 v[88:91], v[170:173], v[186:189], v[88:91]
	v_mfma_f32_16x16x32_f16 v[80:83], v[162:165], v[204:207], v[80:83]
	v_mfma_f32_16x16x32_f16 v[76:79], v[170:173], v[204:207], v[76:79]
	v_mfma_f32_16x16x32_f16 v[72:75], v[162:165], v[224:227], v[72:75]
	v_mfma_f32_16x16x32_f16 v[68:71], v[170:173], v[224:227], v[68:71]
	v_mfma_f32_16x16x32_f16 v[112:115], v[166:169], v[182:185], v[112:115]
	v_mfma_f32_16x16x32_f16 v[104:107], v[174:177], v[182:185], v[104:107]
	v_mfma_f32_16x16x32_f16 v[96:99], v[166:169], v[190:193], v[96:99]
	v_mfma_f32_16x16x32_f16 v[88:91], v[174:177], v[190:193], v[88:91]
	v_mfma_f32_16x16x32_f16 v[80:83], v[166:169], v[220:223], v[80:83]
	v_mfma_f32_16x16x32_f16 v[76:79], v[174:177], v[220:223], v[76:79]
	v_mfma_f32_16x16x32_f16 v[72:75], v[166:169], v[228:231], v[72:75]
	v_mfma_f32_16x16x32_f16 v[68:71], v[174:177], v[228:231], v[68:71]
	s_setprio 0
	s_barrier
	s_add_i32 s66, s67, s25
	v_lshl_add_u64 v[194:195], s[14:15], 0, v[2:3]
	s_mov_b32 m0, s66
	ds_read_b128 v[178:181], v144 offset:16384
	ds_read_b128 v[182:185], v144 offset:17408
	ds_read_b128 v[186:189], v144 offset:18432
	ds_read_b128 v[190:193], v144 offset:19456
	ds_read_b128 v[204:207], v144 offset:20480
	ds_read_b128 v[220:223], v144 offset:21504
	ds_read_b128 v[224:227], v144 offset:22528
	ds_read_b128 v[228:231], v144 offset:23552
	global_load_lds_dwordx4 v[194:195], off
	s_add_i32 m0, s66, 0x2000
	s_add_u32 s66, s14, 0x80000
	v_lshl_add_u64 v[196:197], s[14:15], 0, v[132:133]
	s_addc_u32 s67, s15, 0
	s_add_i32 s65, s65, s25
	global_load_lds_dwordx4 v[196:197], off
	v_lshl_add_u64 v[208:209], s[66:67], 0, v[2:3]
	s_mov_b32 m0, s65
	v_lshl_add_u64 v[232:233], s[16:17], 0, v[134:135]
	global_load_lds_dwordx4 v[208:209], off
	v_lshl_add_u64 v[208:209], s[66:67], 0, v[132:133]
	s_add_i32 m0, s65, 0x2000
	s_nop 0
	global_load_lds_dwordx4 v[208:209], off
	v_lshl_add_u64 v[208:209], s[16:17], 0, v[136:137]
	s_mov_b32 m0, s37
	s_nop 0
	global_load_lds_dwordx4 v[208:209], off
	s_mov_b32 m0, s38
	s_nop 0
	global_load_lds_dwordx4 v[232:233], off
	s_waitcnt vmcnt(8)
	s_waitcnt lgkmcnt(0)
	s_setprio 1
	s_barrier
	v_mfma_f32_16x16x32_f16 v[64:67], v[146:149], v[178:181], v[64:67]
	v_mfma_f32_16x16x32_f16 v[60:63], v[154:157], v[178:181], v[60:63]
	v_mfma_f32_16x16x32_f16 v[56:59], v[146:149], v[186:189], v[56:59]
	v_mfma_f32_16x16x32_f16 v[52:55], v[154:157], v[186:189], v[52:55]
	v_mfma_f32_16x16x32_f16 v[44:47], v[146:149], v[204:207], v[44:47]
	v_mfma_f32_16x16x32_f16 v[36:39], v[154:157], v[204:207], v[36:39]
	v_mfma_f32_16x16x32_f16 v[28:31], v[146:149], v[224:227], v[28:31]
	v_mfma_f32_16x16x32_f16 v[20:23], v[154:157], v[224:227], v[20:23]
	v_mfma_f32_16x16x32_f16 v[64:67], v[150:153], v[182:185], v[64:67]
	v_mfma_f32_16x16x32_f16 v[60:63], v[158:161], v[182:185], v[60:63]
	v_mfma_f32_16x16x32_f16 v[56:59], v[150:153], v[190:193], v[56:59]
	v_mfma_f32_16x16x32_f16 v[52:55], v[158:161], v[190:193], v[52:55]
	v_mfma_f32_16x16x32_f16 v[44:47], v[150:153], v[220:223], v[44:47]
	v_mfma_f32_16x16x32_f16 v[36:39], v[158:161], v[220:223], v[36:39]
	v_mfma_f32_16x16x32_f16 v[28:31], v[150:153], v[228:231], v[28:31]
	v_mfma_f32_16x16x32_f16 v[20:23], v[158:161], v[228:231], v[20:23]
	v_mfma_f32_16x16x32_f16 v[48:51], v[162:165], v[178:181], v[48:51]
	v_mfma_f32_16x16x32_f16 v[40:43], v[170:173], v[178:181], v[40:43]
	v_mfma_f32_16x16x32_f16 v[32:35], v[162:165], v[186:189], v[32:35]
	v_mfma_f32_16x16x32_f16 v[24:27], v[170:173], v[186:189], v[24:27]
	v_mfma_f32_16x16x32_f16 v[16:19], v[162:165], v[204:207], v[16:19]
	v_mfma_f32_16x16x32_f16 v[12:15], v[170:173], v[204:207], v[12:15]
	v_mfma_f32_16x16x32_f16 v[8:11], v[162:165], v[224:227], v[8:11]
	v_mfma_f32_16x16x32_f16 v[4:7], v[170:173], v[224:227], v[4:7]
	v_mfma_f32_16x16x32_f16 v[48:51], v[166:169], v[182:185], v[48:51]
	v_mfma_f32_16x16x32_f16 v[40:43], v[174:177], v[182:185], v[40:43]
	v_mfma_f32_16x16x32_f16 v[32:35], v[166:169], v[190:193], v[32:35]
	v_mfma_f32_16x16x32_f16 v[24:27], v[174:177], v[190:193], v[24:27]
	v_mfma_f32_16x16x32_f16 v[16:19], v[166:169], v[220:223], v[16:19]
	v_mfma_f32_16x16x32_f16 v[12:15], v[174:177], v[220:223], v[12:15]
	v_mfma_f32_16x16x32_f16 v[8:11], v[166:169], v[228:231], v[8:11]
	v_mfma_f32_16x16x32_f16 v[4:7], v[174:177], v[228:231], v[4:7]
	s_setprio 0
	s_barrier
; #define PG8_STAGE(bufoff, gbase, voff) do { _Pragma("unroll") for (int _i = 0; _i < 2; ++_i) \
;         __builtin_amdgcn_global_load_lds((const unsigned*)((const char*)(gbase) + (voff)[_i]), (LAS unsigned*)(lds + (bufoff) + ldsw + _i * 8192), 16, 0, 0); } while (0)
; #define PG8_LDA(dst, b, h) do { _Pragma("unroll") for (int m = 0; m < 4; ++m) _Pragma("unroll") for (int k = 0; k < 2; ++k) dst[m][k] = *(const LAS half8*)(lds + PG8_SA(b, h) + aoff + m * 2048 + k * 1024); } while (0)
; #define PG8_LDB(dst, b, h) do { _Pragma("unroll") for (int n = 0; n < 2; ++n) _Pragma("unroll") for (int k = 0; k < 2; ++k) dst[n][k] = *(const LAS half8*)(lds + PG8_SB(b, h) + boff + n * 2048 + k * 1024); } while (0)
; #define PG8_MMA(ai, bj, At, Bt) do { __builtin_amdgcn_s_setprio(1); _Pragma("unroll") for (int m = 0; m < 4; ++m) _Pragma("unroll") for (int n = 0; n < 2; ++n) _Pragma("unroll") for (int k = 0; k < 2; ++k) \
;         acc[ai][bj][m][n] = __builtin_amdgcn_mfma_f32_16x16x32_f16(Bt[n][k], At[m][k], acc[ai][bj][m][n], 0, 0, 0); __builtin_amdgcn_s_setprio(0); } while (0)
; #define PG8_WAIT_V(n) asm volatile("s_waitcnt vmcnt(" #n ")" ::: "memory")
; #define PG8_WAIT_L(n) asm volatile("s_waitcnt lgkmcnt(" #n ")" ::: "memory")
; #define PG8_BAR __builtin_amdgcn_s_barrier()
; #define PG8_SCHED __builtin_amdgcn_sched_barrier(0)
; template <class Epi, class Sched, bool ALIGN_EPI = false, bool SP2 = false>
; __device__ __forceinline__ void gemm_phase(LAS unsigned char* lds, const Gemm g, const Sched& S, const Epi& E) {
;     ...
;         for (int t = 0; t < nt; t += 2) {
;     ...
;             PG8_LDB(B0, 1, 0); PG8_LDB(B1, 1, 1); PG8_SCHED; PG8_LDA(At, 1, 0); PG8_STAGE(PG8_SA(0, 1), a2 + hstepA, voffA);
;             PG8_WAIT_V(8); PG8_WAIT_L(0); PG8_BAR; PG8_MMA(0, 0, At, B0); PG8_MMA(0, 1, At, B1); PG8_BAR; PG8_SCHED;
;             PG8_LDA(At, 1, 1); PG8_STAGE(PG8_SB(1, 0), b3, voffB); PG8_STAGE(PG8_SB(1, 1), b3 + hstepB, voffB); PG8_STAGE(PG8_SA(1, 0), a3, voffA);
;             PG8_WAIT_V(8); PG8_WAIT_L(0); PG8_BAR; PG8_MMA(1, 0, At, B0); PG8_MMA(1, 1, At, B1); PG8_BAR; PG8_SCHED;
;     ...
;         if constexpr (ALIGN_EPI) { if (wr == 0) PG8_BAR; }
	s_add_i32 s65, 0, 0x18000
	v_add_u32_e32 v145, s65, v143
	s_add_i32 s66, 0, 0x1c000
	ds_read_b128 v[146:149], v145
	ds_read_b128 v[150:153], v145 offset:1024
	ds_read_b128 v[154:157], v145 offset:2048
	ds_read_b128 v[158:161], v145 offset:3072
	v_add_u32_e32 v145, s66, v143
	ds_read_b128 v[162:165], v145
	ds_read_b128 v[166:169], v145 offset:1024
	ds_read_b128 v[170:173], v145 offset:2048
	ds_read_b128 v[174:177], v145 offset:3072
	s_add_u32 s16, s16, 0x80000
	s_addc_u32 s17, s17, 0
	s_mov_b32 m0, s39
	v_lshl_add_u64 v[234:235], s[16:17], 0, v[136:137]
	ds_read_b128 v[178:181], v144 offset:32768
	ds_read_b128 v[182:185], v144 offset:33792
	ds_read_b128 v[186:189], v144 offset:34816
	ds_read_b128 v[190:193], v144 offset:35840
	ds_read_b128 v[204:207], v144 offset:36864
	ds_read_b128 v[220:223], v144 offset:37888
	ds_read_b128 v[224:227], v144 offset:38912
	ds_read_b128 v[228:231], v144 offset:39936
	global_load_lds_dwordx4 v[234:235], off
	v_lshl_add_u64 v[234:235], s[16:17], 0, v[134:135]
	s_mov_b32 m0, s57
	s_nop 0
	global_load_lds_dwordx4 v[234:235], off
	s_waitcnt vmcnt(8)
	s_waitcnt lgkmcnt(0)
	s_setprio 1
	s_barrier
	v_mfma_f32_16x16x32_f16 v[128:131], v[146:149], v[178:181], v[128:131]
	v_mfma_f32_16x16x32_f16 v[124:127], v[154:157], v[178:181], v[124:127]
	v_mfma_f32_16x16x32_f16 v[120:123], v[146:149], v[186:189], v[120:123]
	v_mfma_f32_16x16x32_f16 v[116:119], v[154:157], v[186:189], v[116:119]
	v_mfma_f32_16x16x32_f16 v[108:111], v[146:149], v[204:207], v[108:111]
	v_mfma_f32_16x16x32_f16 v[100:103], v[154:157], v[204:207], v[100:103]
	v_mfma_f32_16x16x32_f16 v[92:95], v[146:149], v[224:227], v[92:95]
	v_mfma_f32_16x16x32_f16 v[84:87], v[154:157], v[224:227], v[84:87]
	v_mfma_f32_16x16x32_f16 v[128:131], v[150:153], v[182:185], v[128:131]
	v_mfma_f32_16x16x32_f16 v[124:127], v[158:161], v[182:185], v[124:127]
	v_mfma_f32_16x16x32_f16 v[120:123], v[150:153], v[190:193], v[120:123]
	v_mfma_f32_16x16x32_f16 v[116:119], v[158:161], v[190:193], v[116:119]
	v_mfma_f32_16x16x32_f16 v[108:111], v[150:153], v[220:223], v[108:111]
	v_mfma_f32_16x16x32_f16 v[100:103], v[158:161], v[220:223], v[100:103]
	v_mfma_f32_16x16x32_f16 v[92:95], v[150:153], v[228:231], v[92:95]
	v_mfma_f32_16x16x32_f16 v[84:87], v[158:161], v[228:231], v[84:87]
	v_mfma_f32_16x16x32_f16 v[112:115], v[162:165], v[178:181], v[112:115]
	v_mfma_f32_16x16x32_f16 v[104:107], v[170:173], v[178:181], v[104:107]
	v_mfma_f32_16x16x32_f16 v[96:99], v[162:165], v[186:189], v[96:99]
	v_mfma_f32_16x16x32_f16 v[88:91], v[170:173], v[186:189], v[88:91]
	v_mfma_f32_16x16x32_f16 v[80:83], v[162:165], v[204:207], v[80:83]
	v_mfma_f32_16x16x32_f16 v[76:79], v[170:173], v[204:207], v[76:79]
	v_mfma_f32_16x16x32_f16 v[72:75], v[162:165], v[224:227], v[72:75]
	v_mfma_f32_16x16x32_f16 v[68:71], v[170:173], v[224:227], v[68:71]
	v_mfma_f32_16x16x32_f16 v[112:115], v[166:169], v[182:185], v[112:115]
	v_mfma_f32_16x16x32_f16 v[104:107], v[174:177], v[182:185], v[104:107]
	v_mfma_f32_16x16x32_f16 v[96:99], v[166:169], v[190:193], v[96:99]
	v_mfma_f32_16x16x32_f16 v[88:91], v[174:177], v[190:193], v[88:91]
	v_mfma_f32_16x16x32_f16 v[80:83], v[166:169], v[220:223], v[80:83]
	v_mfma_f32_16x16x32_f16 v[76:79], v[174:177], v[220:223], v[76:79]
	v_mfma_f32_16x16x32_f16 v[72:75], v[166:169], v[228:231], v[72:75]
	v_mfma_f32_16x16x32_f16 v[68:71], v[174:177], v[228:231], v[68:71]
	s_setprio 0
	s_barrier
	s_add_i32 s16, s65, s25
	v_lshl_add_u64 v[194:195], v[194:195], 0, s[96:97]
	s_mov_b32 m0, s16
	ds_read_b128 v[178:181], v144 offset:49152
	ds_read_b128 v[182:185], v144 offset:50176
	ds_read_b128 v[186:189], v144 offset:51200
	ds_read_b128 v[190:193], v144 offset:52224
	ds_read_b128 v[204:207], v144 offset:53248
	ds_read_b128 v[220:223], v144 offset:54272
	ds_read_b128 v[224:227], v144 offset:55296
	ds_read_b128 v[228:231], v144 offset:56320
	global_load_lds_dwordx4 v[194:195], off
	s_add_i32 m0, s16, 0x2000
	s_add_u32 s14, s14, 0x80080
	v_lshl_add_u64 v[194:195], v[196:197], 0, s[96:97]
	s_addc_u32 s15, s15, 0
	s_add_i32 s16, s66, s25
	global_load_lds_dwordx4 v[194:195], off
	v_lshl_add_u64 v[194:195], s[14:15], 0, v[2:3]
	s_mov_b32 m0, s16
	s_nop 0
	global_load_lds_dwordx4 v[194:195], off
	v_lshl_add_u64 v[194:195], s[14:15], 0, v[132:133]
	s_add_i32 m0, s16, 0x2000
	s_nop 0
	global_load_lds_dwordx4 v[194:195], off
	v_lshl_add_u64 v[194:195], v[208:209], 0, s[96:97]
	s_mov_b32 m0, s60
	s_nop 0
	global_load_lds_dwordx4 v[194:195], off
	v_lshl_add_u64 v[194:195], v[232:233], 0, s[96:97]
	s_mov_b32 m0, s61
	s_nop 0
	global_load_lds_dwordx4 v[194:195], off
	s_waitcnt vmcnt(8)
	s_waitcnt lgkmcnt(0)
	s_setprio 1
	s_barrier
	v_mfma_f32_16x16x32_f16 v[64:67], v[146:149], v[178:181], v[64:67]
	v_mfma_f32_16x16x32_f16 v[60:63], v[154:157], v[178:181], v[60:63]
	v_mfma_f32_16x16x32_f16 v[56:59], v[146:149], v[186:189], v[56:59]
	v_mfma_f32_16x16x32_f16 v[52:55], v[154:157], v[186:189], v[52:55]
	v_mfma_f32_16x16x32_f16 v[44:47], v[146:149], v[204:207], v[44:47]
	v_mfma_f32_16x16x32_f16 v[36:39], v[154:157], v[204:207], v[36:39]
	v_mfma_f32_16x16x32_f16 v[28:31], v[146:149], v[224:227], v[28:31]
	v_mfma_f32_16x16x32_f16 v[20:23], v[154:157], v[224:227], v[20:23]
	v_mfma_f32_16x16x32_f16 v[64:67], v[150:153], v[182:185], v[64:67]
	v_mfma_f32_16x16x32_f16 v[60:63], v[158:161], v[182:185], v[60:63]
	v_mfma_f32_16x16x32_f16 v[56:59], v[150:153], v[190:193], v[56:59]
	v_mfma_f32_16x16x32_f16 v[52:55], v[158:161], v[190:193], v[52:55]
	v_mfma_f32_16x16x32_f16 v[44:47], v[150:153], v[220:223], v[44:47]
	v_mfma_f32_16x16x32_f16 v[36:39], v[158:161], v[220:223], v[36:39]
	v_mfma_f32_16x16x32_f16 v[28:31], v[150:153], v[228:231], v[28:31]
	v_mfma_f32_16x16x32_f16 v[20:23], v[158:161], v[228:231], v[20:23]
	v_mfma_f32_16x16x32_f16 v[48:51], v[162:165], v[178:181], v[48:51]
	v_mfma_f32_16x16x32_f16 v[40:43], v[170:173], v[178:181], v[40:43]
	v_mfma_f32_16x16x32_f16 v[32:35], v[162:165], v[186:189], v[32:35]
	v_mfma_f32_16x16x32_f16 v[24:27], v[170:173], v[186:189], v[24:27]
	v_mfma_f32_16x16x32_f16 v[16:19], v[162:165], v[204:207], v[16:19]
	v_mfma_f32_16x16x32_f16 v[12:15], v[170:173], v[204:207], v[12:15]
	v_mfma_f32_16x16x32_f16 v[8:11], v[162:165], v[224:227], v[8:11]
	v_mfma_f32_16x16x32_f16 v[4:7], v[170:173], v[224:227], v[4:7]
	v_mfma_f32_16x16x32_f16 v[48:51], v[166:169], v[182:185], v[48:51]
	v_mfma_f32_16x16x32_f16 v[40:43], v[174:177], v[182:185], v[40:43]
	v_mfma_f32_16x16x32_f16 v[32:35], v[166:169], v[190:193], v[32:35]
	v_mfma_f32_16x16x32_f16 v[24:27], v[174:177], v[190:193], v[24:27]
	v_mfma_f32_16x16x32_f16 v[16:19], v[166:169], v[220:223], v[16:19]
	v_mfma_f32_16x16x32_f16 v[12:15], v[174:177], v[220:223], v[12:15]
	v_mfma_f32_16x16x32_f16 v[8:11], v[166:169], v[228:231], v[8:11]
	v_mfma_f32_16x16x32_f16 v[4:7], v[174:177], v[228:231], v[4:7]
	s_setprio 0
	s_barrier
	s_add_i32 s64, s64, 2
	s_add_u32 s12, s12, 0x100
	s_addc_u32 s13, s13, 0
	s_cmp_gt_u32 s64, 5
	s_cbranch_scc0 .LBB0_2222
	s_cmpk_lt_u32 s1, 0x100
	s_cbranch_scc0 .LBB0_2225
	s_barrier

; #define PG8_WAIT_V(n) asm volatile("s_waitcnt vmcnt(" #n ")" ::: "memory")
; template <class Epi, class Sched, bool ALIGN_EPI = false, bool SP2 = false>
; __device__ __forceinline__ void gemm_phase(LAS unsigned char* lds, const Gemm g, const Sched& S, const Epi& E) {
;     ...
;     for (int i = 0; i < 2; ++i) { int R, C; stage_rc(tid * 16 + i * 8192, R, C); const int Rb = Epi::PERM ? ((R & ~31) + perm32(R & 31)) : R;
;         voffA[i] = (unsigned)(R * lda + C) * 2u; voffB[i] = (unsigned)(Rb * ldb + C) * 2u; }
;     const size_t kstep = (size_t)(BK * 2);
;     const size_t hstepA = (size_t)HALF * lda * 2, hstepB = (size_t)HALF * ldb * 2;
;     const size_t tstepA = 2 * hstepA, tstepB = 2 * hstepB;
;     const unsigned ldsw = (unsigned)wid * 1024u;
;     const int aoff = lds_byte(wr * 64 + fr, fq * 8), boff = lds_byte(wc * 32 + fr, fq * 8);
;     ...
;     Unit cur, nxt; int ui = 0;
;     if (!S.next(0, cur)) return;
;     f32x4 acc[2][2][4][2];
; #pragma unroll
;     for (int a = 0; a < 2; ++a)
; #pragma unroll
;         for (int b = 0; b < 2; ++b)
; #pragma unroll
;             for (int m = 0; m < 4; ++m)
; #pragma unroll
;                 for (int n = 0; n < 2; ++n) acc[a][b][m][n] = (f32x4){0.f, 0.f, 0.f, 0.f};
;     half8 At[4][2], B0[2][2], B1[2][2];
;     const char* cA = (const char*)g.A + (size_t)cur.pm * tstepA; const char* cB = (const char*)g.Bt + (size_t)cur.pn * tstepB;
;     S.a_ready(cur);
;     if constexpr (SP2) {
;         PG8_STAGE(PG8_SB(0, 0), cB, voffB); PG8_STAGE(PG8_SB(0, 1), cB + hstepB, voffB); PG8_STAGE(PG8_SA(0, 0), cA, voffA); PG8_STAGE(PG8_SA(0, 1), cA + hstepA, voffA);
;         if (wr == 1) PG8_BAR;
;         PG8_WAIT_V(2); PG8_BAR;
;         PG8_STAGE(PG8_SB(1, 0), cB + kstep, voffB); PG8_STAGE(PG8_SA(1, 0), cA + kstep, voffA); PG8_STAGE(PG8_SB(1, 1), cB + hstepB + kstep, voffB);
;         PG8_WAIT_V(6); PG8_BAR;
;     } else {
;         PG8_STAGE(PG8_SB(0, 0), cB, voffB); PG8_STAGE(PG8_SA(0, 0), cA, voffA); PG8_STAGE(PG8_SB(0, 1), cB + hstepB, voffB); PG8_STAGE(PG8_SA(0, 1), cA + hstepA, voffA);
;         if (wr == 1) PG8_BAR;
;         PG8_WAIT_V(4); PG8_BAR;
;         PG8_STAGE(PG8_SB(1, 0), cB + kstep, voffB); PG8_STAGE(PG8_SA(1, 0), cA + kstep, voffA); PG8_STAGE(PG8_SB(1, 1), cB + hstepB + kstep, voffB);
;         PG8_WAIT_V(6); PG8_BAR;
;     }
;     for (;;) {
;         const bool has_next = S.next(ui + 1, nxt);
.LBB0_2229:
	v_lshrrev_b32_e32 v20, 1, v16
	v_and_b32_e32 v19, 15, v16
	v_and_b32_e32 v142, 24, v20
	v_lshl_or_b32 v1, s8, 6, v19
	v_lshlrev_b32_e32 v20, 1, v142
	v_lshlrev_b32_e32 v19, 6, v19
	v_lshlrev_b32_e32 v16, 2, v16
	v_or_b32_e32 v21, v19, v20
	s_lshl_b32 s8, s8, 13
	v_and_b32_e32 v16, 32, v16
	v_bitop3_b32 v19, v19, v16, v20 bitop3:0x36
	v_bitop3_b32 v16, v21, s8, v16 bitop3:0xde
	s_lshl_b32 s8, s15, 12
	s_and_b32 s8, s8, 0x3000
	v_or_b32_e32 v143, s8, v19
	s_lshl_b64 s[8:9], s[40:41], 16
	s_and_b32 s10, s9, 0xffff
	s_and_b32 s11, s8, 0xfffc0000
	s_add_u32 s39, s74, s11
	s_addc_u32 s57, s75, s10
	s_and_b32 s8, s52, 3
	s_lshl_b32 s8, s8, 18
	s_add_u32 s58, s48, s8
	s_addc_u32 s59, s49, 0
	s_add_i32 m0, s24, 0x18000
	v_lshl_add_u64 v[10:11], v[10:11], 0, s[96:97]
	s_waitcnt vmcnt(2)
	s_barrier
	global_load_lds_dwordx4 v[10:11], off
	v_lshl_add_u64 v[8:9], v[8:9], 0, s[96:97]
	s_add_i32 m0, s24, 0x1a000
	s_add_i32 s60, s24, 0x8000
	s_add_i32 s61, s24, 0xa000
	global_load_lds_dwordx4 v[8:9], off
	v_lshl_add_u64 v[6:7], v[6:7], 0, s[96:97]
	s_mov_b32 m0, s60
	s_add_u32 s8, s0, 0x20080
	global_load_lds_dwordx4 v[6:7], off
	v_lshl_add_u64 v[4:5], v[4:5], 0, s[96:97]
	s_mov_b32 m0, s61
	s_addc_u32 s9, s1, 0
	global_load_lds_dwordx4 v[4:5], off
	s_add_i32 m0, s24, 0x1c000
	v_lshl_add_u64 v[4:5], s[8:9], 0, v[2:3]
	global_load_lds_dwordx4 v[4:5], off
	v_lshl_add_u64 v[4:5], s[8:9], 0, v[132:133]
	s_add_i32 m0, s24, 0x1e000
	v_readlane_b32 s8, v254, 49
	global_load_lds_dwordx4 v[4:5], off
	v_lshlrev_b32_e32 v4, 13, v17
	v_and_b32_e32 v4, 0xffffc000, v4
	v_lshl_add_u32 v4, v15, 10, v4
	v_and_b32_e32 v5, 1, v17
	v_lshl_or_b32 v4, v5, 6, v4
	s_add_u32 s8, s8, s11
	v_readlane_b32 s9, v254, 50
	v_lshl_add_u32 v4, v18, 1, v4
	v_mov_b32_e32 v5, v3
	s_addc_u32 s9, s9, s10
	v_lshl_add_u64 v[138:139], s[8:9], 0, v[4:5]
	v_lshlrev_b32_e32 v4, 13, v12
	v_and_b32_e32 v4, 0xffffc000, v4
	v_lshl_add_u32 v4, v13, 10, v4
	v_and_b32_e32 v5, 1, v12
	v_lshl_or_b32 v4, v5, 6, v4
	s_waitcnt vmcnt(6)
	v_lshl_add_u32 v4, v14, 1, v4
	v_mov_b32_e32 v5, v3
	v_lshl_add_u64 v[140:141], s[8:9], 0, v[4:5]
	v_mov_b32_e32 v4, 0
	s_mov_b32 s62, -2
	s_mov_b64 s[8:9], 0
	v_add_u32_e32 v144, 0, v16
	s_waitcnt vmcnt(0)
	s_barrier
	s_add_u32 s10, s39, s8
	s_addc_u32 s11, s57, s9
	s_add_u32 s10, s10, 0x3e900100
	s_addc_u32 s11, s11, 0
	s_add_u32 s63, s58, s8
	s_addc_u32 s64, s59, s9
	s_add_i32 s65, 0, 0x10000
	s_cmpk_eq_i32 s8, 0x300
	s_cselect_b32 s13, s7, s11
	s_cselect_b32 s12, s6, s10
	v_add_u32_e32 v145, s65, v143
	s_cselect_b32 s11, s1, s64
	s_cselect_b32 s10, s0, s63
	s_add_i32 s63, 0, 0x14000
	ds_read_b128 v[146:149], v145
	ds_read_b128 v[150:153], v145 offset:1024
	ds_read_b128 v[154:157], v145 offset:2048
	ds_read_b128 v[158:161], v145 offset:3072
	v_add_u32_e32 v145, s63, v143
	ds_read_b128 v[162:165], v145
	ds_read_b128 v[166:169], v145 offset:1024
	ds_read_b128 v[170:173], v145 offset:2048
	ds_read_b128 v[174:177], v145 offset:3072
	v_lshl_add_u64 v[194:195], v[138:139], 0, s[8:9]
	s_add_i32 m0, s24, 0xc000
	ds_read_b128 v[178:181], v144
	ds_read_b128 v[182:185], v144 offset:1024
	ds_read_b128 v[186:189], v144 offset:2048
	ds_read_b128 v[190:193], v144 offset:3072
	ds_read_b128 v[204:207], v144 offset:4096
	ds_read_b128 v[220:223], v144 offset:5120
	ds_read_b128 v[224:227], v144 offset:6144
	ds_read_b128 v[228:231], v144 offset:7168
	global_load_lds_dwordx4 v[194:195], off
	v_lshl_add_u64 v[194:195], v[140:141], 0, s[8:9]
	s_add_i32 m0, s24, 0xe000
	s_nop 0
	global_load_lds_dwordx4 v[194:195], off
	s_waitcnt vmcnt(8)
	s_waitcnt lgkmcnt(0)
	s_setprio 1
	s_barrier
	v_mfma_f32_16x16x32_f16 v[128:131], v[146:149], v[178:181], 0
	v_mfma_f32_16x16x32_f16 v[124:127], v[154:157], v[178:181], 0
	v_mfma_f32_16x16x32_f16 v[112:115], v[146:149], v[186:189], 0
	v_mfma_f32_16x16x32_f16 v[108:111], v[154:157], v[186:189], 0
	v_mfma_f32_16x16x32_f16 v[96:99], v[146:149], v[204:207], 0
	v_mfma_f32_16x16x32_f16 v[92:95], v[154:157], v[204:207], 0
	v_mfma_f32_16x16x32_f16 v[80:83], v[146:149], v[224:227], 0
	v_mfma_f32_16x16x32_f16 v[76:79], v[154:157], v[224:227], 0
	v_mfma_f32_16x16x32_f16 v[128:131], v[150:153], v[182:185], v[128:131]
	v_mfma_f32_16x16x32_f16 v[124:127], v[158:161], v[182:185], v[124:127]
	v_mfma_f32_16x16x32_f16 v[112:115], v[150:153], v[190:193], v[112:115]
	v_mfma_f32_16x16x32_f16 v[108:111], v[158:161], v[190:193], v[108:111]
	v_mfma_f32_16x16x32_f16 v[96:99], v[150:153], v[220:223], v[96:99]
	v_mfma_f32_16x16x32_f16 v[92:95], v[158:161], v[220:223], v[92:95]
	v_mfma_f32_16x16x32_f16 v[80:83], v[150:153], v[228:231], v[80:83]
	v_mfma_f32_16x16x32_f16 v[76:79], v[158:161], v[228:231], v[76:79]
	v_mfma_f32_16x16x32_f16 v[120:123], v[162:165], v[178:181], 0
	v_mfma_f32_16x16x32_f16 v[116:119], v[170:173], v[178:181], 0
	v_mfma_f32_16x16x32_f16 v[104:107], v[162:165], v[186:189], 0
	v_mfma_f32_16x16x32_f16 v[100:103], v[170:173], v[186:189], 0
	v_mfma_f32_16x16x32_f16 v[88:91], v[162:165], v[204:207], 0
	v_mfma_f32_16x16x32_f16 v[84:87], v[170:173], v[204:207], 0
	v_mfma_f32_16x16x32_f16 v[72:75], v[162:165], v[224:227], 0
	v_mfma_f32_16x16x32_f16 v[68:71], v[170:173], v[224:227], 0
	v_mfma_f32_16x16x32_f16 v[120:123], v[166:169], v[182:185], v[120:123]
	v_mfma_f32_16x16x32_f16 v[116:119], v[174:177], v[182:185], v[116:119]
	v_mfma_f32_16x16x32_f16 v[104:107], v[166:169], v[190:193], v[104:107]
	v_mfma_f32_16x16x32_f16 v[100:103], v[174:177], v[190:193], v[100:103]
	v_mfma_f32_16x16x32_f16 v[88:91], v[166:169], v[220:223], v[88:91]
	v_mfma_f32_16x16x32_f16 v[84:87], v[174:177], v[220:223], v[84:87]
	v_mfma_f32_16x16x32_f16 v[72:75], v[166:169], v[228:231], v[72:75]
	v_mfma_f32_16x16x32_f16 v[68:71], v[174:177], v[228:231], v[68:71]
	s_setprio 0
	s_barrier
; #define PG8_STAGE(bufoff, gbase, voff) do { _Pragma("unroll") for (int _i = 0; _i < 2; ++_i) \
;         __builtin_amdgcn_global_load_lds((const unsigned*)((const char*)(gbase) + (voff)[_i]), (LAS unsigned*)(lds + (bufoff) + ldsw + _i * 8192), 16, 0, 0); } while (0)
; #define PG8_LDA(dst, b, h) do { _Pragma("unroll") for (int m = 0; m < 4; ++m) _Pragma("unroll") for (int k = 0; k < 2; ++k) dst[m][k] = *(const LAS half8*)(lds + PG8_SA(b, h) + aoff + m * 2048 + k * 1024); } while (0)
; #define PG8_LDB(dst, b, h) do { _Pragma("unroll") for (int n = 0; n < 2; ++n) _Pragma("unroll") for (int k = 0; k < 2; ++k) dst[n][k] = *(const LAS half8*)(lds + PG8_SB(b, h) + boff + n * 2048 + k * 1024); } while (0)
; #define PG8_MMA(ai, bj, At, Bt) do { __builtin_amdgcn_s_setprio(1); _Pragma("unroll") for (int m = 0; m < 4; ++m) _Pragma("unroll") for (int n = 0; n < 2; ++n) _Pragma("unroll") for (int k = 0; k < 2; ++k) \
;         acc[ai][bj][m][n] = __builtin_amdgcn_mfma_f32_16x16x32_f16(Bt[n][k], At[m][k], acc[ai][bj][m][n], 0, 0, 0); __builtin_amdgcn_s_setprio(0); } while (0)
; #define PG8_WAIT_V(n) asm volatile("s_waitcnt vmcnt(" #n ")" ::: "memory")
; #define PG8_WAIT_L(n) asm volatile("s_waitcnt lgkmcnt(" #n ")" ::: "memory")
; #define PG8_BAR __builtin_amdgcn_s_barrier()
; #define PG8_SCHED __builtin_amdgcn_sched_barrier(0)
; template <class Epi, class Sched, bool ALIGN_EPI = false, bool SP2 = false>
; __device__ __forceinline__ void gemm_phase(LAS unsigned char* lds, const Gemm g, const Sched& S, const Epi& E) {
;     ...
;             if constexpr (SP2) {
;             PG8_LDB(B0, 0, 0); PG8_LDB(B1, 0, 1); PG8_SCHED; PG8_LDA(At, 0, 0); PG8_STAGE(PG8_SA(1, 1), a1 + hstepA, voffA);
;             PG8_WAIT_V(8); PG8_WAIT_L(0); PG8_BAR; PG8_MMA(0, 0, At, B0); PG8_MMA(0, 1, At, B1); PG8_BAR; PG8_SCHED;
;             PG8_LDA(At, 0, 1); PG8_STAGE(PG8_SB(0, 0), b2, voffB); PG8_STAGE(PG8_SB(0, 1), b2 + hstepB, voffB); PG8_STAGE(PG8_SA(0, 0), a2, voffA);
;             PG8_WAIT_V(8); PG8_WAIT_L(0); PG8_BAR; PG8_MMA(1, 0, At, B0); PG8_MMA(1, 1, At, B1); PG8_BAR; PG8_SCHED;
;             PG8_LDB(B0, 1, 0); PG8_LDB(B1, 1, 1); PG8_SCHED; PG8_LDA(At, 1, 0); PG8_STAGE(PG8_SA(0, 1), a2 + hstepA, voffA);
;             PG8_WAIT_V(8); PG8_WAIT_L(0); PG8_BAR; PG8_MMA(0, 0, At, B0); PG8_MMA(0, 1, At, B1); PG8_BAR; PG8_SCHED;
	s_add_i32 s64, s65, s17
	v_lshl_add_u64 v[194:195], s[10:11], 0, v[2:3]
	s_mov_b32 m0, s64
	ds_read_b128 v[178:181], v144 offset:16384
	ds_read_b128 v[182:185], v144 offset:17408
	ds_read_b128 v[186:189], v144 offset:18432
	ds_read_b128 v[190:193], v144 offset:19456
	ds_read_b128 v[204:207], v144 offset:20480
	ds_read_b128 v[220:223], v144 offset:21504
	ds_read_b128 v[224:227], v144 offset:22528
	ds_read_b128 v[228:231], v144 offset:23552
	global_load_lds_dwordx4 v[194:195], off
	s_add_i32 m0, s64, 0x2000
	s_add_u32 s64, s10, 0x20000
	v_lshl_add_u64 v[196:197], s[10:11], 0, v[132:133]
	s_addc_u32 s65, s11, 0
	s_add_i32 s63, s63, s17
	global_load_lds_dwordx4 v[196:197], off
	v_lshl_add_u64 v[208:209], s[64:65], 0, v[2:3]
	s_mov_b32 m0, s63
	v_lshl_add_u64 v[232:233], s[12:13], 0, v[134:135]
	global_load_lds_dwordx4 v[208:209], off
	v_lshl_add_u64 v[208:209], s[64:65], 0, v[132:133]
	s_add_i32 m0, s63, 0x2000
	s_nop 0
	global_load_lds_dwordx4 v[208:209], off
	v_lshl_add_u64 v[208:209], s[12:13], 0, v[136:137]
	s_mov_b32 m0, s24
	s_nop 0
	global_load_lds_dwordx4 v[208:209], off
	s_mov_b32 m0, s25
	s_nop 0
	global_load_lds_dwordx4 v[232:233], off
	s_waitcnt vmcnt(8)
	s_waitcnt lgkmcnt(0)
	s_setprio 1
	s_barrier
	v_mfma_f32_16x16x32_f16 v[64:67], v[146:149], v[178:181], 0
	v_mfma_f32_16x16x32_f16 v[60:63], v[154:157], v[178:181], 0
	v_mfma_f32_16x16x32_f16 v[48:51], v[146:149], v[186:189], 0
	v_mfma_f32_16x16x32_f16 v[44:47], v[154:157], v[186:189], 0
	v_mfma_f32_16x16x32_f16 v[32:35], v[146:149], v[204:207], 0
	v_mfma_f32_16x16x32_f16 v[28:31], v[154:157], v[204:207], 0
	v_mfma_f32_16x16x32_f16 v[16:19], v[146:149], v[224:227], 0
	v_mfma_f32_16x16x32_f16 v[12:15], v[154:157], v[224:227], 0
	v_mfma_f32_16x16x32_f16 v[64:67], v[150:153], v[182:185], v[64:67]
	v_mfma_f32_16x16x32_f16 v[60:63], v[158:161], v[182:185], v[60:63]
	v_mfma_f32_16x16x32_f16 v[48:51], v[150:153], v[190:193], v[48:51]
	v_mfma_f32_16x16x32_f16 v[44:47], v[158:161], v[190:193], v[44:47]
	v_mfma_f32_16x16x32_f16 v[32:35], v[150:153], v[220:223], v[32:35]
	v_mfma_f32_16x16x32_f16 v[28:31], v[158:161], v[220:223], v[28:31]
	v_mfma_f32_16x16x32_f16 v[16:19], v[150:153], v[228:231], v[16:19]
	v_mfma_f32_16x16x32_f16 v[12:15], v[158:161], v[228:231], v[12:15]
	v_mfma_f32_16x16x32_f16 v[56:59], v[162:165], v[178:181], 0
	v_mfma_f32_16x16x32_f16 v[52:55], v[170:173], v[178:181], 0
	v_mfma_f32_16x16x32_f16 v[40:43], v[162:165], v[186:189], 0
	v_mfma_f32_16x16x32_f16 v[36:39], v[170:173], v[186:189], 0
	v_mfma_f32_16x16x32_f16 v[24:27], v[162:165], v[204:207], 0
	v_mfma_f32_16x16x32_f16 v[20:23], v[170:173], v[204:207], 0
	v_mfma_f32_16x16x32_f16 v[8:11], v[162:165], v[224:227], 0
	v_mfma_f32_16x16x32_f16 v[4:7], v[170:173], v[224:227], 0
	v_mfma_f32_16x16x32_f16 v[56:59], v[166:169], v[182:185], v[56:59]
	v_mfma_f32_16x16x32_f16 v[52:55], v[174:177], v[182:185], v[52:55]
	v_mfma_f32_16x16x32_f16 v[40:43], v[166:169], v[190:193], v[40:43]
	v_mfma_f32_16x16x32_f16 v[36:39], v[174:177], v[190:193], v[36:39]
	v_mfma_f32_16x16x32_f16 v[24:27], v[166:169], v[220:223], v[24:27]
	v_mfma_f32_16x16x32_f16 v[20:23], v[174:177], v[220:223], v[20:23]
	v_mfma_f32_16x16x32_f16 v[8:11], v[166:169], v[228:231], v[8:11]
	v_mfma_f32_16x16x32_f16 v[4:7], v[174:177], v[228:231], v[4:7]
	s_setprio 0
	s_barrier
	s_add_i32 s63, 0, 0x18000
	v_add_u32_e32 v145, s63, v143
	s_add_i32 s64, 0, 0x1c000
	ds_read_b128 v[146:149], v145
	ds_read_b128 v[150:153], v145 offset:1024
	ds_read_b128 v[154:157], v145 offset:2048
	ds_read_b128 v[158:161], v145 offset:3072
	v_add_u32_e32 v145, s64, v143
	ds_read_b128 v[162:165], v145
	ds_read_b128 v[166:169], v145 offset:1024
	ds_read_b128 v[170:173], v145 offset:2048
	ds_read_b128 v[174:177], v145 offset:3072
	s_add_u32 s12, s12, 0x20000
	s_addc_u32 s13, s13, 0
	s_mov_b32 m0, s37
	v_lshl_add_u64 v[234:235], s[12:13], 0, v[136:137]
	ds_read_b128 v[178:181], v144 offset:32768
	ds_read_b128 v[182:185], v144 offset:33792
	ds_read_b128 v[186:189], v144 offset:34816
	ds_read_b128 v[190:193], v144 offset:35840
	ds_read_b128 v[204:207], v144 offset:36864
	ds_read_b128 v[220:223], v144 offset:37888
	ds_read_b128 v[224:227], v144 offset:38912
	ds_read_b128 v[228:231], v144 offset:39936
	global_load_lds_dwordx4 v[234:235], off
	v_lshl_add_u64 v[234:235], s[12:13], 0, v[134:135]
	s_mov_b32 m0, s38
	s_nop 0
	global_load_lds_dwordx4 v[234:235], off
	s_waitcnt vmcnt(8)
	s_waitcnt lgkmcnt(0)
	s_setprio 1
	s_barrier
	v_mfma_f32_16x16x32_f16 v[128:131], v[146:149], v[178:181], v[128:131]
	v_mfma_f32_16x16x32_f16 v[124:127], v[154:157], v[178:181], v[124:127]
	v_mfma_f32_16x16x32_f16 v[112:115], v[146:149], v[186:189], v[112:115]
	v_mfma_f32_16x16x32_f16 v[108:111], v[154:157], v[186:189], v[108:111]
	v_mfma_f32_16x16x32_f16 v[96:99], v[146:149], v[204:207], v[96:99]
	v_mfma_f32_16x16x32_f16 v[92:95], v[154:157], v[204:207], v[92:95]
	v_mfma_f32_16x16x32_f16 v[80:83], v[146:149], v[224:227], v[80:83]
	v_mfma_f32_16x16x32_f16 v[76:79], v[154:157], v[224:227], v[76:79]
	v_mfma_f32_16x16x32_f16 v[128:131], v[150:153], v[182:185], v[128:131]
	v_mfma_f32_16x16x32_f16 v[124:127], v[158:161], v[182:185], v[124:127]
	v_mfma_f32_16x16x32_f16 v[112:115], v[150:153], v[190:193], v[112:115]
	v_mfma_f32_16x16x32_f16 v[108:111], v[158:161], v[190:193], v[108:111]
	v_mfma_f32_16x16x32_f16 v[96:99], v[150:153], v[220:223], v[96:99]
	v_mfma_f32_16x16x32_f16 v[92:95], v[158:161], v[220:223], v[92:95]
	v_mfma_f32_16x16x32_f16 v[80:83], v[150:153], v[228:231], v[80:83]
	v_mfma_f32_16x16x32_f16 v[76:79], v[158:161], v[228:231], v[76:79]
	v_mfma_f32_16x16x32_f16 v[120:123], v[162:165], v[178:181], v[120:123]
	v_mfma_f32_16x16x32_f16 v[116:119], v[170:173], v[178:181], v[116:119]
	v_mfma_f32_16x16x32_f16 v[104:107], v[162:165], v[186:189], v[104:107]
	v_mfma_f32_16x16x32_f16 v[100:103], v[170:173], v[186:189], v[100:103]
	v_mfma_f32_16x16x32_f16 v[88:91], v[162:165], v[204:207], v[88:91]
	v_mfma_f32_16x16x32_f16 v[84:87], v[170:173], v[204:207], v[84:87]
	v_mfma_f32_16x16x32_f16 v[72:75], v[162:165], v[224:227], v[72:75]
	v_mfma_f32_16x16x32_f16 v[68:71], v[170:173], v[224:227], v[68:71]
	v_mfma_f32_16x16x32_f16 v[120:123], v[166:169], v[182:185], v[120:123]
	v_mfma_f32_16x16x32_f16 v[116:119], v[174:177], v[182:185], v[116:119]
	v_mfma_f32_16x16x32_f16 v[104:107], v[166:169], v[190:193], v[104:107]
	v_mfma_f32_16x16x32_f16 v[100:103], v[174:177], v[190:193], v[100:103]
	v_mfma_f32_16x16x32_f16 v[88:91], v[166:169], v[220:223], v[88:91]
	v_mfma_f32_16x16x32_f16 v[84:87], v[174:177], v[220:223], v[84:87]
	v_mfma_f32_16x16x32_f16 v[72:75], v[166:169], v[228:231], v[72:75]
	v_mfma_f32_16x16x32_f16 v[68:71], v[174:177], v[228:231], v[68:71]
	s_setprio 0
	s_barrier
; #define PG8_STAGE(bufoff, gbase, voff) do { _Pragma("unroll") for (int _i = 0; _i < 2; ++_i) \
;         __builtin_amdgcn_global_load_lds((const unsigned*)((const char*)(gbase) + (voff)[_i]), (LAS unsigned*)(lds + (bufoff) + ldsw + _i * 8192), 16, 0, 0); } while (0)
; #define PG8_LDA(dst, b, h) do { _Pragma("unroll") for (int m = 0; m < 4; ++m) _Pragma("unroll") for (int k = 0; k < 2; ++k) dst[m][k] = *(const LAS half8*)(lds + PG8_SA(b, h) + aoff + m * 2048 + k * 1024); } while (0)
; #define PG8_LDB(dst, b, h) do { _Pragma("unroll") for (int n = 0; n < 2; ++n) _Pragma("unroll") for (int k = 0; k < 2; ++k) dst[n][k] = *(const LAS half8*)(lds + PG8_SB(b, h) + boff + n * 2048 + k * 1024); } while (0)
; #define PG8_MMA(ai, bj, At, Bt) do { __builtin_amdgcn_s_setprio(1); _Pragma("unroll") for (int m = 0; m < 4; ++m) _Pragma("unroll") for (int n = 0; n < 2; ++n) _Pragma("unroll") for (int k = 0; k < 2; ++k) \
;         acc[ai][bj][m][n] = __builtin_amdgcn_mfma_f32_16x16x32_f16(Bt[n][k], At[m][k], acc[ai][bj][m][n], 0, 0, 0); __builtin_amdgcn_s_setprio(0); } while (0)
; #define PG8_BAR __builtin_amdgcn_s_barrier()
; template <class Epi, class Sched, bool ALIGN_EPI = false, bool SP2 = false>
; __device__ __forceinline__ void gemm_phase(LAS unsigned char* lds, const Gemm g, const Sched& S, const Epi& E) {
;     ...
;             if constexpr (SP2) {
;             PG8_LDB(B0, 0, 0); PG8_LDB(B1, 0, 1); PG8_SCHED; PG8_LDA(At, 0, 0); PG8_STAGE(PG8_SA(1, 1), a1 + hstepA, voffA);
;             PG8_WAIT_V(8); PG8_WAIT_L(0); PG8_BAR; PG8_MMA(0, 0, At, B0); PG8_MMA(0, 1, At, B1); PG8_BAR; PG8_SCHED;
;             PG8_LDA(At, 0, 1); PG8_STAGE(PG8_SB(0, 0), b2, voffB); PG8_STAGE(PG8_SB(0, 1), b2 + hstepB, voffB); PG8_STAGE(PG8_SA(0, 0), a2, voffA);
;             PG8_WAIT_V(8); PG8_WAIT_L(0); PG8_BAR; PG8_MMA(1, 0, At, B0); PG8_MMA(1, 1, At, B1); PG8_BAR; PG8_SCHED;
;             PG8_LDB(B0, 1, 0); PG8_LDB(B1, 1, 1); PG8_SCHED; PG8_LDA(At, 1, 0); PG8_STAGE(PG8_SA(0, 1), a2 + hstepA, voffA);
;             PG8_WAIT_V(8); PG8_WAIT_L(0); PG8_BAR; PG8_MMA(0, 0, At, B0); PG8_MMA(0, 1, At, B1); PG8_BAR; PG8_SCHED;
;             PG8_LDA(At, 1, 1); PG8_STAGE(PG8_SB(1, 0), b3, voffB); PG8_STAGE(PG8_SB(1, 1), b3 + hstepB, voffB); PG8_STAGE(PG8_SA(1, 0), a3, voffA);
;             PG8_WAIT_V(8); PG8_WAIT_L(0); PG8_BAR; PG8_MMA(1, 0, At, B0); PG8_MMA(1, 1, At, B1); PG8_BAR; PG8_SCHED;
	s_add_i32 s12, s63, s17
	v_lshl_add_u64 v[194:195], v[194:195], 0, s[96:97]
	s_mov_b32 m0, s12
	ds_read_b128 v[178:181], v144 offset:49152
	ds_read_b128 v[182:185], v144 offset:50176
	ds_read_b128 v[186:189], v144 offset:51200
	ds_read_b128 v[190:193], v144 offset:52224
	ds_read_b128 v[204:207], v144 offset:53248
	ds_read_b128 v[220:223], v144 offset:54272
	ds_read_b128 v[224:227], v144 offset:55296
	ds_read_b128 v[228:231], v144 offset:56320
	global_load_lds_dwordx4 v[194:195], off
	s_add_i32 m0, s12, 0x2000
	s_add_u32 s10, s10, 0x20080
	v_lshl_add_u64 v[194:195], v[196:197], 0, s[96:97]
	s_addc_u32 s11, s11, 0
	s_add_i32 s12, s64, s17
	global_load_lds_dwordx4 v[194:195], off
	v_lshl_add_u64 v[194:195], s[10:11], 0, v[2:3]
	s_mov_b32 m0, s12
	s_nop 0
	global_load_lds_dwordx4 v[194:195], off
	v_lshl_add_u64 v[194:195], s[10:11], 0, v[132:133]
	s_add_i32 m0, s12, 0x2000
	s_nop 0
	global_load_lds_dwordx4 v[194:195], off
	v_lshl_add_u64 v[194:195], v[208:209], 0, s[96:97]
	s_mov_b32 m0, s60
	s_nop 0
	global_load_lds_dwordx4 v[194:195], off
	v_lshl_add_u64 v[194:195], v[232:233], 0, s[96:97]
	s_mov_b32 m0, s61
	s_nop 0
	global_load_lds_dwordx4 v[194:195], off
	s_waitcnt vmcnt(8)
	s_waitcnt lgkmcnt(0)
	s_setprio 1
	s_barrier
	v_mfma_f32_16x16x32_f16 v[64:67], v[146:149], v[178:181], v[64:67]
	v_mfma_f32_16x16x32_f16 v[60:63], v[154:157], v[178:181], v[60:63]
	v_mfma_f32_16x16x32_f16 v[48:51], v[146:149], v[186:189], v[48:51]
	v_mfma_f32_16x16x32_f16 v[44:47], v[154:157], v[186:189], v[44:47]
	v_mfma_f32_16x16x32_f16 v[32:35], v[146:149], v[204:207], v[32:35]
	v_mfma_f32_16x16x32_f16 v[28:31], v[154:157], v[204:207], v[28:31]
	v_mfma_f32_16x16x32_f16 v[16:19], v[146:149], v[224:227], v[16:19]
	v_mfma_f32_16x16x32_f16 v[12:15], v[154:157], v[224:227], v[12:15]
	v_mfma_f32_16x16x32_f16 v[64:67], v[150:153], v[182:185], v[64:67]
	v_mfma_f32_16x16x32_f16 v[60:63], v[158:161], v[182:185], v[60:63]
	v_mfma_f32_16x16x32_f16 v[48:51], v[150:153], v[190:193], v[48:51]
	v_mfma_f32_16x16x32_f16 v[44:47], v[158:161], v[190:193], v[44:47]
	v_mfma_f32_16x16x32_f16 v[32:35], v[150:153], v[220:223], v[32:35]
	v_mfma_f32_16x16x32_f16 v[28:31], v[158:161], v[220:223], v[28:31]
	v_mfma_f32_16x16x32_f16 v[16:19], v[150:153], v[228:231], v[16:19]
	v_mfma_f32_16x16x32_f16 v[12:15], v[158:161], v[228:231], v[12:15]
	v_mfma_f32_16x16x32_f16 v[56:59], v[162:165], v[178:181], v[56:59]
	v_mfma_f32_16x16x32_f16 v[52:55], v[170:173], v[178:181], v[52:55]
	v_mfma_f32_16x16x32_f16 v[40:43], v[162:165], v[186:189], v[40:43]
	v_mfma_f32_16x16x32_f16 v[36:39], v[170:173], v[186:189], v[36:39]
	v_mfma_f32_16x16x32_f16 v[24:27], v[162:165], v[204:207], v[24:27]
	v_mfma_f32_16x16x32_f16 v[20:23], v[170:173], v[204:207], v[20:23]
	v_mfma_f32_16x16x32_f16 v[8:11], v[162:165], v[224:227], v[8:11]
	v_mfma_f32_16x16x32_f16 v[4:7], v[170:173], v[224:227], v[4:7]
	v_mfma_f32_16x16x32_f16 v[56:59], v[166:169], v[182:185], v[56:59]
	v_mfma_f32_16x16x32_f16 v[52:55], v[174:177], v[182:185], v[52:55]
	v_mfma_f32_16x16x32_f16 v[40:43], v[166:169], v[190:193], v[40:43]
	v_mfma_f32_16x16x32_f16 v[36:39], v[174:177], v[190:193], v[36:39]
	v_mfma_f32_16x16x32_f16 v[24:27], v[166:169], v[220:223], v[24:27]
	v_mfma_f32_16x16x32_f16 v[20:23], v[174:177], v[220:223], v[20:23]
	v_mfma_f32_16x16x32_f16 v[8:11], v[166:169], v[228:231], v[8:11]
	v_mfma_f32_16x16x32_f16 v[4:7], v[174:177], v[228:231], v[4:7]
	s_setprio 0
	s_barrier
	s_add_i32 s62, s62, 2
	s_add_u32 s8, s8, 0x100
	s_addc_u32 s9, s9, 0
	s_cmp_gt_u32 s62, 5
	s_cbranch_scc0 .LBB0_2230
.LBB0_2230:
	s_add_u32 s10, s39, s8
	s_addc_u32 s11, s57, s9
	s_add_u32 s10, s10, 0x3e900100
	s_addc_u32 s11, s11, 0
	s_add_u32 s63, s58, s8
	s_addc_u32 s64, s59, s9
	s_add_i32 s65, 0, 0x10000
	s_cmpk_eq_i32 s8, 0x300
	s_cselect_b32 s13, s7, s11
	s_cselect_b32 s12, s6, s10
	v_add_u32_e32 v145, s65, v143
	s_cselect_b32 s11, s1, s64
	s_cselect_b32 s10, s0, s63
	s_add_i32 s63, 0, 0x14000
	ds_read_b128 v[146:149], v145
	ds_read_b128 v[150:153], v145 offset:1024
	ds_read_b128 v[154:157], v145 offset:2048
	ds_read_b128 v[158:161], v145 offset:3072
	v_add_u32_e32 v145, s63, v143
	ds_read_b128 v[162:165], v145
	ds_read_b128 v[166:169], v145 offset:1024
	ds_read_b128 v[170:173], v145 offset:2048
	ds_read_b128 v[174:177], v145 offset:3072
	v_lshl_add_u64 v[194:195], v[138:139], 0, s[8:9]
	s_add_i32 m0, s24, 0xc000
	ds_read_b128 v[178:181], v144
	ds_read_b128 v[182:185], v144 offset:1024
	ds_read_b128 v[186:189], v144 offset:2048
	ds_read_b128 v[190:193], v144 offset:3072
	ds_read_b128 v[204:207], v144 offset:4096
	ds_read_b128 v[220:223], v144 offset:5120
	ds_read_b128 v[224:227], v144 offset:6144
	ds_read_b128 v[228:231], v144 offset:7168
	global_load_lds_dwordx4 v[194:195], off
	v_lshl_add_u64 v[194:195], v[140:141], 0, s[8:9]
	s_add_i32 m0, s24, 0xe000
	s_nop 0
	global_load_lds_dwordx4 v[194:195], off
	s_waitcnt vmcnt(8)
	s_waitcnt lgkmcnt(0)
	s_setprio 1
	s_barrier
; #define PG8_STAGE(bufoff, gbase, voff) do { _Pragma("unroll") for (int _i = 0; _i < 2; ++_i) \
;         __builtin_amdgcn_global_load_lds((const unsigned*)((const char*)(gbase) + (voff)[_i]), (LAS unsigned*)(lds + (bufoff) + ldsw + _i * 8192), 16, 0, 0); } while (0)
; #define PG8_LDA(dst, b, h) do { _Pragma("unroll") for (int m = 0; m < 4; ++m) _Pragma("unroll") for (int k = 0; k < 2; ++k) dst[m][k] = *(const LAS half8*)(lds + PG8_SA(b, h) + aoff + m * 2048 + k * 1024); } while (0)
; #define PG8_LDB(dst, b, h) do { _Pragma("unroll") for (int n = 0; n < 2; ++n) _Pragma("unroll") for (int k = 0; k < 2; ++k) dst[n][k] = *(const LAS half8*)(lds + PG8_SB(b, h) + boff + n * 2048 + k * 1024); } while (0)
; #define PG8_MMA(ai, bj, At, Bt) do { __builtin_amdgcn_s_setprio(1); _Pragma("unroll") for (int m = 0; m < 4; ++m) _Pragma("unroll") for (int n = 0; n < 2; ++n) _Pragma("unroll") for (int k = 0; k < 2; ++k) \
;         acc[ai][bj][m][n] = __builtin_amdgcn_mfma_f32_16x16x32_f16(Bt[n][k], At[m][k], acc[ai][bj][m][n], 0, 0, 0); __builtin_amdgcn_s_setprio(0); } while (0)
; #define PG8_BAR __builtin_amdgcn_s_barrier()
; template <class Epi, class Sched, bool ALIGN_EPI = false, bool SP2 = false>
; __device__ __forceinline__ void gemm_phase(LAS unsigned char* lds, const Gemm g, const Sched& S, const Epi& E) {
;     ...
;             if constexpr (SP2) {
;             PG8_LDB(B0, 0, 0); PG8_LDB(B1, 0, 1); PG8_SCHED; PG8_LDA(At, 0, 0); PG8_STAGE(PG8_SA(1, 1), a1 + hstepA, voffA);
;             PG8_WAIT_V(8); PG8_WAIT_L(0); PG8_BAR; PG8_MMA(0, 0, At, B0); PG8_MMA(0, 1, At, B1); PG8_BAR; PG8_SCHED;
;             PG8_LDA(At, 0, 1); PG8_STAGE(PG8_SB(0, 0), b2, voffB); PG8_STAGE(PG8_SB(0, 1), b2 + hstepB, voffB); PG8_STAGE(PG8_SA(0, 0), a2, voffA);
;             PG8_WAIT_V(8); PG8_WAIT_L(0); PG8_BAR; PG8_MMA(1, 0, At, B0); PG8_MMA(1, 1, At, B1); PG8_BAR; PG8_SCHED;
;             PG8_LDB(B0, 1, 0); PG8_LDB(B1, 1, 1); PG8_SCHED; PG8_LDA(At, 1, 0); PG8_STAGE(PG8_SA(0, 1), a2 + hstepA, voffA);
;             PG8_WAIT_V(8); PG8_WAIT_L(0); PG8_BAR; PG8_MMA(0, 0, At, B0); PG8_MMA(0, 1, At, B1); PG8_BAR; PG8_SCHED;
;             PG8_LDA(At, 1, 1); PG8_STAGE(PG8_SB(1, 0), b3, voffB); PG8_STAGE(PG8_SB(1, 1), b3 + hstepB, voffB); PG8_STAGE(PG8_SA(1, 0), a3, voffA);
;             PG8_WAIT_V(8); PG8_WAIT_L(0); PG8_BAR; PG8_MMA(1, 0, At, B0); PG8_MMA(1, 1, At, B1); PG8_BAR; PG8_SCHED;
	v_mfma_f32_16x16x32_f16 v[128:131], v[146:149], v[178:181], v[128:131]
	v_mfma_f32_16x16x32_f16 v[124:127], v[154:157], v[178:181], v[124:127]
	v_mfma_f32_16x16x32_f16 v[112:115], v[146:149], v[186:189], v[112:115]
	v_mfma_f32_16x16x32_f16 v[108:111], v[154:157], v[186:189], v[108:111]
	v_mfma_f32_16x16x32_f16 v[96:99], v[146:149], v[204:207], v[96:99]
	v_mfma_f32_16x16x32_f16 v[92:95], v[154:157], v[204:207], v[92:95]
	v_mfma_f32_16x16x32_f16 v[80:83], v[146:149], v[224:227], v[80:83]
	v_mfma_f32_16x16x32_f16 v[76:79], v[154:157], v[224:227], v[76:79]
	v_mfma_f32_16x16x32_f16 v[128:131], v[150:153], v[182:185], v[128:131]
	v_mfma_f32_16x16x32_f16 v[124:127], v[158:161], v[182:185], v[124:127]
	v_mfma_f32_16x16x32_f16 v[112:115], v[150:153], v[190:193], v[112:115]
	v_mfma_f32_16x16x32_f16 v[108:111], v[158:161], v[190:193], v[108:111]
	v_mfma_f32_16x16x32_f16 v[96:99], v[150:153], v[220:223], v[96:99]
	v_mfma_f32_16x16x32_f16 v[92:95], v[158:161], v[220:223], v[92:95]
	v_mfma_f32_16x16x32_f16 v[80:83], v[150:153], v[228:231], v[80:83]
	v_mfma_f32_16x16x32_f16 v[76:79], v[158:161], v[228:231], v[76:79]
	v_mfma_f32_16x16x32_f16 v[120:123], v[162:165], v[178:181], v[120:123]
	v_mfma_f32_16x16x32_f16 v[116:119], v[170:173], v[178:181], v[116:119]
	v_mfma_f32_16x16x32_f16 v[104:107], v[162:165], v[186:189], v[104:107]
	v_mfma_f32_16x16x32_f16 v[100:103], v[170:173], v[186:189], v[100:103]
	v_mfma_f32_16x16x32_f16 v[88:91], v[162:165], v[204:207], v[88:91]
	v_mfma_f32_16x16x32_f16 v[84:87], v[170:173], v[204:207], v[84:87]
	v_mfma_f32_16x16x32_f16 v[72:75], v[162:165], v[224:227], v[72:75]
	v_mfma_f32_16x16x32_f16 v[68:71], v[170:173], v[224:227], v[68:71]
	v_mfma_f32_16x16x32_f16 v[120:123], v[166:169], v[182:185], v[120:123]
	v_mfma_f32_16x16x32_f16 v[116:119], v[174:177], v[182:185], v[116:119]
	v_mfma_f32_16x16x32_f16 v[104:107], v[166:169], v[190:193], v[104:107]
	v_mfma_f32_16x16x32_f16 v[100:103], v[174:177], v[190:193], v[100:103]
	v_mfma_f32_16x16x32_f16 v[88:91], v[166:169], v[220:223], v[88:91]
	v_mfma_f32_16x16x32_f16 v[84:87], v[174:177], v[220:223], v[84:87]
	v_mfma_f32_16x16x32_f16 v[72:75], v[166:169], v[228:231], v[72:75]
	v_mfma_f32_16x16x32_f16 v[68:71], v[174:177], v[228:231], v[68:71]
	s_setprio 0
	s_barrier
	s_add_i32 s64, s65, s17
	v_lshl_add_u64 v[194:195], s[10:11], 0, v[2:3]
	s_mov_b32 m0, s64
	ds_read_b128 v[178:181], v144 offset:16384
	ds_read_b128 v[182:185], v144 offset:17408
	ds_read_b128 v[186:189], v144 offset:18432
	ds_read_b128 v[190:193], v144 offset:19456
	ds_read_b128 v[204:207], v144 offset:20480
	ds_read_b128 v[220:223], v144 offset:21504
	ds_read_b128 v[224:227], v144 offset:22528
	ds_read_b128 v[228:231], v144 offset:23552
	global_load_lds_dwordx4 v[194:195], off
	s_add_i32 m0, s64, 0x2000
	s_add_u32 s64, s10, 0x20000
	v_lshl_add_u64 v[196:197], s[10:11], 0, v[132:133]
	s_addc_u32 s65, s11, 0
	s_add_i32 s63, s63, s17
	global_load_lds_dwordx4 v[196:197], off
	v_lshl_add_u64 v[208:209], s[64:65], 0, v[2:3]
	s_mov_b32 m0, s63
	v_lshl_add_u64 v[232:233], s[12:13], 0, v[134:135]
	global_load_lds_dwordx4 v[208:209], off
	v_lshl_add_u64 v[208:209], s[64:65], 0, v[132:133]
	s_add_i32 m0, s63, 0x2000
	s_nop 0
	global_load_lds_dwordx4 v[208:209], off
	v_lshl_add_u64 v[208:209], s[12:13], 0, v[136:137]
	s_mov_b32 m0, s24
	s_nop 0
	global_load_lds_dwordx4 v[208:209], off
	s_mov_b32 m0, s25
	s_nop 0
	global_load_lds_dwordx4 v[232:233], off
	s_waitcnt vmcnt(8)
	s_waitcnt lgkmcnt(0)
	s_setprio 1
	s_barrier
	v_mfma_f32_16x16x32_f16 v[64:67], v[146:149], v[178:181], v[64:67]
	v_mfma_f32_16x16x32_f16 v[60:63], v[154:157], v[178:181], v[60:63]
	v_mfma_f32_16x16x32_f16 v[48:51], v[146:149], v[186:189], v[48:51]
	v_mfma_f32_16x16x32_f16 v[44:47], v[154:157], v[186:189], v[44:47]
	v_mfma_f32_16x16x32_f16 v[32:35], v[146:149], v[204:207], v[32:35]
	v_mfma_f32_16x16x32_f16 v[28:31], v[154:157], v[204:207], v[28:31]
	v_mfma_f32_16x16x32_f16 v[16:19], v[146:149], v[224:227], v[16:19]
	v_mfma_f32_16x16x32_f16 v[12:15], v[154:157], v[224:227], v[12:15]
	v_mfma_f32_16x16x32_f16 v[64:67], v[150:153], v[182:185], v[64:67]
	v_mfma_f32_16x16x32_f16 v[60:63], v[158:161], v[182:185], v[60:63]
	v_mfma_f32_16x16x32_f16 v[48:51], v[150:153], v[190:193], v[48:51]
	v_mfma_f32_16x16x32_f16 v[44:47], v[158:161], v[190:193], v[44:47]
	v_mfma_f32_16x16x32_f16 v[32:35], v[150:153], v[220:223], v[32:35]
	v_mfma_f32_16x16x32_f16 v[28:31], v[158:161], v[220:223], v[28:31]
	v_mfma_f32_16x16x32_f16 v[16:19], v[150:153], v[228:231], v[16:19]
	v_mfma_f32_16x16x32_f16 v[12:15], v[158:161], v[228:231], v[12:15]
	v_mfma_f32_16x16x32_f16 v[56:59], v[162:165], v[178:181], v[56:59]
	v_mfma_f32_16x16x32_f16 v[52:55], v[170:173], v[178:181], v[52:55]
	v_mfma_f32_16x16x32_f16 v[40:43], v[162:165], v[186:189], v[40:43]
	v_mfma_f32_16x16x32_f16 v[36:39], v[170:173], v[186:189], v[36:39]
	v_mfma_f32_16x16x32_f16 v[24:27], v[162:165], v[204:207], v[24:27]
	v_mfma_f32_16x16x32_f16 v[20:23], v[170:173], v[204:207], v[20:23]
	v_mfma_f32_16x16x32_f16 v[8:11], v[162:165], v[224:227], v[8:11]
	v_mfma_f32_16x16x32_f16 v[4:7], v[170:173], v[224:227], v[4:7]
	v_mfma_f32_16x16x32_f16 v[56:59], v[166:169], v[182:185], v[56:59]
	v_mfma_f32_16x16x32_f16 v[52:55], v[174:177], v[182:185], v[52:55]
	v_mfma_f32_16x16x32_f16 v[40:43], v[166:169], v[190:193], v[40:43]
	v_mfma_f32_16x16x32_f16 v[36:39], v[174:177], v[190:193], v[36:39]
	v_mfma_f32_16x16x32_f16 v[24:27], v[166:169], v[220:223], v[24:27]
	v_mfma_f32_16x16x32_f16 v[20:23], v[174:177], v[220:223], v[20:23]
	v_mfma_f32_16x16x32_f16 v[8:11], v[166:169], v[228:231], v[8:11]
	v_mfma_f32_16x16x32_f16 v[4:7], v[174:177], v[228:231], v[4:7]
	s_setprio 0
	s_barrier
; #define PG8_STAGE(bufoff, gbase, voff) do { _Pragma("unroll") for (int _i = 0; _i < 2; ++_i) \
;         __builtin_amdgcn_global_load_lds((const unsigned*)((const char*)(gbase) + (voff)[_i]), (LAS unsigned*)(lds + (bufoff) + ldsw + _i * 8192), 16, 0, 0); } while (0)
; #define PG8_LDA(dst, b, h) do { _Pragma("unroll") for (int m = 0; m < 4; ++m) _Pragma("unroll") for (int k = 0; k < 2; ++k) dst[m][k] = *(const LAS half8*)(lds + PG8_SA(b, h) + aoff + m * 2048 + k * 1024); } while (0)
; #define PG8_LDB(dst, b, h) do { _Pragma("unroll") for (int n = 0; n < 2; ++n) _Pragma("unroll") for (int k = 0; k < 2; ++k) dst[n][k] = *(const LAS half8*)(lds + PG8_SB(b, h) + boff + n * 2048 + k * 1024); } while (0)
; #define PG8_MMA(ai, bj, At, Bt) do { __builtin_amdgcn_s_setprio(1); _Pragma("unroll") for (int m = 0; m < 4; ++m) _Pragma("unroll") for (int n = 0; n < 2; ++n) _Pragma("unroll") for (int k = 0; k < 2; ++k) \
;         acc[ai][bj][m][n] = __builtin_amdgcn_mfma_f32_16x16x32_f16(Bt[n][k], At[m][k], acc[ai][bj][m][n], 0, 0, 0); __builtin_amdgcn_s_setprio(0); } while (0)
; template <class Epi, class Sched, bool ALIGN_EPI = false, bool SP2 = false>
; __device__ __forceinline__ void gemm_phase(LAS unsigned char* lds, const Gemm g, const Sched& S, const Epi& E) {
;     ...
;             if constexpr (SP2) {
;             PG8_LDB(B0, 0, 0); PG8_LDB(B1, 0, 1); PG8_SCHED; PG8_LDA(At, 0, 0); PG8_STAGE(PG8_SA(1, 1), a1 + hstepA, voffA);
;             PG8_WAIT_V(8); PG8_WAIT_L(0); PG8_BAR; PG8_MMA(0, 0, At, B0); PG8_MMA(0, 1, At, B1); PG8_BAR; PG8_SCHED;
;             PG8_LDA(At, 0, 1); PG8_STAGE(PG8_SB(0, 0), b2, voffB); PG8_STAGE(PG8_SB(0, 1), b2 + hstepB, voffB); PG8_STAGE(PG8_SA(0, 0), a2, voffA);
;             PG8_WAIT_V(8); PG8_WAIT_L(0); PG8_BAR; PG8_MMA(1, 0, At, B0); PG8_MMA(1, 1, At, B1); PG8_BAR; PG8_SCHED;
;             PG8_LDB(B0, 1, 0); PG8_LDB(B1, 1, 1); PG8_SCHED; PG8_LDA(At, 1, 0); PG8_STAGE(PG8_SA(0, 1), a2 + hstepA, voffA);
;             PG8_WAIT_V(8); PG8_WAIT_L(0); PG8_BAR; PG8_MMA(0, 0, At, B0); PG8_MMA(0, 1, At, B1); PG8_BAR; PG8_SCHED;
;             PG8_LDA(At, 1, 1); PG8_STAGE(PG8_SB(1, 0), b3, voffB); PG8_STAGE(PG8_SB(1, 1), b3 + hstepB, voffB); PG8_STAGE(PG8_SA(1, 0), a3, voffA);
;             PG8_WAIT_V(8); PG8_WAIT_L(0); PG8_BAR; PG8_MMA(1, 0, At, B0); PG8_MMA(1, 1, At, B1); PG8_BAR; PG8_SCHED;
;     ...
;         if constexpr (ALIGN_EPI) { if (wr == 0) PG8_BAR; }
	s_add_i32 s63, 0, 0x18000
	v_add_u32_e32 v145, s63, v143
	s_add_i32 s64, 0, 0x1c000
	ds_read_b128 v[146:149], v145
	ds_read_b128 v[150:153], v145 offset:1024
	ds_read_b128 v[154:157], v145 offset:2048
	ds_read_b128 v[158:161], v145 offset:3072
	v_add_u32_e32 v145, s64, v143
	ds_read_b128 v[162:165], v145
	ds_read_b128 v[166:169], v145 offset:1024
	ds_read_b128 v[170:173], v145 offset:2048
	ds_read_b128 v[174:177], v145 offset:3072
	s_add_u32 s12, s12, 0x20000
	s_addc_u32 s13, s13, 0
	s_mov_b32 m0, s37
	v_lshl_add_u64 v[234:235], s[12:13], 0, v[136:137]
	ds_read_b128 v[178:181], v144 offset:32768
	ds_read_b128 v[182:185], v144 offset:33792
	ds_read_b128 v[186:189], v144 offset:34816
	ds_read_b128 v[190:193], v144 offset:35840
	ds_read_b128 v[204:207], v144 offset:36864
	ds_read_b128 v[220:223], v144 offset:37888
	ds_read_b128 v[224:227], v144 offset:38912
	ds_read_b128 v[228:231], v144 offset:39936
	global_load_lds_dwordx4 v[234:235], off
	v_lshl_add_u64 v[234:235], s[12:13], 0, v[134:135]
	s_mov_b32 m0, s38
	s_nop 0
	global_load_lds_dwordx4 v[234:235], off
	s_waitcnt vmcnt(8)
	s_waitcnt lgkmcnt(0)
	s_setprio 1
	s_barrier
	v_mfma_f32_16x16x32_f16 v[128:131], v[146:149], v[178:181], v[128:131]
	v_mfma_f32_16x16x32_f16 v[124:127], v[154:157], v[178:181], v[124:127]
	v_mfma_f32_16x16x32_f16 v[112:115], v[146:149], v[186:189], v[112:115]
	v_mfma_f32_16x16x32_f16 v[108:111], v[154:157], v[186:189], v[108:111]
	v_mfma_f32_16x16x32_f16 v[96:99], v[146:149], v[204:207], v[96:99]
	v_mfma_f32_16x16x32_f16 v[92:95], v[154:157], v[204:207], v[92:95]
	v_mfma_f32_16x16x32_f16 v[80:83], v[146:149], v[224:227], v[80:83]
	v_mfma_f32_16x16x32_f16 v[76:79], v[154:157], v[224:227], v[76:79]
	v_mfma_f32_16x16x32_f16 v[128:131], v[150:153], v[182:185], v[128:131]
	v_mfma_f32_16x16x32_f16 v[124:127], v[158:161], v[182:185], v[124:127]
	v_mfma_f32_16x16x32_f16 v[112:115], v[150:153], v[190:193], v[112:115]
	v_mfma_f32_16x16x32_f16 v[108:111], v[158:161], v[190:193], v[108:111]
	v_mfma_f32_16x16x32_f16 v[96:99], v[150:153], v[220:223], v[96:99]
	v_mfma_f32_16x16x32_f16 v[92:95], v[158:161], v[220:223], v[92:95]
	v_mfma_f32_16x16x32_f16 v[80:83], v[150:153], v[228:231], v[80:83]
	v_mfma_f32_16x16x32_f16 v[76:79], v[158:161], v[228:231], v[76:79]
	v_mfma_f32_16x16x32_f16 v[120:123], v[162:165], v[178:181], v[120:123]
	v_mfma_f32_16x16x32_f16 v[116:119], v[170:173], v[178:181], v[116:119]
	v_mfma_f32_16x16x32_f16 v[104:107], v[162:165], v[186:189], v[104:107]
	v_mfma_f32_16x16x32_f16 v[100:103], v[170:173], v[186:189], v[100:103]
	v_mfma_f32_16x16x32_f16 v[88:91], v[162:165], v[204:207], v[88:91]
	v_mfma_f32_16x16x32_f16 v[84:87], v[170:173], v[204:207], v[84:87]
	v_mfma_f32_16x16x32_f16 v[72:75], v[162:165], v[224:227], v[72:75]
	v_mfma_f32_16x16x32_f16 v[68:71], v[170:173], v[224:227], v[68:71]
	v_mfma_f32_16x16x32_f16 v[120:123], v[166:169], v[182:185], v[120:123]
	v_mfma_f32_16x16x32_f16 v[116:119], v[174:177], v[182:185], v[116:119]
	v_mfma_f32_16x16x32_f16 v[104:107], v[166:169], v[190:193], v[104:107]
	v_mfma_f32_16x16x32_f16 v[100:103], v[174:177], v[190:193], v[100:103]
	v_mfma_f32_16x16x32_f16 v[88:91], v[166:169], v[220:223], v[88:91]
	v_mfma_f32_16x16x32_f16 v[84:87], v[174:177], v[220:223], v[84:87]
	v_mfma_f32_16x16x32_f16 v[72:75], v[166:169], v[228:231], v[72:75]
	v_mfma_f32_16x16x32_f16 v[68:71], v[174:177], v[228:231], v[68:71]
	s_setprio 0
	s_barrier
	s_add_i32 s12, s63, s17
	v_lshl_add_u64 v[194:195], v[194:195], 0, s[96:97]
	s_mov_b32 m0, s12
	ds_read_b128 v[178:181], v144 offset:49152
	ds_read_b128 v[182:185], v144 offset:50176
	ds_read_b128 v[186:189], v144 offset:51200
	ds_read_b128 v[190:193], v144 offset:52224
	ds_read_b128 v[204:207], v144 offset:53248
	ds_read_b128 v[220:223], v144 offset:54272
	ds_read_b128 v[224:227], v144 offset:55296
	ds_read_b128 v[228:231], v144 offset:56320
	global_load_lds_dwordx4 v[194:195], off
	s_add_i32 m0, s12, 0x2000
	s_add_u32 s10, s10, 0x20080
	v_lshl_add_u64 v[194:195], v[196:197], 0, s[96:97]
	s_addc_u32 s11, s11, 0
	s_add_i32 s12, s64, s17
	global_load_lds_dwordx4 v[194:195], off
	v_lshl_add_u64 v[194:195], s[10:11], 0, v[2:3]
	s_mov_b32 m0, s12
	s_nop 0
	global_load_lds_dwordx4 v[194:195], off
	v_lshl_add_u64 v[194:195], s[10:11], 0, v[132:133]
	s_add_i32 m0, s12, 0x2000
	s_nop 0
	global_load_lds_dwordx4 v[194:195], off
	v_lshl_add_u64 v[194:195], v[208:209], 0, s[96:97]
	s_mov_b32 m0, s60
	s_nop 0
	global_load_lds_dwordx4 v[194:195], off
	v_lshl_add_u64 v[194:195], v[232:233], 0, s[96:97]
	s_mov_b32 m0, s61
	s_nop 0
	global_load_lds_dwordx4 v[194:195], off
	s_waitcnt vmcnt(8)
	s_waitcnt lgkmcnt(0)
	s_setprio 1
	s_barrier
	v_mfma_f32_16x16x32_f16 v[64:67], v[146:149], v[178:181], v[64:67]
	v_mfma_f32_16x16x32_f16 v[60:63], v[154:157], v[178:181], v[60:63]
	v_mfma_f32_16x16x32_f16 v[48:51], v[146:149], v[186:189], v[48:51]
	v_mfma_f32_16x16x32_f16 v[44:47], v[154:157], v[186:189], v[44:47]
	v_mfma_f32_16x16x32_f16 v[32:35], v[146:149], v[204:207], v[32:35]
	v_mfma_f32_16x16x32_f16 v[28:31], v[154:157], v[204:207], v[28:31]
	v_mfma_f32_16x16x32_f16 v[16:19], v[146:149], v[224:227], v[16:19]
	v_mfma_f32_16x16x32_f16 v[12:15], v[154:157], v[224:227], v[12:15]
	v_mfma_f32_16x16x32_f16 v[64:67], v[150:153], v[182:185], v[64:67]
	v_mfma_f32_16x16x32_f16 v[60:63], v[158:161], v[182:185], v[60:63]
	v_mfma_f32_16x16x32_f16 v[48:51], v[150:153], v[190:193], v[48:51]
	v_mfma_f32_16x16x32_f16 v[44:47], v[158:161], v[190:193], v[44:47]
	v_mfma_f32_16x16x32_f16 v[32:35], v[150:153], v[220:223], v[32:35]
	v_mfma_f32_16x16x32_f16 v[28:31], v[158:161], v[220:223], v[28:31]
	v_mfma_f32_16x16x32_f16 v[16:19], v[150:153], v[228:231], v[16:19]
	v_mfma_f32_16x16x32_f16 v[12:15], v[158:161], v[228:231], v[12:15]
	v_mfma_f32_16x16x32_f16 v[56:59], v[162:165], v[178:181], v[56:59]
	v_mfma_f32_16x16x32_f16 v[52:55], v[170:173], v[178:181], v[52:55]
	v_mfma_f32_16x16x32_f16 v[40:43], v[162:165], v[186:189], v[40:43]
	v_mfma_f32_16x16x32_f16 v[36:39], v[170:173], v[186:189], v[36:39]
	v_mfma_f32_16x16x32_f16 v[24:27], v[162:165], v[204:207], v[24:27]
	v_mfma_f32_16x16x32_f16 v[20:23], v[170:173], v[204:207], v[20:23]
	v_mfma_f32_16x16x32_f16 v[8:11], v[162:165], v[224:227], v[8:11]
	v_mfma_f32_16x16x32_f16 v[4:7], v[170:173], v[224:227], v[4:7]
	v_mfma_f32_16x16x32_f16 v[56:59], v[166:169], v[182:185], v[56:59]
	v_mfma_f32_16x16x32_f16 v[52:55], v[174:177], v[182:185], v[52:55]
	v_mfma_f32_16x16x32_f16 v[40:43], v[166:169], v[190:193], v[40:43]
	v_mfma_f32_16x16x32_f16 v[36:39], v[174:177], v[190:193], v[36:39]
	v_mfma_f32_16x16x32_f16 v[24:27], v[166:169], v[220:223], v[24:27]
	v_mfma_f32_16x16x32_f16 v[20:23], v[174:177], v[220:223], v[20:23]
	v_mfma_f32_16x16x32_f16 v[8:11], v[166:169], v[228:231], v[8:11]
	v_mfma_f32_16x16x32_f16 v[4:7], v[174:177], v[228:231], v[4:7]
	s_setprio 0
	s_barrier
	s_add_i32 s62, s62, 2
	s_add_u32 s8, s8, 0x100
	s_addc_u32 s9, s9, 0
	s_cmp_gt_u32 s62, 5
	s_cbranch_scc0 .LBB0_2230
	s_cmpk_lt_u32 s16, 0x100
	s_cbranch_scc0 .LBB0_2233
	s_barrier

; #define PG8_STAGE(bufoff, gbase, voff) do { _Pragma("unroll") for (int _i = 0; _i < 2; ++_i) \
;         __builtin_amdgcn_global_load_lds((const unsigned*)((const char*)(gbase) + (voff)[_i]), (LAS unsigned*)(lds + (bufoff) + ldsw + _i * 8192), 16, 0, 0); } while (0)
; #define PG8_LDA(dst, b, h) do { _Pragma("unroll") for (int m = 0; m < 4; ++m) _Pragma("unroll") for (int k = 0; k < 2; ++k) dst[m][k] = *(const LAS half8*)(lds + PG8_SA(b, h) + aoff + m * 2048 + k * 1024); } while (0)
; #define PG8_WAIT_V(n) asm volatile("s_waitcnt vmcnt(" #n ")" ::: "memory")
; #define PG8_WAIT_L(n) asm volatile("s_waitcnt lgkmcnt(" #n ")" ::: "memory")
; #define PG8_BAR __builtin_amdgcn_s_barrier()
; template <class Epi, class Sched, bool ALIGN_EPI = false, bool SP2 = false>
; __device__ __forceinline__ void gemm_phase(LAS unsigned char* lds, const Gemm g, const Sched& S, const Epi& E) {
;     ...
;     if constexpr (SP2) {
;         PG8_STAGE(PG8_SB(0, 0), cB, voffB); PG8_STAGE(PG8_SB(0, 1), cB + hstepB, voffB); PG8_STAGE(PG8_SA(0, 0), cA, voffA); PG8_STAGE(PG8_SA(0, 1), cA + hstepA, voffA);
;         if (wr == 1) PG8_BAR;
;         PG8_WAIT_V(2); PG8_BAR;
;         PG8_STAGE(PG8_SB(1, 0), cB + kstep, voffB); PG8_STAGE(PG8_SA(1, 0), cA + kstep, voffA); PG8_STAGE(PG8_SB(1, 1), cB + hstepB + kstep, voffB);
;         PG8_WAIT_V(6); PG8_BAR;
;     ...
;             if constexpr (SP2) {
;             PG8_LDB(B0, 0, 0); PG8_LDB(B1, 0, 1); PG8_SCHED; PG8_LDA(At, 0, 0); PG8_STAGE(PG8_SA(1, 1), a1 + hstepA, voffA);
;             PG8_WAIT_V(8); PG8_WAIT_L(0); PG8_BAR; PG8_MMA(0, 0, At, B0); PG8_MMA(0, 1, At, B1); PG8_BAR; PG8_SCHED;
;             PG8_LDA(At, 0, 1); PG8_STAGE(PG8_SB(0, 0), b2, voffB); PG8_STAGE(PG8_SB(0, 1), b2 + hstepB, voffB); PG8_STAGE(PG8_SA(0, 0), a2, voffA);
;             PG8_WAIT_V(8); PG8_WAIT_L(0); PG8_BAR; PG8_MMA(1, 0, At, B0); PG8_MMA(1, 1, At, B1); PG8_BAR; PG8_SCHED;
;             PG8_LDB(B0, 1, 0); PG8_LDB(B1, 1, 1); PG8_SCHED; PG8_LDA(At, 1, 0); PG8_STAGE(PG8_SA(0, 1), a2 + hstepA, voffA);
;             PG8_WAIT_V(8); PG8_WAIT_L(0); PG8_BAR; PG8_MMA(0, 0, At, B0); PG8_MMA(0, 1, At, B1); PG8_BAR; PG8_SCHED;
;             PG8_LDA(At, 1, 1); PG8_STAGE(PG8_SB(1, 0), b3, voffB); PG8_STAGE(PG8_SB(1, 1), b3 + hstepB, voffB); PG8_STAGE(PG8_SA(1, 0), a3, voffA);
;             PG8_WAIT_V(8); PG8_WAIT_L(0); PG8_BAR; PG8_MMA(1, 0, At, B0); PG8_MMA(1, 1, At, B1); PG8_BAR; PG8_SCHED;
.LBB0_2238:
	v_lshrrev_b32_e32 v1, 1, v15
	v_and_b32_e32 v1, 24, v1
	v_and_b32_e32 v19, 15, v15
	v_lshlrev_b32_e32 v20, 1, v1
	v_lshlrev_b32_e32 v15, 2, v15
	s_and_b32 s25, s17, 3
	v_lshl_or_b32 v142, s16, 6, v19
	v_lshl_or_b32 v19, v19, 6, v20
	s_lshl_b32 s16, s16, 13
	v_and_b32_e32 v15, 32, v15
	s_add_i32 m0, s1, 0x18000
	v_lshl_add_u64 v[10:11], v[10:11], 0, s[96:97]
	v_bitop3_b32 v20, v19, s16, v15 bitop3:0xde
	s_lshl_b32 s16, s25, 12
	s_waitcnt vmcnt(2)
	s_barrier
	global_load_lds_dwordx4 v[10:11], off
	v_lshl_add_u64 v[8:9], v[8:9], 0, s[96:97]
	s_add_i32 m0, s1, 0x1a000
	s_add_i32 s39, s1, 0x8000
	s_add_i32 s57, s1, 0xa000
	v_bitop3_b32 v143, v19, s16, v15 bitop3:0xde
	global_load_lds_dwordx4 v[8:9], off
	v_lshl_add_u64 v[6:7], v[6:7], 0, s[96:97]
	s_mov_b32 m0, s39
	s_add_u32 s16, s8, 0x20080
	global_load_lds_dwordx4 v[6:7], off
	v_lshl_add_u64 v[4:5], v[4:5], 0, s[96:97]
	s_mov_b32 m0, s57
	s_addc_u32 s17, s9, 0
	global_load_lds_dwordx4 v[4:5], off
	s_add_i32 m0, s1, 0x1c000
	v_lshl_add_u64 v[4:5], s[16:17], 0, v[2:3]
	global_load_lds_dwordx4 v[4:5], off
	v_lshl_add_u64 v[4:5], s[16:17], 0, v[132:133]
	s_add_i32 m0, s1, 0x1e000
	s_add_u32 s58, s74, s14
	global_load_lds_dwordx4 v[4:5], off
	v_lshlrev_b32_e32 v4, 13, v17
	v_and_b32_e32 v4, 0xffffc000, v4
	s_addc_u32 s59, s75, s15
	v_lshl_add_u32 v4, v16, 10, v4
	v_and_b32_e32 v5, 1, v17
	v_readlane_b32 s16, v254, 53
	v_lshl_or_b32 v4, v5, 6, v4
	s_add_u32 s14, s16, s14
	v_readlane_b32 s16, v254, 54
	v_lshl_add_u32 v4, v18, 1, v4
	v_mov_b32_e32 v5, v3
	s_addc_u32 s15, s16, s15
	v_lshl_add_u64 v[138:139], s[14:15], 0, v[4:5]
	v_lshlrev_b32_e32 v4, 13, v12
	v_and_b32_e32 v4, 0xffffc000, v4
	v_lshl_add_u32 v4, v13, 10, v4
	v_and_b32_e32 v5, 1, v12
	v_lshl_or_b32 v4, v5, 6, v4
	s_waitcnt vmcnt(6)
	v_lshl_add_u32 v4, v14, 1, v4
	v_mov_b32_e32 v5, v3
	v_lshl_add_u64 v[140:141], s[14:15], 0, v[4:5]
	s_add_u32 s60, s50, s12
	v_mov_b32_e32 v4, 0
	s_addc_u32 s61, s51, s13
	s_mov_b32 s62, -2
	s_mov_b64 s[12:13], 0
	v_add_u32_e32 v144, 0, v20
	s_waitcnt vmcnt(0)
	s_barrier
	s_add_u32 s14, s58, s12
	s_addc_u32 s15, s59, s13
	s_add_u32 s14, s14, 0x3e100100
	s_addc_u32 s15, s15, 0
	s_add_u32 s63, s60, s12
	s_addc_u32 s64, s61, s13
	s_add_i32 s65, 0, 0x10000
	s_cmpk_eq_i32 s12, 0x300
	s_cselect_b32 s17, s11, s15
	s_cselect_b32 s16, s10, s14
	v_add_u32_e32 v145, s65, v143
	s_cselect_b32 s15, s9, s64
	s_cselect_b32 s14, s8, s63
	s_add_i32 s63, 0, 0x14000
	ds_read_b128 v[146:149], v145
	ds_read_b128 v[150:153], v145 offset:1024
	ds_read_b128 v[154:157], v145 offset:2048
	ds_read_b128 v[158:161], v145 offset:3072
	v_add_u32_e32 v145, s63, v143
	ds_read_b128 v[162:165], v145
	ds_read_b128 v[166:169], v145 offset:1024
	ds_read_b128 v[170:173], v145 offset:2048
	ds_read_b128 v[174:177], v145 offset:3072
	v_lshl_add_u64 v[194:195], v[138:139], 0, s[12:13]
	s_add_i32 m0, s1, 0xc000
	ds_read_b128 v[178:181], v144
	ds_read_b128 v[182:185], v144 offset:1024
	ds_read_b128 v[186:189], v144 offset:2048
	ds_read_b128 v[190:193], v144 offset:3072
	ds_read_b128 v[204:207], v144 offset:4096
	ds_read_b128 v[220:223], v144 offset:5120
	ds_read_b128 v[224:227], v144 offset:6144
	ds_read_b128 v[228:231], v144 offset:7168
	global_load_lds_dwordx4 v[194:195], off
	v_lshl_add_u64 v[194:195], v[140:141], 0, s[12:13]
	s_add_i32 m0, s1, 0xe000
	s_nop 0
	global_load_lds_dwordx4 v[194:195], off
	s_waitcnt vmcnt(8)
	s_waitcnt lgkmcnt(0)
	s_setprio 1
	s_barrier
	v_mfma_f32_16x16x32_f16 v[128:131], v[146:149], v[178:181], 0
	v_mfma_f32_16x16x32_f16 v[124:127], v[154:157], v[178:181], 0
	v_mfma_f32_16x16x32_f16 v[112:115], v[146:149], v[186:189], 0
	v_mfma_f32_16x16x32_f16 v[108:111], v[154:157], v[186:189], 0
	v_mfma_f32_16x16x32_f16 v[96:99], v[146:149], v[204:207], 0
	v_mfma_f32_16x16x32_f16 v[92:95], v[154:157], v[204:207], 0
	v_mfma_f32_16x16x32_f16 v[80:83], v[146:149], v[224:227], 0
	v_mfma_f32_16x16x32_f16 v[76:79], v[154:157], v[224:227], 0
	v_mfma_f32_16x16x32_f16 v[128:131], v[150:153], v[182:185], v[128:131]
	v_mfma_f32_16x16x32_f16 v[124:127], v[158:161], v[182:185], v[124:127]
	v_mfma_f32_16x16x32_f16 v[112:115], v[150:153], v[190:193], v[112:115]
	v_mfma_f32_16x16x32_f16 v[108:111], v[158:161], v[190:193], v[108:111]
	v_mfma_f32_16x16x32_f16 v[96:99], v[150:153], v[220:223], v[96:99]
	v_mfma_f32_16x16x32_f16 v[92:95], v[158:161], v[220:223], v[92:95]
	v_mfma_f32_16x16x32_f16 v[80:83], v[150:153], v[228:231], v[80:83]
	v_mfma_f32_16x16x32_f16 v[76:79], v[158:161], v[228:231], v[76:79]
	v_mfma_f32_16x16x32_f16 v[120:123], v[162:165], v[178:181], 0
	v_mfma_f32_16x16x32_f16 v[116:119], v[170:173], v[178:181], 0
	v_mfma_f32_16x16x32_f16 v[104:107], v[162:165], v[186:189], 0
	v_mfma_f32_16x16x32_f16 v[100:103], v[170:173], v[186:189], 0
	v_mfma_f32_16x16x32_f16 v[88:91], v[162:165], v[204:207], 0
	v_mfma_f32_16x16x32_f16 v[84:87], v[170:173], v[204:207], 0
	v_mfma_f32_16x16x32_f16 v[72:75], v[162:165], v[224:227], 0
	v_mfma_f32_16x16x32_f16 v[68:71], v[170:173], v[224:227], 0
	v_mfma_f32_16x16x32_f16 v[120:123], v[166:169], v[182:185], v[120:123]
	v_mfma_f32_16x16x32_f16 v[116:119], v[174:177], v[182:185], v[116:119]
	v_mfma_f32_16x16x32_f16 v[104:107], v[166:169], v[190:193], v[104:107]
	v_mfma_f32_16x16x32_f16 v[100:103], v[174:177], v[190:193], v[100:103]
	v_mfma_f32_16x16x32_f16 v[88:91], v[166:169], v[220:223], v[88:91]
	v_mfma_f32_16x16x32_f16 v[84:87], v[174:177], v[220:223], v[84:87]
	v_mfma_f32_16x16x32_f16 v[72:75], v[166:169], v[228:231], v[72:75]
	v_mfma_f32_16x16x32_f16 v[68:71], v[174:177], v[228:231], v[68:71]
	s_setprio 0
	s_barrier
; #define PG8_STAGE(bufoff, gbase, voff) do { _Pragma("unroll") for (int _i = 0; _i < 2; ++_i) \
;         __builtin_amdgcn_global_load_lds((const unsigned*)((const char*)(gbase) + (voff)[_i]), (LAS unsigned*)(lds + (bufoff) + ldsw + _i * 8192), 16, 0, 0); } while (0)
; #define PG8_LDA(dst, b, h) do { _Pragma("unroll") for (int m = 0; m < 4; ++m) _Pragma("unroll") for (int k = 0; k < 2; ++k) dst[m][k] = *(const LAS half8*)(lds + PG8_SA(b, h) + aoff + m * 2048 + k * 1024); } while (0)
; #define PG8_LDB(dst, b, h) do { _Pragma("unroll") for (int n = 0; n < 2; ++n) _Pragma("unroll") for (int k = 0; k < 2; ++k) dst[n][k] = *(const LAS half8*)(lds + PG8_SB(b, h) + boff + n * 2048 + k * 1024); } while (0)
; #define PG8_MMA(ai, bj, At, Bt) do { __builtin_amdgcn_s_setprio(1); _Pragma("unroll") for (int m = 0; m < 4; ++m) _Pragma("unroll") for (int n = 0; n < 2; ++n) _Pragma("unroll") for (int k = 0; k < 2; ++k) \
;         acc[ai][bj][m][n] = __builtin_amdgcn_mfma_f32_16x16x32_f16(Bt[n][k], At[m][k], acc[ai][bj][m][n], 0, 0, 0); __builtin_amdgcn_s_setprio(0); } while (0)
; #define PG8_BAR __builtin_amdgcn_s_barrier()
; template <class Epi, class Sched, bool ALIGN_EPI = false, bool SP2 = false>
; __device__ __forceinline__ void gemm_phase(LAS unsigned char* lds, const Gemm g, const Sched& S, const Epi& E) {
;     ...
;             if constexpr (SP2) {
;             PG8_LDB(B0, 0, 0); PG8_LDB(B1, 0, 1); PG8_SCHED; PG8_LDA(At, 0, 0); PG8_STAGE(PG8_SA(1, 1), a1 + hstepA, voffA);
;             PG8_WAIT_V(8); PG8_WAIT_L(0); PG8_BAR; PG8_MMA(0, 0, At, B0); PG8_MMA(0, 1, At, B1); PG8_BAR; PG8_SCHED;
;             PG8_LDA(At, 0, 1); PG8_STAGE(PG8_SB(0, 0), b2, voffB); PG8_STAGE(PG8_SB(0, 1), b2 + hstepB, voffB); PG8_STAGE(PG8_SA(0, 0), a2, voffA);
;             PG8_WAIT_V(8); PG8_WAIT_L(0); PG8_BAR; PG8_MMA(1, 0, At, B0); PG8_MMA(1, 1, At, B1); PG8_BAR; PG8_SCHED;
;             PG8_LDB(B0, 1, 0); PG8_LDB(B1, 1, 1); PG8_SCHED; PG8_LDA(At, 1, 0); PG8_STAGE(PG8_SA(0, 1), a2 + hstepA, voffA);
;             PG8_WAIT_V(8); PG8_WAIT_L(0); PG8_BAR; PG8_MMA(0, 0, At, B0); PG8_MMA(0, 1, At, B1); PG8_BAR; PG8_SCHED;
;             PG8_LDA(At, 1, 1); PG8_STAGE(PG8_SB(1, 0), b3, voffB); PG8_STAGE(PG8_SB(1, 1), b3 + hstepB, voffB); PG8_STAGE(PG8_SA(1, 0), a3, voffA);
;             PG8_WAIT_V(8); PG8_WAIT_L(0); PG8_BAR; PG8_MMA(1, 0, At, B0); PG8_MMA(1, 1, At, B1); PG8_BAR; PG8_SCHED;
	s_add_i32 s64, s65, s24
	v_lshl_add_u64 v[194:195], s[14:15], 0, v[2:3]
	s_mov_b32 m0, s64
	ds_read_b128 v[178:181], v144 offset:16384
	ds_read_b128 v[182:185], v144 offset:17408
	ds_read_b128 v[186:189], v144 offset:18432
	ds_read_b128 v[190:193], v144 offset:19456
	ds_read_b128 v[204:207], v144 offset:20480
	ds_read_b128 v[220:223], v144 offset:21504
	ds_read_b128 v[224:227], v144 offset:22528
	ds_read_b128 v[228:231], v144 offset:23552
	global_load_lds_dwordx4 v[194:195], off
	s_add_i32 m0, s64, 0x2000
	s_add_u32 s64, s14, 0x20000
	v_lshl_add_u64 v[196:197], s[14:15], 0, v[132:133]
	s_addc_u32 s65, s15, 0
	s_add_i32 s63, s63, s24
	global_load_lds_dwordx4 v[196:197], off
	v_lshl_add_u64 v[208:209], s[64:65], 0, v[2:3]
	s_mov_b32 m0, s63
	v_lshl_add_u64 v[232:233], s[16:17], 0, v[134:135]
	global_load_lds_dwordx4 v[208:209], off
	v_lshl_add_u64 v[208:209], s[64:65], 0, v[132:133]
	s_add_i32 m0, s63, 0x2000
	s_nop 0
	global_load_lds_dwordx4 v[208:209], off
	v_lshl_add_u64 v[208:209], s[16:17], 0, v[136:137]
	s_mov_b32 m0, s1
	s_nop 0
	global_load_lds_dwordx4 v[208:209], off
	s_mov_b32 m0, s7
	s_nop 0
	global_load_lds_dwordx4 v[232:233], off
	s_waitcnt vmcnt(8)
	s_waitcnt lgkmcnt(0)
	s_setprio 1
	s_barrier
	v_mfma_f32_16x16x32_f16 v[64:67], v[146:149], v[178:181], 0
	v_mfma_f32_16x16x32_f16 v[60:63], v[154:157], v[178:181], 0
	v_mfma_f32_16x16x32_f16 v[48:51], v[146:149], v[186:189], 0
	v_mfma_f32_16x16x32_f16 v[44:47], v[154:157], v[186:189], 0
	v_mfma_f32_16x16x32_f16 v[32:35], v[146:149], v[204:207], 0
	v_mfma_f32_16x16x32_f16 v[28:31], v[154:157], v[204:207], 0
	v_mfma_f32_16x16x32_f16 v[16:19], v[146:149], v[224:227], 0
	v_mfma_f32_16x16x32_f16 v[12:15], v[154:157], v[224:227], 0
	v_mfma_f32_16x16x32_f16 v[64:67], v[150:153], v[182:185], v[64:67]
	v_mfma_f32_16x16x32_f16 v[60:63], v[158:161], v[182:185], v[60:63]
	v_mfma_f32_16x16x32_f16 v[48:51], v[150:153], v[190:193], v[48:51]
	v_mfma_f32_16x16x32_f16 v[44:47], v[158:161], v[190:193], v[44:47]
	v_mfma_f32_16x16x32_f16 v[32:35], v[150:153], v[220:223], v[32:35]
	v_mfma_f32_16x16x32_f16 v[28:31], v[158:161], v[220:223], v[28:31]
	v_mfma_f32_16x16x32_f16 v[16:19], v[150:153], v[228:231], v[16:19]
	v_mfma_f32_16x16x32_f16 v[12:15], v[158:161], v[228:231], v[12:15]
	v_mfma_f32_16x16x32_f16 v[56:59], v[162:165], v[178:181], 0
	v_mfma_f32_16x16x32_f16 v[52:55], v[170:173], v[178:181], 0
	v_mfma_f32_16x16x32_f16 v[40:43], v[162:165], v[186:189], 0
	v_mfma_f32_16x16x32_f16 v[36:39], v[170:173], v[186:189], 0
	v_mfma_f32_16x16x32_f16 v[24:27], v[162:165], v[204:207], 0
	v_mfma_f32_16x16x32_f16 v[20:23], v[170:173], v[204:207], 0
	v_mfma_f32_16x16x32_f16 v[8:11], v[162:165], v[224:227], 0
	v_mfma_f32_16x16x32_f16 v[4:7], v[170:173], v[224:227], 0
	v_mfma_f32_16x16x32_f16 v[56:59], v[166:169], v[182:185], v[56:59]
	v_mfma_f32_16x16x32_f16 v[52:55], v[174:177], v[182:185], v[52:55]
	v_mfma_f32_16x16x32_f16 v[40:43], v[166:169], v[190:193], v[40:43]
	v_mfma_f32_16x16x32_f16 v[36:39], v[174:177], v[190:193], v[36:39]
	v_mfma_f32_16x16x32_f16 v[24:27], v[166:169], v[220:223], v[24:27]
	v_mfma_f32_16x16x32_f16 v[20:23], v[174:177], v[220:223], v[20:23]
	v_mfma_f32_16x16x32_f16 v[8:11], v[166:169], v[228:231], v[8:11]
	v_mfma_f32_16x16x32_f16 v[4:7], v[174:177], v[228:231], v[4:7]
	s_setprio 0
	s_barrier
	s_add_i32 s63, 0, 0x18000
	v_add_u32_e32 v145, s63, v143
	s_add_i32 s64, 0, 0x1c000
	ds_read_b128 v[146:149], v145
	ds_read_b128 v[150:153], v145 offset:1024
	ds_read_b128 v[154:157], v145 offset:2048
	ds_read_b128 v[158:161], v145 offset:3072
	v_add_u32_e32 v145, s64, v143
	ds_read_b128 v[162:165], v145
	ds_read_b128 v[166:169], v145 offset:1024
	ds_read_b128 v[170:173], v145 offset:2048
	ds_read_b128 v[174:177], v145 offset:3072
	s_add_u32 s16, s16, 0x20000
	s_addc_u32 s17, s17, 0
	s_mov_b32 m0, s37
	v_lshl_add_u64 v[234:235], s[16:17], 0, v[136:137]
	ds_read_b128 v[178:181], v144 offset:32768
	ds_read_b128 v[182:185], v144 offset:33792
	ds_read_b128 v[186:189], v144 offset:34816
	ds_read_b128 v[190:193], v144 offset:35840
	ds_read_b128 v[204:207], v144 offset:36864
	ds_read_b128 v[220:223], v144 offset:37888
	ds_read_b128 v[224:227], v144 offset:38912
	ds_read_b128 v[228:231], v144 offset:39936
	global_load_lds_dwordx4 v[234:235], off
	v_lshl_add_u64 v[234:235], s[16:17], 0, v[134:135]
	s_mov_b32 m0, s38
	s_nop 0
	global_load_lds_dwordx4 v[234:235], off
	s_waitcnt vmcnt(8)
	s_waitcnt lgkmcnt(0)
	s_setprio 1
	s_barrier
	v_mfma_f32_16x16x32_f16 v[128:131], v[146:149], v[178:181], v[128:131]
	v_mfma_f32_16x16x32_f16 v[124:127], v[154:157], v[178:181], v[124:127]
	v_mfma_f32_16x16x32_f16 v[112:115], v[146:149], v[186:189], v[112:115]
	v_mfma_f32_16x16x32_f16 v[108:111], v[154:157], v[186:189], v[108:111]
	v_mfma_f32_16x16x32_f16 v[96:99], v[146:149], v[204:207], v[96:99]
	v_mfma_f32_16x16x32_f16 v[92:95], v[154:157], v[204:207], v[92:95]
	v_mfma_f32_16x16x32_f16 v[80:83], v[146:149], v[224:227], v[80:83]
	v_mfma_f32_16x16x32_f16 v[76:79], v[154:157], v[224:227], v[76:79]
	v_mfma_f32_16x16x32_f16 v[128:131], v[150:153], v[182:185], v[128:131]
	v_mfma_f32_16x16x32_f16 v[124:127], v[158:161], v[182:185], v[124:127]
	v_mfma_f32_16x16x32_f16 v[112:115], v[150:153], v[190:193], v[112:115]
	v_mfma_f32_16x16x32_f16 v[108:111], v[158:161], v[190:193], v[108:111]
	v_mfma_f32_16x16x32_f16 v[96:99], v[150:153], v[220:223], v[96:99]
	v_mfma_f32_16x16x32_f16 v[92:95], v[158:161], v[220:223], v[92:95]
	v_mfma_f32_16x16x32_f16 v[80:83], v[150:153], v[228:231], v[80:83]
	v_mfma_f32_16x16x32_f16 v[76:79], v[158:161], v[228:231], v[76:79]
	v_mfma_f32_16x16x32_f16 v[120:123], v[162:165], v[178:181], v[120:123]
	v_mfma_f32_16x16x32_f16 v[116:119], v[170:173], v[178:181], v[116:119]
	v_mfma_f32_16x16x32_f16 v[104:107], v[162:165], v[186:189], v[104:107]
	v_mfma_f32_16x16x32_f16 v[100:103], v[170:173], v[186:189], v[100:103]
	v_mfma_f32_16x16x32_f16 v[88:91], v[162:165], v[204:207], v[88:91]
	v_mfma_f32_16x16x32_f16 v[84:87], v[170:173], v[204:207], v[84:87]
	v_mfma_f32_16x16x32_f16 v[72:75], v[162:165], v[224:227], v[72:75]
	v_mfma_f32_16x16x32_f16 v[68:71], v[170:173], v[224:227], v[68:71]
	v_mfma_f32_16x16x32_f16 v[120:123], v[166:169], v[182:185], v[120:123]
	v_mfma_f32_16x16x32_f16 v[116:119], v[174:177], v[182:185], v[116:119]
	v_mfma_f32_16x16x32_f16 v[104:107], v[166:169], v[190:193], v[104:107]
	v_mfma_f32_16x16x32_f16 v[100:103], v[174:177], v[190:193], v[100:103]
	v_mfma_f32_16x16x32_f16 v[88:91], v[166:169], v[220:223], v[88:91]
	v_mfma_f32_16x16x32_f16 v[84:87], v[174:177], v[220:223], v[84:87]
	v_mfma_f32_16x16x32_f16 v[72:75], v[166:169], v[228:231], v[72:75]
	v_mfma_f32_16x16x32_f16 v[68:71], v[174:177], v[228:231], v[68:71]
	s_setprio 0
	s_barrier
; #define PG8_STAGE(bufoff, gbase, voff) do { _Pragma("unroll") for (int _i = 0; _i < 2; ++_i) \
;         __builtin_amdgcn_global_load_lds((const unsigned*)((const char*)(gbase) + (voff)[_i]), (LAS unsigned*)(lds + (bufoff) + ldsw + _i * 8192), 16, 0, 0); } while (0)
; #define PG8_LDA(dst, b, h) do { _Pragma("unroll") for (int m = 0; m < 4; ++m) _Pragma("unroll") for (int k = 0; k < 2; ++k) dst[m][k] = *(const LAS half8*)(lds + PG8_SA(b, h) + aoff + m * 2048 + k * 1024); } while (0)
; #define PG8_LDB(dst, b, h) do { _Pragma("unroll") for (int n = 0; n < 2; ++n) _Pragma("unroll") for (int k = 0; k < 2; ++k) dst[n][k] = *(const LAS half8*)(lds + PG8_SB(b, h) + boff + n * 2048 + k * 1024); } while (0)
; template <class Epi, class Sched, bool ALIGN_EPI = false, bool SP2 = false>
; __device__ __forceinline__ void gemm_phase(LAS unsigned char* lds, const Gemm g, const Sched& S, const Epi& E) {
;     ...
;         for (int t = 0; t < nt; t += 2) {
;             const bool last = (t == nt - 2);
;             const char* a1 = cA + (size_t)(t + 1) * kstep;
;             const char* a2 = last ? nA : cA + (size_t)(t + 2) * kstep; const char* b2 = last ? nB : cB + (size_t)(t + 2) * kstep;
;             const char* a3 = a2 + kstep; const char* b3 = b2 + kstep;
;             if (last && has_next) S.a_ready(nxt);
;             if constexpr (SP2) {
;             PG8_LDB(B0, 0, 0); PG8_LDB(B1, 0, 1); PG8_SCHED; PG8_LDA(At, 0, 0); PG8_STAGE(PG8_SA(1, 1), a1 + hstepA, voffA);
;             PG8_WAIT_V(8); PG8_WAIT_L(0); PG8_BAR; PG8_MMA(0, 0, At, B0); PG8_MMA(0, 1, At, B1); PG8_BAR; PG8_SCHED;
;             PG8_LDA(At, 0, 1); PG8_STAGE(PG8_SB(0, 0), b2, voffB); PG8_STAGE(PG8_SB(0, 1), b2 + hstepB, voffB); PG8_STAGE(PG8_SA(0, 0), a2, voffA);
;             PG8_WAIT_V(8); PG8_WAIT_L(0); PG8_BAR; PG8_MMA(1, 0, At, B0); PG8_MMA(1, 1, At, B1); PG8_BAR; PG8_SCHED;
;             PG8_LDB(B0, 1, 0); PG8_LDB(B1, 1, 1); PG8_SCHED; PG8_LDA(At, 1, 0); PG8_STAGE(PG8_SA(0, 1), a2 + hstepA, voffA);
;             PG8_WAIT_V(8); PG8_WAIT_L(0); PG8_BAR; PG8_MMA(0, 0, At, B0); PG8_MMA(0, 1, At, B1); PG8_BAR; PG8_SCHED;
;             PG8_LDA(At, 1, 1); PG8_STAGE(PG8_SB(1, 0), b3, voffB); PG8_STAGE(PG8_SB(1, 1), b3 + hstepB, voffB); PG8_STAGE(PG8_SA(1, 0), a3, voffA);
;             PG8_WAIT_V(8); PG8_WAIT_L(0); PG8_BAR; PG8_MMA(1, 0, At, B0); PG8_MMA(1, 1, At, B1); PG8_BAR; PG8_SCHED;
	s_add_i32 s16, s63, s24
	v_lshl_add_u64 v[194:195], v[194:195], 0, s[96:97]
	s_mov_b32 m0, s16
	ds_read_b128 v[178:181], v144 offset:49152
	ds_read_b128 v[182:185], v144 offset:50176
	ds_read_b128 v[186:189], v144 offset:51200
	ds_read_b128 v[190:193], v144 offset:52224
	ds_read_b128 v[204:207], v144 offset:53248
	ds_read_b128 v[220:223], v144 offset:54272
	ds_read_b128 v[224:227], v144 offset:55296
	ds_read_b128 v[228:231], v144 offset:56320
	global_load_lds_dwordx4 v[194:195], off
	s_add_i32 m0, s16, 0x2000
	s_add_u32 s14, s14, 0x20080
	v_lshl_add_u64 v[194:195], v[196:197], 0, s[96:97]
	s_addc_u32 s15, s15, 0
	s_add_i32 s16, s64, s24
	global_load_lds_dwordx4 v[194:195], off
	v_lshl_add_u64 v[194:195], s[14:15], 0, v[2:3]
	s_mov_b32 m0, s16
	s_nop 0
	global_load_lds_dwordx4 v[194:195], off
	v_lshl_add_u64 v[194:195], s[14:15], 0, v[132:133]
	s_add_i32 m0, s16, 0x2000
	s_nop 0
	global_load_lds_dwordx4 v[194:195], off
	v_lshl_add_u64 v[194:195], v[208:209], 0, s[96:97]
	s_mov_b32 m0, s39
	s_nop 0
	global_load_lds_dwordx4 v[194:195], off
	v_lshl_add_u64 v[194:195], v[232:233], 0, s[96:97]
	s_mov_b32 m0, s57
	s_nop 0
	global_load_lds_dwordx4 v[194:195], off
	s_waitcnt vmcnt(8)
	s_waitcnt lgkmcnt(0)
	s_setprio 1
	s_barrier
	v_mfma_f32_16x16x32_f16 v[64:67], v[146:149], v[178:181], v[64:67]
	v_mfma_f32_16x16x32_f16 v[60:63], v[154:157], v[178:181], v[60:63]
	v_mfma_f32_16x16x32_f16 v[48:51], v[146:149], v[186:189], v[48:51]
	v_mfma_f32_16x16x32_f16 v[44:47], v[154:157], v[186:189], v[44:47]
	v_mfma_f32_16x16x32_f16 v[32:35], v[146:149], v[204:207], v[32:35]
	v_mfma_f32_16x16x32_f16 v[28:31], v[154:157], v[204:207], v[28:31]
	v_mfma_f32_16x16x32_f16 v[16:19], v[146:149], v[224:227], v[16:19]
	v_mfma_f32_16x16x32_f16 v[12:15], v[154:157], v[224:227], v[12:15]
	v_mfma_f32_16x16x32_f16 v[64:67], v[150:153], v[182:185], v[64:67]
	v_mfma_f32_16x16x32_f16 v[60:63], v[158:161], v[182:185], v[60:63]
	v_mfma_f32_16x16x32_f16 v[48:51], v[150:153], v[190:193], v[48:51]
	v_mfma_f32_16x16x32_f16 v[44:47], v[158:161], v[190:193], v[44:47]
	v_mfma_f32_16x16x32_f16 v[32:35], v[150:153], v[220:223], v[32:35]
	v_mfma_f32_16x16x32_f16 v[28:31], v[158:161], v[220:223], v[28:31]
	v_mfma_f32_16x16x32_f16 v[16:19], v[150:153], v[228:231], v[16:19]
	v_mfma_f32_16x16x32_f16 v[12:15], v[158:161], v[228:231], v[12:15]
	v_mfma_f32_16x16x32_f16 v[56:59], v[162:165], v[178:181], v[56:59]
	v_mfma_f32_16x16x32_f16 v[52:55], v[170:173], v[178:181], v[52:55]
	v_mfma_f32_16x16x32_f16 v[40:43], v[162:165], v[186:189], v[40:43]
	v_mfma_f32_16x16x32_f16 v[36:39], v[170:173], v[186:189], v[36:39]
	v_mfma_f32_16x16x32_f16 v[24:27], v[162:165], v[204:207], v[24:27]
	v_mfma_f32_16x16x32_f16 v[20:23], v[170:173], v[204:207], v[20:23]
	v_mfma_f32_16x16x32_f16 v[8:11], v[162:165], v[224:227], v[8:11]
	v_mfma_f32_16x16x32_f16 v[4:7], v[170:173], v[224:227], v[4:7]
	v_mfma_f32_16x16x32_f16 v[56:59], v[166:169], v[182:185], v[56:59]
	v_mfma_f32_16x16x32_f16 v[52:55], v[174:177], v[182:185], v[52:55]
	v_mfma_f32_16x16x32_f16 v[40:43], v[166:169], v[190:193], v[40:43]
	v_mfma_f32_16x16x32_f16 v[36:39], v[174:177], v[190:193], v[36:39]
	v_mfma_f32_16x16x32_f16 v[24:27], v[166:169], v[220:223], v[24:27]
	v_mfma_f32_16x16x32_f16 v[20:23], v[174:177], v[220:223], v[20:23]
	v_mfma_f32_16x16x32_f16 v[8:11], v[166:169], v[228:231], v[8:11]
	v_mfma_f32_16x16x32_f16 v[4:7], v[174:177], v[228:231], v[4:7]
	s_setprio 0
	s_barrier
	s_add_i32 s62, s62, 2
	s_add_u32 s12, s12, 0x100
	s_addc_u32 s13, s13, 0
	s_cmp_gt_u32 s62, 5
	s_cbranch_scc0 .LBB0_2239
.LBB0_2239:
	s_add_u32 s14, s58, s12
	s_addc_u32 s15, s59, s13
	s_add_u32 s14, s14, 0x3e100100
	s_addc_u32 s15, s15, 0
	s_add_u32 s63, s60, s12
	s_addc_u32 s64, s61, s13
	s_add_i32 s65, 0, 0x10000
	s_cmpk_eq_i32 s12, 0x300
	s_cselect_b32 s17, s11, s15
	s_cselect_b32 s16, s10, s14
	v_add_u32_e32 v145, s65, v143
	s_cselect_b32 s15, s9, s64
	s_cselect_b32 s14, s8, s63
	s_add_i32 s63, 0, 0x14000
	ds_read_b128 v[146:149], v145
	ds_read_b128 v[150:153], v145 offset:1024
	ds_read_b128 v[154:157], v145 offset:2048
	ds_read_b128 v[158:161], v145 offset:3072
	v_add_u32_e32 v145, s63, v143
	ds_read_b128 v[162:165], v145
	ds_read_b128 v[166:169], v145 offset:1024
	ds_read_b128 v[170:173], v145 offset:2048
	ds_read_b128 v[174:177], v145 offset:3072
	v_lshl_add_u64 v[194:195], v[138:139], 0, s[12:13]
	s_add_i32 m0, s1, 0xc000
	ds_read_b128 v[178:181], v144
	ds_read_b128 v[182:185], v144 offset:1024
	ds_read_b128 v[186:189], v144 offset:2048
	ds_read_b128 v[190:193], v144 offset:3072
	ds_read_b128 v[204:207], v144 offset:4096
	ds_read_b128 v[220:223], v144 offset:5120
	ds_read_b128 v[224:227], v144 offset:6144
	ds_read_b128 v[228:231], v144 offset:7168
	global_load_lds_dwordx4 v[194:195], off
	v_lshl_add_u64 v[194:195], v[140:141], 0, s[12:13]
	s_add_i32 m0, s1, 0xe000
	s_nop 0
	global_load_lds_dwordx4 v[194:195], off
	s_waitcnt vmcnt(8)
	s_waitcnt lgkmcnt(0)
	s_setprio 1
	s_barrier
; #define PG8_STAGE(bufoff, gbase, voff) do { _Pragma("unroll") for (int _i = 0; _i < 2; ++_i) \
;         __builtin_amdgcn_global_load_lds((const unsigned*)((const char*)(gbase) + (voff)[_i]), (LAS unsigned*)(lds + (bufoff) + ldsw + _i * 8192), 16, 0, 0); } while (0)
; #define PG8_LDA(dst, b, h) do { _Pragma("unroll") for (int m = 0; m < 4; ++m) _Pragma("unroll") for (int k = 0; k < 2; ++k) dst[m][k] = *(const LAS half8*)(lds + PG8_SA(b, h) + aoff + m * 2048 + k * 1024); } while (0)
; #define PG8_LDB(dst, b, h) do { _Pragma("unroll") for (int n = 0; n < 2; ++n) _Pragma("unroll") for (int k = 0; k < 2; ++k) dst[n][k] = *(const LAS half8*)(lds + PG8_SB(b, h) + boff + n * 2048 + k * 1024); } while (0)
; #define PG8_MMA(ai, bj, At, Bt) do { __builtin_amdgcn_s_setprio(1); _Pragma("unroll") for (int m = 0; m < 4; ++m) _Pragma("unroll") for (int n = 0; n < 2; ++n) _Pragma("unroll") for (int k = 0; k < 2; ++k) \
;         acc[ai][bj][m][n] = __builtin_amdgcn_mfma_f32_16x16x32_f16(Bt[n][k], At[m][k], acc[ai][bj][m][n], 0, 0, 0); __builtin_amdgcn_s_setprio(0); } while (0)
; #define PG8_BAR __builtin_amdgcn_s_barrier()
; template <class Epi, class Sched, bool ALIGN_EPI = false, bool SP2 = false>
; __device__ __forceinline__ void gemm_phase(LAS unsigned char* lds, const Gemm g, const Sched& S, const Epi& E) {
;     ...
;             if constexpr (SP2) {
;             PG8_LDB(B0, 0, 0); PG8_LDB(B1, 0, 1); PG8_SCHED; PG8_LDA(At, 0, 0); PG8_STAGE(PG8_SA(1, 1), a1 + hstepA, voffA);
;             PG8_WAIT_V(8); PG8_WAIT_L(0); PG8_BAR; PG8_MMA(0, 0, At, B0); PG8_MMA(0, 1, At, B1); PG8_BAR; PG8_SCHED;
;             PG8_LDA(At, 0, 1); PG8_STAGE(PG8_SB(0, 0), b2, voffB); PG8_STAGE(PG8_SB(0, 1), b2 + hstepB, voffB); PG8_STAGE(PG8_SA(0, 0), a2, voffA);
;             PG8_WAIT_V(8); PG8_WAIT_L(0); PG8_BAR; PG8_MMA(1, 0, At, B0); PG8_MMA(1, 1, At, B1); PG8_BAR; PG8_SCHED;
;             PG8_LDB(B0, 1, 0); PG8_LDB(B1, 1, 1); PG8_SCHED; PG8_LDA(At, 1, 0); PG8_STAGE(PG8_SA(0, 1), a2 + hstepA, voffA);
;             PG8_WAIT_V(8); PG8_WAIT_L(0); PG8_BAR; PG8_MMA(0, 0, At, B0); PG8_MMA(0, 1, At, B1); PG8_BAR; PG8_SCHED;
;             PG8_LDA(At, 1, 1); PG8_STAGE(PG8_SB(1, 0), b3, voffB); PG8_STAGE(PG8_SB(1, 1), b3 + hstepB, voffB); PG8_STAGE(PG8_SA(1, 0), a3, voffA);
;             PG8_WAIT_V(8); PG8_WAIT_L(0); PG8_BAR; PG8_MMA(1, 0, At, B0); PG8_MMA(1, 1, At, B1); PG8_BAR; PG8_SCHED;
	v_mfma_f32_16x16x32_f16 v[128:131], v[146:149], v[178:181], v[128:131]
	v_mfma_f32_16x16x32_f16 v[124:127], v[154:157], v[178:181], v[124:127]
	v_mfma_f32_16x16x32_f16 v[112:115], v[146:149], v[186:189], v[112:115]
	v_mfma_f32_16x16x32_f16 v[108:111], v[154:157], v[186:189], v[108:111]
	v_mfma_f32_16x16x32_f16 v[96:99], v[146:149], v[204:207], v[96:99]
	v_mfma_f32_16x16x32_f16 v[92:95], v[154:157], v[204:207], v[92:95]
	v_mfma_f32_16x16x32_f16 v[80:83], v[146:149], v[224:227], v[80:83]
	v_mfma_f32_16x16x32_f16 v[76:79], v[154:157], v[224:227], v[76:79]
	v_mfma_f32_16x16x32_f16 v[128:131], v[150:153], v[182:185], v[128:131]
	v_mfma_f32_16x16x32_f16 v[124:127], v[158:161], v[182:185], v[124:127]
	v_mfma_f32_16x16x32_f16 v[112:115], v[150:153], v[190:193], v[112:115]
	v_mfma_f32_16x16x32_f16 v[108:111], v[158:161], v[190:193], v[108:111]
	v_mfma_f32_16x16x32_f16 v[96:99], v[150:153], v[220:223], v[96:99]
	v_mfma_f32_16x16x32_f16 v[92:95], v[158:161], v[220:223], v[92:95]
	v_mfma_f32_16x16x32_f16 v[80:83], v[150:153], v[228:231], v[80:83]
	v_mfma_f32_16x16x32_f16 v[76:79], v[158:161], v[228:231], v[76:79]
	v_mfma_f32_16x16x32_f16 v[120:123], v[162:165], v[178:181], v[120:123]
	v_mfma_f32_16x16x32_f16 v[116:119], v[170:173], v[178:181], v[116:119]
	v_mfma_f32_16x16x32_f16 v[104:107], v[162:165], v[186:189], v[104:107]
	v_mfma_f32_16x16x32_f16 v[100:103], v[170:173], v[186:189], v[100:103]
	v_mfma_f32_16x16x32_f16 v[88:91], v[162:165], v[204:207], v[88:91]
	v_mfma_f32_16x16x32_f16 v[84:87], v[170:173], v[204:207], v[84:87]
	v_mfma_f32_16x16x32_f16 v[72:75], v[162:165], v[224:227], v[72:75]
	v_mfma_f32_16x16x32_f16 v[68:71], v[170:173], v[224:227], v[68:71]
	v_mfma_f32_16x16x32_f16 v[120:123], v[166:169], v[182:185], v[120:123]
	v_mfma_f32_16x16x32_f16 v[116:119], v[174:177], v[182:185], v[116:119]
	v_mfma_f32_16x16x32_f16 v[104:107], v[166:169], v[190:193], v[104:107]
	v_mfma_f32_16x16x32_f16 v[100:103], v[174:177], v[190:193], v[100:103]
	v_mfma_f32_16x16x32_f16 v[88:91], v[166:169], v[220:223], v[88:91]
	v_mfma_f32_16x16x32_f16 v[84:87], v[174:177], v[220:223], v[84:87]
	v_mfma_f32_16x16x32_f16 v[72:75], v[166:169], v[228:231], v[72:75]
	v_mfma_f32_16x16x32_f16 v[68:71], v[174:177], v[228:231], v[68:71]
	s_setprio 0
	s_barrier
	s_add_i32 s64, s65, s24
	v_lshl_add_u64 v[194:195], s[14:15], 0, v[2:3]
	s_mov_b32 m0, s64
	ds_read_b128 v[178:181], v144 offset:16384
	ds_read_b128 v[182:185], v144 offset:17408
	ds_read_b128 v[186:189], v144 offset:18432
	ds_read_b128 v[190:193], v144 offset:19456
	ds_read_b128 v[204:207], v144 offset:20480
	ds_read_b128 v[220:223], v144 offset:21504
	ds_read_b128 v[224:227], v144 offset:22528
	ds_read_b128 v[228:231], v144 offset:23552
	global_load_lds_dwordx4 v[194:195], off
	s_add_i32 m0, s64, 0x2000
	s_add_u32 s64, s14, 0x20000
	v_lshl_add_u64 v[196:197], s[14:15], 0, v[132:133]
	s_addc_u32 s65, s15, 0
	s_add_i32 s63, s63, s24
	global_load_lds_dwordx4 v[196:197], off
	v_lshl_add_u64 v[208:209], s[64:65], 0, v[2:3]
	s_mov_b32 m0, s63
	v_lshl_add_u64 v[232:233], s[16:17], 0, v[134:135]
	global_load_lds_dwordx4 v[208:209], off
	v_lshl_add_u64 v[208:209], s[64:65], 0, v[132:133]
	s_add_i32 m0, s63, 0x2000
	s_nop 0
	global_load_lds_dwordx4 v[208:209], off
	v_lshl_add_u64 v[208:209], s[16:17], 0, v[136:137]
	s_mov_b32 m0, s1
	s_nop 0
	global_load_lds_dwordx4 v[208:209], off
	s_mov_b32 m0, s7
	s_nop 0
	global_load_lds_dwordx4 v[232:233], off
	s_waitcnt vmcnt(8)
	s_waitcnt lgkmcnt(0)
	s_setprio 1
	s_barrier
	v_mfma_f32_16x16x32_f16 v[64:67], v[146:149], v[178:181], v[64:67]
	v_mfma_f32_16x16x32_f16 v[60:63], v[154:157], v[178:181], v[60:63]
	v_mfma_f32_16x16x32_f16 v[48:51], v[146:149], v[186:189], v[48:51]
	v_mfma_f32_16x16x32_f16 v[44:47], v[154:157], v[186:189], v[44:47]
	v_mfma_f32_16x16x32_f16 v[32:35], v[146:149], v[204:207], v[32:35]
	v_mfma_f32_16x16x32_f16 v[28:31], v[154:157], v[204:207], v[28:31]
	v_mfma_f32_16x16x32_f16 v[16:19], v[146:149], v[224:227], v[16:19]
	v_mfma_f32_16x16x32_f16 v[12:15], v[154:157], v[224:227], v[12:15]
	v_mfma_f32_16x16x32_f16 v[64:67], v[150:153], v[182:185], v[64:67]
	v_mfma_f32_16x16x32_f16 v[60:63], v[158:161], v[182:185], v[60:63]
	v_mfma_f32_16x16x32_f16 v[48:51], v[150:153], v[190:193], v[48:51]
	v_mfma_f32_16x16x32_f16 v[44:47], v[158:161], v[190:193], v[44:47]
	v_mfma_f32_16x16x32_f16 v[32:35], v[150:153], v[220:223], v[32:35]
	v_mfma_f32_16x16x32_f16 v[28:31], v[158:161], v[220:223], v[28:31]
	v_mfma_f32_16x16x32_f16 v[16:19], v[150:153], v[228:231], v[16:19]
	v_mfma_f32_16x16x32_f16 v[12:15], v[158:161], v[228:231], v[12:15]
	v_mfma_f32_16x16x32_f16 v[56:59], v[162:165], v[178:181], v[56:59]
	v_mfma_f32_16x16x32_f16 v[52:55], v[170:173], v[178:181], v[52:55]
	v_mfma_f32_16x16x32_f16 v[40:43], v[162:165], v[186:189], v[40:43]
	v_mfma_f32_16x16x32_f16 v[36:39], v[170:173], v[186:189], v[36:39]
	v_mfma_f32_16x16x32_f16 v[24:27], v[162:165], v[204:207], v[24:27]
	v_mfma_f32_16x16x32_f16 v[20:23], v[170:173], v[204:207], v[20:23]
	v_mfma_f32_16x16x32_f16 v[8:11], v[162:165], v[224:227], v[8:11]
	v_mfma_f32_16x16x32_f16 v[4:7], v[170:173], v[224:227], v[4:7]
	v_mfma_f32_16x16x32_f16 v[56:59], v[166:169], v[182:185], v[56:59]
	v_mfma_f32_16x16x32_f16 v[52:55], v[174:177], v[182:185], v[52:55]
	v_mfma_f32_16x16x32_f16 v[40:43], v[166:169], v[190:193], v[40:43]
	v_mfma_f32_16x16x32_f16 v[36:39], v[174:177], v[190:193], v[36:39]
	v_mfma_f32_16x16x32_f16 v[24:27], v[166:169], v[220:223], v[24:27]
	v_mfma_f32_16x16x32_f16 v[20:23], v[174:177], v[220:223], v[20:23]
	v_mfma_f32_16x16x32_f16 v[8:11], v[166:169], v[228:231], v[8:11]
	v_mfma_f32_16x16x32_f16 v[4:7], v[174:177], v[228:231], v[4:7]
	s_setprio 0
	s_barrier
; #define PG8_STAGE(bufoff, gbase, voff) do { _Pragma("unroll") for (int _i = 0; _i < 2; ++_i) \
;         __builtin_amdgcn_global_load_lds((const unsigned*)((const char*)(gbase) + (voff)[_i]), (LAS unsigned*)(lds + (bufoff) + ldsw + _i * 8192), 16, 0, 0); } while (0)
; #define PG8_LDA(dst, b, h) do { _Pragma("unroll") for (int m = 0; m < 4; ++m) _Pragma("unroll") for (int k = 0; k < 2; ++k) dst[m][k] = *(const LAS half8*)(lds + PG8_SA(b, h) + aoff + m * 2048 + k * 1024); } while (0)
; #define PG8_LDB(dst, b, h) do { _Pragma("unroll") for (int n = 0; n < 2; ++n) _Pragma("unroll") for (int k = 0; k < 2; ++k) dst[n][k] = *(const LAS half8*)(lds + PG8_SB(b, h) + boff + n * 2048 + k * 1024); } while (0)
; #define PG8_MMA(ai, bj, At, Bt) do { __builtin_amdgcn_s_setprio(1); _Pragma("unroll") for (int m = 0; m < 4; ++m) _Pragma("unroll") for (int n = 0; n < 2; ++n) _Pragma("unroll") for (int k = 0; k < 2; ++k) \
;         acc[ai][bj][m][n] = __builtin_amdgcn_mfma_f32_16x16x32_f16(Bt[n][k], At[m][k], acc[ai][bj][m][n], 0, 0, 0); __builtin_amdgcn_s_setprio(0); } while (0)
; template <class Epi, class Sched, bool ALIGN_EPI = false, bool SP2 = false>
; __device__ __forceinline__ void gemm_phase(LAS unsigned char* lds, const Gemm g, const Sched& S, const Epi& E) {
;     ...
;             if constexpr (SP2) {
;             PG8_LDB(B0, 0, 0); PG8_LDB(B1, 0, 1); PG8_SCHED; PG8_LDA(At, 0, 0); PG8_STAGE(PG8_SA(1, 1), a1 + hstepA, voffA);
;             PG8_WAIT_V(8); PG8_WAIT_L(0); PG8_BAR; PG8_MMA(0, 0, At, B0); PG8_MMA(0, 1, At, B1); PG8_BAR; PG8_SCHED;
;             PG8_LDA(At, 0, 1); PG8_STAGE(PG8_SB(0, 0), b2, voffB); PG8_STAGE(PG8_SB(0, 1), b2 + hstepB, voffB); PG8_STAGE(PG8_SA(0, 0), a2, voffA);
;             PG8_WAIT_V(8); PG8_WAIT_L(0); PG8_BAR; PG8_MMA(1, 0, At, B0); PG8_MMA(1, 1, At, B1); PG8_BAR; PG8_SCHED;
;             PG8_LDB(B0, 1, 0); PG8_LDB(B1, 1, 1); PG8_SCHED; PG8_LDA(At, 1, 0); PG8_STAGE(PG8_SA(0, 1), a2 + hstepA, voffA);
;             PG8_WAIT_V(8); PG8_WAIT_L(0); PG8_BAR; PG8_MMA(0, 0, At, B0); PG8_MMA(0, 1, At, B1); PG8_BAR; PG8_SCHED;
;             PG8_LDA(At, 1, 1); PG8_STAGE(PG8_SB(1, 0), b3, voffB); PG8_STAGE(PG8_SB(1, 1), b3 + hstepB, voffB); PG8_STAGE(PG8_SA(1, 0), a3, voffA);
;             PG8_WAIT_V(8); PG8_WAIT_L(0); PG8_BAR; PG8_MMA(1, 0, At, B0); PG8_MMA(1, 1, At, B1); PG8_BAR; PG8_SCHED;
;     ...
;         if constexpr (ALIGN_EPI) { if (wr == 0) PG8_BAR; }
	s_add_i32 s63, 0, 0x18000
	v_add_u32_e32 v145, s63, v143
	s_add_i32 s64, 0, 0x1c000
	ds_read_b128 v[146:149], v145
	ds_read_b128 v[150:153], v145 offset:1024
	ds_read_b128 v[154:157], v145 offset:2048
	ds_read_b128 v[158:161], v145 offset:3072
	v_add_u32_e32 v145, s64, v143
	ds_read_b128 v[162:165], v145
	ds_read_b128 v[166:169], v145 offset:1024
	ds_read_b128 v[170:173], v145 offset:2048
	ds_read_b128 v[174:177], v145 offset:3072
	s_add_u32 s16, s16, 0x20000
	s_addc_u32 s17, s17, 0
	s_mov_b32 m0, s37
	v_lshl_add_u64 v[234:235], s[16:17], 0, v[136:137]
	ds_read_b128 v[178:181], v144 offset:32768
	ds_read_b128 v[182:185], v144 offset:33792
	ds_read_b128 v[186:189], v144 offset:34816
	ds_read_b128 v[190:193], v144 offset:35840
	ds_read_b128 v[204:207], v144 offset:36864
	ds_read_b128 v[220:223], v144 offset:37888
	ds_read_b128 v[224:227], v144 offset:38912
	ds_read_b128 v[228:231], v144 offset:39936
	global_load_lds_dwordx4 v[234:235], off
	v_lshl_add_u64 v[234:235], s[16:17], 0, v[134:135]
	s_mov_b32 m0, s38
	s_nop 0
	global_load_lds_dwordx4 v[234:235], off
	s_waitcnt vmcnt(8)
	s_waitcnt lgkmcnt(0)
	s_setprio 1
	s_barrier
	v_mfma_f32_16x16x32_f16 v[128:131], v[146:149], v[178:181], v[128:131]
	v_mfma_f32_16x16x32_f16 v[124:127], v[154:157], v[178:181], v[124:127]
	v_mfma_f32_16x16x32_f16 v[112:115], v[146:149], v[186:189], v[112:115]
	v_mfma_f32_16x16x32_f16 v[108:111], v[154:157], v[186:189], v[108:111]
	v_mfma_f32_16x16x32_f16 v[96:99], v[146:149], v[204:207], v[96:99]
	v_mfma_f32_16x16x32_f16 v[92:95], v[154:157], v[204:207], v[92:95]
	v_mfma_f32_16x16x32_f16 v[80:83], v[146:149], v[224:227], v[80:83]
	v_mfma_f32_16x16x32_f16 v[76:79], v[154:157], v[224:227], v[76:79]
	v_mfma_f32_16x16x32_f16 v[128:131], v[150:153], v[182:185], v[128:131]
	v_mfma_f32_16x16x32_f16 v[124:127], v[158:161], v[182:185], v[124:127]
	v_mfma_f32_16x16x32_f16 v[112:115], v[150:153], v[190:193], v[112:115]
	v_mfma_f32_16x16x32_f16 v[108:111], v[158:161], v[190:193], v[108:111]
	v_mfma_f32_16x16x32_f16 v[96:99], v[150:153], v[220:223], v[96:99]
	v_mfma_f32_16x16x32_f16 v[92:95], v[158:161], v[220:223], v[92:95]
	v_mfma_f32_16x16x32_f16 v[80:83], v[150:153], v[228:231], v[80:83]
	v_mfma_f32_16x16x32_f16 v[76:79], v[158:161], v[228:231], v[76:79]
	v_mfma_f32_16x16x32_f16 v[120:123], v[162:165], v[178:181], v[120:123]
	v_mfma_f32_16x16x32_f16 v[116:119], v[170:173], v[178:181], v[116:119]
	v_mfma_f32_16x16x32_f16 v[104:107], v[162:165], v[186:189], v[104:107]
	v_mfma_f32_16x16x32_f16 v[100:103], v[170:173], v[186:189], v[100:103]
	v_mfma_f32_16x16x32_f16 v[88:91], v[162:165], v[204:207], v[88:91]
	v_mfma_f32_16x16x32_f16 v[84:87], v[170:173], v[204:207], v[84:87]
	v_mfma_f32_16x16x32_f16 v[72:75], v[162:165], v[224:227], v[72:75]
	v_mfma_f32_16x16x32_f16 v[68:71], v[170:173], v[224:227], v[68:71]
	v_mfma_f32_16x16x32_f16 v[120:123], v[166:169], v[182:185], v[120:123]
	v_mfma_f32_16x16x32_f16 v[116:119], v[174:177], v[182:185], v[116:119]
	v_mfma_f32_16x16x32_f16 v[104:107], v[166:169], v[190:193], v[104:107]
	v_mfma_f32_16x16x32_f16 v[100:103], v[174:177], v[190:193], v[100:103]
	v_mfma_f32_16x16x32_f16 v[88:91], v[166:169], v[220:223], v[88:91]
	v_mfma_f32_16x16x32_f16 v[84:87], v[174:177], v[220:223], v[84:87]
	v_mfma_f32_16x16x32_f16 v[72:75], v[166:169], v[228:231], v[72:75]
	v_mfma_f32_16x16x32_f16 v[68:71], v[174:177], v[228:231], v[68:71]
	s_setprio 0
	s_barrier
	s_add_i32 s16, s63, s24
	v_lshl_add_u64 v[194:195], v[194:195], 0, s[96:97]
	s_mov_b32 m0, s16
	ds_read_b128 v[178:181], v144 offset:49152
	ds_read_b128 v[182:185], v144 offset:50176
	ds_read_b128 v[186:189], v144 offset:51200
	ds_read_b128 v[190:193], v144 offset:52224
	ds_read_b128 v[204:207], v144 offset:53248
	ds_read_b128 v[220:223], v144 offset:54272
	ds_read_b128 v[224:227], v144 offset:55296
	ds_read_b128 v[228:231], v144 offset:56320
	global_load_lds_dwordx4 v[194:195], off
	s_add_i32 m0, s16, 0x2000
	s_add_u32 s14, s14, 0x20080
	v_lshl_add_u64 v[194:195], v[196:197], 0, s[96:97]
	s_addc_u32 s15, s15, 0
	s_add_i32 s16, s64, s24
	global_load_lds_dwordx4 v[194:195], off
	v_lshl_add_u64 v[194:195], s[14:15], 0, v[2:3]
	s_mov_b32 m0, s16
	s_nop 0
	global_load_lds_dwordx4 v[194:195], off
	v_lshl_add_u64 v[194:195], s[14:15], 0, v[132:133]
	s_add_i32 m0, s16, 0x2000
	s_nop 0
	global_load_lds_dwordx4 v[194:195], off
	v_lshl_add_u64 v[194:195], v[208:209], 0, s[96:97]
	s_mov_b32 m0, s39
	s_nop 0
	global_load_lds_dwordx4 v[194:195], off
	v_lshl_add_u64 v[194:195], v[232:233], 0, s[96:97]
	s_mov_b32 m0, s57
	s_nop 0
	global_load_lds_dwordx4 v[194:195], off
	s_waitcnt vmcnt(8)
	s_waitcnt lgkmcnt(0)
	s_setprio 1
	s_barrier
	v_mfma_f32_16x16x32_f16 v[64:67], v[146:149], v[178:181], v[64:67]
	v_mfma_f32_16x16x32_f16 v[60:63], v[154:157], v[178:181], v[60:63]
	v_mfma_f32_16x16x32_f16 v[48:51], v[146:149], v[186:189], v[48:51]
	v_mfma_f32_16x16x32_f16 v[44:47], v[154:157], v[186:189], v[44:47]
	v_mfma_f32_16x16x32_f16 v[32:35], v[146:149], v[204:207], v[32:35]
	v_mfma_f32_16x16x32_f16 v[28:31], v[154:157], v[204:207], v[28:31]
	v_mfma_f32_16x16x32_f16 v[16:19], v[146:149], v[224:227], v[16:19]
	v_mfma_f32_16x16x32_f16 v[12:15], v[154:157], v[224:227], v[12:15]
	v_mfma_f32_16x16x32_f16 v[64:67], v[150:153], v[182:185], v[64:67]
	v_mfma_f32_16x16x32_f16 v[60:63], v[158:161], v[182:185], v[60:63]
	v_mfma_f32_16x16x32_f16 v[48:51], v[150:153], v[190:193], v[48:51]
	v_mfma_f32_16x16x32_f16 v[44:47], v[158:161], v[190:193], v[44:47]
	v_mfma_f32_16x16x32_f16 v[32:35], v[150:153], v[220:223], v[32:35]
	v_mfma_f32_16x16x32_f16 v[28:31], v[158:161], v[220:223], v[28:31]
	v_mfma_f32_16x16x32_f16 v[16:19], v[150:153], v[228:231], v[16:19]
	v_mfma_f32_16x16x32_f16 v[12:15], v[158:161], v[228:231], v[12:15]
	v_mfma_f32_16x16x32_f16 v[56:59], v[162:165], v[178:181], v[56:59]
	v_mfma_f32_16x16x32_f16 v[52:55], v[170:173], v[178:181], v[52:55]
	v_mfma_f32_16x16x32_f16 v[40:43], v[162:165], v[186:189], v[40:43]
	v_mfma_f32_16x16x32_f16 v[36:39], v[170:173], v[186:189], v[36:39]
	v_mfma_f32_16x16x32_f16 v[24:27], v[162:165], v[204:207], v[24:27]
	v_mfma_f32_16x16x32_f16 v[20:23], v[170:173], v[204:207], v[20:23]
	v_mfma_f32_16x16x32_f16 v[8:11], v[162:165], v[224:227], v[8:11]
	v_mfma_f32_16x16x32_f16 v[4:7], v[170:173], v[224:227], v[4:7]
	v_mfma_f32_16x16x32_f16 v[56:59], v[166:169], v[182:185], v[56:59]
	v_mfma_f32_16x16x32_f16 v[52:55], v[174:177], v[182:185], v[52:55]
	v_mfma_f32_16x16x32_f16 v[40:43], v[166:169], v[190:193], v[40:43]
	v_mfma_f32_16x16x32_f16 v[36:39], v[174:177], v[190:193], v[36:39]
	v_mfma_f32_16x16x32_f16 v[24:27], v[166:169], v[220:223], v[24:27]
	v_mfma_f32_16x16x32_f16 v[20:23], v[174:177], v[220:223], v[20:23]
	v_mfma_f32_16x16x32_f16 v[8:11], v[166:169], v[228:231], v[8:11]
	v_mfma_f32_16x16x32_f16 v[4:7], v[174:177], v[228:231], v[4:7]
	s_setprio 0
	s_barrier
	s_add_i32 s62, s62, 2
	s_add_u32 s12, s12, 0x100
	s_addc_u32 s13, s13, 0
	s_cmp_gt_u32 s62, 5
	s_cbranch_scc0 .LBB0_2239
	s_cmpk_lt_u32 s2, 0x100
	s_cbranch_scc0 .LBB0_2242
	s_barrier

; #define PG8_STAGE(bufoff, gbase, voff) do { _Pragma("unroll") for (int _i = 0; _i < 2; ++_i) \
;         __builtin_amdgcn_global_load_lds((const unsigned*)((const char*)(gbase) + (voff)[_i]), (LAS unsigned*)(lds + (bufoff) + ldsw + _i * 8192), 16, 0, 0); } while (0)
; #define PG8_LDA(dst, b, h) do { _Pragma("unroll") for (int m = 0; m < 4; ++m) _Pragma("unroll") for (int k = 0; k < 2; ++k) dst[m][k] = *(const LAS half8*)(lds + PG8_SA(b, h) + aoff + m * 2048 + k * 1024); } while (0)
; #define PG8_LDB(dst, b, h) do { _Pragma("unroll") for (int n = 0; n < 2; ++n) _Pragma("unroll") for (int k = 0; k < 2; ++k) dst[n][k] = *(const LAS half8*)(lds + PG8_SB(b, h) + boff + n * 2048 + k * 1024); } while (0)
; template <class Epi, class Sched, bool ALIGN_EPI = false, bool SP2 = false>
; __device__ __forceinline__ void gemm_phase(LAS unsigned char* lds, const Gemm g, const Sched& S, const Epi& E) {
;     ...
;         for (int t = 0; t < nt; t += 2) {
;             const bool last = (t == nt - 2);
;             const char* a1 = cA + (size_t)(t + 1) * kstep;
;             const char* a2 = last ? nA : cA + (size_t)(t + 2) * kstep; const char* b2 = last ? nB : cB + (size_t)(t + 2) * kstep;
;             const char* a3 = a2 + kstep; const char* b3 = b2 + kstep;
;             if (last && has_next) S.a_ready(nxt);
;             if constexpr (SP2) {
;             PG8_LDB(B0, 0, 0); PG8_LDB(B1, 0, 1); PG8_SCHED; PG8_LDA(At, 0, 0); PG8_STAGE(PG8_SA(1, 1), a1 + hstepA, voffA);
;             PG8_WAIT_V(8); PG8_WAIT_L(0); PG8_BAR; PG8_MMA(0, 0, At, B0); PG8_MMA(0, 1, At, B1); PG8_BAR; PG8_SCHED;
;             PG8_LDA(At, 0, 1); PG8_STAGE(PG8_SB(0, 0), b2, voffB); PG8_STAGE(PG8_SB(0, 1), b2 + hstepB, voffB); PG8_STAGE(PG8_SA(0, 0), a2, voffA);
;             PG8_WAIT_V(8); PG8_WAIT_L(0); PG8_BAR; PG8_MMA(1, 0, At, B0); PG8_MMA(1, 1, At, B1); PG8_BAR; PG8_SCHED;
;             PG8_LDB(B0, 1, 0); PG8_LDB(B1, 1, 1); PG8_SCHED; PG8_LDA(At, 1, 0); PG8_STAGE(PG8_SA(0, 1), a2 + hstepA, voffA);
;             PG8_WAIT_V(8); PG8_WAIT_L(0); PG8_BAR; PG8_MMA(0, 0, At, B0); PG8_MMA(0, 1, At, B1); PG8_BAR; PG8_SCHED;
;             PG8_LDA(At, 1, 1); PG8_STAGE(PG8_SB(1, 0), b3, voffB); PG8_STAGE(PG8_SB(1, 1), b3 + hstepB, voffB); PG8_STAGE(PG8_SA(1, 0), a3, voffA);
;             PG8_WAIT_V(8); PG8_WAIT_L(0); PG8_BAR; PG8_MMA(1, 0, At, B0); PG8_MMA(1, 1, At, B1); PG8_BAR; PG8_SCHED;
.LBB0_5097:
	s_add_i32 s69, s12, 2
	s_add_u32 s70, s10, 0x80
	s_addc_u32 s13, s11, 0
	s_add_i32 s80, 0, 0x10000
	s_cmp_eq_u32 s61, s12
	s_cselect_b32 s13, s9, s13
	s_cselect_b32 s12, s8, s70
	v_add_u32_e32 v142, s80, v144
	s_cselect_b32 s71, s39, s68
	s_cselect_b32 s70, s38, s67
	s_add_i32 s81, 0, 0x14000
	ds_read_b128 v[138:141], v142
	ds_read_b128 v[148:151], v142 offset:1024
	ds_read_b128 v[152:155], v142 offset:2048
	ds_read_b128 v[156:159], v142 offset:3072
	v_add_u32_e32 v142, s81, v144
	ds_read_b128 v[160:163], v142
	ds_read_b128 v[164:167], v142 offset:1024
	ds_read_b128 v[168:171], v142 offset:2048
	ds_read_b128 v[172:175], v142 offset:3072
	v_lshl_add_u64 v[142:143], s[10:11], 0, v[134:135]
	s_add_i32 m0, s16, 0xc000
	ds_read_b128 v[176:179], v146
	ds_read_b128 v[180:183], v146 offset:1024
	ds_read_b128 v[184:187], v146 offset:2048
	ds_read_b128 v[188:191], v146 offset:3072
	ds_read_b128 v[192:195], v146 offset:4096
	ds_read_b128 v[204:207], v146 offset:5120
	ds_read_b128 v[220:223], v146 offset:6144
	ds_read_b128 v[224:227], v146 offset:7168
	global_load_lds_dwordx4 v[142:143], off
	v_lshl_add_u64 v[142:143], s[10:11], 0, v[136:137]
	s_add_i32 m0, s16, 0xe000
	s_nop 0
	global_load_lds_dwordx4 v[142:143], off
	s_waitcnt vmcnt(8)
	s_waitcnt lgkmcnt(0)
	s_setprio 1
	s_barrier
	v_mfma_f32_16x16x32_f16 v[128:131], v[138:141], v[176:179], v[128:131]
	v_mfma_f32_16x16x32_f16 v[124:127], v[152:155], v[176:179], v[124:127]
	v_mfma_f32_16x16x32_f16 v[112:115], v[138:141], v[184:187], v[112:115]
	v_mfma_f32_16x16x32_f16 v[108:111], v[152:155], v[184:187], v[108:111]
	v_mfma_f32_16x16x32_f16 v[96:99], v[138:141], v[192:195], v[96:99]
	v_mfma_f32_16x16x32_f16 v[92:95], v[152:155], v[192:195], v[92:95]
	v_mfma_f32_16x16x32_f16 v[80:83], v[138:141], v[220:223], v[80:83]
	v_mfma_f32_16x16x32_f16 v[76:79], v[152:155], v[220:223], v[76:79]
	v_mfma_f32_16x16x32_f16 v[128:131], v[148:151], v[180:183], v[128:131]
	v_mfma_f32_16x16x32_f16 v[124:127], v[156:159], v[180:183], v[124:127]
	v_mfma_f32_16x16x32_f16 v[112:115], v[148:151], v[188:191], v[112:115]
	v_mfma_f32_16x16x32_f16 v[108:111], v[156:159], v[188:191], v[108:111]
	v_mfma_f32_16x16x32_f16 v[96:99], v[148:151], v[204:207], v[96:99]
	v_mfma_f32_16x16x32_f16 v[92:95], v[156:159], v[204:207], v[92:95]
	v_mfma_f32_16x16x32_f16 v[80:83], v[148:151], v[224:227], v[80:83]
	v_mfma_f32_16x16x32_f16 v[76:79], v[156:159], v[224:227], v[76:79]
	v_mfma_f32_16x16x32_f16 v[120:123], v[160:163], v[176:179], v[120:123]
	v_mfma_f32_16x16x32_f16 v[116:119], v[168:171], v[176:179], v[116:119]
	v_mfma_f32_16x16x32_f16 v[104:107], v[160:163], v[184:187], v[104:107]
	v_mfma_f32_16x16x32_f16 v[100:103], v[168:171], v[184:187], v[100:103]
	v_mfma_f32_16x16x32_f16 v[88:91], v[160:163], v[192:195], v[88:91]
	v_mfma_f32_16x16x32_f16 v[84:87], v[168:171], v[192:195], v[84:87]
	v_mfma_f32_16x16x32_f16 v[72:75], v[160:163], v[220:223], v[72:75]
	v_mfma_f32_16x16x32_f16 v[68:71], v[168:171], v[220:223], v[68:71]
	v_mfma_f32_16x16x32_f16 v[120:123], v[164:167], v[180:183], v[120:123]
	v_mfma_f32_16x16x32_f16 v[116:119], v[172:175], v[180:183], v[116:119]
	v_mfma_f32_16x16x32_f16 v[104:107], v[164:167], v[188:191], v[104:107]
	v_mfma_f32_16x16x32_f16 v[100:103], v[172:175], v[188:191], v[100:103]
	v_mfma_f32_16x16x32_f16 v[88:91], v[164:167], v[204:207], v[88:91]
	v_mfma_f32_16x16x32_f16 v[84:87], v[172:175], v[204:207], v[84:87]
	v_mfma_f32_16x16x32_f16 v[72:75], v[164:167], v[224:227], v[72:75]
	v_mfma_f32_16x16x32_f16 v[68:71], v[172:175], v[224:227], v[68:71]
	s_setprio 0
	s_barrier
	s_add_i32 s80, s80, s15
	v_lshl_add_u64 v[142:143], s[70:71], 0, v[2:3]
	s_mov_b32 m0, s80
	ds_read_b128 v[176:179], v146 offset:16384
	ds_read_b128 v[180:183], v146 offset:17408
	ds_read_b128 v[184:187], v146 offset:18432
	ds_read_b128 v[188:191], v146 offset:19456
	ds_read_b128 v[192:195], v146 offset:20480
	ds_read_b128 v[204:207], v146 offset:21504
	ds_read_b128 v[220:223], v146 offset:22528
	ds_read_b128 v[224:227], v146 offset:23552
	global_load_lds_dwordx4 v[142:143], off
	s_add_i32 m0, s80, 0x2000
	v_lshl_add_u64 v[196:197], s[70:71], 0, v[132:133]
	s_add_u32 s70, s70, s2
	s_addc_u32 s71, s71, 0
	s_add_i32 s80, s81, s15
	global_load_lds_dwordx4 v[196:197], off
	v_lshl_add_u64 v[208:209], s[70:71], 0, v[2:3]
	s_mov_b32 m0, s80
	v_lshl_add_u64 v[228:229], s[70:71], 0, v[132:133]
	global_load_lds_dwordx4 v[208:209], off
	s_add_i32 m0, s80, 0x2000
	v_lshl_add_u64 v[230:231], s[12:13], 0, v[2:3]
	global_load_lds_dwordx4 v[228:229], off
	s_mov_b32 m0, s16
	v_lshl_add_u64 v[232:233], s[12:13], 0, v[132:133]
	global_load_lds_dwordx4 v[230:231], off
	s_mov_b32 m0, s17
	s_nop 0
	global_load_lds_dwordx4 v[232:233], off
	s_waitcnt vmcnt(8)
	s_waitcnt lgkmcnt(0)
	s_setprio 1
	s_barrier
; #define PG8_STAGE(bufoff, gbase, voff) do { _Pragma("unroll") for (int _i = 0; _i < 2; ++_i) \
;         __builtin_amdgcn_global_load_lds((const unsigned*)((const char*)(gbase) + (voff)[_i]), (LAS unsigned*)(lds + (bufoff) + ldsw + _i * 8192), 16, 0, 0); } while (0)
; #define PG8_LDA(dst, b, h) do { _Pragma("unroll") for (int m = 0; m < 4; ++m) _Pragma("unroll") for (int k = 0; k < 2; ++k) dst[m][k] = *(const LAS half8*)(lds + PG8_SA(b, h) + aoff + m * 2048 + k * 1024); } while (0)
; #define PG8_LDB(dst, b, h) do { _Pragma("unroll") for (int n = 0; n < 2; ++n) _Pragma("unroll") for (int k = 0; k < 2; ++k) dst[n][k] = *(const LAS half8*)(lds + PG8_SB(b, h) + boff + n * 2048 + k * 1024); } while (0)
; #define PG8_MMA(ai, bj, At, Bt) do { __builtin_amdgcn_s_setprio(1); _Pragma("unroll") for (int m = 0; m < 4; ++m) _Pragma("unroll") for (int n = 0; n < 2; ++n) _Pragma("unroll") for (int k = 0; k < 2; ++k) \
;         acc[ai][bj][m][n] = __builtin_amdgcn_mfma_f32_16x16x32_f16(Bt[n][k], At[m][k], acc[ai][bj][m][n], 0, 0, 0); __builtin_amdgcn_s_setprio(0); } while (0)
; #define PG8_BAR __builtin_amdgcn_s_barrier()
; template <class Epi, class Sched, bool ALIGN_EPI = false, bool SP2 = false>
; __device__ __forceinline__ void gemm_phase(LAS unsigned char* lds, const Gemm g, const Sched& S, const Epi& E) {
;     ...
;             if constexpr (SP2) {
;             PG8_LDB(B0, 0, 0); PG8_LDB(B1, 0, 1); PG8_SCHED; PG8_LDA(At, 0, 0); PG8_STAGE(PG8_SA(1, 1), a1 + hstepA, voffA);
;             PG8_WAIT_V(8); PG8_WAIT_L(0); PG8_BAR; PG8_MMA(0, 0, At, B0); PG8_MMA(0, 1, At, B1); PG8_BAR; PG8_SCHED;
;             PG8_LDA(At, 0, 1); PG8_STAGE(PG8_SB(0, 0), b2, voffB); PG8_STAGE(PG8_SB(0, 1), b2 + hstepB, voffB); PG8_STAGE(PG8_SA(0, 0), a2, voffA);
;             PG8_WAIT_V(8); PG8_WAIT_L(0); PG8_BAR; PG8_MMA(1, 0, At, B0); PG8_MMA(1, 1, At, B1); PG8_BAR; PG8_SCHED;
;             PG8_LDB(B0, 1, 0); PG8_LDB(B1, 1, 1); PG8_SCHED; PG8_LDA(At, 1, 0); PG8_STAGE(PG8_SA(0, 1), a2 + hstepA, voffA);
;             PG8_WAIT_V(8); PG8_WAIT_L(0); PG8_BAR; PG8_MMA(0, 0, At, B0); PG8_MMA(0, 1, At, B1); PG8_BAR; PG8_SCHED;
;             PG8_LDA(At, 1, 1); PG8_STAGE(PG8_SB(1, 0), b3, voffB); PG8_STAGE(PG8_SB(1, 1), b3 + hstepB, voffB); PG8_STAGE(PG8_SA(1, 0), a3, voffA);
;             PG8_WAIT_V(8); PG8_WAIT_L(0); PG8_BAR; PG8_MMA(1, 0, At, B0); PG8_MMA(1, 1, At, B1); PG8_BAR; PG8_SCHED;
	v_mfma_f32_16x16x32_f16 v[64:67], v[138:141], v[176:179], v[64:67]
	v_mfma_f32_16x16x32_f16 v[60:63], v[152:155], v[176:179], v[60:63]
	v_mfma_f32_16x16x32_f16 v[48:51], v[138:141], v[184:187], v[48:51]
	v_mfma_f32_16x16x32_f16 v[44:47], v[152:155], v[184:187], v[44:47]
	v_mfma_f32_16x16x32_f16 v[32:35], v[138:141], v[192:195], v[32:35]
	v_mfma_f32_16x16x32_f16 v[28:31], v[152:155], v[192:195], v[28:31]
	v_mfma_f32_16x16x32_f16 v[16:19], v[138:141], v[220:223], v[16:19]
	v_mfma_f32_16x16x32_f16 v[12:15], v[152:155], v[220:223], v[12:15]
	v_mfma_f32_16x16x32_f16 v[64:67], v[148:151], v[180:183], v[64:67]
	v_mfma_f32_16x16x32_f16 v[60:63], v[156:159], v[180:183], v[60:63]
	v_mfma_f32_16x16x32_f16 v[48:51], v[148:151], v[188:191], v[48:51]
	v_mfma_f32_16x16x32_f16 v[44:47], v[156:159], v[188:191], v[44:47]
	v_mfma_f32_16x16x32_f16 v[32:35], v[148:151], v[204:207], v[32:35]
	v_mfma_f32_16x16x32_f16 v[28:31], v[156:159], v[204:207], v[28:31]
	v_mfma_f32_16x16x32_f16 v[16:19], v[148:151], v[224:227], v[16:19]
	v_mfma_f32_16x16x32_f16 v[12:15], v[156:159], v[224:227], v[12:15]
	v_mfma_f32_16x16x32_f16 v[56:59], v[160:163], v[176:179], v[56:59]
	v_mfma_f32_16x16x32_f16 v[52:55], v[168:171], v[176:179], v[52:55]
	v_mfma_f32_16x16x32_f16 v[40:43], v[160:163], v[184:187], v[40:43]
	v_mfma_f32_16x16x32_f16 v[36:39], v[168:171], v[184:187], v[36:39]
	v_mfma_f32_16x16x32_f16 v[24:27], v[160:163], v[192:195], v[24:27]
	v_mfma_f32_16x16x32_f16 v[20:23], v[168:171], v[192:195], v[20:23]
	v_mfma_f32_16x16x32_f16 v[8:11], v[160:163], v[220:223], v[8:11]
	v_mfma_f32_16x16x32_f16 v[4:7], v[168:171], v[220:223], v[4:7]
	v_mfma_f32_16x16x32_f16 v[56:59], v[164:167], v[180:183], v[56:59]
	v_mfma_f32_16x16x32_f16 v[52:55], v[172:175], v[180:183], v[52:55]
	v_mfma_f32_16x16x32_f16 v[40:43], v[164:167], v[188:191], v[40:43]
	v_mfma_f32_16x16x32_f16 v[36:39], v[172:175], v[188:191], v[36:39]
	v_mfma_f32_16x16x32_f16 v[24:27], v[164:167], v[204:207], v[24:27]
	v_mfma_f32_16x16x32_f16 v[20:23], v[172:175], v[204:207], v[20:23]
	v_mfma_f32_16x16x32_f16 v[8:11], v[164:167], v[224:227], v[8:11]
	v_mfma_f32_16x16x32_f16 v[4:7], v[172:175], v[224:227], v[4:7]
	s_setprio 0
	s_barrier
	s_add_i32 s70, 0, 0x18000
	v_add_u32_e32 v147, s70, v144
	s_add_i32 s71, 0, 0x1c000
	ds_read_b128 v[138:141], v147
	ds_read_b128 v[148:151], v147 offset:1024
	ds_read_b128 v[152:155], v147 offset:2048
	ds_read_b128 v[156:159], v147 offset:3072
	v_add_u32_e32 v147, s71, v144
	ds_read_b128 v[160:163], v147
	ds_read_b128 v[164:167], v147 offset:1024
	ds_read_b128 v[168:171], v147 offset:2048
	ds_read_b128 v[172:175], v147 offset:3072
	s_add_u32 s12, s12, s2
	s_addc_u32 s13, s13, 0
	s_mov_b32 m0, s22
	v_lshl_add_u64 v[234:235], s[12:13], 0, v[2:3]
	ds_read_b128 v[176:179], v146 offset:32768
	ds_read_b128 v[180:183], v146 offset:33792
	ds_read_b128 v[184:187], v146 offset:34816
	ds_read_b128 v[188:191], v146 offset:35840
	ds_read_b128 v[192:195], v146 offset:36864
	ds_read_b128 v[204:207], v146 offset:37888
	ds_read_b128 v[220:223], v146 offset:38912
	ds_read_b128 v[224:227], v146 offset:39936
	global_load_lds_dwordx4 v[234:235], off
	v_lshl_add_u64 v[234:235], s[12:13], 0, v[132:133]
	s_mov_b32 m0, s23
	s_nop 0
	global_load_lds_dwordx4 v[234:235], off
	s_waitcnt vmcnt(8)
	s_waitcnt lgkmcnt(0)
	s_setprio 1
	s_barrier
	v_mfma_f32_16x16x32_f16 v[128:131], v[138:141], v[176:179], v[128:131]
	v_mfma_f32_16x16x32_f16 v[124:127], v[152:155], v[176:179], v[124:127]
	v_mfma_f32_16x16x32_f16 v[112:115], v[138:141], v[184:187], v[112:115]
	v_mfma_f32_16x16x32_f16 v[108:111], v[152:155], v[184:187], v[108:111]
	v_mfma_f32_16x16x32_f16 v[96:99], v[138:141], v[192:195], v[96:99]
	v_mfma_f32_16x16x32_f16 v[92:95], v[152:155], v[192:195], v[92:95]
	v_mfma_f32_16x16x32_f16 v[80:83], v[138:141], v[220:223], v[80:83]
	v_mfma_f32_16x16x32_f16 v[76:79], v[152:155], v[220:223], v[76:79]
	v_mfma_f32_16x16x32_f16 v[128:131], v[148:151], v[180:183], v[128:131]
	v_mfma_f32_16x16x32_f16 v[124:127], v[156:159], v[180:183], v[124:127]
	v_mfma_f32_16x16x32_f16 v[112:115], v[148:151], v[188:191], v[112:115]
	v_mfma_f32_16x16x32_f16 v[108:111], v[156:159], v[188:191], v[108:111]
	v_mfma_f32_16x16x32_f16 v[96:99], v[148:151], v[204:207], v[96:99]
	v_mfma_f32_16x16x32_f16 v[92:95], v[156:159], v[204:207], v[92:95]
	v_mfma_f32_16x16x32_f16 v[80:83], v[148:151], v[224:227], v[80:83]
	v_mfma_f32_16x16x32_f16 v[76:79], v[156:159], v[224:227], v[76:79]
	v_mfma_f32_16x16x32_f16 v[120:123], v[160:163], v[176:179], v[120:123]
	v_mfma_f32_16x16x32_f16 v[116:119], v[168:171], v[176:179], v[116:119]
	v_mfma_f32_16x16x32_f16 v[104:107], v[160:163], v[184:187], v[104:107]
	v_mfma_f32_16x16x32_f16 v[100:103], v[168:171], v[184:187], v[100:103]
	v_mfma_f32_16x16x32_f16 v[88:91], v[160:163], v[192:195], v[88:91]
	v_mfma_f32_16x16x32_f16 v[84:87], v[168:171], v[192:195], v[84:87]
	v_mfma_f32_16x16x32_f16 v[72:75], v[160:163], v[220:223], v[72:75]
	v_mfma_f32_16x16x32_f16 v[68:71], v[168:171], v[220:223], v[68:71]
	v_mfma_f32_16x16x32_f16 v[120:123], v[164:167], v[180:183], v[120:123]
	v_mfma_f32_16x16x32_f16 v[116:119], v[172:175], v[180:183], v[116:119]
	v_mfma_f32_16x16x32_f16 v[104:107], v[164:167], v[188:191], v[104:107]
	v_mfma_f32_16x16x32_f16 v[100:103], v[172:175], v[188:191], v[100:103]
	v_mfma_f32_16x16x32_f16 v[88:91], v[164:167], v[204:207], v[88:91]
	v_mfma_f32_16x16x32_f16 v[84:87], v[172:175], v[204:207], v[84:87]
	v_mfma_f32_16x16x32_f16 v[72:75], v[164:167], v[224:227], v[72:75]
	v_mfma_f32_16x16x32_f16 v[68:71], v[172:175], v[224:227], v[68:71]
	s_setprio 0
	s_barrier
; #define PG8_STAGE(bufoff, gbase, voff) do { _Pragma("unroll") for (int _i = 0; _i < 2; ++_i) \
;         __builtin_amdgcn_global_load_lds((const unsigned*)((const char*)(gbase) + (voff)[_i]), (LAS unsigned*)(lds + (bufoff) + ldsw + _i * 8192), 16, 0, 0); } while (0)
; #define PG8_LDA(dst, b, h) do { _Pragma("unroll") for (int m = 0; m < 4; ++m) _Pragma("unroll") for (int k = 0; k < 2; ++k) dst[m][k] = *(const LAS half8*)(lds + PG8_SA(b, h) + aoff + m * 2048 + k * 1024); } while (0)
; #define PG8_LDB(dst, b, h) do { _Pragma("unroll") for (int n = 0; n < 2; ++n) _Pragma("unroll") for (int k = 0; k < 2; ++k) dst[n][k] = *(const LAS half8*)(lds + PG8_SB(b, h) + boff + n * 2048 + k * 1024); } while (0)
; #define PG8_MMA(ai, bj, At, Bt) do { __builtin_amdgcn_s_setprio(1); _Pragma("unroll") for (int m = 0; m < 4; ++m) _Pragma("unroll") for (int n = 0; n < 2; ++n) _Pragma("unroll") for (int k = 0; k < 2; ++k) \
;         acc[ai][bj][m][n] = __builtin_amdgcn_mfma_f32_16x16x32_f16(Bt[n][k], At[m][k], acc[ai][bj][m][n], 0, 0, 0); __builtin_amdgcn_s_setprio(0); } while (0)
; template <class Epi, class Sched, bool ALIGN_EPI = false, bool SP2 = false>
; __device__ __forceinline__ void gemm_phase(LAS unsigned char* lds, const Gemm g, const Sched& S, const Epi& E) {
;     ...
;             if constexpr (SP2) {
;             PG8_LDB(B0, 0, 0); PG8_LDB(B1, 0, 1); PG8_SCHED; PG8_LDA(At, 0, 0); PG8_STAGE(PG8_SA(1, 1), a1 + hstepA, voffA);
;             PG8_WAIT_V(8); PG8_WAIT_L(0); PG8_BAR; PG8_MMA(0, 0, At, B0); PG8_MMA(0, 1, At, B1); PG8_BAR; PG8_SCHED;
;             PG8_LDA(At, 0, 1); PG8_STAGE(PG8_SB(0, 0), b2, voffB); PG8_STAGE(PG8_SB(0, 1), b2 + hstepB, voffB); PG8_STAGE(PG8_SA(0, 0), a2, voffA);
;             PG8_WAIT_V(8); PG8_WAIT_L(0); PG8_BAR; PG8_MMA(1, 0, At, B0); PG8_MMA(1, 1, At, B1); PG8_BAR; PG8_SCHED;
;             PG8_LDB(B0, 1, 0); PG8_LDB(B1, 1, 1); PG8_SCHED; PG8_LDA(At, 1, 0); PG8_STAGE(PG8_SA(0, 1), a2 + hstepA, voffA);
;             PG8_WAIT_V(8); PG8_WAIT_L(0); PG8_BAR; PG8_MMA(0, 0, At, B0); PG8_MMA(0, 1, At, B1); PG8_BAR; PG8_SCHED;
;             PG8_LDA(At, 1, 1); PG8_STAGE(PG8_SB(1, 0), b3, voffB); PG8_STAGE(PG8_SB(1, 1), b3 + hstepB, voffB); PG8_STAGE(PG8_SA(1, 0), a3, voffA);
;             PG8_WAIT_V(8); PG8_WAIT_L(0); PG8_BAR; PG8_MMA(1, 0, At, B0); PG8_MMA(1, 1, At, B1); PG8_BAR; PG8_SCHED;
;     ...
;         if constexpr (ALIGN_EPI) { if (wr == 0) PG8_BAR; }
	s_add_i32 s12, s70, s15
	v_lshl_add_u64 v[142:143], v[142:143], 0, s[96:97]
	s_mov_b32 m0, s12
	ds_read_b128 v[176:179], v146 offset:49152
	ds_read_b128 v[180:183], v146 offset:50176
	ds_read_b128 v[184:187], v146 offset:51200
	ds_read_b128 v[188:191], v146 offset:52224
	ds_read_b128 v[192:195], v146 offset:53248
	ds_read_b128 v[204:207], v146 offset:54272
	ds_read_b128 v[220:223], v146 offset:55296
	ds_read_b128 v[224:227], v146 offset:56320
	global_load_lds_dwordx4 v[142:143], off
	v_lshl_add_u64 v[142:143], v[196:197], 0, s[96:97]
	s_add_i32 m0, s12, 0x2000
	s_add_i32 s12, s71, s15
	global_load_lds_dwordx4 v[142:143], off
	v_lshl_add_u64 v[142:143], v[208:209], 0, s[96:97]
	s_mov_b32 m0, s12
	s_nop 0
	global_load_lds_dwordx4 v[142:143], off
	v_lshl_add_u64 v[142:143], v[228:229], 0, s[96:97]
	s_add_i32 m0, s12, 0x2000
	s_nop 0
	global_load_lds_dwordx4 v[142:143], off
	v_lshl_add_u64 v[142:143], v[230:231], 0, s[96:97]
	s_mov_b32 m0, s25
	s_nop 0
	global_load_lds_dwordx4 v[142:143], off
	v_lshl_add_u64 v[142:143], v[232:233], 0, s[96:97]
	s_mov_b32 m0, s37
	s_nop 0
	global_load_lds_dwordx4 v[142:143], off
	s_waitcnt vmcnt(8)
	s_waitcnt lgkmcnt(0)
	s_setprio 1
	s_barrier
	v_mfma_f32_16x16x32_f16 v[64:67], v[138:141], v[176:179], v[64:67]
	v_mfma_f32_16x16x32_f16 v[60:63], v[152:155], v[176:179], v[60:63]
	v_mfma_f32_16x16x32_f16 v[48:51], v[138:141], v[184:187], v[48:51]
	v_mfma_f32_16x16x32_f16 v[44:47], v[152:155], v[184:187], v[44:47]
	v_mfma_f32_16x16x32_f16 v[32:35], v[138:141], v[192:195], v[32:35]
	v_mfma_f32_16x16x32_f16 v[28:31], v[152:155], v[192:195], v[28:31]
	v_mfma_f32_16x16x32_f16 v[16:19], v[138:141], v[220:223], v[16:19]
	v_mfma_f32_16x16x32_f16 v[12:15], v[152:155], v[220:223], v[12:15]
	v_mfma_f32_16x16x32_f16 v[64:67], v[148:151], v[180:183], v[64:67]
	v_mfma_f32_16x16x32_f16 v[60:63], v[156:159], v[180:183], v[60:63]
	v_mfma_f32_16x16x32_f16 v[48:51], v[148:151], v[188:191], v[48:51]
	v_mfma_f32_16x16x32_f16 v[44:47], v[156:159], v[188:191], v[44:47]
	v_mfma_f32_16x16x32_f16 v[32:35], v[148:151], v[204:207], v[32:35]
	v_mfma_f32_16x16x32_f16 v[28:31], v[156:159], v[204:207], v[28:31]
	v_mfma_f32_16x16x32_f16 v[16:19], v[148:151], v[224:227], v[16:19]
	v_mfma_f32_16x16x32_f16 v[12:15], v[156:159], v[224:227], v[12:15]
	v_mfma_f32_16x16x32_f16 v[56:59], v[160:163], v[176:179], v[56:59]
	v_mfma_f32_16x16x32_f16 v[52:55], v[168:171], v[176:179], v[52:55]
	v_mfma_f32_16x16x32_f16 v[40:43], v[160:163], v[184:187], v[40:43]
	v_mfma_f32_16x16x32_f16 v[36:39], v[168:171], v[184:187], v[36:39]
	v_mfma_f32_16x16x32_f16 v[24:27], v[160:163], v[192:195], v[24:27]
	v_mfma_f32_16x16x32_f16 v[20:23], v[168:171], v[192:195], v[20:23]
	v_mfma_f32_16x16x32_f16 v[8:11], v[160:163], v[220:223], v[8:11]
	v_mfma_f32_16x16x32_f16 v[4:7], v[168:171], v[220:223], v[4:7]
	v_mfma_f32_16x16x32_f16 v[56:59], v[164:167], v[180:183], v[56:59]
	v_mfma_f32_16x16x32_f16 v[52:55], v[172:175], v[180:183], v[52:55]
	v_mfma_f32_16x16x32_f16 v[40:43], v[164:167], v[188:191], v[40:43]
	v_mfma_f32_16x16x32_f16 v[36:39], v[172:175], v[188:191], v[36:39]
	v_mfma_f32_16x16x32_f16 v[24:27], v[164:167], v[204:207], v[24:27]
	v_mfma_f32_16x16x32_f16 v[20:23], v[172:175], v[204:207], v[20:23]
	v_mfma_f32_16x16x32_f16 v[8:11], v[164:167], v[224:227], v[8:11]
	v_mfma_f32_16x16x32_f16 v[4:7], v[172:175], v[224:227], v[4:7]
	s_setprio 0
	s_barrier
	s_add_u32 s10, s10, 0x100
	s_addc_u32 s11, s11, 0
	s_add_u32 s67, s67, 0x100
	s_addc_u32 s68, s68, 0
	s_cmp_ge_u32 s69, s24
	s_mov_b32 s12, s69
	s_cbranch_scc0 .LBB0_5097
	s_and_b64 vcc, exec, s[56:57]
	s_cbranch_vccz .LBB0_5100
	s_barrier

; #define PG8_STAGE(bufoff, gbase, voff) do { _Pragma("unroll") for (int _i = 0; _i < 2; ++_i) \
;         __builtin_amdgcn_global_load_lds((const unsigned*)((const char*)(gbase) + (voff)[_i]), (LAS unsigned*)(lds + (bufoff) + ldsw + _i * 8192), 16, 0, 0); } while (0)
; #define PG8_LDA(dst, b, h) do { _Pragma("unroll") for (int m = 0; m < 4; ++m) _Pragma("unroll") for (int k = 0; k < 2; ++k) dst[m][k] = *(const LAS half8*)(lds + PG8_SA(b, h) + aoff + m * 2048 + k * 1024); } while (0)
; #define PG8_LDB(dst, b, h) do { _Pragma("unroll") for (int n = 0; n < 2; ++n) _Pragma("unroll") for (int k = 0; k < 2; ++k) dst[n][k] = *(const LAS half8*)(lds + PG8_SB(b, h) + boff + n * 2048 + k * 1024); } while (0)
; template <class Epi, class Sched, bool ALIGN_EPI = false, bool SP2 = false>
; __device__ __forceinline__ void gemm_phase(LAS unsigned char* lds, const Gemm g, const Sched& S, const Epi& E) {
;     ...
;         for (int t = 0; t < nt; t += 2) {
;             const bool last = (t == nt - 2);
;             const char* a1 = cA + (size_t)(t + 1) * kstep;
;             const char* a2 = last ? nA : cA + (size_t)(t + 2) * kstep; const char* b2 = last ? nB : cB + (size_t)(t + 2) * kstep;
;             const char* a3 = a2 + kstep; const char* b3 = b2 + kstep;
;             if (last && has_next) S.a_ready(nxt);
;             if constexpr (SP2) {
;             PG8_LDB(B0, 0, 0); PG8_LDB(B1, 0, 1); PG8_SCHED; PG8_LDA(At, 0, 0); PG8_STAGE(PG8_SA(1, 1), a1 + hstepA, voffA);
;             PG8_WAIT_V(8); PG8_WAIT_L(0); PG8_BAR; PG8_MMA(0, 0, At, B0); PG8_MMA(0, 1, At, B1); PG8_BAR; PG8_SCHED;
;             PG8_LDA(At, 0, 1); PG8_STAGE(PG8_SB(0, 0), b2, voffB); PG8_STAGE(PG8_SB(0, 1), b2 + hstepB, voffB); PG8_STAGE(PG8_SA(0, 0), a2, voffA);
;             PG8_WAIT_V(8); PG8_WAIT_L(0); PG8_BAR; PG8_MMA(1, 0, At, B0); PG8_MMA(1, 1, At, B1); PG8_BAR; PG8_SCHED;
;             PG8_LDB(B0, 1, 0); PG8_LDB(B1, 1, 1); PG8_SCHED; PG8_LDA(At, 1, 0); PG8_STAGE(PG8_SA(0, 1), a2 + hstepA, voffA);
;             PG8_WAIT_V(8); PG8_WAIT_L(0); PG8_BAR; PG8_MMA(0, 0, At, B0); PG8_MMA(0, 1, At, B1); PG8_BAR; PG8_SCHED;
;             PG8_LDA(At, 1, 1); PG8_STAGE(PG8_SB(1, 0), b3, voffB); PG8_STAGE(PG8_SB(1, 1), b3 + hstepB, voffB); PG8_STAGE(PG8_SA(1, 0), a3, voffA);
;             PG8_WAIT_V(8); PG8_WAIT_L(0); PG8_BAR; PG8_MMA(1, 0, At, B0); PG8_MMA(1, 1, At, B1); PG8_BAR; PG8_SCHED;
.LBB0_5227:
	s_add_i32 s41, s41, 2
	s_add_u32 s16, s8, s22
	s_addc_u32 s17, s9, s23
	s_add_u32 s16, s16, 0x100
	s_addc_u32 s17, s17, 0
	s_add_u32 s80, s13, s22
	s_addc_u32 s81, s40, s23
	s_add_i32 s86, 0, 0x10000
	s_cmp_eq_u32 s68, s22
	s_cselect_b32 s17, s15, s17
	s_cselect_b32 s16, s14, s16
	s_cselect_b32 s81, s11, s81
	s_cselect_b32 s80, s10, s80
	s_add_i32 s88, 0, 0x14000
	v_add_u32_e32 v160, s86, v146
	v_add_u32_e32 v176, s88, v146
	ds_read_b128 v[148:151], v160
	ds_read_b128 v[152:155], v160 offset:1024
	ds_read_b128 v[156:159], v160 offset:2048
	ds_read_b128 v[160:163], v160 offset:3072
	ds_read_b128 v[164:167], v176
	ds_read_b128 v[168:171], v176 offset:1024
	ds_read_b128 v[172:175], v176 offset:2048
	ds_read_b128 v[176:179], v176 offset:3072
	v_lshl_add_u64 v[196:197], v[142:143], 0, s[22:23]
	s_add_i32 m0, s61, 0xc000
	ds_read_b128 v[180:183], v147
	ds_read_b128 v[184:187], v147 offset:1024
	ds_read_b128 v[188:191], v147 offset:2048
	ds_read_b128 v[192:195], v147 offset:3072
	ds_read_b128 v[206:209], v147 offset:4096
	ds_read_b128 v[220:223], v147 offset:5120
	ds_read_b128 v[224:227], v147 offset:6144
	ds_read_b128 v[228:231], v147 offset:7168
	global_load_lds_dwordx4 v[196:197], off
	v_lshl_add_u64 v[196:197], v[144:145], 0, s[22:23]
	s_add_i32 m0, s61, 0xe000
	s_nop 0
	global_load_lds_dwordx4 v[196:197], off
	s_waitcnt vmcnt(8)
	s_waitcnt lgkmcnt(0)
	s_setprio 1
	s_barrier
	v_mfma_f32_16x16x32_f16 v[128:131], v[148:151], v[180:183], v[128:131]
	v_mfma_f32_16x16x32_f16 v[124:127], v[156:159], v[180:183], v[124:127]
	v_mfma_f32_16x16x32_f16 v[112:115], v[148:151], v[188:191], v[112:115]
	v_mfma_f32_16x16x32_f16 v[108:111], v[156:159], v[188:191], v[108:111]
	v_mfma_f32_16x16x32_f16 v[96:99], v[148:151], v[206:209], v[96:99]
	v_mfma_f32_16x16x32_f16 v[92:95], v[156:159], v[206:209], v[92:95]
	v_mfma_f32_16x16x32_f16 v[80:83], v[148:151], v[224:227], v[80:83]
	v_mfma_f32_16x16x32_f16 v[76:79], v[156:159], v[224:227], v[76:79]
	v_mfma_f32_16x16x32_f16 v[128:131], v[152:155], v[184:187], v[128:131]
	v_mfma_f32_16x16x32_f16 v[124:127], v[160:163], v[184:187], v[124:127]
	v_mfma_f32_16x16x32_f16 v[112:115], v[152:155], v[192:195], v[112:115]
	v_mfma_f32_16x16x32_f16 v[108:111], v[160:163], v[192:195], v[108:111]
	v_mfma_f32_16x16x32_f16 v[96:99], v[152:155], v[220:223], v[96:99]
	v_mfma_f32_16x16x32_f16 v[92:95], v[160:163], v[220:223], v[92:95]
	v_mfma_f32_16x16x32_f16 v[80:83], v[152:155], v[228:231], v[80:83]
	v_mfma_f32_16x16x32_f16 v[76:79], v[160:163], v[228:231], v[76:79]
	v_mfma_f32_16x16x32_f16 v[120:123], v[164:167], v[180:183], v[120:123]
	v_mfma_f32_16x16x32_f16 v[116:119], v[172:175], v[180:183], v[116:119]
	v_mfma_f32_16x16x32_f16 v[104:107], v[164:167], v[188:191], v[104:107]
	v_mfma_f32_16x16x32_f16 v[100:103], v[172:175], v[188:191], v[100:103]
	v_mfma_f32_16x16x32_f16 v[88:91], v[164:167], v[206:209], v[88:91]
	v_mfma_f32_16x16x32_f16 v[84:87], v[172:175], v[206:209], v[84:87]
	v_mfma_f32_16x16x32_f16 v[72:75], v[164:167], v[224:227], v[72:75]
	v_mfma_f32_16x16x32_f16 v[68:71], v[172:175], v[224:227], v[68:71]
	v_mfma_f32_16x16x32_f16 v[120:123], v[168:171], v[184:187], v[120:123]
	v_mfma_f32_16x16x32_f16 v[116:119], v[176:179], v[184:187], v[116:119]
	v_mfma_f32_16x16x32_f16 v[104:107], v[168:171], v[192:195], v[104:107]
	v_mfma_f32_16x16x32_f16 v[100:103], v[176:179], v[192:195], v[100:103]
	v_mfma_f32_16x16x32_f16 v[88:91], v[168:171], v[220:223], v[88:91]
	v_mfma_f32_16x16x32_f16 v[84:87], v[176:179], v[220:223], v[84:87]
	v_mfma_f32_16x16x32_f16 v[72:75], v[168:171], v[228:231], v[72:75]
	v_mfma_f32_16x16x32_f16 v[68:71], v[176:179], v[228:231], v[68:71]
	s_setprio 0
	s_barrier
	s_add_i32 s86, s86, s59
	v_lshl_add_u64 v[196:197], s[80:81], 0, v[2:3]
	s_mov_b32 m0, s86
	ds_read_b128 v[180:183], v147 offset:16384
	ds_read_b128 v[184:187], v147 offset:17408
	ds_read_b128 v[188:191], v147 offset:18432
	ds_read_b128 v[192:195], v147 offset:19456
	ds_read_b128 v[206:209], v147 offset:20480
	ds_read_b128 v[220:223], v147 offset:21504
	ds_read_b128 v[224:227], v147 offset:22528
	ds_read_b128 v[228:231], v147 offset:23552
	global_load_lds_dwordx4 v[196:197], off
	s_add_i32 m0, s86, 0x2000
	v_lshl_add_u64 v[232:233], s[80:81], 0, v[132:133]
	s_add_u32 s80, s80, s2
	s_addc_u32 s81, s81, 0
	s_add_i32 s86, s88, s59
	global_load_lds_dwordx4 v[232:233], off
	v_lshl_add_u64 v[234:235], s[80:81], 0, v[2:3]
	s_mov_b32 m0, s86
	v_lshl_add_u64 v[236:237], s[80:81], 0, v[132:133]
	global_load_lds_dwordx4 v[234:235], off
	s_add_i32 m0, s86, 0x2000
	v_lshl_add_u64 v[240:241], s[16:17], 0, v[136:137]
	global_load_lds_dwordx4 v[236:237], off
	s_mov_b32 m0, s61
	v_lshl_add_u64 v[242:243], s[16:17], 0, v[134:135]
	global_load_lds_dwordx4 v[240:241], off
	s_mov_b32 m0, s62
	s_nop 0
	global_load_lds_dwordx4 v[242:243], off
	s_waitcnt vmcnt(8)
	s_waitcnt lgkmcnt(0)
	s_setprio 1
	s_barrier
; #define PG8_STAGE(bufoff, gbase, voff) do { _Pragma("unroll") for (int _i = 0; _i < 2; ++_i) \
;         __builtin_amdgcn_global_load_lds((const unsigned*)((const char*)(gbase) + (voff)[_i]), (LAS unsigned*)(lds + (bufoff) + ldsw + _i * 8192), 16, 0, 0); } while (0)
; #define PG8_LDA(dst, b, h) do { _Pragma("unroll") for (int m = 0; m < 4; ++m) _Pragma("unroll") for (int k = 0; k < 2; ++k) dst[m][k] = *(const LAS half8*)(lds + PG8_SA(b, h) + aoff + m * 2048 + k * 1024); } while (0)
; #define PG8_LDB(dst, b, h) do { _Pragma("unroll") for (int n = 0; n < 2; ++n) _Pragma("unroll") for (int k = 0; k < 2; ++k) dst[n][k] = *(const LAS half8*)(lds + PG8_SB(b, h) + boff + n * 2048 + k * 1024); } while (0)
; #define PG8_MMA(ai, bj, At, Bt) do { __builtin_amdgcn_s_setprio(1); _Pragma("unroll") for (int m = 0; m < 4; ++m) _Pragma("unroll") for (int n = 0; n < 2; ++n) _Pragma("unroll") for (int k = 0; k < 2; ++k) \
;         acc[ai][bj][m][n] = __builtin_amdgcn_mfma_f32_16x16x32_f16(Bt[n][k], At[m][k], acc[ai][bj][m][n], 0, 0, 0); __builtin_amdgcn_s_setprio(0); } while (0)
; #define PG8_BAR __builtin_amdgcn_s_barrier()
; template <class Epi, class Sched, bool ALIGN_EPI = false, bool SP2 = false>
; __device__ __forceinline__ void gemm_phase(LAS unsigned char* lds, const Gemm g, const Sched& S, const Epi& E) {
;     ...
;             if constexpr (SP2) {
;             PG8_LDB(B0, 0, 0); PG8_LDB(B1, 0, 1); PG8_SCHED; PG8_LDA(At, 0, 0); PG8_STAGE(PG8_SA(1, 1), a1 + hstepA, voffA);
;             PG8_WAIT_V(8); PG8_WAIT_L(0); PG8_BAR; PG8_MMA(0, 0, At, B0); PG8_MMA(0, 1, At, B1); PG8_BAR; PG8_SCHED;
;             PG8_LDA(At, 0, 1); PG8_STAGE(PG8_SB(0, 0), b2, voffB); PG8_STAGE(PG8_SB(0, 1), b2 + hstepB, voffB); PG8_STAGE(PG8_SA(0, 0), a2, voffA);
;             PG8_WAIT_V(8); PG8_WAIT_L(0); PG8_BAR; PG8_MMA(1, 0, At, B0); PG8_MMA(1, 1, At, B1); PG8_BAR; PG8_SCHED;
;             PG8_LDB(B0, 1, 0); PG8_LDB(B1, 1, 1); PG8_SCHED; PG8_LDA(At, 1, 0); PG8_STAGE(PG8_SA(0, 1), a2 + hstepA, voffA);
;             PG8_WAIT_V(8); PG8_WAIT_L(0); PG8_BAR; PG8_MMA(0, 0, At, B0); PG8_MMA(0, 1, At, B1); PG8_BAR; PG8_SCHED;
;             PG8_LDA(At, 1, 1); PG8_STAGE(PG8_SB(1, 0), b3, voffB); PG8_STAGE(PG8_SB(1, 1), b3 + hstepB, voffB); PG8_STAGE(PG8_SA(1, 0), a3, voffA);
;             PG8_WAIT_V(8); PG8_WAIT_L(0); PG8_BAR; PG8_MMA(1, 0, At, B0); PG8_MMA(1, 1, At, B1); PG8_BAR; PG8_SCHED;
	v_mfma_f32_16x16x32_f16 v[64:67], v[148:151], v[180:183], v[64:67]
	v_mfma_f32_16x16x32_f16 v[60:63], v[156:159], v[180:183], v[60:63]
	v_mfma_f32_16x16x32_f16 v[48:51], v[148:151], v[188:191], v[48:51]
	v_mfma_f32_16x16x32_f16 v[44:47], v[156:159], v[188:191], v[44:47]
	v_mfma_f32_16x16x32_f16 v[32:35], v[148:151], v[206:209], v[32:35]
	v_mfma_f32_16x16x32_f16 v[28:31], v[156:159], v[206:209], v[28:31]
	v_mfma_f32_16x16x32_f16 v[16:19], v[148:151], v[224:227], v[16:19]
	v_mfma_f32_16x16x32_f16 v[12:15], v[156:159], v[224:227], v[12:15]
	v_mfma_f32_16x16x32_f16 v[64:67], v[152:155], v[184:187], v[64:67]
	v_mfma_f32_16x16x32_f16 v[60:63], v[160:163], v[184:187], v[60:63]
	v_mfma_f32_16x16x32_f16 v[48:51], v[152:155], v[192:195], v[48:51]
	v_mfma_f32_16x16x32_f16 v[44:47], v[160:163], v[192:195], v[44:47]
	v_mfma_f32_16x16x32_f16 v[32:35], v[152:155], v[220:223], v[32:35]
	v_mfma_f32_16x16x32_f16 v[28:31], v[160:163], v[220:223], v[28:31]
	v_mfma_f32_16x16x32_f16 v[16:19], v[152:155], v[228:231], v[16:19]
	v_mfma_f32_16x16x32_f16 v[12:15], v[160:163], v[228:231], v[12:15]
	v_mfma_f32_16x16x32_f16 v[56:59], v[164:167], v[180:183], v[56:59]
	v_mfma_f32_16x16x32_f16 v[52:55], v[172:175], v[180:183], v[52:55]
	v_mfma_f32_16x16x32_f16 v[40:43], v[164:167], v[188:191], v[40:43]
	v_mfma_f32_16x16x32_f16 v[36:39], v[172:175], v[188:191], v[36:39]
	v_mfma_f32_16x16x32_f16 v[24:27], v[164:167], v[206:209], v[24:27]
	v_mfma_f32_16x16x32_f16 v[20:23], v[172:175], v[206:209], v[20:23]
	v_mfma_f32_16x16x32_f16 v[8:11], v[164:167], v[224:227], v[8:11]
	v_mfma_f32_16x16x32_f16 v[4:7], v[172:175], v[224:227], v[4:7]
	v_mfma_f32_16x16x32_f16 v[56:59], v[168:171], v[184:187], v[56:59]
	v_mfma_f32_16x16x32_f16 v[52:55], v[176:179], v[184:187], v[52:55]
	v_mfma_f32_16x16x32_f16 v[40:43], v[168:171], v[192:195], v[40:43]
	v_mfma_f32_16x16x32_f16 v[36:39], v[176:179], v[192:195], v[36:39]
	v_mfma_f32_16x16x32_f16 v[24:27], v[168:171], v[220:223], v[24:27]
	v_mfma_f32_16x16x32_f16 v[20:23], v[176:179], v[220:223], v[20:23]
	v_mfma_f32_16x16x32_f16 v[8:11], v[168:171], v[228:231], v[8:11]
	v_mfma_f32_16x16x32_f16 v[4:7], v[176:179], v[228:231], v[4:7]
	s_setprio 0
	s_barrier
	s_add_i32 s80, 0, 0x18000
	s_add_i32 s81, 0, 0x1c000
	v_add_u32_e32 v160, s80, v146
	v_add_u32_e32 v176, s81, v146
	ds_read_b128 v[148:151], v160
	ds_read_b128 v[152:155], v160 offset:1024
	ds_read_b128 v[156:159], v160 offset:2048
	ds_read_b128 v[160:163], v160 offset:3072
	ds_read_b128 v[164:167], v176
	ds_read_b128 v[168:171], v176 offset:1024
	ds_read_b128 v[172:175], v176 offset:2048
	ds_read_b128 v[176:179], v176 offset:3072
	s_add_u32 s16, s16, s2
	s_addc_u32 s17, s17, 0
	s_mov_b32 m0, s63
	v_lshl_add_u64 v[244:245], s[16:17], 0, v[136:137]
	ds_read_b128 v[180:183], v147 offset:32768
	ds_read_b128 v[184:187], v147 offset:33792
	ds_read_b128 v[188:191], v147 offset:34816
	ds_read_b128 v[192:195], v147 offset:35840
	ds_read_b128 v[206:209], v147 offset:36864
	ds_read_b128 v[220:223], v147 offset:37888
	ds_read_b128 v[224:227], v147 offset:38912
	ds_read_b128 v[228:231], v147 offset:39936
	global_load_lds_dwordx4 v[244:245], off
	v_lshl_add_u64 v[244:245], s[16:17], 0, v[134:135]
	s_mov_b32 m0, s64
	s_nop 0
	global_load_lds_dwordx4 v[244:245], off
	s_waitcnt vmcnt(8)
	s_waitcnt lgkmcnt(0)
	s_setprio 1
	s_barrier
	v_mfma_f32_16x16x32_f16 v[128:131], v[148:151], v[180:183], v[128:131]
	v_mfma_f32_16x16x32_f16 v[124:127], v[156:159], v[180:183], v[124:127]
	v_mfma_f32_16x16x32_f16 v[112:115], v[148:151], v[188:191], v[112:115]
	v_mfma_f32_16x16x32_f16 v[108:111], v[156:159], v[188:191], v[108:111]
	v_mfma_f32_16x16x32_f16 v[96:99], v[148:151], v[206:209], v[96:99]
	v_mfma_f32_16x16x32_f16 v[92:95], v[156:159], v[206:209], v[92:95]
	v_mfma_f32_16x16x32_f16 v[80:83], v[148:151], v[224:227], v[80:83]
	v_mfma_f32_16x16x32_f16 v[76:79], v[156:159], v[224:227], v[76:79]
	v_mfma_f32_16x16x32_f16 v[128:131], v[152:155], v[184:187], v[128:131]
	v_mfma_f32_16x16x32_f16 v[124:127], v[160:163], v[184:187], v[124:127]
	v_mfma_f32_16x16x32_f16 v[112:115], v[152:155], v[192:195], v[112:115]
	v_mfma_f32_16x16x32_f16 v[108:111], v[160:163], v[192:195], v[108:111]
	v_mfma_f32_16x16x32_f16 v[96:99], v[152:155], v[220:223], v[96:99]
	v_mfma_f32_16x16x32_f16 v[92:95], v[160:163], v[220:223], v[92:95]
	v_mfma_f32_16x16x32_f16 v[80:83], v[152:155], v[228:231], v[80:83]
	v_mfma_f32_16x16x32_f16 v[76:79], v[160:163], v[228:231], v[76:79]
	v_mfma_f32_16x16x32_f16 v[120:123], v[164:167], v[180:183], v[120:123]
	v_mfma_f32_16x16x32_f16 v[116:119], v[172:175], v[180:183], v[116:119]
	v_mfma_f32_16x16x32_f16 v[104:107], v[164:167], v[188:191], v[104:107]
	v_mfma_f32_16x16x32_f16 v[100:103], v[172:175], v[188:191], v[100:103]
	v_mfma_f32_16x16x32_f16 v[88:91], v[164:167], v[206:209], v[88:91]
	v_mfma_f32_16x16x32_f16 v[84:87], v[172:175], v[206:209], v[84:87]
	v_mfma_f32_16x16x32_f16 v[72:75], v[164:167], v[224:227], v[72:75]
	v_mfma_f32_16x16x32_f16 v[68:71], v[172:175], v[224:227], v[68:71]
	v_mfma_f32_16x16x32_f16 v[120:123], v[168:171], v[184:187], v[120:123]
	v_mfma_f32_16x16x32_f16 v[116:119], v[176:179], v[184:187], v[116:119]
	v_mfma_f32_16x16x32_f16 v[104:107], v[168:171], v[192:195], v[104:107]
	v_mfma_f32_16x16x32_f16 v[100:103], v[176:179], v[192:195], v[100:103]
	v_mfma_f32_16x16x32_f16 v[88:91], v[168:171], v[220:223], v[88:91]
	v_mfma_f32_16x16x32_f16 v[84:87], v[176:179], v[220:223], v[84:87]
	v_mfma_f32_16x16x32_f16 v[72:75], v[168:171], v[228:231], v[72:75]
	v_mfma_f32_16x16x32_f16 v[68:71], v[176:179], v[228:231], v[68:71]
	s_setprio 0
	s_barrier
; #define PG8_STAGE(bufoff, gbase, voff) do { _Pragma("unroll") for (int _i = 0; _i < 2; ++_i) \
;         __builtin_amdgcn_global_load_lds((const unsigned*)((const char*)(gbase) + (voff)[_i]), (LAS unsigned*)(lds + (bufoff) + ldsw + _i * 8192), 16, 0, 0); } while (0)
; #define PG8_LDA(dst, b, h) do { _Pragma("unroll") for (int m = 0; m < 4; ++m) _Pragma("unroll") for (int k = 0; k < 2; ++k) dst[m][k] = *(const LAS half8*)(lds + PG8_SA(b, h) + aoff + m * 2048 + k * 1024); } while (0)
; #define PG8_LDB(dst, b, h) do { _Pragma("unroll") for (int n = 0; n < 2; ++n) _Pragma("unroll") for (int k = 0; k < 2; ++k) dst[n][k] = *(const LAS half8*)(lds + PG8_SB(b, h) + boff + n * 2048 + k * 1024); } while (0)
; #define PG8_WAIT_V(n) asm volatile("s_waitcnt vmcnt(" #n ")" ::: "memory")
; template <class Epi, class Sched, bool ALIGN_EPI = false, bool SP2 = false>
; __device__ __forceinline__ void gemm_phase(LAS unsigned char* lds, const Gemm g, const Sched& S, const Epi& E) {
;     ...
;             if constexpr (SP2) {
;             PG8_LDB(B0, 0, 0); PG8_LDB(B1, 0, 1); PG8_SCHED; PG8_LDA(At, 0, 0); PG8_STAGE(PG8_SA(1, 1), a1 + hstepA, voffA);
;             PG8_WAIT_V(8); PG8_WAIT_L(0); PG8_BAR; PG8_MMA(0, 0, At, B0); PG8_MMA(0, 1, At, B1); PG8_BAR; PG8_SCHED;
;             PG8_LDA(At, 0, 1); PG8_STAGE(PG8_SB(0, 0), b2, voffB); PG8_STAGE(PG8_SB(0, 1), b2 + hstepB, voffB); PG8_STAGE(PG8_SA(0, 0), a2, voffA);
;             PG8_WAIT_V(8); PG8_WAIT_L(0); PG8_BAR; PG8_MMA(1, 0, At, B0); PG8_MMA(1, 1, At, B1); PG8_BAR; PG8_SCHED;
;             PG8_LDB(B0, 1, 0); PG8_LDB(B1, 1, 1); PG8_SCHED; PG8_LDA(At, 1, 0); PG8_STAGE(PG8_SA(0, 1), a2 + hstepA, voffA);
;             PG8_WAIT_V(8); PG8_WAIT_L(0); PG8_BAR; PG8_MMA(0, 0, At, B0); PG8_MMA(0, 1, At, B1); PG8_BAR; PG8_SCHED;
;             PG8_LDA(At, 1, 1); PG8_STAGE(PG8_SB(1, 0), b3, voffB); PG8_STAGE(PG8_SB(1, 1), b3 + hstepB, voffB); PG8_STAGE(PG8_SA(1, 0), a3, voffA);
;             PG8_WAIT_V(8); PG8_WAIT_L(0); PG8_BAR; PG8_MMA(1, 0, At, B0); PG8_MMA(1, 1, At, B1); PG8_BAR; PG8_SCHED;
;     ...
; #pragma unroll
;         for (int a = 0; a < 2; ++a)
; #pragma unroll
;             for (int b = 0; b < 2; ++b)
; #pragma unroll
;                 for (int m = 0; m < 4; ++m)
; #pragma unroll
;                     for (int n = 0; n < 2; ++n) acc[a][b][m][n] = (f32x4){0.f, 0.f, 0.f, 0.f};
;         cur = nxt; cA = nA; cB = nB; ++ui;
	s_add_i32 s16, s80, s59
	v_lshl_add_u64 v[196:197], v[196:197], 0, s[96:97]
	s_mov_b32 m0, s16
	ds_read_b128 v[180:183], v147 offset:49152
	ds_read_b128 v[184:187], v147 offset:50176
	ds_read_b128 v[188:191], v147 offset:51200
	ds_read_b128 v[192:195], v147 offset:52224
	ds_read_b128 v[206:209], v147 offset:53248
	ds_read_b128 v[220:223], v147 offset:54272
	ds_read_b128 v[224:227], v147 offset:55296
	ds_read_b128 v[228:231], v147 offset:56320
	global_load_lds_dwordx4 v[196:197], off
	v_lshl_add_u64 v[196:197], v[232:233], 0, s[96:97]
	s_add_i32 m0, s16, 0x2000
	s_add_i32 s16, s81, s59
	global_load_lds_dwordx4 v[196:197], off
	v_lshl_add_u64 v[196:197], v[234:235], 0, s[96:97]
	s_mov_b32 m0, s16
	s_nop 0
	global_load_lds_dwordx4 v[196:197], off
	v_lshl_add_u64 v[196:197], v[236:237], 0, s[96:97]
	s_add_i32 m0, s16, 0x2000
	s_nop 0
	global_load_lds_dwordx4 v[196:197], off
	v_lshl_add_u64 v[196:197], v[240:241], 0, s[96:97]
	s_mov_b32 m0, s65
	s_nop 0
	global_load_lds_dwordx4 v[196:197], off
	v_lshl_add_u64 v[196:197], v[242:243], 0, s[96:97]
	s_mov_b32 m0, s66
	s_nop 0
	global_load_lds_dwordx4 v[196:197], off
	s_waitcnt vmcnt(8)
	s_waitcnt lgkmcnt(0)
	s_setprio 1
	s_barrier
	v_mfma_f32_16x16x32_f16 v[64:67], v[148:151], v[180:183], v[64:67]
	v_mfma_f32_16x16x32_f16 v[60:63], v[156:159], v[180:183], v[60:63]
	v_mfma_f32_16x16x32_f16 v[48:51], v[148:151], v[188:191], v[48:51]
	v_mfma_f32_16x16x32_f16 v[44:47], v[156:159], v[188:191], v[44:47]
	v_mfma_f32_16x16x32_f16 v[32:35], v[148:151], v[206:209], v[32:35]
	v_mfma_f32_16x16x32_f16 v[28:31], v[156:159], v[206:209], v[28:31]
	v_mfma_f32_16x16x32_f16 v[16:19], v[148:151], v[224:227], v[16:19]
	v_mfma_f32_16x16x32_f16 v[12:15], v[156:159], v[224:227], v[12:15]
	v_mfma_f32_16x16x32_f16 v[64:67], v[152:155], v[184:187], v[64:67]
	v_mfma_f32_16x16x32_f16 v[60:63], v[160:163], v[184:187], v[60:63]
	v_mfma_f32_16x16x32_f16 v[48:51], v[152:155], v[192:195], v[48:51]
	v_mfma_f32_16x16x32_f16 v[44:47], v[160:163], v[192:195], v[44:47]
	v_mfma_f32_16x16x32_f16 v[32:35], v[152:155], v[220:223], v[32:35]
	v_mfma_f32_16x16x32_f16 v[28:31], v[160:163], v[220:223], v[28:31]
	v_mfma_f32_16x16x32_f16 v[16:19], v[152:155], v[228:231], v[16:19]
	v_mfma_f32_16x16x32_f16 v[12:15], v[160:163], v[228:231], v[12:15]
	v_mfma_f32_16x16x32_f16 v[56:59], v[164:167], v[180:183], v[56:59]
	v_mfma_f32_16x16x32_f16 v[52:55], v[172:175], v[180:183], v[52:55]
	v_mfma_f32_16x16x32_f16 v[40:43], v[164:167], v[188:191], v[40:43]
	v_mfma_f32_16x16x32_f16 v[36:39], v[172:175], v[188:191], v[36:39]
	v_mfma_f32_16x16x32_f16 v[24:27], v[164:167], v[206:209], v[24:27]
	v_mfma_f32_16x16x32_f16 v[20:23], v[172:175], v[206:209], v[20:23]
	v_mfma_f32_16x16x32_f16 v[8:11], v[164:167], v[224:227], v[8:11]
	v_mfma_f32_16x16x32_f16 v[4:7], v[172:175], v[224:227], v[4:7]
	v_mfma_f32_16x16x32_f16 v[56:59], v[168:171], v[184:187], v[56:59]
	v_mfma_f32_16x16x32_f16 v[52:55], v[176:179], v[184:187], v[52:55]
	v_mfma_f32_16x16x32_f16 v[40:43], v[168:171], v[192:195], v[40:43]
	v_mfma_f32_16x16x32_f16 v[36:39], v[176:179], v[192:195], v[36:39]
	v_mfma_f32_16x16x32_f16 v[24:27], v[168:171], v[220:223], v[24:27]
	v_mfma_f32_16x16x32_f16 v[20:23], v[176:179], v[220:223], v[20:23]
	v_mfma_f32_16x16x32_f16 v[8:11], v[168:171], v[228:231], v[8:11]
	v_mfma_f32_16x16x32_f16 v[4:7], v[176:179], v[228:231], v[4:7]
	s_setprio 0
	s_barrier
	s_add_u32 s22, s22, 0x100
	s_addc_u32 s23, s23, 0
	s_cmp_ge_u32 s41, s67
	s_cbranch_scc0 .LBB0_5227
	s_add_u32 s16, s13, 0xffffff00
	s_addc_u32 s17, s40, -1
	s_and_b64 vcc, exec, s[38:39]
	s_cbranch_vccnz .LBB0_5214
	v_mov_b32_e32 v4, 0
	s_mov_b32 s6, s70
	s_mov_b32 s37, s71
	s_mov_b64 s[8:9], s[14:15]
	s_mov_b32 s69, s12
	v_mov_b32_e32 v5, v4
	v_mov_b32_e32 v6, v4
	v_mov_b32_e32 v7, v4
	v_mov_b32_e32 v8, v4
	v_mov_b32_e32 v9, v4
	v_mov_b32_e32 v10, v4
	v_mov_b32_e32 v11, v4
	v_mov_b32_e32 v20, v4
	v_mov_b32_e32 v21, v4
	v_mov_b32_e32 v22, v4
	v_mov_b32_e32 v23, v4
	v_mov_b32_e32 v24, v4
	v_mov_b32_e32 v25, v4
	v_mov_b32_e32 v26, v4
	v_mov_b32_e32 v27, v4
	v_mov_b32_e32 v36, v4
	v_mov_b32_e32 v37, v4
	v_mov_b32_e32 v38, v4
	v_mov_b32_e32 v39, v4
	v_mov_b32_e32 v40, v4
	v_mov_b32_e32 v41, v4
	v_mov_b32_e32 v42, v4
	v_mov_b32_e32 v43, v4
	v_mov_b32_e32 v52, v4
	v_mov_b32_e32 v53, v4
	v_mov_b32_e32 v54, v4
	v_mov_b32_e32 v55, v4
	v_mov_b32_e32 v56, v4
	v_mov_b32_e32 v57, v4
	v_mov_b32_e32 v58, v4
	v_mov_b32_e32 v59, v4
	v_mov_b32_e32 v12, v4
	v_mov_b32_e32 v13, v4
	v_mov_b32_e32 v14, v4
	v_mov_b32_e32 v15, v4
	v_mov_b32_e32 v16, v4
	v_mov_b32_e32 v17, v4
	v_mov_b32_e32 v18, v4
	v_mov_b32_e32 v19, v4
	v_mov_b32_e32 v28, v4
	v_mov_b32_e32 v29, v4
	v_mov_b32_e32 v30, v4
	v_mov_b32_e32 v31, v4
	v_mov_b32_e32 v32, v4
	v_mov_b32_e32 v33, v4
	v_mov_b32_e32 v34, v4
	v_mov_b32_e32 v35, v4
	v_mov_b32_e32 v44, v4
	v_mov_b32_e32 v45, v4
	v_mov_b32_e32 v46, v4
	v_mov_b32_e32 v47, v4
	v_mov_b32_e32 v48, v4
	v_mov_b32_e32 v49, v4
	v_mov_b32_e32 v50, v4
	v_mov_b32_e32 v51, v4
	v_mov_b32_e32 v60, v4
	v_mov_b32_e32 v61, v4
	v_mov_b32_e32 v62, v4
	v_mov_b32_e32 v63, v4
	v_mov_b32_e32 v64, v4
	v_mov_b32_e32 v65, v4
	v_mov_b32_e32 v66, v4
	v_mov_b32_e32 v67, v4
	v_mov_b32_e32 v68, v4
	v_mov_b32_e32 v69, v4
	v_mov_b32_e32 v70, v4
	v_mov_b32_e32 v71, v4
	v_mov_b32_e32 v72, v4
	v_mov_b32_e32 v73, v4
	v_mov_b32_e32 v74, v4
	v_mov_b32_e32 v75, v4
	v_mov_b32_e32 v84, v4
	v_mov_b32_e32 v85, v4
	v_mov_b32_e32 v86, v4
	v_mov_b32_e32 v87, v4
	v_mov_b32_e32 v88, v4
	v_mov_b32_e32 v89, v4
	v_mov_b32_e32 v90, v4
	v_mov_b32_e32 v91, v4
	v_mov_b32_e32 v100, v4
	v_mov_b32_e32 v101, v4
	v_mov_b32_e32 v102, v4
	v_mov_b32_e32 v103, v4
	v_mov_b32_e32 v104, v4
	v_mov_b32_e32 v105, v4
	v_mov_b32_e32 v106, v4
	v_mov_b32_e32 v107, v4
	v_mov_b32_e32 v116, v4
	v_mov_b32_e32 v117, v4
	v_mov_b32_e32 v118, v4
	v_mov_b32_e32 v119, v4
	v_mov_b32_e32 v120, v4
	v_mov_b32_e32 v121, v4
	v_mov_b32_e32 v122, v4
	v_mov_b32_e32 v123, v4
	v_mov_b32_e32 v76, v4
	v_mov_b32_e32 v77, v4
	v_mov_b32_e32 v78, v4
	v_mov_b32_e32 v79, v4
	v_mov_b32_e32 v80, v4
	v_mov_b32_e32 v81, v4
	v_mov_b32_e32 v82, v4
	v_mov_b32_e32 v83, v4
	v_mov_b32_e32 v92, v4
	v_mov_b32_e32 v93, v4
	v_mov_b32_e32 v94, v4
	v_mov_b32_e32 v95, v4
	v_mov_b32_e32 v96, v4
	v_mov_b32_e32 v97, v4
	v_mov_b32_e32 v98, v4
	v_mov_b32_e32 v99, v4
	v_mov_b32_e32 v108, v4
	v_mov_b32_e32 v109, v4
	v_mov_b32_e32 v110, v4
	v_mov_b32_e32 v111, v4
	v_mov_b32_e32 v112, v4
	v_mov_b32_e32 v113, v4
	v_mov_b32_e32 v114, v4
	v_mov_b32_e32 v115, v4
	v_mov_b32_e32 v124, v4
	v_mov_b32_e32 v125, v4
	v_mov_b32_e32 v126, v4
	v_mov_b32_e32 v127, v4
	v_mov_b32_e32 v128, v4
	v_mov_b32_e32 v129, v4
	v_mov_b32_e32 v130, v4
	v_mov_b32_e32 v131, v4
	s_andn2_b64 vcc, exec, s[0:1]
	s_cbranch_vccnz .LBB0_5215
